# per-half barrier thinning in all looped GEMMs: leading half keeps post-MFMA barriers, trailing half keeps pre-MFMA barriers (2 instead of 4 per K-tile)
# baseline (speedup 1.0000x reference)
.LBB0_234:
	s_andn2_b64 vcc, exec, s[14:15]
	s_cbranch_vccnz .LBB0_274
	v_ashrrev_i32_e32 v3, 31, v10
	v_lshrrev_b32_e32 v3, 26, v3
	v_add_u32_e32 v3, v10, v3
	v_ashrrev_i32_e32 v11, 6, v3
	v_bfe_i32 v3, v10, 27, 1
	v_lshlrev_b32_e32 v2, 4, v10
	v_lshrrev_b32_e32 v3, 22, v3
	v_add_u32_e32 v3, v2, v3
	v_and_b32_e32 v3, 0xfffffc00, v3
	v_sub_u32_e32 v3, v2, v3
	v_lshrrev_b32_e32 v4, 4, v3
	v_bitop3_b32 v3, v4, v3, 32 bitop3:0x6c
	v_ashrrev_i32_e32 v5, 31, v3
	v_lshrrev_b32_e32 v5, 26, v5
	v_lshlrev_b32_e32 v4, 3, v11
	v_add_u32_e32 v5, v3, v5
	s_waitcnt lgkmcnt(0)
	s_add_u32 s3, s8, 0xa400000
	v_and_b32_e32 v4, -16, v4
	v_ashrrev_i32_e32 v13, 6, v5
	v_and_b32_e32 v5, 0xc0, v5
	s_addc_u32 s23, s9, 0
	v_add_u32_e32 v4, v13, v4
	v_lshlrev_b32_e32 v6, 5, v11
	v_sub_u32_e32 v3, v3, v5
	v_mov_b32_e32 v5, 1
	s_add_u32 s29, s12, 0x3000000
	v_and_b32_e32 v12, 32, v6
	v_ashrrev_i16_sdwa v3, v5, sext(v3) dst_sel:DWORD dst_unused:UNUSED_PAD src0_sel:DWORD src1_sel:BYTE_0
	v_lshlrev_b32_e32 v6, 1, v4
	v_lshrrev_b32_e32 v7, 2, v4
	v_and_b32_e32 v8, 3, v13
	s_mov_b32 s12, 0xffffe0
	v_bfe_i32 v14, v3, 0, 16
	v_and_b32_e32 v6, 24, v6
	v_and_b32_e32 v7, 4, v7
	v_and_or_b32 v8, v4, s12, v8
	s_movk_i32 s9, 0xb00
	v_add_u32_e32 v3, v12, v14
	v_or3_b32 v6, v8, v7, v6
	v_mul_lo_u32 v4, v4, s9
	v_add_lshl_u32 v194, v3, v4, 1
	v_mul_u32_u24_e32 v4, 0xb00, v6
	v_add_u32_e32 v2, 0x2000, v2
	v_add_lshl_u32 v196, v4, v3, 1
	v_ashrrev_i32_e32 v3, 31, v2
	v_lshrrev_b32_e32 v3, 22, v3
	v_add_u32_e32 v3, v2, v3
	v_ashrrev_i32_e32 v15, 10, v3
	v_mul_i32_i24_e32 v3, 0x400, v15
	v_sub_u32_e32 v2, v2, v3
	v_lshrrev_b32_e32 v3, 4, v2
	v_bitop3_b32 v2, v3, v2, 32 bitop3:0x6c
	v_ashrrev_i32_e32 v4, 31, v2
	v_lshrrev_b32_e32 v4, 26, v4
	v_lshlrev_b32_e32 v3, 3, v15
	v_add_u32_e32 v4, v2, v4
	s_addc_u32 s31, s13, 0
	v_and_b32_e32 v3, -16, v3
	v_ashrrev_i32_e32 v16, 6, v4
	v_lshlrev_b32_e32 v6, 5, v15
	v_and_b32_e32 v4, 0xc0, v4
	s_ashr_i32 s24, s26, 6
	s_ashr_i32 s8, s26, 8
	v_add_u32_e32 v3, v16, v3
	v_and_b32_e32 v17, 32, v6
	v_sub_u32_e32 v2, v2, v4
	v_and_b32_e32 v6, 3, v16
	s_lshl_b32 s52, s24, 10
	s_mul_i32 s13, s68, 0x160000
	v_ashrrev_i16_sdwa v2, v5, sext(v2) dst_sel:DWORD dst_unused:UNUSED_PAD src0_sel:DWORD src1_sel:BYTE_0
	v_lshlrev_b32_e32 v4, 1, v3
	v_lshrrev_b32_e32 v5, 2, v3
	v_and_or_b32 v6, v3, s12, v6
	s_mul_hi_i32 s12, s68, 0x160000
	s_add_u32 s46, s29, s13
	v_bfe_i32 v18, v2, 0, 16
	v_and_b32_e32 v4, 24, v4
	v_and_b32_e32 v5, 4, v5
	s_addc_u32 s47, s31, s12
	s_add_i32 s53, s52, 0
	v_add_u32_e32 v2, v17, v18
	v_or3_b32 v4, v6, v5, v4
	v_mul_lo_u32 v3, v3, s9
	s_add_i32 m0, s53, 0x10000
	v_add_lshl_u32 v198, v2, v3, 1
	v_mul_u32_u24_e32 v3, 0xb00, v4
	global_load_lds_dwordx4 v196, s[46:47]
	s_add_i32 m0, s53, 0x12000
	v_add_lshl_u32 v200, v3, v2, 1
	s_add_u32 s12, s46, 0xb0000
	global_load_lds_dwordx4 v200, s[46:47]
	s_addc_u32 s13, s47, 0
	s_add_i32 m0, s53, 0x14000
	s_mul_i32 s15, s67, 0x160000
	global_load_lds_dwordx4 v196, s[12:13]
	s_add_i32 m0, s53, 0x16000
	s_mul_hi_i32 s14, s67, 0x160000
	s_add_u32 s44, s3, s15
	s_addc_u32 s45, s23, s14
	s_add_i32 s54, s53, 0x2000
	global_load_lds_dwordx4 v200, s[12:13]
	s_mov_b32 m0, s53
	s_add_u32 s12, s44, 0xb0000
	global_load_lds_dwordx4 v194, s[44:45]
	s_mov_b32 m0, s54
	s_addc_u32 s13, s45, 0
	s_add_i32 s55, s53, 0x4000
	global_load_lds_dwordx4 v198, s[44:45]
	s_mov_b32 m0, s55
	s_add_i32 s56, s53, 0x6000
	global_load_lds_dwordx4 v194, s[12:13]
	s_mov_b32 m0, s56
	v_mov_b32_e32 v203, 0
	global_load_lds_dwordx4 v198, s[12:13]
	v_mov_b32_e32 v197, v203
	v_mov_b32_e32 v201, v203
	v_mov_b32_e32 v195, v203
	v_mov_b32_e32 v199, v203
	s_cmp_eq_u32 s8, 1
	s_mov_b32 s57, 0
	v_lshl_add_u64 v[8:9], s[46:47], 0, v[196:197]
	v_lshl_add_u64 v[6:7], s[46:47], 0, v[200:201]
	v_lshl_add_u64 v[2:3], s[44:45], 0, v[194:195]
	s_cselect_b64 s[12:13], -1, 0
	s_cmp_lg_u32 s8, 1
	v_lshl_add_u64 v[4:5], s[44:45], 0, v[198:199]
	s_cbranch_scc1 .LBB0_237
.LBB0_237:
	s_add_u32 s14, s4, 0x6400000
	s_addc_u32 s15, s5, 0
	s_add_u32 s16, s6, 0x20000
	s_addc_u32 s17, s7, 0
	s_lshl_b32 s4, s24, 5
	s_mov_b64 s[24:25], 0x80
	s_and_b32 s42, s4, 0x60
	s_add_i32 m0, s53, 0x18000
	v_lshl_add_u64 v[8:9], v[8:9], 0, s[24:25]
	s_lshl_b32 s6, s8, 13
	s_lshl_b32 s7, s42, 7
	s_waitcnt vmcnt(2)
	s_barrier
	global_load_lds_dwordx4 v[8:9], off
	v_lshl_add_u64 v[6:7], v[6:7], 0, s[24:25]
	s_add_i32 m0, s53, 0x1a000
	s_add_i32 s58, s53, 0x8000
	s_add_i32 s59, s53, 0xa000
	global_load_lds_dwordx4 v[6:7], off
	v_lshl_add_u64 v[2:3], v[2:3], 0, s[24:25]
	s_mov_b32 m0, s58
	s_add_u32 s4, s46, 0xb0080
	global_load_lds_dwordx4 v[2:3], off
	v_lshl_add_u64 v[2:3], v[4:5], 0, s[24:25]
	s_mov_b32 m0, s59
	s_addc_u32 s5, s47, 0
	global_load_lds_dwordx4 v[2:3], off
	s_add_i32 m0, s53, 0x1c000
	v_lshl_add_u64 v[2:3], s[4:5], 0, v[196:197]
	global_load_lds_dwordx4 v[2:3], off
	v_lshl_add_u64 v[2:3], s[4:5], 0, v[200:201]
	s_add_i32 m0, s53, 0x1e000
	s_cmpk_lt_u32 s26, 0x100
	global_load_lds_dwordx4 v[2:3], off
	v_bfe_u32 v3, v10, 4, 2
	v_and_b32_e32 v2, 15, v10
	v_lshlrev_b32_e32 v4, 4, v3
	v_lshl_or_b32 v243, s8, 6, v2
	v_lshl_or_b32 v2, v2, 6, v4
	v_lshlrev_b32_e32 v4, 2, v10
	v_and_b32_e32 v4, 32, v4
	v_bitop3_b32 v6, v2, s6, v4 bitop3:0xde
	v_bitop3_b32 v244, v2, s7, v4 bitop3:0xde
	v_lshl_or_b32 v2, v3, 3, s42
	v_cmp_eq_u32_e64 s[4:5], 0, v3
	v_lshrrev_b32_e32 v3, 1, v11
	v_mul_lo_u32 v4, v13, s9
	s_mov_b32 s8, 0xb000
	v_mad_u64_u32 v[4:5], s[42:43], v3, s8, v[4:5]
	v_lshlrev_b32_e32 v202, 1, v2
	v_or_b32_e32 v3, v4, v12
	v_lshl_add_u64 v[204:205], s[14:15], 0, v[202:203]
	v_add_lshl_u32 v202, v3, v14, 1
	v_lshrrev_b32_e32 v3, 1, v15
	v_mul_lo_u32 v4, v16, s9
	v_mad_u64_u32 v[4:5], s[8:9], v3, s8, v[4:5]
	s_mov_b64 s[6:7], 0xb0080
	s_waitcnt vmcnt(6)
	v_or_b32_e32 v3, v4, v17
	s_cselect_b64 s[26:27], -1, 0
	v_lshl_add_u64 v[206:207], v[202:203], 0, s[6:7]
	v_add_lshl_u32 v202, v3, v18, 1
	s_add_i32 s63, 0, 0x10000
	s_add_i32 s64, 0, 0x14000
	v_mbcnt_lo_u32_b32 v3, -1, 0
	s_ashr_i32 s60, s38, 31
	s_mov_b32 s61, s38
	s_ashr_i32 s62, s2, 31
	v_lshl_add_u64 v[208:209], v[202:203], 0, s[6:7]
	v_add_u32_e32 v245, s63, v244
	v_add_u32_e32 v246, s64, v244
	v_add_u32_e32 v247, 0, v6
	v_mbcnt_hi_u32_b32 v248, -1, v3
	v_lshlrev_b32_e32 v202, 1, v2
	s_barrier
	s_branch .LBB0_240

.LBB0_250:
	s_add_u32 s69, s46, 0x100
	v_mov_b32_e32 v2, 0
	s_addc_u32 s70, s47, 0
	s_mov_b32 s71, -2
	v_mov_b32_e32 v3, v2
	v_mov_b32_e32 v4, v2
	v_mov_b32_e32 v5, v2
	v_mov_b32_e32 v6, v2
	v_mov_b32_e32 v7, v2
	v_mov_b32_e32 v8, v2
	v_mov_b32_e32 v9, v2
	v_mov_b32_e32 v18, v2
	v_mov_b32_e32 v19, v2
	v_mov_b32_e32 v20, v2
	v_mov_b32_e32 v21, v2
	v_mov_b32_e32 v22, v2
	v_mov_b32_e32 v23, v2
	v_mov_b32_e32 v24, v2
	v_mov_b32_e32 v25, v2
	v_mov_b32_e32 v34, v2
	v_mov_b32_e32 v35, v2
	v_mov_b32_e32 v36, v2
	v_mov_b32_e32 v37, v2
	v_mov_b32_e32 v38, v2
	v_mov_b32_e32 v39, v2
	v_mov_b32_e32 v40, v2
	v_mov_b32_e32 v41, v2
	v_mov_b32_e32 v50, v2
	v_mov_b32_e32 v51, v2
	v_mov_b32_e32 v52, v2
	v_mov_b32_e32 v53, v2
	v_mov_b32_e32 v54, v2
	v_mov_b32_e32 v55, v2
	v_mov_b32_e32 v56, v2
	v_mov_b32_e32 v57, v2
	v_mov_b32_e32 v10, v2
	v_mov_b32_e32 v11, v2
	v_mov_b32_e32 v12, v2
	v_mov_b32_e32 v13, v2
	v_mov_b32_e32 v14, v2
	v_mov_b32_e32 v15, v2
	v_mov_b32_e32 v16, v2
	v_mov_b32_e32 v17, v2
	v_mov_b32_e32 v26, v2
	v_mov_b32_e32 v27, v2
	v_mov_b32_e32 v28, v2
	v_mov_b32_e32 v29, v2
	v_mov_b32_e32 v30, v2
	v_mov_b32_e32 v31, v2
	v_mov_b32_e32 v32, v2
	v_mov_b32_e32 v33, v2
	v_mov_b32_e32 v42, v2
	v_mov_b32_e32 v43, v2
	v_mov_b32_e32 v44, v2
	v_mov_b32_e32 v45, v2
	v_mov_b32_e32 v46, v2
	v_mov_b32_e32 v47, v2
	v_mov_b32_e32 v48, v2
	v_mov_b32_e32 v49, v2
	v_mov_b32_e32 v58, v2
	v_mov_b32_e32 v59, v2
	v_mov_b32_e32 v60, v2
	v_mov_b32_e32 v61, v2
	v_mov_b32_e32 v62, v2
	v_mov_b32_e32 v63, v2
	v_mov_b32_e32 v64, v2
	v_mov_b32_e32 v65, v2
	v_mov_b32_e32 v66, v2
	v_mov_b32_e32 v67, v2
	v_mov_b32_e32 v68, v2
	v_mov_b32_e32 v69, v2
	v_mov_b32_e32 v70, v2
	v_mov_b32_e32 v71, v2
	v_mov_b32_e32 v72, v2
	v_mov_b32_e32 v73, v2
	v_mov_b32_e32 v82, v2
	v_mov_b32_e32 v83, v2
	v_mov_b32_e32 v84, v2
	v_mov_b32_e32 v85, v2
	v_mov_b32_e32 v86, v2
	v_mov_b32_e32 v87, v2
	v_mov_b32_e32 v88, v2
	v_mov_b32_e32 v89, v2
	v_mov_b32_e32 v98, v2
	v_mov_b32_e32 v99, v2
	v_mov_b32_e32 v100, v2
	v_mov_b32_e32 v101, v2
	v_mov_b32_e32 v102, v2
	v_mov_b32_e32 v103, v2
	v_mov_b32_e32 v104, v2
	v_mov_b32_e32 v105, v2
	v_mov_b32_e32 v114, v2
	v_mov_b32_e32 v115, v2
	v_mov_b32_e32 v116, v2
	v_mov_b32_e32 v117, v2
	v_mov_b32_e32 v118, v2
	v_mov_b32_e32 v119, v2
	v_mov_b32_e32 v120, v2
	v_mov_b32_e32 v121, v2
	v_mov_b32_e32 v74, v2
	v_mov_b32_e32 v75, v2
	v_mov_b32_e32 v76, v2
	v_mov_b32_e32 v77, v2
	v_mov_b32_e32 v78, v2
	v_mov_b32_e32 v79, v2
	v_mov_b32_e32 v80, v2
	v_mov_b32_e32 v81, v2
	v_mov_b32_e32 v90, v2
	v_mov_b32_e32 v91, v2
	v_mov_b32_e32 v92, v2
	v_mov_b32_e32 v93, v2
	v_mov_b32_e32 v94, v2
	v_mov_b32_e32 v95, v2
	v_mov_b32_e32 v96, v2
	v_mov_b32_e32 v97, v2
	v_mov_b32_e32 v106, v2
	v_mov_b32_e32 v107, v2
	v_mov_b32_e32 v108, v2
	v_mov_b32_e32 v109, v2
	v_mov_b32_e32 v110, v2
	v_mov_b32_e32 v111, v2
	v_mov_b32_e32 v112, v2
	v_mov_b32_e32 v113, v2
	v_mov_b32_e32 v150, v2
	v_mov_b32_e32 v151, v2
	v_mov_b32_e32 v152, v2
	v_mov_b32_e32 v153, v2
	v_mov_b32_e32 v154, v2
	v_mov_b32_e32 v155, v2
	v_mov_b32_e32 v156, v2
	v_mov_b32_e32 v157, v2
	s_cmp_eq_u64 s[26:27], 0
	s_cbranch_scc1 .Lhb_B_p2
.LBB0_251:
	ds_read_b128 v[122:125], v245
	ds_read_b128 v[126:129], v245 offset:1024
	ds_read_b128 v[130:133], v245 offset:2048
	ds_read_b128 v[134:137], v245 offset:3072
	ds_read_b128 v[138:141], v246
	ds_read_b128 v[142:145], v246 offset:1024
	ds_read_b128 v[146:149], v246 offset:2048
	ds_read_b128 v[158:161], v246 offset:3072
	s_add_u32 s46, s44, 0x100
	s_addc_u32 s47, s45, 0
	s_cmp_eq_u32 s71, 40
	s_cselect_b32 s51, s9, s47
	s_cselect_b32 s50, s8, s46
	s_cselect_b32 s49, s43, s70
	s_cselect_b32 s48, s42, s69
	v_lshl_add_u64 v[210:211], s[44:45], 0, v[206:207]
	s_add_i32 m0, s53, 0xc000
	ds_read_b128 v[162:165], v247
	ds_read_b128 v[166:169], v247 offset:1024
	ds_read_b128 v[170:173], v247 offset:2048
	ds_read_b128 v[174:177], v247 offset:3072
	ds_read_b128 v[178:181], v247 offset:4096
	ds_read_b128 v[182:185], v247 offset:5120
	ds_read_b128 v[186:189], v247 offset:6144
	ds_read_b128 v[190:193], v247 offset:7168
	global_load_lds_dwordx4 v[210:211], off
	v_lshl_add_u64 v[210:211], s[44:45], 0, v[208:209]
	s_add_i32 m0, s53, 0xe000
	s_nop 0
	global_load_lds_dwordx4 v[210:211], off
	s_waitcnt vmcnt(8)
	s_waitcnt lgkmcnt(0)
	s_setprio 1
	v_mfma_f32_16x16x32_bf16 v[154:157], v[122:125], v[162:165], v[154:157]
	v_mfma_f32_16x16x32_bf16 v[150:153], v[130:133], v[162:165], v[150:153]
	v_mfma_f32_16x16x32_bf16 v[110:113], v[122:125], v[170:173], v[110:113]
	v_mfma_f32_16x16x32_bf16 v[106:109], v[130:133], v[170:173], v[106:109]
	v_mfma_f32_16x16x32_bf16 v[94:97], v[122:125], v[178:181], v[94:97]
	v_mfma_f32_16x16x32_bf16 v[90:93], v[130:133], v[178:181], v[90:93]
	v_mfma_f32_16x16x32_bf16 v[78:81], v[122:125], v[186:189], v[78:81]
	v_mfma_f32_16x16x32_bf16 v[74:77], v[130:133], v[186:189], v[74:77]
	v_mfma_f32_16x16x32_bf16 v[154:157], v[126:129], v[166:169], v[154:157]
	v_mfma_f32_16x16x32_bf16 v[150:153], v[134:137], v[166:169], v[150:153]
	v_mfma_f32_16x16x32_bf16 v[110:113], v[126:129], v[174:177], v[110:113]
	v_mfma_f32_16x16x32_bf16 v[106:109], v[134:137], v[174:177], v[106:109]
	v_mfma_f32_16x16x32_bf16 v[94:97], v[126:129], v[182:185], v[94:97]
	v_mfma_f32_16x16x32_bf16 v[90:93], v[134:137], v[182:185], v[90:93]
	v_mfma_f32_16x16x32_bf16 v[78:81], v[126:129], v[190:193], v[78:81]
	v_mfma_f32_16x16x32_bf16 v[74:77], v[134:137], v[190:193], v[74:77]
	s_setprio 0
	s_setprio 1
	v_mfma_f32_16x16x32_bf16 v[118:121], v[138:141], v[162:165], v[118:121]
	v_mfma_f32_16x16x32_bf16 v[114:117], v[146:149], v[162:165], v[114:117]
	v_mfma_f32_16x16x32_bf16 v[102:105], v[138:141], v[170:173], v[102:105]
	v_mfma_f32_16x16x32_bf16 v[98:101], v[146:149], v[170:173], v[98:101]
	v_mfma_f32_16x16x32_bf16 v[86:89], v[138:141], v[178:181], v[86:89]
	v_mfma_f32_16x16x32_bf16 v[82:85], v[146:149], v[178:181], v[82:85]
	v_mfma_f32_16x16x32_bf16 v[70:73], v[138:141], v[186:189], v[70:73]
	v_mfma_f32_16x16x32_bf16 v[66:69], v[146:149], v[186:189], v[66:69]
	v_mfma_f32_16x16x32_bf16 v[118:121], v[142:145], v[166:169], v[118:121]
	v_mfma_f32_16x16x32_bf16 v[114:117], v[158:161], v[166:169], v[114:117]
	v_mfma_f32_16x16x32_bf16 v[102:105], v[142:145], v[174:177], v[102:105]
	v_mfma_f32_16x16x32_bf16 v[98:101], v[158:161], v[174:177], v[98:101]
	v_mfma_f32_16x16x32_bf16 v[86:89], v[142:145], v[182:185], v[86:89]
	v_mfma_f32_16x16x32_bf16 v[82:85], v[158:161], v[182:185], v[82:85]
	v_mfma_f32_16x16x32_bf16 v[70:73], v[142:145], v[190:193], v[70:73]
	v_mfma_f32_16x16x32_bf16 v[66:69], v[158:161], v[190:193], v[66:69]
	s_setprio 0
	s_barrier
	s_add_i32 s44, s63, s52
	v_lshl_add_u64 v[210:211], s[48:49], 0, v[196:197]
	s_mov_b32 m0, s44
	ds_read_b128 v[162:165], v247 offset:16384
	ds_read_b128 v[166:169], v247 offset:17408
	ds_read_b128 v[170:173], v247 offset:18432
	ds_read_b128 v[174:177], v247 offset:19456
	ds_read_b128 v[178:181], v247 offset:20480
	ds_read_b128 v[182:185], v247 offset:21504
	ds_read_b128 v[186:189], v247 offset:22528
	ds_read_b128 v[190:193], v247 offset:23552
	global_load_lds_dwordx4 v[210:211], off
	s_add_i32 m0, s44, 0x2000
	s_add_u32 s44, s48, 0xb0000
	v_lshl_add_u64 v[212:213], s[48:49], 0, v[200:201]
	s_addc_u32 s45, s49, 0
	s_add_i32 s72, s64, s52
	global_load_lds_dwordx4 v[212:213], off
	v_lshl_add_u64 v[214:215], s[44:45], 0, v[196:197]
	s_mov_b32 m0, s72
	v_lshl_add_u64 v[216:217], s[50:51], 0, v[198:199]
	global_load_lds_dwordx4 v[214:215], off
	v_lshl_add_u64 v[214:215], s[44:45], 0, v[200:201]
	s_add_i32 m0, s72, 0x2000
	s_nop 0
	global_load_lds_dwordx4 v[214:215], off
	v_lshl_add_u64 v[214:215], s[50:51], 0, v[194:195]
	s_mov_b32 m0, s53
	s_nop 0
	global_load_lds_dwordx4 v[214:215], off
	s_mov_b32 m0, s54
	s_nop 0
	global_load_lds_dwordx4 v[216:217], off
	s_waitcnt vmcnt(8)
	s_waitcnt lgkmcnt(0)
	s_setprio 1
	v_mfma_f32_16x16x32_bf16 v[62:65], v[122:125], v[162:165], v[62:65]
	v_mfma_f32_16x16x32_bf16 v[58:61], v[130:133], v[162:165], v[58:61]
	v_mfma_f32_16x16x32_bf16 v[46:49], v[122:125], v[170:173], v[46:49]
	v_mfma_f32_16x16x32_bf16 v[42:45], v[130:133], v[170:173], v[42:45]
	v_mfma_f32_16x16x32_bf16 v[30:33], v[122:125], v[178:181], v[30:33]
	v_mfma_f32_16x16x32_bf16 v[26:29], v[130:133], v[178:181], v[26:29]
	v_mfma_f32_16x16x32_bf16 v[14:17], v[122:125], v[186:189], v[14:17]
	v_mfma_f32_16x16x32_bf16 v[10:13], v[130:133], v[186:189], v[10:13]
	v_mfma_f32_16x16x32_bf16 v[62:65], v[126:129], v[166:169], v[62:65]
	v_mfma_f32_16x16x32_bf16 v[58:61], v[134:137], v[166:169], v[58:61]
	v_mfma_f32_16x16x32_bf16 v[46:49], v[126:129], v[174:177], v[46:49]
	v_mfma_f32_16x16x32_bf16 v[42:45], v[134:137], v[174:177], v[42:45]
	v_mfma_f32_16x16x32_bf16 v[30:33], v[126:129], v[182:185], v[30:33]
	v_mfma_f32_16x16x32_bf16 v[26:29], v[134:137], v[182:185], v[26:29]
	v_mfma_f32_16x16x32_bf16 v[14:17], v[126:129], v[190:193], v[14:17]
	v_mfma_f32_16x16x32_bf16 v[10:13], v[134:137], v[190:193], v[10:13]
	s_setprio 0
	s_setprio 1
	v_mfma_f32_16x16x32_bf16 v[54:57], v[138:141], v[162:165], v[54:57]
	v_mfma_f32_16x16x32_bf16 v[50:53], v[146:149], v[162:165], v[50:53]
	v_mfma_f32_16x16x32_bf16 v[38:41], v[138:141], v[170:173], v[38:41]
	v_mfma_f32_16x16x32_bf16 v[34:37], v[146:149], v[170:173], v[34:37]
	v_mfma_f32_16x16x32_bf16 v[22:25], v[138:141], v[178:181], v[22:25]
	v_mfma_f32_16x16x32_bf16 v[18:21], v[146:149], v[178:181], v[18:21]
	v_mfma_f32_16x16x32_bf16 v[6:9], v[138:141], v[186:189], v[6:9]
	v_mfma_f32_16x16x32_bf16 v[2:5], v[146:149], v[186:189], v[2:5]
	v_mfma_f32_16x16x32_bf16 v[54:57], v[142:145], v[166:169], v[54:57]
	v_mfma_f32_16x16x32_bf16 v[50:53], v[158:161], v[166:169], v[50:53]
	v_mfma_f32_16x16x32_bf16 v[38:41], v[142:145], v[174:177], v[38:41]
	v_mfma_f32_16x16x32_bf16 v[34:37], v[158:161], v[174:177], v[34:37]
	v_mfma_f32_16x16x32_bf16 v[22:25], v[142:145], v[182:185], v[22:25]
	v_mfma_f32_16x16x32_bf16 v[18:21], v[158:161], v[182:185], v[18:21]
	v_mfma_f32_16x16x32_bf16 v[6:9], v[142:145], v[190:193], v[6:9]
	v_mfma_f32_16x16x32_bf16 v[2:5], v[158:161], v[190:193], v[2:5]
	s_setprio 0
	s_barrier
	s_add_i32 s72, 0, 0x18000
	s_add_i32 s73, 0, 0x1c000
	v_add_u32_e32 v134, s72, v244
	v_add_u32_e32 v158, s73, v244
	ds_read_b128 v[122:125], v134
	ds_read_b128 v[126:129], v134 offset:1024
	ds_read_b128 v[130:133], v134 offset:2048
	ds_read_b128 v[134:137], v134 offset:3072
	ds_read_b128 v[138:141], v158
	ds_read_b128 v[142:145], v158 offset:1024
	ds_read_b128 v[146:149], v158 offset:2048
	ds_read_b128 v[158:161], v158 offset:3072
	s_add_u32 s44, s50, 0xb0000
	s_addc_u32 s45, s51, 0
	s_mov_b32 m0, s55
	v_lshl_add_u64 v[218:219], s[44:45], 0, v[194:195]
	ds_read_b128 v[162:165], v247 offset:32768
	ds_read_b128 v[166:169], v247 offset:33792
	ds_read_b128 v[170:173], v247 offset:34816
	ds_read_b128 v[174:177], v247 offset:35840
	ds_read_b128 v[178:181], v247 offset:36864
	ds_read_b128 v[182:185], v247 offset:37888
	ds_read_b128 v[186:189], v247 offset:38912
	ds_read_b128 v[190:193], v247 offset:39936
	global_load_lds_dwordx4 v[218:219], off
	v_lshl_add_u64 v[218:219], s[44:45], 0, v[198:199]
	s_mov_b32 m0, s56
	s_nop 0
	global_load_lds_dwordx4 v[218:219], off
	s_waitcnt vmcnt(8)
	s_waitcnt lgkmcnt(0)
	s_setprio 1
	v_mfma_f32_16x16x32_bf16 v[154:157], v[122:125], v[162:165], v[154:157]
	v_mfma_f32_16x16x32_bf16 v[150:153], v[130:133], v[162:165], v[150:153]
	v_mfma_f32_16x16x32_bf16 v[110:113], v[122:125], v[170:173], v[110:113]
	v_mfma_f32_16x16x32_bf16 v[106:109], v[130:133], v[170:173], v[106:109]
	v_mfma_f32_16x16x32_bf16 v[94:97], v[122:125], v[178:181], v[94:97]
	v_mfma_f32_16x16x32_bf16 v[90:93], v[130:133], v[178:181], v[90:93]
	v_mfma_f32_16x16x32_bf16 v[78:81], v[122:125], v[186:189], v[78:81]
	v_mfma_f32_16x16x32_bf16 v[74:77], v[130:133], v[186:189], v[74:77]
	v_mfma_f32_16x16x32_bf16 v[154:157], v[126:129], v[166:169], v[154:157]
	v_mfma_f32_16x16x32_bf16 v[150:153], v[134:137], v[166:169], v[150:153]
	v_mfma_f32_16x16x32_bf16 v[110:113], v[126:129], v[174:177], v[110:113]
	v_mfma_f32_16x16x32_bf16 v[106:109], v[134:137], v[174:177], v[106:109]
	v_mfma_f32_16x16x32_bf16 v[94:97], v[126:129], v[182:185], v[94:97]
	v_mfma_f32_16x16x32_bf16 v[90:93], v[134:137], v[182:185], v[90:93]
	v_mfma_f32_16x16x32_bf16 v[78:81], v[126:129], v[190:193], v[78:81]
	v_mfma_f32_16x16x32_bf16 v[74:77], v[134:137], v[190:193], v[74:77]
	s_setprio 0
	s_setprio 1
	v_mfma_f32_16x16x32_bf16 v[118:121], v[138:141], v[162:165], v[118:121]
	v_mfma_f32_16x16x32_bf16 v[114:117], v[146:149], v[162:165], v[114:117]
	v_mfma_f32_16x16x32_bf16 v[102:105], v[138:141], v[170:173], v[102:105]
	v_mfma_f32_16x16x32_bf16 v[98:101], v[146:149], v[170:173], v[98:101]
	v_mfma_f32_16x16x32_bf16 v[86:89], v[138:141], v[178:181], v[86:89]
	v_mfma_f32_16x16x32_bf16 v[82:85], v[146:149], v[178:181], v[82:85]
	v_mfma_f32_16x16x32_bf16 v[70:73], v[138:141], v[186:189], v[70:73]
	v_mfma_f32_16x16x32_bf16 v[66:69], v[146:149], v[186:189], v[66:69]
	v_mfma_f32_16x16x32_bf16 v[118:121], v[142:145], v[166:169], v[118:121]
	v_mfma_f32_16x16x32_bf16 v[114:117], v[158:161], v[166:169], v[114:117]
	v_mfma_f32_16x16x32_bf16 v[102:105], v[142:145], v[174:177], v[102:105]
	v_mfma_f32_16x16x32_bf16 v[98:101], v[158:161], v[174:177], v[98:101]
	v_mfma_f32_16x16x32_bf16 v[86:89], v[142:145], v[182:185], v[86:89]
	v_mfma_f32_16x16x32_bf16 v[82:85], v[158:161], v[182:185], v[82:85]
	v_mfma_f32_16x16x32_bf16 v[70:73], v[142:145], v[190:193], v[70:73]
	v_mfma_f32_16x16x32_bf16 v[66:69], v[158:161], v[190:193], v[66:69]
	s_setprio 0
	s_barrier
	s_add_i32 s44, s72, s52
	v_lshl_add_u64 v[210:211], v[210:211], 0, s[24:25]
	s_mov_b32 m0, s44
	ds_read_b128 v[162:165], v247 offset:49152
	ds_read_b128 v[166:169], v247 offset:50176
	ds_read_b128 v[170:173], v247 offset:51200
	ds_read_b128 v[174:177], v247 offset:52224
	ds_read_b128 v[178:181], v247 offset:53248
	ds_read_b128 v[182:185], v247 offset:54272
	ds_read_b128 v[186:189], v247 offset:55296
	ds_read_b128 v[190:193], v247 offset:56320
	global_load_lds_dwordx4 v[210:211], off
	s_add_i32 m0, s44, 0x2000
	s_add_u32 s44, s48, 0xb0080
	v_lshl_add_u64 v[210:211], v[212:213], 0, s[24:25]
	s_addc_u32 s45, s49, 0
	s_add_i32 s48, s73, s52
	global_load_lds_dwordx4 v[210:211], off
	v_lshl_add_u64 v[210:211], s[44:45], 0, v[196:197]
	s_mov_b32 m0, s48
	s_nop 0
	global_load_lds_dwordx4 v[210:211], off
	v_lshl_add_u64 v[210:211], s[44:45], 0, v[200:201]
	s_add_i32 m0, s48, 0x2000
	s_nop 0
	global_load_lds_dwordx4 v[210:211], off
	v_lshl_add_u64 v[210:211], v[214:215], 0, s[24:25]
	s_mov_b32 m0, s58
	s_nop 0
	global_load_lds_dwordx4 v[210:211], off
	v_lshl_add_u64 v[210:211], v[216:217], 0, s[24:25]
	s_mov_b32 m0, s59
	s_nop 0
	global_load_lds_dwordx4 v[210:211], off
	s_waitcnt vmcnt(8)
	s_waitcnt lgkmcnt(0)
	s_setprio 1
	v_mfma_f32_16x16x32_bf16 v[62:65], v[122:125], v[162:165], v[62:65]
	v_mfma_f32_16x16x32_bf16 v[58:61], v[130:133], v[162:165], v[58:61]
	v_mfma_f32_16x16x32_bf16 v[46:49], v[122:125], v[170:173], v[46:49]
	v_mfma_f32_16x16x32_bf16 v[42:45], v[130:133], v[170:173], v[42:45]
	v_mfma_f32_16x16x32_bf16 v[30:33], v[122:125], v[178:181], v[30:33]
	v_mfma_f32_16x16x32_bf16 v[26:29], v[130:133], v[178:181], v[26:29]
	v_mfma_f32_16x16x32_bf16 v[14:17], v[122:125], v[186:189], v[14:17]
	v_mfma_f32_16x16x32_bf16 v[10:13], v[130:133], v[186:189], v[10:13]
	v_mfma_f32_16x16x32_bf16 v[62:65], v[126:129], v[166:169], v[62:65]
	v_mfma_f32_16x16x32_bf16 v[58:61], v[134:137], v[166:169], v[58:61]
	v_mfma_f32_16x16x32_bf16 v[46:49], v[126:129], v[174:177], v[46:49]
	v_mfma_f32_16x16x32_bf16 v[42:45], v[134:137], v[174:177], v[42:45]
	v_mfma_f32_16x16x32_bf16 v[30:33], v[126:129], v[182:185], v[30:33]
	v_mfma_f32_16x16x32_bf16 v[26:29], v[134:137], v[182:185], v[26:29]
	v_mfma_f32_16x16x32_bf16 v[14:17], v[126:129], v[190:193], v[14:17]
	v_mfma_f32_16x16x32_bf16 v[10:13], v[134:137], v[190:193], v[10:13]
	s_setprio 0
	s_setprio 1
	v_mfma_f32_16x16x32_bf16 v[54:57], v[138:141], v[162:165], v[54:57]
	v_mfma_f32_16x16x32_bf16 v[50:53], v[146:149], v[162:165], v[50:53]
	v_mfma_f32_16x16x32_bf16 v[38:41], v[138:141], v[170:173], v[38:41]
	v_mfma_f32_16x16x32_bf16 v[34:37], v[146:149], v[170:173], v[34:37]
	v_mfma_f32_16x16x32_bf16 v[22:25], v[138:141], v[178:181], v[22:25]
	v_mfma_f32_16x16x32_bf16 v[18:21], v[146:149], v[178:181], v[18:21]
	v_mfma_f32_16x16x32_bf16 v[6:9], v[138:141], v[186:189], v[6:9]
	v_mfma_f32_16x16x32_bf16 v[2:5], v[146:149], v[186:189], v[2:5]
	v_mfma_f32_16x16x32_bf16 v[54:57], v[142:145], v[166:169], v[54:57]
	v_mfma_f32_16x16x32_bf16 v[50:53], v[158:161], v[166:169], v[50:53]
	v_mfma_f32_16x16x32_bf16 v[38:41], v[142:145], v[174:177], v[38:41]
	v_mfma_f32_16x16x32_bf16 v[34:37], v[158:161], v[174:177], v[34:37]
	v_mfma_f32_16x16x32_bf16 v[22:25], v[142:145], v[182:185], v[22:25]
	v_mfma_f32_16x16x32_bf16 v[18:21], v[158:161], v[182:185], v[18:21]
	v_mfma_f32_16x16x32_bf16 v[6:9], v[142:145], v[190:193], v[6:9]
	v_mfma_f32_16x16x32_bf16 v[2:5], v[158:161], v[190:193], v[2:5]
	s_setprio 0
	s_barrier
	s_add_i32 s71, s71, 2
	s_add_u32 s69, s69, 0x100
	s_addc_u32 s70, s70, 0
	s_cmp_gt_u32 s71, 41
	s_mov_b64 s[44:45], s[46:47]
	s_cbranch_scc0 .LBB0_251
	s_branch .Lhb_exit_p2
.Lhb_B_p2:
	ds_read_b128 v[122:125], v245
	ds_read_b128 v[126:129], v245 offset:1024
	ds_read_b128 v[130:133], v245 offset:2048
	ds_read_b128 v[134:137], v245 offset:3072
	ds_read_b128 v[138:141], v246
	ds_read_b128 v[142:145], v246 offset:1024
	ds_read_b128 v[146:149], v246 offset:2048
	ds_read_b128 v[158:161], v246 offset:3072
	s_add_u32 s46, s44, 0x100
	s_addc_u32 s47, s45, 0
	s_cmp_eq_u32 s71, 40
	s_cselect_b32 s51, s9, s47
	s_cselect_b32 s50, s8, s46
	s_cselect_b32 s49, s43, s70
	s_cselect_b32 s48, s42, s69
	v_lshl_add_u64 v[210:211], s[44:45], 0, v[206:207]
	s_add_i32 m0, s53, 0xc000
	ds_read_b128 v[162:165], v247
	ds_read_b128 v[166:169], v247 offset:1024
	ds_read_b128 v[170:173], v247 offset:2048
	ds_read_b128 v[174:177], v247 offset:3072
	ds_read_b128 v[178:181], v247 offset:4096
	ds_read_b128 v[182:185], v247 offset:5120
	ds_read_b128 v[186:189], v247 offset:6144
	ds_read_b128 v[190:193], v247 offset:7168
	global_load_lds_dwordx4 v[210:211], off
	v_lshl_add_u64 v[210:211], s[44:45], 0, v[208:209]
	s_add_i32 m0, s53, 0xe000
	s_nop 0
	global_load_lds_dwordx4 v[210:211], off
	s_waitcnt vmcnt(8)
	s_waitcnt lgkmcnt(0)
	s_setprio 1
	s_barrier
	v_mfma_f32_16x16x32_bf16 v[154:157], v[122:125], v[162:165], v[154:157]
	v_mfma_f32_16x16x32_bf16 v[150:153], v[130:133], v[162:165], v[150:153]
	v_mfma_f32_16x16x32_bf16 v[110:113], v[122:125], v[170:173], v[110:113]
	v_mfma_f32_16x16x32_bf16 v[106:109], v[130:133], v[170:173], v[106:109]
	v_mfma_f32_16x16x32_bf16 v[94:97], v[122:125], v[178:181], v[94:97]
	v_mfma_f32_16x16x32_bf16 v[90:93], v[130:133], v[178:181], v[90:93]
	v_mfma_f32_16x16x32_bf16 v[78:81], v[122:125], v[186:189], v[78:81]
	v_mfma_f32_16x16x32_bf16 v[74:77], v[130:133], v[186:189], v[74:77]
	v_mfma_f32_16x16x32_bf16 v[154:157], v[126:129], v[166:169], v[154:157]
	v_mfma_f32_16x16x32_bf16 v[150:153], v[134:137], v[166:169], v[150:153]
	v_mfma_f32_16x16x32_bf16 v[110:113], v[126:129], v[174:177], v[110:113]
	v_mfma_f32_16x16x32_bf16 v[106:109], v[134:137], v[174:177], v[106:109]
	v_mfma_f32_16x16x32_bf16 v[94:97], v[126:129], v[182:185], v[94:97]
	v_mfma_f32_16x16x32_bf16 v[90:93], v[134:137], v[182:185], v[90:93]
	v_mfma_f32_16x16x32_bf16 v[78:81], v[126:129], v[190:193], v[78:81]
	v_mfma_f32_16x16x32_bf16 v[74:77], v[134:137], v[190:193], v[74:77]
	s_setprio 0
	s_setprio 1
	v_mfma_f32_16x16x32_bf16 v[118:121], v[138:141], v[162:165], v[118:121]
	v_mfma_f32_16x16x32_bf16 v[114:117], v[146:149], v[162:165], v[114:117]
	v_mfma_f32_16x16x32_bf16 v[102:105], v[138:141], v[170:173], v[102:105]
	v_mfma_f32_16x16x32_bf16 v[98:101], v[146:149], v[170:173], v[98:101]
	v_mfma_f32_16x16x32_bf16 v[86:89], v[138:141], v[178:181], v[86:89]
	v_mfma_f32_16x16x32_bf16 v[82:85], v[146:149], v[178:181], v[82:85]
	v_mfma_f32_16x16x32_bf16 v[70:73], v[138:141], v[186:189], v[70:73]
	v_mfma_f32_16x16x32_bf16 v[66:69], v[146:149], v[186:189], v[66:69]
	v_mfma_f32_16x16x32_bf16 v[118:121], v[142:145], v[166:169], v[118:121]
	v_mfma_f32_16x16x32_bf16 v[114:117], v[158:161], v[166:169], v[114:117]
	v_mfma_f32_16x16x32_bf16 v[102:105], v[142:145], v[174:177], v[102:105]
	v_mfma_f32_16x16x32_bf16 v[98:101], v[158:161], v[174:177], v[98:101]
	v_mfma_f32_16x16x32_bf16 v[86:89], v[142:145], v[182:185], v[86:89]
	v_mfma_f32_16x16x32_bf16 v[82:85], v[158:161], v[182:185], v[82:85]
	v_mfma_f32_16x16x32_bf16 v[70:73], v[142:145], v[190:193], v[70:73]
	v_mfma_f32_16x16x32_bf16 v[66:69], v[158:161], v[190:193], v[66:69]
	s_setprio 0
	s_add_i32 s44, s63, s52
	v_lshl_add_u64 v[210:211], s[48:49], 0, v[196:197]
	s_mov_b32 m0, s44
	ds_read_b128 v[162:165], v247 offset:16384
	ds_read_b128 v[166:169], v247 offset:17408
	ds_read_b128 v[170:173], v247 offset:18432
	ds_read_b128 v[174:177], v247 offset:19456
	ds_read_b128 v[178:181], v247 offset:20480
	ds_read_b128 v[182:185], v247 offset:21504
	ds_read_b128 v[186:189], v247 offset:22528
	ds_read_b128 v[190:193], v247 offset:23552
	global_load_lds_dwordx4 v[210:211], off
	s_add_i32 m0, s44, 0x2000
	s_add_u32 s44, s48, 0xb0000
	v_lshl_add_u64 v[212:213], s[48:49], 0, v[200:201]
	s_addc_u32 s45, s49, 0
	s_add_i32 s72, s64, s52
	global_load_lds_dwordx4 v[212:213], off
	v_lshl_add_u64 v[214:215], s[44:45], 0, v[196:197]
	s_mov_b32 m0, s72
	v_lshl_add_u64 v[216:217], s[50:51], 0, v[198:199]
	global_load_lds_dwordx4 v[214:215], off
	v_lshl_add_u64 v[214:215], s[44:45], 0, v[200:201]
	s_add_i32 m0, s72, 0x2000
	s_nop 0
	global_load_lds_dwordx4 v[214:215], off
	v_lshl_add_u64 v[214:215], s[50:51], 0, v[194:195]
	s_mov_b32 m0, s53
	s_nop 0
	global_load_lds_dwordx4 v[214:215], off
	s_mov_b32 m0, s54
	s_nop 0
	global_load_lds_dwordx4 v[216:217], off
	s_waitcnt vmcnt(8)
	s_waitcnt lgkmcnt(0)
	s_setprio 1
	s_barrier
	v_mfma_f32_16x16x32_bf16 v[62:65], v[122:125], v[162:165], v[62:65]
	v_mfma_f32_16x16x32_bf16 v[58:61], v[130:133], v[162:165], v[58:61]
	v_mfma_f32_16x16x32_bf16 v[46:49], v[122:125], v[170:173], v[46:49]
	v_mfma_f32_16x16x32_bf16 v[42:45], v[130:133], v[170:173], v[42:45]
	v_mfma_f32_16x16x32_bf16 v[30:33], v[122:125], v[178:181], v[30:33]
	v_mfma_f32_16x16x32_bf16 v[26:29], v[130:133], v[178:181], v[26:29]
	v_mfma_f32_16x16x32_bf16 v[14:17], v[122:125], v[186:189], v[14:17]
	v_mfma_f32_16x16x32_bf16 v[10:13], v[130:133], v[186:189], v[10:13]
	v_mfma_f32_16x16x32_bf16 v[62:65], v[126:129], v[166:169], v[62:65]
	v_mfma_f32_16x16x32_bf16 v[58:61], v[134:137], v[166:169], v[58:61]
	v_mfma_f32_16x16x32_bf16 v[46:49], v[126:129], v[174:177], v[46:49]
	v_mfma_f32_16x16x32_bf16 v[42:45], v[134:137], v[174:177], v[42:45]
	v_mfma_f32_16x16x32_bf16 v[30:33], v[126:129], v[182:185], v[30:33]
	v_mfma_f32_16x16x32_bf16 v[26:29], v[134:137], v[182:185], v[26:29]
	v_mfma_f32_16x16x32_bf16 v[14:17], v[126:129], v[190:193], v[14:17]
	v_mfma_f32_16x16x32_bf16 v[10:13], v[134:137], v[190:193], v[10:13]
	s_setprio 0
	s_setprio 1
	v_mfma_f32_16x16x32_bf16 v[54:57], v[138:141], v[162:165], v[54:57]
	v_mfma_f32_16x16x32_bf16 v[50:53], v[146:149], v[162:165], v[50:53]
	v_mfma_f32_16x16x32_bf16 v[38:41], v[138:141], v[170:173], v[38:41]
	v_mfma_f32_16x16x32_bf16 v[34:37], v[146:149], v[170:173], v[34:37]
	v_mfma_f32_16x16x32_bf16 v[22:25], v[138:141], v[178:181], v[22:25]
	v_mfma_f32_16x16x32_bf16 v[18:21], v[146:149], v[178:181], v[18:21]
	v_mfma_f32_16x16x32_bf16 v[6:9], v[138:141], v[186:189], v[6:9]
	v_mfma_f32_16x16x32_bf16 v[2:5], v[146:149], v[186:189], v[2:5]
	v_mfma_f32_16x16x32_bf16 v[54:57], v[142:145], v[166:169], v[54:57]
	v_mfma_f32_16x16x32_bf16 v[50:53], v[158:161], v[166:169], v[50:53]
	v_mfma_f32_16x16x32_bf16 v[38:41], v[142:145], v[174:177], v[38:41]
	v_mfma_f32_16x16x32_bf16 v[34:37], v[158:161], v[174:177], v[34:37]
	v_mfma_f32_16x16x32_bf16 v[22:25], v[142:145], v[182:185], v[22:25]
	v_mfma_f32_16x16x32_bf16 v[18:21], v[158:161], v[182:185], v[18:21]
	v_mfma_f32_16x16x32_bf16 v[6:9], v[142:145], v[190:193], v[6:9]
	v_mfma_f32_16x16x32_bf16 v[2:5], v[158:161], v[190:193], v[2:5]
	s_setprio 0
	s_add_i32 s72, 0, 0x18000
	s_add_i32 s73, 0, 0x1c000
	v_add_u32_e32 v134, s72, v244
	v_add_u32_e32 v158, s73, v244
	ds_read_b128 v[122:125], v134
	ds_read_b128 v[126:129], v134 offset:1024
	ds_read_b128 v[130:133], v134 offset:2048
	ds_read_b128 v[134:137], v134 offset:3072
	ds_read_b128 v[138:141], v158
	ds_read_b128 v[142:145], v158 offset:1024
	ds_read_b128 v[146:149], v158 offset:2048
	ds_read_b128 v[158:161], v158 offset:3072
	s_add_u32 s44, s50, 0xb0000
	s_addc_u32 s45, s51, 0
	s_mov_b32 m0, s55
	v_lshl_add_u64 v[218:219], s[44:45], 0, v[194:195]
	ds_read_b128 v[162:165], v247 offset:32768
	ds_read_b128 v[166:169], v247 offset:33792
	ds_read_b128 v[170:173], v247 offset:34816
	ds_read_b128 v[174:177], v247 offset:35840
	ds_read_b128 v[178:181], v247 offset:36864
	ds_read_b128 v[182:185], v247 offset:37888
	ds_read_b128 v[186:189], v247 offset:38912
	ds_read_b128 v[190:193], v247 offset:39936
	global_load_lds_dwordx4 v[218:219], off
	v_lshl_add_u64 v[218:219], s[44:45], 0, v[198:199]
	s_mov_b32 m0, s56
	s_nop 0
	global_load_lds_dwordx4 v[218:219], off
	s_waitcnt vmcnt(8)
	s_waitcnt lgkmcnt(0)
	s_setprio 1
	s_barrier
	v_mfma_f32_16x16x32_bf16 v[154:157], v[122:125], v[162:165], v[154:157]
	v_mfma_f32_16x16x32_bf16 v[150:153], v[130:133], v[162:165], v[150:153]
	v_mfma_f32_16x16x32_bf16 v[110:113], v[122:125], v[170:173], v[110:113]
	v_mfma_f32_16x16x32_bf16 v[106:109], v[130:133], v[170:173], v[106:109]
	v_mfma_f32_16x16x32_bf16 v[94:97], v[122:125], v[178:181], v[94:97]
	v_mfma_f32_16x16x32_bf16 v[90:93], v[130:133], v[178:181], v[90:93]
	v_mfma_f32_16x16x32_bf16 v[78:81], v[122:125], v[186:189], v[78:81]
	v_mfma_f32_16x16x32_bf16 v[74:77], v[130:133], v[186:189], v[74:77]
	v_mfma_f32_16x16x32_bf16 v[154:157], v[126:129], v[166:169], v[154:157]
	v_mfma_f32_16x16x32_bf16 v[150:153], v[134:137], v[166:169], v[150:153]
	v_mfma_f32_16x16x32_bf16 v[110:113], v[126:129], v[174:177], v[110:113]
	v_mfma_f32_16x16x32_bf16 v[106:109], v[134:137], v[174:177], v[106:109]
	v_mfma_f32_16x16x32_bf16 v[94:97], v[126:129], v[182:185], v[94:97]
	v_mfma_f32_16x16x32_bf16 v[90:93], v[134:137], v[182:185], v[90:93]
	v_mfma_f32_16x16x32_bf16 v[78:81], v[126:129], v[190:193], v[78:81]
	v_mfma_f32_16x16x32_bf16 v[74:77], v[134:137], v[190:193], v[74:77]
	s_setprio 0
	s_setprio 1
	v_mfma_f32_16x16x32_bf16 v[118:121], v[138:141], v[162:165], v[118:121]
	v_mfma_f32_16x16x32_bf16 v[114:117], v[146:149], v[162:165], v[114:117]
	v_mfma_f32_16x16x32_bf16 v[102:105], v[138:141], v[170:173], v[102:105]
	v_mfma_f32_16x16x32_bf16 v[98:101], v[146:149], v[170:173], v[98:101]
	v_mfma_f32_16x16x32_bf16 v[86:89], v[138:141], v[178:181], v[86:89]
	v_mfma_f32_16x16x32_bf16 v[82:85], v[146:149], v[178:181], v[82:85]
	v_mfma_f32_16x16x32_bf16 v[70:73], v[138:141], v[186:189], v[70:73]
	v_mfma_f32_16x16x32_bf16 v[66:69], v[146:149], v[186:189], v[66:69]
	v_mfma_f32_16x16x32_bf16 v[118:121], v[142:145], v[166:169], v[118:121]
	v_mfma_f32_16x16x32_bf16 v[114:117], v[158:161], v[166:169], v[114:117]
	v_mfma_f32_16x16x32_bf16 v[102:105], v[142:145], v[174:177], v[102:105]
	v_mfma_f32_16x16x32_bf16 v[98:101], v[158:161], v[174:177], v[98:101]
	v_mfma_f32_16x16x32_bf16 v[86:89], v[142:145], v[182:185], v[86:89]
	v_mfma_f32_16x16x32_bf16 v[82:85], v[158:161], v[182:185], v[82:85]
	v_mfma_f32_16x16x32_bf16 v[70:73], v[142:145], v[190:193], v[70:73]
	v_mfma_f32_16x16x32_bf16 v[66:69], v[158:161], v[190:193], v[66:69]
	s_setprio 0
	s_add_i32 s44, s72, s52
	v_lshl_add_u64 v[210:211], v[210:211], 0, s[24:25]
	s_mov_b32 m0, s44
	ds_read_b128 v[162:165], v247 offset:49152
	ds_read_b128 v[166:169], v247 offset:50176
	ds_read_b128 v[170:173], v247 offset:51200
	ds_read_b128 v[174:177], v247 offset:52224
	ds_read_b128 v[178:181], v247 offset:53248
	ds_read_b128 v[182:185], v247 offset:54272
	ds_read_b128 v[186:189], v247 offset:55296
	ds_read_b128 v[190:193], v247 offset:56320
	global_load_lds_dwordx4 v[210:211], off
	s_add_i32 m0, s44, 0x2000
	s_add_u32 s44, s48, 0xb0080
	v_lshl_add_u64 v[210:211], v[212:213], 0, s[24:25]
	s_addc_u32 s45, s49, 0
	s_add_i32 s48, s73, s52
	global_load_lds_dwordx4 v[210:211], off
	v_lshl_add_u64 v[210:211], s[44:45], 0, v[196:197]
	s_mov_b32 m0, s48
	s_nop 0
	global_load_lds_dwordx4 v[210:211], off
	v_lshl_add_u64 v[210:211], s[44:45], 0, v[200:201]
	s_add_i32 m0, s48, 0x2000
	s_nop 0
	global_load_lds_dwordx4 v[210:211], off
	v_lshl_add_u64 v[210:211], v[214:215], 0, s[24:25]
	s_mov_b32 m0, s58
	s_nop 0
	global_load_lds_dwordx4 v[210:211], off
	v_lshl_add_u64 v[210:211], v[216:217], 0, s[24:25]
	s_mov_b32 m0, s59
	s_nop 0
	global_load_lds_dwordx4 v[210:211], off
	s_waitcnt vmcnt(8)
	s_waitcnt lgkmcnt(0)
	s_setprio 1
	s_barrier
	v_mfma_f32_16x16x32_bf16 v[62:65], v[122:125], v[162:165], v[62:65]
	v_mfma_f32_16x16x32_bf16 v[58:61], v[130:133], v[162:165], v[58:61]
	v_mfma_f32_16x16x32_bf16 v[46:49], v[122:125], v[170:173], v[46:49]
	v_mfma_f32_16x16x32_bf16 v[42:45], v[130:133], v[170:173], v[42:45]
	v_mfma_f32_16x16x32_bf16 v[30:33], v[122:125], v[178:181], v[30:33]
	v_mfma_f32_16x16x32_bf16 v[26:29], v[130:133], v[178:181], v[26:29]
	v_mfma_f32_16x16x32_bf16 v[14:17], v[122:125], v[186:189], v[14:17]
	v_mfma_f32_16x16x32_bf16 v[10:13], v[130:133], v[186:189], v[10:13]
	v_mfma_f32_16x16x32_bf16 v[62:65], v[126:129], v[166:169], v[62:65]
	v_mfma_f32_16x16x32_bf16 v[58:61], v[134:137], v[166:169], v[58:61]
	v_mfma_f32_16x16x32_bf16 v[46:49], v[126:129], v[174:177], v[46:49]
	v_mfma_f32_16x16x32_bf16 v[42:45], v[134:137], v[174:177], v[42:45]
	v_mfma_f32_16x16x32_bf16 v[30:33], v[126:129], v[182:185], v[30:33]
	v_mfma_f32_16x16x32_bf16 v[26:29], v[134:137], v[182:185], v[26:29]
	v_mfma_f32_16x16x32_bf16 v[14:17], v[126:129], v[190:193], v[14:17]
	v_mfma_f32_16x16x32_bf16 v[10:13], v[134:137], v[190:193], v[10:13]
	s_setprio 0
	s_setprio 1
	v_mfma_f32_16x16x32_bf16 v[54:57], v[138:141], v[162:165], v[54:57]
	v_mfma_f32_16x16x32_bf16 v[50:53], v[146:149], v[162:165], v[50:53]
	v_mfma_f32_16x16x32_bf16 v[38:41], v[138:141], v[170:173], v[38:41]
	v_mfma_f32_16x16x32_bf16 v[34:37], v[146:149], v[170:173], v[34:37]
	v_mfma_f32_16x16x32_bf16 v[22:25], v[138:141], v[178:181], v[22:25]
	v_mfma_f32_16x16x32_bf16 v[18:21], v[146:149], v[178:181], v[18:21]
	v_mfma_f32_16x16x32_bf16 v[6:9], v[138:141], v[186:189], v[6:9]
	v_mfma_f32_16x16x32_bf16 v[2:5], v[146:149], v[186:189], v[2:5]
	v_mfma_f32_16x16x32_bf16 v[54:57], v[142:145], v[166:169], v[54:57]
	v_mfma_f32_16x16x32_bf16 v[50:53], v[158:161], v[166:169], v[50:53]
	v_mfma_f32_16x16x32_bf16 v[38:41], v[142:145], v[174:177], v[38:41]
	v_mfma_f32_16x16x32_bf16 v[34:37], v[158:161], v[174:177], v[34:37]
	v_mfma_f32_16x16x32_bf16 v[22:25], v[142:145], v[182:185], v[22:25]
	v_mfma_f32_16x16x32_bf16 v[18:21], v[158:161], v[182:185], v[18:21]
	v_mfma_f32_16x16x32_bf16 v[6:9], v[142:145], v[190:193], v[6:9]
	v_mfma_f32_16x16x32_bf16 v[2:5], v[158:161], v[190:193], v[2:5]
	s_setprio 0
	s_add_i32 s71, s71, 2
	s_add_u32 s69, s69, 0x100
	s_addc_u32 s70, s70, 0
	s_cmp_gt_u32 s71, 41
	s_mov_b64 s[44:45], s[46:47]
	s_cbranch_scc0 .Lhb_B_p2
.Lhb_exit_p2:
	s_and_b64 vcc, exec, s[26:27]
	s_cbranch_vccz .LBB0_254
.LBB0_254:
	s_lshl_b32 s44, s68, 8
	v_lshl_add_u32 v238, s67, 8, v243
	s_ashr_i32 s45, s44, 31
	s_lshl_b64 s[46:47], s[44:45], 1
	v_ashrrev_i32_e32 v239, 31, v238
	v_lshl_add_u64 v[126:127], v[204:205], 0, s[46:47]
	v_lshlrev_b64 v[240:241], 11, v[238:239]
	v_lshl_add_u64 v[122:123], v[126:127], 0, v[240:241]
	global_load_dwordx4 v[190:193], v[122:123], off
	global_load_dwordx4 v[186:189], v[122:123], off offset:256
	v_or_b32_e32 v234, 16, v238
	v_ashrrev_i32_e32 v235, 31, v234
	v_or_b32_e32 v230, 32, v238
	v_lshlrev_b64 v[236:237], 11, v[234:235]
	v_ashrrev_i32_e32 v231, 31, v230
	v_or_b32_e32 v226, 48, v238
	v_lshl_add_u64 v[122:123], v[126:127], 0, v[236:237]
	v_lshlrev_b64 v[232:233], 11, v[230:231]
	v_ashrrev_i32_e32 v227, 31, v226
	v_add_u32_e32 v222, 0x80, v238
	global_load_dwordx4 v[182:185], v[122:123], off
	global_load_dwordx4 v[178:181], v[122:123], off offset:256
	v_lshl_add_u64 v[122:123], v[126:127], 0, v[232:233]
	v_lshlrev_b64 v[228:229], 11, v[226:227]
	v_ashrrev_i32_e32 v223, 31, v222
	v_add_u32_e32 v218, 0x90, v238
	global_load_dwordx4 v[174:177], v[122:123], off
	global_load_dwordx4 v[170:173], v[122:123], off offset:256
	v_lshl_add_u64 v[122:123], v[126:127], 0, v[228:229]
	v_lshlrev_b64 v[224:225], 11, v[222:223]
	v_ashrrev_i32_e32 v219, 31, v218
	v_add_u32_e32 v212, 0xa0, v238
	v_add_u32_e32 v210, 0xb0, v238
	global_load_dwordx4 v[166:169], v[122:123], off
	global_load_dwordx4 v[162:165], v[122:123], off offset:256
	v_lshl_add_u64 v[122:123], v[126:127], 0, v[224:225]
	v_lshlrev_b64 v[220:221], 11, v[218:219]
	v_ashrrev_i32_e32 v213, 31, v212
	v_ashrrev_i32_e32 v211, 31, v210
	global_load_dwordx4 v[158:161], v[122:123], off
	global_load_dwordx4 v[146:149], v[122:123], off offset:256
	v_lshl_add_u64 v[122:123], v[126:127], 0, v[220:221]
	v_lshlrev_b64 v[216:217], 11, v[212:213]
	v_lshlrev_b64 v[214:215], 11, v[210:211]
	global_load_dwordx4 v[142:145], v[122:123], off
	global_load_dwordx4 v[138:141], v[122:123], off offset:256
	v_lshl_add_u64 v[122:123], v[126:127], 0, v[216:217]
	v_lshl_add_u64 v[126:127], v[126:127], 0, v[214:215]
	global_load_dwordx4 v[130:133], v[122:123], off
	s_nop 0
	global_load_dwordx4 v[122:125], v[122:123], off offset:256
	s_nop 0
	global_load_dwordx4 v[134:137], v[126:127], off
	s_nop 0
	global_load_dwordx4 v[126:129], v[126:127], off offset:256
	v_lshl_add_u64 v[240:241], s[14:15], 0, v[240:241]
	v_lshl_add_u64 v[240:241], v[240:241], 0, s[46:47]
	v_lshl_add_u64 v[240:241], v[240:241], 0, v[202:203]
	v_and_b32_e32 v250, 64, v248
	v_xor_b32_e32 v249, 16, v248
	v_add_u32_e32 v250, 64, v250
	v_cmp_lt_i32_e32 vcc, v249, v250
	v_xor_b32_e32 v251, 32, v248
	s_waitcnt vmcnt(0)
	v_lshlrev_b32_e32 v252, 16, v190
	v_and_b32_e32 v253, 0xffff0000, v190
	v_lshlrev_b32_e32 v190, 16, v191
	v_and_b32_e32 v191, 0xffff0000, v191
	v_lshlrev_b32_e32 v254, 16, v192
	v_and_b32_e32 v255, 0xffff0000, v192
	v_lshlrev_b32_e32 v192, 16, v193
	v_and_b32_e32 v193, 0xffff0000, v193
	v_pk_fma_f32 v[156:157], v[156:157], 0.5, v[190:191] op_sel_hi:[1,0,1]
	v_pk_fma_f32 v[154:155], v[154:155], 0.5, v[252:253] op_sel_hi:[1,0,1]
	v_pk_fma_f32 v[190:191], v[152:153], 0.5, v[192:193] op_sel_hi:[1,0,1]
	v_pk_fma_f32 v[192:193], v[150:151], 0.5, v[254:255] op_sel_hi:[1,0,1]
	v_cvt_pk_bf16_f32 v150, v154, v155
	v_cvt_pk_bf16_f32 v151, v156, v157
	v_cvt_pk_bf16_f32 v152, v192, v193
	v_cvt_pk_bf16_f32 v153, v190, v191
	global_store_dwordx4 v[240:241], v[150:153], off
	v_cndmask_b32_e32 v249, v248, v249, vcc
	v_lshlrev_b32_e32 v249, 2, v249
	v_mul_f32_e32 v150, v155, v155
	v_mul_f32_e32 v151, v157, v157
	v_fmac_f32_e32 v150, v154, v154
	v_fmac_f32_e32 v151, v156, v156
	v_add_f32_e32 v150, v150, v151
	v_mul_f32_e32 v151, v193, v193
	v_mul_f32_e32 v152, v191, v191
	v_fmac_f32_e32 v151, v192, v192
	v_fmac_f32_e32 v152, v190, v190
	v_add_f32_e32 v151, v151, v152
	v_add_f32_e32 v190, v150, v151
	v_lshlrev_b32_e32 v150, 16, v186
	v_and_b32_e32 v151, 0xffff0000, v186
	v_lshlrev_b32_e32 v152, 16, v187
	v_and_b32_e32 v153, 0xffff0000, v187
	v_lshlrev_b32_e32 v154, 16, v188
	v_and_b32_e32 v155, 0xffff0000, v188
	v_lshlrev_b32_e32 v156, 16, v189
	v_and_b32_e32 v157, 0xffff0000, v189
	v_pk_fma_f32 v[120:121], v[120:121], 0.5, v[152:153] op_sel_hi:[1,0,1]
	v_pk_fma_f32 v[118:119], v[118:119], 0.5, v[150:151] op_sel_hi:[1,0,1]
	v_pk_fma_f32 v[150:151], v[116:117], 0.5, v[156:157] op_sel_hi:[1,0,1]
	v_pk_fma_f32 v[152:153], v[114:115], 0.5, v[154:155] op_sel_hi:[1,0,1]
	v_cvt_pk_bf16_f32 v114, v118, v119
	v_cvt_pk_bf16_f32 v115, v120, v121
	v_cvt_pk_bf16_f32 v116, v152, v153
	v_cvt_pk_bf16_f32 v117, v150, v151
	global_store_dwordx4 v[240:241], v[114:117], off offset:256
	v_cmp_lt_i32_e32 vcc, v251, v250
	s_nop 0
	v_mul_f32_e32 v114, v119, v119
	v_mul_f32_e32 v115, v121, v121
	v_fmac_f32_e32 v114, v118, v118
	v_fmac_f32_e32 v115, v120, v120
	v_add_f32_e32 v114, v114, v115
	v_mul_f32_e32 v115, v153, v153
	v_mul_f32_e32 v116, v151, v151
	v_fmac_f32_e32 v115, v152, v152
	v_fmac_f32_e32 v116, v150, v150
	v_add_f32_e32 v115, v115, v116
	v_add_f32_e32 v114, v114, v115
	v_add_f32_e32 v114, v190, v114
	ds_bpermute_b32 v115, v249, v114
	v_cndmask_b32_e32 v250, v248, v251, vcc
	v_lshlrev_b32_e32 v250, 2, v250
	s_waitcnt lgkmcnt(0)
	v_add_f32_e32 v114, v114, v115
	ds_bpermute_b32 v115, v250, v114
	s_and_saveexec_b64 s[46:47], s[4:5]
	s_cbranch_execz .LBB0_256
	v_lshl_add_u64 v[116:117], v[238:239], 2, s[16:17]
	s_waitcnt lgkmcnt(0)
	v_add_f32_e32 v114, v114, v115
	global_atomic_add_f32 v[116:117], v114, off

.LBB0_270:
	s_or_b64 exec, exec, s[44:45]
	s_and_b64 vcc, exec, s[6:7]
	s_mov_b64 s[6:7], -1
	s_cbranch_vccnz .LBB0_239
	s_andn2_b64 vcc, exec, s[12:13]
	s_cbranch_vccnz .LBB0_238
	s_branch .LBB0_238

.LBB0_341:
.LBB0_342:
	s_cmp_lt_i32 s20, 4
	s_cselect_b64 s[6:7], -1, 0
	s_and_b64 s[8:9], s[6:7], s[4:5]
	s_andn2_b64 vcc, exec, s[8:9]
	s_cbranch_vccnz .LBB0_359
	s_mov_b64 s[4:5], s[0:1]
	s_mov_b64 s[10:11], s[0:1]
	s_mov_b64 s[6:7], s[0:1]
	s_mov_b64 s[12:13], s[0:1]
	v_mov_b32_e32 v10, v1
	s_cmpk_gt_i32 s2, 0x5ff
	v_readfirstlane_b32 s25, v10
	s_cbranch_scc1 .LBB0_359
	v_lshlrev_b32_e32 v2, 4, v10
	v_add_u32_e32 v3, 0x2000, v2
	v_ashrrev_i32_e32 v4, 31, v3
	v_lshrrev_b32_e32 v4, 22, v4
	v_add_u32_e32 v4, v3, v4
	v_ashrrev_i32_e32 v11, 10, v4
	v_mul_i32_i24_e32 v4, 0x400, v11
	v_sub_u32_e32 v3, v3, v4
	v_lshrrev_b32_e32 v4, 4, v3
	v_bitop3_b32 v3, v4, v3, 32 bitop3:0x6c
	v_ashrrev_i32_e32 v4, 31, v3
	v_lshrrev_b32_e32 v4, 26, v4
	v_add_u32_e32 v4, v3, v4
	v_lshlrev_b32_e32 v5, 3, v11
	v_ashrrev_i32_e32 v12, 6, v4
	v_and_b32_e32 v5, -16, v5
	v_add_u32_e32 v5, v12, v5
	s_load_dwordx2 s[14:15], s[6:7], 0xa8
	s_load_dwordx2 s[16:17], s[12:13], 0xa8
	v_and_b32_e32 v6, 3, v12
	s_mov_b32 s6, 0x1fffe0
	v_lshrrev_b32_e32 v7, 2, v5
	v_lshlrev_b32_e32 v8, 1, v5
	v_and_b32_e32 v4, 0xc0, v4
	v_and_or_b32 v6, v5, s6, v6
	v_and_b32_e32 v7, 4, v7
	v_and_b32_e32 v8, 24, v8
	v_sub_u32_e32 v3, v3, v4
	v_mov_b32_e32 v4, 1
	v_or3_b32 v6, v6, v7, v8
	v_lshlrev_b32_e32 v7, 5, v11
	v_ashrrev_i16_sdwa v3, v4, sext(v3) dst_sel:DWORD dst_unused:UNUSED_PAD src0_sel:DWORD src1_sel:BYTE_0
	v_and_b32_e32 v7, 32, v7
	v_bfe_i32 v13, v3, 0, 16
	v_add_lshl_u32 v3, v7, v13, 1
	v_lshl_add_u32 v130, v6, 11, v3
	v_lshl_add_u32 v132, v5, 11, v3
	v_bfe_i32 v3, v10, 27, 1
	v_lshrrev_b32_e32 v3, 22, v3
	v_add_u32_e32 v3, v2, v3
	v_and_b32_e32 v3, 0xfffffc00, v3
	v_sub_u32_e32 v2, v2, v3
	v_lshrrev_b32_e32 v3, 4, v2
	v_ashrrev_i32_e32 v5, 31, v10
	v_bitop3_b32 v2, v3, v2, 32 bitop3:0x6c
	v_lshrrev_b32_e32 v5, 26, v5
	v_ashrrev_i32_e32 v3, 31, v2
	v_add_u32_e32 v5, v10, v5
	s_waitcnt lgkmcnt(0)
	s_add_u32 s3, s14, 0x6400000
	v_lshrrev_b32_e32 v3, 26, v3
	v_ashrrev_i32_e32 v15, 6, v5
	s_addc_u32 s23, s15, 0
	v_add_u32_e32 v3, v2, v3
	v_lshlrev_b32_e32 v5, 3, v15
	s_add_u32 s29, s16, 0x4600000
	v_ashrrev_i32_e32 v14, 6, v3
	v_and_b32_e32 v5, -16, v5
	s_addc_u32 s31, s17, 0
	v_add_u32_e32 v5, v14, v5
	v_and_b32_e32 v6, 3, v14
	s_ashr_i32 s55, s2, 31
	v_and_or_b32 v6, v5, s6, v6
	s_lshr_b32 s6, s55, 29
	s_add_i32 s6, s2, s6
	s_ashr_i32 s16, s25, 6
	s_ashr_i32 s7, s6, 3
	s_and_b32 s6, s6, -8
	s_ashr_i32 s26, s25, 8
	s_lshl_b32 s54, s16, 10
	s_sub_i32 s6, s2, s6
	s_cmp_lt_i32 s6, 0
	s_movk_i32 s56, 0xc1
	s_cselect_b32 s12, s56, 0xc0
	s_mul_i32 s6, s6, s12
	s_add_i32 s6, s6, s7
	s_mul_hi_i32 s7, s6, 0x2aaaaaab
	s_lshr_b32 s12, s7, 31
	s_ashr_i32 s7, s7, 4
	s_add_i32 s7, s7, s12
	s_lshl_b32 s12, s7, 3
	s_mulk_i32 s7, 0x60
	s_sub_i32 s6, s6, s7
	s_bfe_i32 s7, s6, 0x80000
	s_bfe_u32 s7, s7, 0x3000c
	s_add_i32 s7, s6, s7
	s_bfe_i32 s13, s7, 0x80000
	s_and_b32 s7, s7, 0xf8
	s_sub_i32 s6, s6, s7
	s_sext_i32_i16 s13, s13
	s_sext_i32_i8 s6, s6
	v_lshrrev_b32_e32 v7, 2, v5
	v_lshlrev_b32_e32 v8, 1, v5
	v_and_b32_e32 v3, 0xc0, v3
	s_lshr_b32 s24, s13, 3
	s_add_i32 s6, s12, s6
	v_and_b32_e32 v7, 4, v7
	v_and_b32_e32 v8, 24, v8
	v_sub_u32_e32 v2, v2, v3
	s_ashr_i32 s7, s6, 31
	s_bfe_i64 s[14:15], s[24:25], 0x100000
	v_or3_b32 v6, v6, v7, v8
	v_lshlrev_b32_e32 v7, 5, v15
	v_ashrrev_i16_sdwa v2, v4, sext(v2) dst_sel:DWORD dst_unused:UNUSED_PAD src0_sel:DWORD src1_sel:BYTE_0
	s_lshl_b64 s[12:13], s[6:7], 19
	s_lshl_b64 s[14:15], s[14:15], 19
	v_and_b32_e32 v7, 32, v7
	v_bfe_i32 v16, v2, 0, 16
	s_add_u32 s50, s29, s14
	v_add_lshl_u32 v2, v7, v16, 1
	s_addc_u32 s51, s31, s15
	s_add_i32 s57, s54, 0
	v_lshl_add_u32 v134, v6, 11, v2
	s_add_i32 m0, s57, 0x10000
	v_lshl_add_u32 v136, v5, 11, v2
	global_load_lds_dwordx4 v134, s[50:51]
	s_add_i32 m0, s57, 0x12000
	s_add_u32 s14, s50, 0x40000
	global_load_lds_dwordx4 v130, s[50:51]
	s_addc_u32 s15, s51, 0
	s_add_i32 m0, s57, 0x14000
	v_mov_b32_e32 v139, 0
	global_load_lds_dwordx4 v134, s[14:15]
	s_add_i32 m0, s57, 0x16000
	s_add_u32 s48, s3, s12
	s_addc_u32 s49, s23, s13
	s_add_i32 s58, s57, 0x2000
	global_load_lds_dwordx4 v130, s[14:15]
	s_mov_b32 m0, s57
	s_add_u32 s12, s48, 0x40000
	global_load_lds_dwordx4 v136, s[48:49]
	s_mov_b32 m0, s58
	s_addc_u32 s13, s49, 0
	s_add_i32 s59, s57, 0x4000
	global_load_lds_dwordx4 v132, s[48:49]
	s_mov_b32 m0, s59
	s_add_i32 s60, s57, 0x6000
	global_load_lds_dwordx4 v136, s[12:13]
	s_mov_b32 m0, s60
	v_mov_b32_e32 v135, v139
	global_load_lds_dwordx4 v132, s[12:13]
	s_load_dwordx2 s[14:15], s[4:5], 0xa8
	s_nop 0
	s_load_dwordx2 s[4:5], s[10:11], 0xa8
	v_mov_b32_e32 v131, v139
	v_mov_b32_e32 v137, v139
	v_mov_b32_e32 v133, v139
	s_cmp_eq_u32 s26, 1
	s_mov_b32 s11, 0
	v_lshl_add_u64 v[8:9], s[50:51], 0, v[134:135]
	v_lshl_add_u64 v[6:7], s[50:51], 0, v[130:131]
	v_lshl_add_u64 v[2:3], s[48:49], 0, v[136:137]
	s_cselect_b64 s[12:13], -1, 0
	s_cmp_lg_u32 s26, 1
	v_lshl_add_u64 v[4:5], s[48:49], 0, v[132:133]
	s_cbranch_scc1 .LBB0_346
.LBB0_346:
	s_waitcnt lgkmcnt(0)
	s_add_u32 s14, s14, 0x20000
	s_addc_u32 s15, s15, 0
	s_add_u32 s61, s4, 0xa400000
	s_addc_u32 s62, s5, 0
	s_lshl_b32 s4, s16, 5
	s_mov_b64 s[16:17], 0x80
	s_and_b32 s27, s4, 0x60
	s_add_i32 m0, s57, 0x18000
	v_lshl_add_u64 v[8:9], v[8:9], 0, s[16:17]
	s_lshl_b32 s7, s26, 13
	s_lshl_b32 s42, s27, 7
	s_waitcnt vmcnt(2)
	s_barrier
	global_load_lds_dwordx4 v[8:9], off
	v_lshl_add_u64 v[6:7], v[6:7], 0, s[16:17]
	s_add_i32 m0, s57, 0x1a000
	s_add_i32 s63, s57, 0x8000
	s_add_i32 s64, s57, 0xa000
	global_load_lds_dwordx4 v[6:7], off
	v_lshl_add_u64 v[2:3], v[2:3], 0, s[16:17]
	s_mov_b32 m0, s63
	s_add_u32 s4, s50, 0x40080
	global_load_lds_dwordx4 v[2:3], off
	v_lshl_add_u64 v[2:3], v[4:5], 0, s[16:17]
	s_mov_b32 m0, s64
	s_addc_u32 s5, s51, 0
	global_load_lds_dwordx4 v[2:3], off
	s_add_i32 m0, s57, 0x1c000
	v_lshl_add_u64 v[2:3], s[4:5], 0, v[134:135]
	global_load_lds_dwordx4 v[2:3], off
	v_lshl_add_u64 v[2:3], s[4:5], 0, v[130:131]
	s_add_i32 m0, s57, 0x1e000
	s_cmpk_lt_u32 s25, 0x100
	global_load_lds_dwordx4 v[2:3], off
	v_lshrrev_b32_e32 v3, 1, v10
	v_and_b32_e32 v3, 24, v3
	v_and_b32_e32 v2, 15, v10
	v_lshlrev_b32_e32 v4, 1, v3
	v_lshl_or_b32 v150, s26, 6, v2
	v_lshl_or_b32 v2, v2, 6, v4
	v_lshlrev_b32_e32 v4, 2, v10
	v_and_b32_e32 v4, 32, v4
	v_bitop3_b32 v5, v2, s7, v4 bitop3:0xde
	v_bitop3_b32 v151, v2, s42, v4 bitop3:0xde
	v_or_b32_e32 v2, s27, v3
	v_lshlrev_b32_e32 v3, 14, v15
	v_and_b32_e32 v3, 0xffff8000, v3
	v_lshl_add_u32 v3, v14, 11, v3
	v_and_b32_e32 v4, 1, v15
	v_lshl_or_b32 v3, v4, 6, v3
	v_lshl_add_u32 v140, v16, 1, v3
	v_lshlrev_b32_e32 v3, 14, v11
	v_and_b32_e32 v3, 0xffff8000, v3
	s_waitcnt vmcnt(6)
	v_lshl_add_u32 v3, v12, 11, v3
	v_and_b32_e32 v4, 1, v11
	s_sext_i32_i8 s10, s24
	s_cselect_b64 s[24:25], -1, 0
	v_lshl_or_b32 v3, v4, 6, v3
	s_add_i32 s67, 0, 0x10000
	s_add_i32 s68, 0, 0x14000
	s_ashr_i32 s65, s38, 31
	s_mov_b32 s66, s38
	v_mov_b32_e32 v141, v139
	v_lshl_add_u32 v142, v13, 1, v3
	v_mov_b32_e32 v143, v139
	v_mov_b64_e32 v[144:145], 0x600
	v_mov_b64_e32 v[146:147], 0x5ff
	v_add_u32_e32 v152, s67, v151
	v_add_u32_e32 v153, s68, v151
	v_add_u32_e32 v154, 0, v5
	v_mov_b32_e32 v155, 0x358637bd
	v_lshlrev_b32_e32 v138, 1, v2
	s_mov_b32 s69, 0
	s_barrier
	s_branch .LBB0_349

.LBB0_351:
	s_ashr_i32 s43, s42, 31
	s_lshl_b64 s[44:45], s[42:43], 19
	s_add_u32 s44, s3, s44
	s_addc_u32 s45, s23, s45
	s_and_b64 s[46:47], s[4:5], exec
	s_cselect_b32 s7, s45, s49
	s_cselect_b32 s43, s44, s48
	s_ashr_i32 s27, s26, 31
	s_lshl_b64 s[46:47], s[26:27], 19
	s_add_u32 s46, s29, s46
	s_addc_u32 s47, s31, s47
	s_and_b64 s[52:53], s[4:5], exec
	s_cselect_b32 s27, s47, s51
	s_cselect_b32 s70, s46, s50
	s_add_u32 s48, s48, 0x40080
	s_addc_u32 s49, s49, 0
	s_add_u32 s71, s50, 0x100
	v_mov_b32_e32 v2, 0
	s_addc_u32 s72, s51, 0
	s_mov_b32 s73, -2
	v_mov_b32_e32 v3, v2
	v_mov_b32_e32 v4, v2
	v_mov_b32_e32 v5, v2
	v_mov_b32_e32 v6, v2
	v_mov_b32_e32 v7, v2
	v_mov_b32_e32 v8, v2
	v_mov_b32_e32 v9, v2
	v_mov_b32_e32 v18, v2
	v_mov_b32_e32 v19, v2
	v_mov_b32_e32 v20, v2
	v_mov_b32_e32 v21, v2
	v_mov_b32_e32 v22, v2
	v_mov_b32_e32 v23, v2
	v_mov_b32_e32 v24, v2
	v_mov_b32_e32 v25, v2
	v_mov_b32_e32 v34, v2
	v_mov_b32_e32 v35, v2
	v_mov_b32_e32 v36, v2
	v_mov_b32_e32 v37, v2
	v_mov_b32_e32 v38, v2
	v_mov_b32_e32 v39, v2
	v_mov_b32_e32 v40, v2
	v_mov_b32_e32 v41, v2
	v_mov_b32_e32 v50, v2
	v_mov_b32_e32 v51, v2
	v_mov_b32_e32 v52, v2
	v_mov_b32_e32 v53, v2
	v_mov_b32_e32 v54, v2
	v_mov_b32_e32 v55, v2
	v_mov_b32_e32 v56, v2
	v_mov_b32_e32 v57, v2
	v_mov_b32_e32 v10, v2
	v_mov_b32_e32 v11, v2
	v_mov_b32_e32 v12, v2
	v_mov_b32_e32 v13, v2
	v_mov_b32_e32 v14, v2
	v_mov_b32_e32 v15, v2
	v_mov_b32_e32 v16, v2
	v_mov_b32_e32 v17, v2
	v_mov_b32_e32 v26, v2
	v_mov_b32_e32 v27, v2
	v_mov_b32_e32 v28, v2
	v_mov_b32_e32 v29, v2
	v_mov_b32_e32 v30, v2
	v_mov_b32_e32 v31, v2
	v_mov_b32_e32 v32, v2
	v_mov_b32_e32 v33, v2
	v_mov_b32_e32 v42, v2
	v_mov_b32_e32 v43, v2
	v_mov_b32_e32 v44, v2
	v_mov_b32_e32 v45, v2
	v_mov_b32_e32 v46, v2
	v_mov_b32_e32 v47, v2
	v_mov_b32_e32 v48, v2
	v_mov_b32_e32 v49, v2
	v_mov_b32_e32 v58, v2
	v_mov_b32_e32 v59, v2
	v_mov_b32_e32 v60, v2
	v_mov_b32_e32 v61, v2
	v_mov_b32_e32 v62, v2
	v_mov_b32_e32 v63, v2
	v_mov_b32_e32 v64, v2
	v_mov_b32_e32 v65, v2
	v_mov_b32_e32 v66, v2
	v_mov_b32_e32 v67, v2
	v_mov_b32_e32 v68, v2
	v_mov_b32_e32 v69, v2
	v_mov_b32_e32 v70, v2
	v_mov_b32_e32 v71, v2
	v_mov_b32_e32 v72, v2
	v_mov_b32_e32 v73, v2
	v_mov_b32_e32 v82, v2
	v_mov_b32_e32 v83, v2
	v_mov_b32_e32 v84, v2
	v_mov_b32_e32 v85, v2
	v_mov_b32_e32 v86, v2
	v_mov_b32_e32 v87, v2
	v_mov_b32_e32 v88, v2
	v_mov_b32_e32 v89, v2
	v_mov_b32_e32 v98, v2
	v_mov_b32_e32 v99, v2
	v_mov_b32_e32 v100, v2
	v_mov_b32_e32 v101, v2
	v_mov_b32_e32 v102, v2
	v_mov_b32_e32 v103, v2
	v_mov_b32_e32 v104, v2
	v_mov_b32_e32 v105, v2
	v_mov_b32_e32 v114, v2
	v_mov_b32_e32 v115, v2
	v_mov_b32_e32 v116, v2
	v_mov_b32_e32 v117, v2
	v_mov_b32_e32 v118, v2
	v_mov_b32_e32 v119, v2
	v_mov_b32_e32 v120, v2
	v_mov_b32_e32 v121, v2
	v_mov_b32_e32 v74, v2
	v_mov_b32_e32 v75, v2
	v_mov_b32_e32 v76, v2
	v_mov_b32_e32 v77, v2
	v_mov_b32_e32 v78, v2
	v_mov_b32_e32 v79, v2
	v_mov_b32_e32 v80, v2
	v_mov_b32_e32 v81, v2
	v_mov_b32_e32 v90, v2
	v_mov_b32_e32 v91, v2
	v_mov_b32_e32 v92, v2
	v_mov_b32_e32 v93, v2
	v_mov_b32_e32 v94, v2
	v_mov_b32_e32 v95, v2
	v_mov_b32_e32 v96, v2
	v_mov_b32_e32 v97, v2
	v_mov_b32_e32 v106, v2
	v_mov_b32_e32 v107, v2
	v_mov_b32_e32 v108, v2
	v_mov_b32_e32 v109, v2
	v_mov_b32_e32 v110, v2
	v_mov_b32_e32 v111, v2
	v_mov_b32_e32 v112, v2
	v_mov_b32_e32 v113, v2
	v_mov_b32_e32 v122, v2
	v_mov_b32_e32 v123, v2
	v_mov_b32_e32 v124, v2
	v_mov_b32_e32 v125, v2
	v_mov_b32_e32 v126, v2
	v_mov_b32_e32 v127, v2
	v_mov_b32_e32 v128, v2
	v_mov_b32_e32 v129, v2
	s_cmp_eq_u64 s[24:25], 0
	s_cbranch_scc1 .Lhb_B_p3
.LBB0_352:
	ds_read_b128 v[156:159], v152
	ds_read_b128 v[160:163], v152 offset:1024
	ds_read_b128 v[164:167], v152 offset:2048
	ds_read_b128 v[168:171], v152 offset:3072
	ds_read_b128 v[172:175], v153
	ds_read_b128 v[176:179], v153 offset:1024
	ds_read_b128 v[180:183], v153 offset:2048
	ds_read_b128 v[184:187], v153 offset:3072
	s_add_u32 s50, s48, 0xfffc0080
	s_addc_u32 s51, s49, -1
	s_cmp_eq_u32 s73, 12
	s_cselect_b32 s53, s7, s51
	s_cselect_b32 s52, s43, s50
	s_cselect_b32 s51, s27, s72
	s_cselect_b32 s50, s70, s71
	v_lshl_add_u64 v[148:149], s[48:49], 0, v[140:141]
	s_add_i32 m0, s57, 0xc000
	ds_read_b128 v[188:191], v154
	ds_read_b128 v[192:195], v154 offset:1024
	ds_read_b128 v[196:199], v154 offset:2048
	ds_read_b128 v[200:203], v154 offset:3072
	ds_read_b128 v[204:207], v154 offset:4096
	ds_read_b128 v[208:211], v154 offset:5120
	ds_read_b128 v[212:215], v154 offset:6144
	ds_read_b128 v[216:219], v154 offset:7168
	global_load_lds_dwordx4 v[148:149], off
	v_lshl_add_u64 v[148:149], s[48:49], 0, v[142:143]
	s_add_i32 m0, s57, 0xe000
	s_nop 0
	global_load_lds_dwordx4 v[148:149], off
	s_waitcnt vmcnt(8)
	s_waitcnt lgkmcnt(0)
	s_setprio 1
	v_mfma_f32_16x16x32_bf16 v[126:129], v[156:159], v[188:191], v[126:129]
	v_mfma_f32_16x16x32_bf16 v[122:125], v[164:167], v[188:191], v[122:125]
	v_mfma_f32_16x16x32_bf16 v[110:113], v[156:159], v[196:199], v[110:113]
	v_mfma_f32_16x16x32_bf16 v[106:109], v[164:167], v[196:199], v[106:109]
	v_mfma_f32_16x16x32_bf16 v[94:97], v[156:159], v[204:207], v[94:97]
	v_mfma_f32_16x16x32_bf16 v[90:93], v[164:167], v[204:207], v[90:93]
	v_mfma_f32_16x16x32_bf16 v[78:81], v[156:159], v[212:215], v[78:81]
	v_mfma_f32_16x16x32_bf16 v[74:77], v[164:167], v[212:215], v[74:77]
	v_mfma_f32_16x16x32_bf16 v[126:129], v[160:163], v[192:195], v[126:129]
	v_mfma_f32_16x16x32_bf16 v[122:125], v[168:171], v[192:195], v[122:125]
	v_mfma_f32_16x16x32_bf16 v[110:113], v[160:163], v[200:203], v[110:113]
	v_mfma_f32_16x16x32_bf16 v[106:109], v[168:171], v[200:203], v[106:109]
	v_mfma_f32_16x16x32_bf16 v[94:97], v[160:163], v[208:211], v[94:97]
	v_mfma_f32_16x16x32_bf16 v[90:93], v[168:171], v[208:211], v[90:93]
	v_mfma_f32_16x16x32_bf16 v[78:81], v[160:163], v[216:219], v[78:81]
	v_mfma_f32_16x16x32_bf16 v[74:77], v[168:171], v[216:219], v[74:77]
	s_setprio 0
	s_setprio 1
	v_mfma_f32_16x16x32_bf16 v[118:121], v[172:175], v[188:191], v[118:121]
	v_mfma_f32_16x16x32_bf16 v[114:117], v[180:183], v[188:191], v[114:117]
	v_mfma_f32_16x16x32_bf16 v[102:105], v[172:175], v[196:199], v[102:105]
	v_mfma_f32_16x16x32_bf16 v[98:101], v[180:183], v[196:199], v[98:101]
	v_mfma_f32_16x16x32_bf16 v[86:89], v[172:175], v[204:207], v[86:89]
	v_mfma_f32_16x16x32_bf16 v[82:85], v[180:183], v[204:207], v[82:85]
	v_mfma_f32_16x16x32_bf16 v[70:73], v[172:175], v[212:215], v[70:73]
	v_mfma_f32_16x16x32_bf16 v[66:69], v[180:183], v[212:215], v[66:69]
	v_mfma_f32_16x16x32_bf16 v[118:121], v[176:179], v[192:195], v[118:121]
	v_mfma_f32_16x16x32_bf16 v[114:117], v[184:187], v[192:195], v[114:117]
	v_mfma_f32_16x16x32_bf16 v[102:105], v[176:179], v[200:203], v[102:105]
	v_mfma_f32_16x16x32_bf16 v[98:101], v[184:187], v[200:203], v[98:101]
	v_mfma_f32_16x16x32_bf16 v[86:89], v[176:179], v[208:211], v[86:89]
	v_mfma_f32_16x16x32_bf16 v[82:85], v[184:187], v[208:211], v[82:85]
	v_mfma_f32_16x16x32_bf16 v[70:73], v[176:179], v[216:219], v[70:73]
	v_mfma_f32_16x16x32_bf16 v[66:69], v[184:187], v[216:219], v[66:69]
	s_setprio 0
	s_barrier
	s_add_i32 s74, s67, s54
	v_lshl_add_u64 v[148:149], s[50:51], 0, v[134:135]
	s_mov_b32 m0, s74
	ds_read_b128 v[188:191], v154 offset:16384
	ds_read_b128 v[192:195], v154 offset:17408
	ds_read_b128 v[196:199], v154 offset:18432
	ds_read_b128 v[200:203], v154 offset:19456
	ds_read_b128 v[204:207], v154 offset:20480
	ds_read_b128 v[208:211], v154 offset:21504
	ds_read_b128 v[212:215], v154 offset:22528
	ds_read_b128 v[216:219], v154 offset:23552
	global_load_lds_dwordx4 v[148:149], off
	s_add_i32 m0, s74, 0x2000
	s_add_u32 s74, s50, 0x40000
	v_lshl_add_u64 v[220:221], s[50:51], 0, v[130:131]
	s_addc_u32 s75, s51, 0
	s_add_i32 s76, s68, s54
	global_load_lds_dwordx4 v[220:221], off
	v_lshl_add_u64 v[222:223], s[74:75], 0, v[134:135]
	s_mov_b32 m0, s76
	v_lshl_add_u64 v[224:225], s[52:53], 0, v[132:133]
	global_load_lds_dwordx4 v[222:223], off
	v_lshl_add_u64 v[222:223], s[74:75], 0, v[130:131]
	s_add_i32 m0, s76, 0x2000
	s_nop 0
	global_load_lds_dwordx4 v[222:223], off
	v_lshl_add_u64 v[222:223], s[52:53], 0, v[136:137]
	s_mov_b32 m0, s57
	s_nop 0
	global_load_lds_dwordx4 v[222:223], off
	s_mov_b32 m0, s58
	s_nop 0
	global_load_lds_dwordx4 v[224:225], off
	s_waitcnt vmcnt(8)
	s_waitcnt lgkmcnt(0)
	s_setprio 1
	v_mfma_f32_16x16x32_bf16 v[62:65], v[156:159], v[188:191], v[62:65]
	v_mfma_f32_16x16x32_bf16 v[58:61], v[164:167], v[188:191], v[58:61]
	v_mfma_f32_16x16x32_bf16 v[46:49], v[156:159], v[196:199], v[46:49]
	v_mfma_f32_16x16x32_bf16 v[42:45], v[164:167], v[196:199], v[42:45]
	v_mfma_f32_16x16x32_bf16 v[30:33], v[156:159], v[204:207], v[30:33]
	v_mfma_f32_16x16x32_bf16 v[26:29], v[164:167], v[204:207], v[26:29]
	v_mfma_f32_16x16x32_bf16 v[14:17], v[156:159], v[212:215], v[14:17]
	v_mfma_f32_16x16x32_bf16 v[10:13], v[164:167], v[212:215], v[10:13]
	v_mfma_f32_16x16x32_bf16 v[62:65], v[160:163], v[192:195], v[62:65]
	v_mfma_f32_16x16x32_bf16 v[58:61], v[168:171], v[192:195], v[58:61]
	v_mfma_f32_16x16x32_bf16 v[46:49], v[160:163], v[200:203], v[46:49]
	v_mfma_f32_16x16x32_bf16 v[42:45], v[168:171], v[200:203], v[42:45]
	v_mfma_f32_16x16x32_bf16 v[30:33], v[160:163], v[208:211], v[30:33]
	v_mfma_f32_16x16x32_bf16 v[26:29], v[168:171], v[208:211], v[26:29]
	v_mfma_f32_16x16x32_bf16 v[14:17], v[160:163], v[216:219], v[14:17]
	v_mfma_f32_16x16x32_bf16 v[10:13], v[168:171], v[216:219], v[10:13]
	s_setprio 0
	s_setprio 1
	v_mfma_f32_16x16x32_bf16 v[54:57], v[172:175], v[188:191], v[54:57]
	v_mfma_f32_16x16x32_bf16 v[50:53], v[180:183], v[188:191], v[50:53]
	v_mfma_f32_16x16x32_bf16 v[38:41], v[172:175], v[196:199], v[38:41]
	v_mfma_f32_16x16x32_bf16 v[34:37], v[180:183], v[196:199], v[34:37]
	v_mfma_f32_16x16x32_bf16 v[22:25], v[172:175], v[204:207], v[22:25]
	v_mfma_f32_16x16x32_bf16 v[18:21], v[180:183], v[204:207], v[18:21]
	v_mfma_f32_16x16x32_bf16 v[6:9], v[172:175], v[212:215], v[6:9]
	v_mfma_f32_16x16x32_bf16 v[2:5], v[180:183], v[212:215], v[2:5]
	v_mfma_f32_16x16x32_bf16 v[54:57], v[176:179], v[192:195], v[54:57]
	v_mfma_f32_16x16x32_bf16 v[50:53], v[184:187], v[192:195], v[50:53]
	v_mfma_f32_16x16x32_bf16 v[38:41], v[176:179], v[200:203], v[38:41]
	v_mfma_f32_16x16x32_bf16 v[34:37], v[184:187], v[200:203], v[34:37]
	v_mfma_f32_16x16x32_bf16 v[22:25], v[176:179], v[208:211], v[22:25]
	v_mfma_f32_16x16x32_bf16 v[18:21], v[184:187], v[208:211], v[18:21]
	v_mfma_f32_16x16x32_bf16 v[6:9], v[176:179], v[216:219], v[6:9]
	v_mfma_f32_16x16x32_bf16 v[2:5], v[184:187], v[216:219], v[2:5]
	s_setprio 0
	s_barrier
	s_add_i32 s74, 0, 0x18000
	s_add_i32 s75, 0, 0x1c000
	v_add_u32_e32 v168, s74, v151
	v_add_u32_e32 v184, s75, v151
	ds_read_b128 v[156:159], v168
	ds_read_b128 v[160:163], v168 offset:1024
	ds_read_b128 v[164:167], v168 offset:2048
	ds_read_b128 v[168:171], v168 offset:3072
	ds_read_b128 v[172:175], v184
	ds_read_b128 v[176:179], v184 offset:1024
	ds_read_b128 v[180:183], v184 offset:2048
	ds_read_b128 v[184:187], v184 offset:3072
	s_add_u32 s52, s52, 0x40000
	s_addc_u32 s53, s53, 0
	s_mov_b32 m0, s59
	v_lshl_add_u64 v[226:227], s[52:53], 0, v[136:137]
	ds_read_b128 v[188:191], v154 offset:32768
	ds_read_b128 v[192:195], v154 offset:33792
	ds_read_b128 v[196:199], v154 offset:34816
	ds_read_b128 v[200:203], v154 offset:35840
	ds_read_b128 v[204:207], v154 offset:36864
	ds_read_b128 v[208:211], v154 offset:37888
	ds_read_b128 v[212:215], v154 offset:38912
	ds_read_b128 v[216:219], v154 offset:39936
	global_load_lds_dwordx4 v[226:227], off
	v_lshl_add_u64 v[226:227], s[52:53], 0, v[132:133]
	s_mov_b32 m0, s60
	s_nop 0
	global_load_lds_dwordx4 v[226:227], off
	s_waitcnt vmcnt(8)
	s_waitcnt lgkmcnt(0)
	s_setprio 1
	v_mfma_f32_16x16x32_bf16 v[126:129], v[156:159], v[188:191], v[126:129]
	v_mfma_f32_16x16x32_bf16 v[122:125], v[164:167], v[188:191], v[122:125]
	v_mfma_f32_16x16x32_bf16 v[110:113], v[156:159], v[196:199], v[110:113]
	v_mfma_f32_16x16x32_bf16 v[106:109], v[164:167], v[196:199], v[106:109]
	v_mfma_f32_16x16x32_bf16 v[94:97], v[156:159], v[204:207], v[94:97]
	v_mfma_f32_16x16x32_bf16 v[90:93], v[164:167], v[204:207], v[90:93]
	v_mfma_f32_16x16x32_bf16 v[78:81], v[156:159], v[212:215], v[78:81]
	v_mfma_f32_16x16x32_bf16 v[74:77], v[164:167], v[212:215], v[74:77]
	v_mfma_f32_16x16x32_bf16 v[126:129], v[160:163], v[192:195], v[126:129]
	v_mfma_f32_16x16x32_bf16 v[122:125], v[168:171], v[192:195], v[122:125]
	v_mfma_f32_16x16x32_bf16 v[110:113], v[160:163], v[200:203], v[110:113]
	v_mfma_f32_16x16x32_bf16 v[106:109], v[168:171], v[200:203], v[106:109]
	v_mfma_f32_16x16x32_bf16 v[94:97], v[160:163], v[208:211], v[94:97]
	v_mfma_f32_16x16x32_bf16 v[90:93], v[168:171], v[208:211], v[90:93]
	v_mfma_f32_16x16x32_bf16 v[78:81], v[160:163], v[216:219], v[78:81]
	v_mfma_f32_16x16x32_bf16 v[74:77], v[168:171], v[216:219], v[74:77]
	s_setprio 0
	s_setprio 1
	v_mfma_f32_16x16x32_bf16 v[118:121], v[172:175], v[188:191], v[118:121]
	v_mfma_f32_16x16x32_bf16 v[114:117], v[180:183], v[188:191], v[114:117]
	v_mfma_f32_16x16x32_bf16 v[102:105], v[172:175], v[196:199], v[102:105]
	v_mfma_f32_16x16x32_bf16 v[98:101], v[180:183], v[196:199], v[98:101]
	v_mfma_f32_16x16x32_bf16 v[86:89], v[172:175], v[204:207], v[86:89]
	v_mfma_f32_16x16x32_bf16 v[82:85], v[180:183], v[204:207], v[82:85]
	v_mfma_f32_16x16x32_bf16 v[70:73], v[172:175], v[212:215], v[70:73]
	v_mfma_f32_16x16x32_bf16 v[66:69], v[180:183], v[212:215], v[66:69]
	v_mfma_f32_16x16x32_bf16 v[118:121], v[176:179], v[192:195], v[118:121]
	v_mfma_f32_16x16x32_bf16 v[114:117], v[184:187], v[192:195], v[114:117]
	v_mfma_f32_16x16x32_bf16 v[102:105], v[176:179], v[200:203], v[102:105]
	v_mfma_f32_16x16x32_bf16 v[98:101], v[184:187], v[200:203], v[98:101]
	v_mfma_f32_16x16x32_bf16 v[86:89], v[176:179], v[208:211], v[86:89]
	v_mfma_f32_16x16x32_bf16 v[82:85], v[184:187], v[208:211], v[82:85]
	v_mfma_f32_16x16x32_bf16 v[70:73], v[176:179], v[216:219], v[70:73]
	v_mfma_f32_16x16x32_bf16 v[66:69], v[184:187], v[216:219], v[66:69]
	s_setprio 0
	s_barrier
	s_add_i32 s52, s74, s54
	v_lshl_add_u64 v[148:149], v[148:149], 0, s[16:17]
	s_mov_b32 m0, s52
	ds_read_b128 v[188:191], v154 offset:49152
	ds_read_b128 v[192:195], v154 offset:50176
	ds_read_b128 v[196:199], v154 offset:51200
	ds_read_b128 v[200:203], v154 offset:52224
	ds_read_b128 v[204:207], v154 offset:53248
	ds_read_b128 v[208:211], v154 offset:54272
	ds_read_b128 v[212:215], v154 offset:55296
	ds_read_b128 v[216:219], v154 offset:56320
	global_load_lds_dwordx4 v[148:149], off
	s_add_i32 m0, s52, 0x2000
	s_add_u32 s50, s50, 0x40080
	v_lshl_add_u64 v[148:149], v[220:221], 0, s[16:17]
	s_addc_u32 s51, s51, 0
	s_add_i32 s52, s75, s54
	global_load_lds_dwordx4 v[148:149], off
	v_lshl_add_u64 v[148:149], s[50:51], 0, v[134:135]
	s_mov_b32 m0, s52
	s_nop 0
	global_load_lds_dwordx4 v[148:149], off
	v_lshl_add_u64 v[148:149], s[50:51], 0, v[130:131]
	s_add_i32 m0, s52, 0x2000
	s_nop 0
	global_load_lds_dwordx4 v[148:149], off
	v_lshl_add_u64 v[148:149], v[222:223], 0, s[16:17]
	s_mov_b32 m0, s63
	s_nop 0
	global_load_lds_dwordx4 v[148:149], off
	v_lshl_add_u64 v[148:149], v[224:225], 0, s[16:17]
	s_mov_b32 m0, s64
	s_nop 0
	global_load_lds_dwordx4 v[148:149], off
	s_waitcnt vmcnt(8)
	s_waitcnt lgkmcnt(0)
	s_setprio 1
	v_mfma_f32_16x16x32_bf16 v[62:65], v[156:159], v[188:191], v[62:65]
	v_mfma_f32_16x16x32_bf16 v[58:61], v[164:167], v[188:191], v[58:61]
	v_mfma_f32_16x16x32_bf16 v[46:49], v[156:159], v[196:199], v[46:49]
	v_mfma_f32_16x16x32_bf16 v[42:45], v[164:167], v[196:199], v[42:45]
	v_mfma_f32_16x16x32_bf16 v[30:33], v[156:159], v[204:207], v[30:33]
	v_mfma_f32_16x16x32_bf16 v[26:29], v[164:167], v[204:207], v[26:29]
	v_mfma_f32_16x16x32_bf16 v[14:17], v[156:159], v[212:215], v[14:17]
	v_mfma_f32_16x16x32_bf16 v[10:13], v[164:167], v[212:215], v[10:13]
	v_mfma_f32_16x16x32_bf16 v[62:65], v[160:163], v[192:195], v[62:65]
	v_mfma_f32_16x16x32_bf16 v[58:61], v[168:171], v[192:195], v[58:61]
	v_mfma_f32_16x16x32_bf16 v[46:49], v[160:163], v[200:203], v[46:49]
	v_mfma_f32_16x16x32_bf16 v[42:45], v[168:171], v[200:203], v[42:45]
	v_mfma_f32_16x16x32_bf16 v[30:33], v[160:163], v[208:211], v[30:33]
	v_mfma_f32_16x16x32_bf16 v[26:29], v[168:171], v[208:211], v[26:29]
	v_mfma_f32_16x16x32_bf16 v[14:17], v[160:163], v[216:219], v[14:17]
	v_mfma_f32_16x16x32_bf16 v[10:13], v[168:171], v[216:219], v[10:13]
	s_setprio 0
	s_setprio 1
	v_mfma_f32_16x16x32_bf16 v[54:57], v[172:175], v[188:191], v[54:57]
	v_mfma_f32_16x16x32_bf16 v[50:53], v[180:183], v[188:191], v[50:53]
	v_mfma_f32_16x16x32_bf16 v[38:41], v[172:175], v[196:199], v[38:41]
	v_mfma_f32_16x16x32_bf16 v[34:37], v[180:183], v[196:199], v[34:37]
	v_mfma_f32_16x16x32_bf16 v[22:25], v[172:175], v[204:207], v[22:25]
	v_mfma_f32_16x16x32_bf16 v[18:21], v[180:183], v[204:207], v[18:21]
	v_mfma_f32_16x16x32_bf16 v[6:9], v[172:175], v[212:215], v[6:9]
	v_mfma_f32_16x16x32_bf16 v[2:5], v[180:183], v[212:215], v[2:5]
	v_mfma_f32_16x16x32_bf16 v[54:57], v[176:179], v[192:195], v[54:57]
	v_mfma_f32_16x16x32_bf16 v[50:53], v[184:187], v[192:195], v[50:53]
	v_mfma_f32_16x16x32_bf16 v[38:41], v[176:179], v[200:203], v[38:41]
	v_mfma_f32_16x16x32_bf16 v[34:37], v[184:187], v[200:203], v[34:37]
	v_mfma_f32_16x16x32_bf16 v[22:25], v[176:179], v[208:211], v[22:25]
	v_mfma_f32_16x16x32_bf16 v[18:21], v[184:187], v[208:211], v[18:21]
	v_mfma_f32_16x16x32_bf16 v[6:9], v[176:179], v[216:219], v[6:9]
	v_mfma_f32_16x16x32_bf16 v[2:5], v[184:187], v[216:219], v[2:5]
	s_setprio 0
	s_barrier
	s_add_i32 s73, s73, 2
	s_add_u32 s48, s48, 0x100
	s_addc_u32 s49, s49, 0
	s_add_u32 s71, s71, 0x100
	s_addc_u32 s72, s72, 0
	s_cmp_gt_u32 s73, 13
	s_cbranch_scc0 .LBB0_352
	s_branch .Lhb_exit_p3
.Lhb_B_p3:
	ds_read_b128 v[156:159], v152
	ds_read_b128 v[160:163], v152 offset:1024
	ds_read_b128 v[164:167], v152 offset:2048
	ds_read_b128 v[168:171], v152 offset:3072
	ds_read_b128 v[172:175], v153
	ds_read_b128 v[176:179], v153 offset:1024
	ds_read_b128 v[180:183], v153 offset:2048
	ds_read_b128 v[184:187], v153 offset:3072
	s_add_u32 s50, s48, 0xfffc0080
	s_addc_u32 s51, s49, -1
	s_cmp_eq_u32 s73, 12
	s_cselect_b32 s53, s7, s51
	s_cselect_b32 s52, s43, s50
	s_cselect_b32 s51, s27, s72
	s_cselect_b32 s50, s70, s71
	v_lshl_add_u64 v[148:149], s[48:49], 0, v[140:141]
	s_add_i32 m0, s57, 0xc000
	ds_read_b128 v[188:191], v154
	ds_read_b128 v[192:195], v154 offset:1024
	ds_read_b128 v[196:199], v154 offset:2048
	ds_read_b128 v[200:203], v154 offset:3072
	ds_read_b128 v[204:207], v154 offset:4096
	ds_read_b128 v[208:211], v154 offset:5120
	ds_read_b128 v[212:215], v154 offset:6144
	ds_read_b128 v[216:219], v154 offset:7168
	global_load_lds_dwordx4 v[148:149], off
	v_lshl_add_u64 v[148:149], s[48:49], 0, v[142:143]
	s_add_i32 m0, s57, 0xe000
	s_nop 0
	global_load_lds_dwordx4 v[148:149], off
	s_waitcnt vmcnt(8)
	s_waitcnt lgkmcnt(0)
	s_setprio 1
	s_barrier
	v_mfma_f32_16x16x32_bf16 v[126:129], v[156:159], v[188:191], v[126:129]
	v_mfma_f32_16x16x32_bf16 v[122:125], v[164:167], v[188:191], v[122:125]
	v_mfma_f32_16x16x32_bf16 v[110:113], v[156:159], v[196:199], v[110:113]
	v_mfma_f32_16x16x32_bf16 v[106:109], v[164:167], v[196:199], v[106:109]
	v_mfma_f32_16x16x32_bf16 v[94:97], v[156:159], v[204:207], v[94:97]
	v_mfma_f32_16x16x32_bf16 v[90:93], v[164:167], v[204:207], v[90:93]
	v_mfma_f32_16x16x32_bf16 v[78:81], v[156:159], v[212:215], v[78:81]
	v_mfma_f32_16x16x32_bf16 v[74:77], v[164:167], v[212:215], v[74:77]
	v_mfma_f32_16x16x32_bf16 v[126:129], v[160:163], v[192:195], v[126:129]
	v_mfma_f32_16x16x32_bf16 v[122:125], v[168:171], v[192:195], v[122:125]
	v_mfma_f32_16x16x32_bf16 v[110:113], v[160:163], v[200:203], v[110:113]
	v_mfma_f32_16x16x32_bf16 v[106:109], v[168:171], v[200:203], v[106:109]
	v_mfma_f32_16x16x32_bf16 v[94:97], v[160:163], v[208:211], v[94:97]
	v_mfma_f32_16x16x32_bf16 v[90:93], v[168:171], v[208:211], v[90:93]
	v_mfma_f32_16x16x32_bf16 v[78:81], v[160:163], v[216:219], v[78:81]
	v_mfma_f32_16x16x32_bf16 v[74:77], v[168:171], v[216:219], v[74:77]
	s_setprio 0
	s_setprio 1
	v_mfma_f32_16x16x32_bf16 v[118:121], v[172:175], v[188:191], v[118:121]
	v_mfma_f32_16x16x32_bf16 v[114:117], v[180:183], v[188:191], v[114:117]
	v_mfma_f32_16x16x32_bf16 v[102:105], v[172:175], v[196:199], v[102:105]
	v_mfma_f32_16x16x32_bf16 v[98:101], v[180:183], v[196:199], v[98:101]
	v_mfma_f32_16x16x32_bf16 v[86:89], v[172:175], v[204:207], v[86:89]
	v_mfma_f32_16x16x32_bf16 v[82:85], v[180:183], v[204:207], v[82:85]
	v_mfma_f32_16x16x32_bf16 v[70:73], v[172:175], v[212:215], v[70:73]
	v_mfma_f32_16x16x32_bf16 v[66:69], v[180:183], v[212:215], v[66:69]
	v_mfma_f32_16x16x32_bf16 v[118:121], v[176:179], v[192:195], v[118:121]
	v_mfma_f32_16x16x32_bf16 v[114:117], v[184:187], v[192:195], v[114:117]
	v_mfma_f32_16x16x32_bf16 v[102:105], v[176:179], v[200:203], v[102:105]
	v_mfma_f32_16x16x32_bf16 v[98:101], v[184:187], v[200:203], v[98:101]
	v_mfma_f32_16x16x32_bf16 v[86:89], v[176:179], v[208:211], v[86:89]
	v_mfma_f32_16x16x32_bf16 v[82:85], v[184:187], v[208:211], v[82:85]
	v_mfma_f32_16x16x32_bf16 v[70:73], v[176:179], v[216:219], v[70:73]
	v_mfma_f32_16x16x32_bf16 v[66:69], v[184:187], v[216:219], v[66:69]
	s_setprio 0
	s_add_i32 s74, s67, s54
	v_lshl_add_u64 v[148:149], s[50:51], 0, v[134:135]
	s_mov_b32 m0, s74
	ds_read_b128 v[188:191], v154 offset:16384
	ds_read_b128 v[192:195], v154 offset:17408
	ds_read_b128 v[196:199], v154 offset:18432
	ds_read_b128 v[200:203], v154 offset:19456
	ds_read_b128 v[204:207], v154 offset:20480
	ds_read_b128 v[208:211], v154 offset:21504
	ds_read_b128 v[212:215], v154 offset:22528
	ds_read_b128 v[216:219], v154 offset:23552
	global_load_lds_dwordx4 v[148:149], off
	s_add_i32 m0, s74, 0x2000
	s_add_u32 s74, s50, 0x40000
	v_lshl_add_u64 v[220:221], s[50:51], 0, v[130:131]
	s_addc_u32 s75, s51, 0
	s_add_i32 s76, s68, s54
	global_load_lds_dwordx4 v[220:221], off
	v_lshl_add_u64 v[222:223], s[74:75], 0, v[134:135]
	s_mov_b32 m0, s76
	v_lshl_add_u64 v[224:225], s[52:53], 0, v[132:133]
	global_load_lds_dwordx4 v[222:223], off
	v_lshl_add_u64 v[222:223], s[74:75], 0, v[130:131]
	s_add_i32 m0, s76, 0x2000
	s_nop 0
	global_load_lds_dwordx4 v[222:223], off
	v_lshl_add_u64 v[222:223], s[52:53], 0, v[136:137]
	s_mov_b32 m0, s57
	s_nop 0
	global_load_lds_dwordx4 v[222:223], off
	s_mov_b32 m0, s58
	s_nop 0
	global_load_lds_dwordx4 v[224:225], off
	s_waitcnt vmcnt(8)
	s_waitcnt lgkmcnt(0)
	s_setprio 1
	s_barrier
	v_mfma_f32_16x16x32_bf16 v[62:65], v[156:159], v[188:191], v[62:65]
	v_mfma_f32_16x16x32_bf16 v[58:61], v[164:167], v[188:191], v[58:61]
	v_mfma_f32_16x16x32_bf16 v[46:49], v[156:159], v[196:199], v[46:49]
	v_mfma_f32_16x16x32_bf16 v[42:45], v[164:167], v[196:199], v[42:45]
	v_mfma_f32_16x16x32_bf16 v[30:33], v[156:159], v[204:207], v[30:33]
	v_mfma_f32_16x16x32_bf16 v[26:29], v[164:167], v[204:207], v[26:29]
	v_mfma_f32_16x16x32_bf16 v[14:17], v[156:159], v[212:215], v[14:17]
	v_mfma_f32_16x16x32_bf16 v[10:13], v[164:167], v[212:215], v[10:13]
	v_mfma_f32_16x16x32_bf16 v[62:65], v[160:163], v[192:195], v[62:65]
	v_mfma_f32_16x16x32_bf16 v[58:61], v[168:171], v[192:195], v[58:61]
	v_mfma_f32_16x16x32_bf16 v[46:49], v[160:163], v[200:203], v[46:49]
	v_mfma_f32_16x16x32_bf16 v[42:45], v[168:171], v[200:203], v[42:45]
	v_mfma_f32_16x16x32_bf16 v[30:33], v[160:163], v[208:211], v[30:33]
	v_mfma_f32_16x16x32_bf16 v[26:29], v[168:171], v[208:211], v[26:29]
	v_mfma_f32_16x16x32_bf16 v[14:17], v[160:163], v[216:219], v[14:17]
	v_mfma_f32_16x16x32_bf16 v[10:13], v[168:171], v[216:219], v[10:13]
	s_setprio 0
	s_setprio 1
	v_mfma_f32_16x16x32_bf16 v[54:57], v[172:175], v[188:191], v[54:57]
	v_mfma_f32_16x16x32_bf16 v[50:53], v[180:183], v[188:191], v[50:53]
	v_mfma_f32_16x16x32_bf16 v[38:41], v[172:175], v[196:199], v[38:41]
	v_mfma_f32_16x16x32_bf16 v[34:37], v[180:183], v[196:199], v[34:37]
	v_mfma_f32_16x16x32_bf16 v[22:25], v[172:175], v[204:207], v[22:25]
	v_mfma_f32_16x16x32_bf16 v[18:21], v[180:183], v[204:207], v[18:21]
	v_mfma_f32_16x16x32_bf16 v[6:9], v[172:175], v[212:215], v[6:9]
	v_mfma_f32_16x16x32_bf16 v[2:5], v[180:183], v[212:215], v[2:5]
	v_mfma_f32_16x16x32_bf16 v[54:57], v[176:179], v[192:195], v[54:57]
	v_mfma_f32_16x16x32_bf16 v[50:53], v[184:187], v[192:195], v[50:53]
	v_mfma_f32_16x16x32_bf16 v[38:41], v[176:179], v[200:203], v[38:41]
	v_mfma_f32_16x16x32_bf16 v[34:37], v[184:187], v[200:203], v[34:37]
	v_mfma_f32_16x16x32_bf16 v[22:25], v[176:179], v[208:211], v[22:25]
	v_mfma_f32_16x16x32_bf16 v[18:21], v[184:187], v[208:211], v[18:21]
	v_mfma_f32_16x16x32_bf16 v[6:9], v[176:179], v[216:219], v[6:9]
	v_mfma_f32_16x16x32_bf16 v[2:5], v[184:187], v[216:219], v[2:5]
	s_setprio 0
	s_add_i32 s74, 0, 0x18000
	s_add_i32 s75, 0, 0x1c000
	v_add_u32_e32 v168, s74, v151
	v_add_u32_e32 v184, s75, v151
	ds_read_b128 v[156:159], v168
	ds_read_b128 v[160:163], v168 offset:1024
	ds_read_b128 v[164:167], v168 offset:2048
	ds_read_b128 v[168:171], v168 offset:3072
	ds_read_b128 v[172:175], v184
	ds_read_b128 v[176:179], v184 offset:1024
	ds_read_b128 v[180:183], v184 offset:2048
	ds_read_b128 v[184:187], v184 offset:3072
	s_add_u32 s52, s52, 0x40000
	s_addc_u32 s53, s53, 0
	s_mov_b32 m0, s59
	v_lshl_add_u64 v[226:227], s[52:53], 0, v[136:137]
	ds_read_b128 v[188:191], v154 offset:32768
	ds_read_b128 v[192:195], v154 offset:33792
	ds_read_b128 v[196:199], v154 offset:34816
	ds_read_b128 v[200:203], v154 offset:35840
	ds_read_b128 v[204:207], v154 offset:36864
	ds_read_b128 v[208:211], v154 offset:37888
	ds_read_b128 v[212:215], v154 offset:38912
	ds_read_b128 v[216:219], v154 offset:39936
	global_load_lds_dwordx4 v[226:227], off
	v_lshl_add_u64 v[226:227], s[52:53], 0, v[132:133]
	s_mov_b32 m0, s60
	s_nop 0
	global_load_lds_dwordx4 v[226:227], off
	s_waitcnt vmcnt(8)
	s_waitcnt lgkmcnt(0)
	s_setprio 1
	s_barrier
	v_mfma_f32_16x16x32_bf16 v[126:129], v[156:159], v[188:191], v[126:129]
	v_mfma_f32_16x16x32_bf16 v[122:125], v[164:167], v[188:191], v[122:125]
	v_mfma_f32_16x16x32_bf16 v[110:113], v[156:159], v[196:199], v[110:113]
	v_mfma_f32_16x16x32_bf16 v[106:109], v[164:167], v[196:199], v[106:109]
	v_mfma_f32_16x16x32_bf16 v[94:97], v[156:159], v[204:207], v[94:97]
	v_mfma_f32_16x16x32_bf16 v[90:93], v[164:167], v[204:207], v[90:93]
	v_mfma_f32_16x16x32_bf16 v[78:81], v[156:159], v[212:215], v[78:81]
	v_mfma_f32_16x16x32_bf16 v[74:77], v[164:167], v[212:215], v[74:77]
	v_mfma_f32_16x16x32_bf16 v[126:129], v[160:163], v[192:195], v[126:129]
	v_mfma_f32_16x16x32_bf16 v[122:125], v[168:171], v[192:195], v[122:125]
	v_mfma_f32_16x16x32_bf16 v[110:113], v[160:163], v[200:203], v[110:113]
	v_mfma_f32_16x16x32_bf16 v[106:109], v[168:171], v[200:203], v[106:109]
	v_mfma_f32_16x16x32_bf16 v[94:97], v[160:163], v[208:211], v[94:97]
	v_mfma_f32_16x16x32_bf16 v[90:93], v[168:171], v[208:211], v[90:93]
	v_mfma_f32_16x16x32_bf16 v[78:81], v[160:163], v[216:219], v[78:81]
	v_mfma_f32_16x16x32_bf16 v[74:77], v[168:171], v[216:219], v[74:77]
	s_setprio 0
	s_setprio 1
	v_mfma_f32_16x16x32_bf16 v[118:121], v[172:175], v[188:191], v[118:121]
	v_mfma_f32_16x16x32_bf16 v[114:117], v[180:183], v[188:191], v[114:117]
	v_mfma_f32_16x16x32_bf16 v[102:105], v[172:175], v[196:199], v[102:105]
	v_mfma_f32_16x16x32_bf16 v[98:101], v[180:183], v[196:199], v[98:101]
	v_mfma_f32_16x16x32_bf16 v[86:89], v[172:175], v[204:207], v[86:89]
	v_mfma_f32_16x16x32_bf16 v[82:85], v[180:183], v[204:207], v[82:85]
	v_mfma_f32_16x16x32_bf16 v[70:73], v[172:175], v[212:215], v[70:73]
	v_mfma_f32_16x16x32_bf16 v[66:69], v[180:183], v[212:215], v[66:69]
	v_mfma_f32_16x16x32_bf16 v[118:121], v[176:179], v[192:195], v[118:121]
	v_mfma_f32_16x16x32_bf16 v[114:117], v[184:187], v[192:195], v[114:117]
	v_mfma_f32_16x16x32_bf16 v[102:105], v[176:179], v[200:203], v[102:105]
	v_mfma_f32_16x16x32_bf16 v[98:101], v[184:187], v[200:203], v[98:101]
	v_mfma_f32_16x16x32_bf16 v[86:89], v[176:179], v[208:211], v[86:89]
	v_mfma_f32_16x16x32_bf16 v[82:85], v[184:187], v[208:211], v[82:85]
	v_mfma_f32_16x16x32_bf16 v[70:73], v[176:179], v[216:219], v[70:73]
	v_mfma_f32_16x16x32_bf16 v[66:69], v[184:187], v[216:219], v[66:69]
	s_setprio 0
	s_add_i32 s52, s74, s54
	v_lshl_add_u64 v[148:149], v[148:149], 0, s[16:17]
	s_mov_b32 m0, s52
	ds_read_b128 v[188:191], v154 offset:49152
	ds_read_b128 v[192:195], v154 offset:50176
	ds_read_b128 v[196:199], v154 offset:51200
	ds_read_b128 v[200:203], v154 offset:52224
	ds_read_b128 v[204:207], v154 offset:53248
	ds_read_b128 v[208:211], v154 offset:54272
	ds_read_b128 v[212:215], v154 offset:55296
	ds_read_b128 v[216:219], v154 offset:56320
	global_load_lds_dwordx4 v[148:149], off
	s_add_i32 m0, s52, 0x2000
	s_add_u32 s50, s50, 0x40080
	v_lshl_add_u64 v[148:149], v[220:221], 0, s[16:17]
	s_addc_u32 s51, s51, 0
	s_add_i32 s52, s75, s54
	global_load_lds_dwordx4 v[148:149], off
	v_lshl_add_u64 v[148:149], s[50:51], 0, v[134:135]
	s_mov_b32 m0, s52
	s_nop 0
	global_load_lds_dwordx4 v[148:149], off
	v_lshl_add_u64 v[148:149], s[50:51], 0, v[130:131]
	s_add_i32 m0, s52, 0x2000
	s_nop 0
	global_load_lds_dwordx4 v[148:149], off
	v_lshl_add_u64 v[148:149], v[222:223], 0, s[16:17]
	s_mov_b32 m0, s63
	s_nop 0
	global_load_lds_dwordx4 v[148:149], off
	v_lshl_add_u64 v[148:149], v[224:225], 0, s[16:17]
	s_mov_b32 m0, s64
	s_nop 0
	global_load_lds_dwordx4 v[148:149], off
	s_waitcnt vmcnt(8)
	s_waitcnt lgkmcnt(0)
	s_setprio 1
	s_barrier
	v_mfma_f32_16x16x32_bf16 v[62:65], v[156:159], v[188:191], v[62:65]
	v_mfma_f32_16x16x32_bf16 v[58:61], v[164:167], v[188:191], v[58:61]
	v_mfma_f32_16x16x32_bf16 v[46:49], v[156:159], v[196:199], v[46:49]
	v_mfma_f32_16x16x32_bf16 v[42:45], v[164:167], v[196:199], v[42:45]
	v_mfma_f32_16x16x32_bf16 v[30:33], v[156:159], v[204:207], v[30:33]
	v_mfma_f32_16x16x32_bf16 v[26:29], v[164:167], v[204:207], v[26:29]
	v_mfma_f32_16x16x32_bf16 v[14:17], v[156:159], v[212:215], v[14:17]
	v_mfma_f32_16x16x32_bf16 v[10:13], v[164:167], v[212:215], v[10:13]
	v_mfma_f32_16x16x32_bf16 v[62:65], v[160:163], v[192:195], v[62:65]
	v_mfma_f32_16x16x32_bf16 v[58:61], v[168:171], v[192:195], v[58:61]
	v_mfma_f32_16x16x32_bf16 v[46:49], v[160:163], v[200:203], v[46:49]
	v_mfma_f32_16x16x32_bf16 v[42:45], v[168:171], v[200:203], v[42:45]
	v_mfma_f32_16x16x32_bf16 v[30:33], v[160:163], v[208:211], v[30:33]
	v_mfma_f32_16x16x32_bf16 v[26:29], v[168:171], v[208:211], v[26:29]
	v_mfma_f32_16x16x32_bf16 v[14:17], v[160:163], v[216:219], v[14:17]
	v_mfma_f32_16x16x32_bf16 v[10:13], v[168:171], v[216:219], v[10:13]
	s_setprio 0
	s_setprio 1
	v_mfma_f32_16x16x32_bf16 v[54:57], v[172:175], v[188:191], v[54:57]
	v_mfma_f32_16x16x32_bf16 v[50:53], v[180:183], v[188:191], v[50:53]
	v_mfma_f32_16x16x32_bf16 v[38:41], v[172:175], v[196:199], v[38:41]
	v_mfma_f32_16x16x32_bf16 v[34:37], v[180:183], v[196:199], v[34:37]
	v_mfma_f32_16x16x32_bf16 v[22:25], v[172:175], v[204:207], v[22:25]
	v_mfma_f32_16x16x32_bf16 v[18:21], v[180:183], v[204:207], v[18:21]
	v_mfma_f32_16x16x32_bf16 v[6:9], v[172:175], v[212:215], v[6:9]
	v_mfma_f32_16x16x32_bf16 v[2:5], v[180:183], v[212:215], v[2:5]
	v_mfma_f32_16x16x32_bf16 v[54:57], v[176:179], v[192:195], v[54:57]
	v_mfma_f32_16x16x32_bf16 v[50:53], v[184:187], v[192:195], v[50:53]
	v_mfma_f32_16x16x32_bf16 v[38:41], v[176:179], v[200:203], v[38:41]
	v_mfma_f32_16x16x32_bf16 v[34:37], v[184:187], v[200:203], v[34:37]
	v_mfma_f32_16x16x32_bf16 v[22:25], v[176:179], v[208:211], v[22:25]
	v_mfma_f32_16x16x32_bf16 v[18:21], v[184:187], v[208:211], v[18:21]
	v_mfma_f32_16x16x32_bf16 v[6:9], v[176:179], v[216:219], v[6:9]
	v_mfma_f32_16x16x32_bf16 v[2:5], v[184:187], v[216:219], v[2:5]
	s_setprio 0
	s_add_i32 s73, s73, 2
	s_add_u32 s48, s48, 0x100
	s_addc_u32 s49, s49, 0
	s_add_u32 s71, s71, 0x100
	s_addc_u32 s72, s72, 0
	s_cmp_gt_u32 s73, 13
	s_cbranch_scc0 .Lhb_B_p3
.Lhb_exit_p3:
	s_and_b64 vcc, exec, s[24:25]
	s_cbranch_vccz .LBB0_355
.LBB0_355:
	v_lshl_add_u32 v148, s6, 8, v150
	v_ashrrev_i32_e32 v149, 31, v148
	v_lshl_add_u64 v[156:157], v[148:149], 2, s[14:15]
	global_load_dword v232, v[156:157], off offset:64
	global_load_dword v233, v[156:157], off offset:128
	global_load_dword v234, v[156:157], off offset:192
	global_load_dword v235, v[156:157], off offset:512
	global_load_dword v236, v[156:157], off offset:576
	global_load_dword v237, v[156:157], off offset:640
	global_load_dword v238, v[156:157], off offset:704
	global_load_dword v157, v[156:157], off
	s_ashr_i32 s6, s10, 2
	v_lshlrev_b64 v[158:159], 11, v[148:149]
	s_ashr_i32 s7, s6, 31
	s_lshl_b64 s[48:49], s[6:7], 26
	s_cmp_lt_u32 s10, 4
	s_cselect_b64 s[6:7], -1, 0
	s_add_u32 s48, s61, s48
	s_addc_u32 s49, s62, s49
	s_lshl_b32 s10, s10, 9
	v_lshl_add_u64 v[158:159], s[48:49], 0, v[158:159]
	s_and_b32 s10, s10, 0x600
	v_or_b32_e32 v156, 16, v148
	v_lshl_add_u64 v[158:159], v[158:159], 0, s[10:11]
	s_andn2_b64 vcc, exec, s[4:5]
	s_mov_b64 s[4:5], -1
	s_waitcnt vmcnt(0)
	v_fmamk_f32 v149, v157, 0x3a800000, v155
	v_rsq_f32_e32 v149, v149
	v_ashrrev_i32_e32 v157, 31, v156
	v_mul_f32_e32 v162, 0x3e38aa3b, v149
	v_cndmask_b32_e64 v162, v149, v162, s[6:7]
	v_pk_mul_f32 v[128:129], v[128:129], v[162:163] op_sel_hi:[1,0]
	v_pk_mul_f32 v[126:127], v[126:127], v[162:163] op_sel_hi:[1,0]
	v_pk_mul_f32 v[124:125], v[124:125], v[162:163] op_sel_hi:[1,0]
	v_pk_mul_f32 v[122:123], v[122:123], v[162:163] op_sel_hi:[1,0]
	v_pk_mul_f32 v[120:121], v[120:121], v[162:163] op_sel_hi:[1,0]
	v_pk_mul_f32 v[118:119], v[118:119], v[162:163] op_sel_hi:[1,0]
	v_pk_mul_f32 v[164:165], v[116:117], v[162:163] op_sel_hi:[1,0]
	v_pk_mul_f32 v[162:163], v[114:115], v[162:163] op_sel_hi:[1,0]
	v_cvt_pk_bf16_f32 v114, v126, v127
	v_cvt_pk_bf16_f32 v115, v128, v129
	v_cvt_pk_bf16_f32 v116, v122, v123
	v_cvt_pk_bf16_f32 v117, v124, v125
	v_lshl_add_u64 v[122:123], v[158:159], 0, v[138:139]
	v_cvt_pk_bf16_f32 v118, v118, v119
	v_cvt_pk_bf16_f32 v119, v120, v121
	v_cvt_pk_bf16_f32 v120, v162, v163
	v_cvt_pk_bf16_f32 v121, v164, v165
	global_store_dwordx4 v[122:123], v[114:117], off
	global_store_dwordx4 v[122:123], v[118:121], off offset:256
	s_nop 0
	v_lshlrev_b64 v[116:117], 11, v[156:157]
	v_lshl_add_u64 v[116:117], s[48:49], 0, v[116:117]
	v_or_b32_e32 v114, 32, v148
	v_lshl_add_u64 v[116:117], v[116:117], 0, s[10:11]
	v_ashrrev_i32_e32 v115, 31, v114
	v_lshl_add_u64 v[116:117], v[116:117], 0, v[138:139]
	v_fmamk_f32 v120, v232, 0x3a800000, v155
	v_rsq_f32_e32 v120, v120
	s_nop 0
	v_mul_f32_e32 v121, 0x3e38aa3b, v120
	v_cndmask_b32_e64 v120, v120, v121, s[6:7]
	v_pk_mul_f32 v[112:113], v[112:113], v[120:121] op_sel_hi:[1,0]
	v_pk_mul_f32 v[110:111], v[110:111], v[120:121] op_sel_hi:[1,0]
	v_pk_mul_f32 v[108:109], v[108:109], v[120:121] op_sel_hi:[1,0]
	v_pk_mul_f32 v[106:107], v[106:107], v[120:121] op_sel_hi:[1,0]
	v_pk_mul_f32 v[104:105], v[104:105], v[120:121] op_sel_hi:[1,0]
	v_pk_mul_f32 v[102:103], v[102:103], v[120:121] op_sel_hi:[1,0]
	v_pk_mul_f32 v[122:123], v[100:101], v[120:121] op_sel_hi:[1,0]
	v_pk_mul_f32 v[120:121], v[98:99], v[120:121] op_sel_hi:[1,0]
	v_cvt_pk_bf16_f32 v98, v110, v111
	v_cvt_pk_bf16_f32 v99, v112, v113
	v_cvt_pk_bf16_f32 v100, v106, v107
	v_cvt_pk_bf16_f32 v101, v108, v109
	v_cvt_pk_bf16_f32 v102, v102, v103
	v_cvt_pk_bf16_f32 v103, v104, v105
	v_cvt_pk_bf16_f32 v104, v120, v121
	v_cvt_pk_bf16_f32 v105, v122, v123
	global_store_dwordx4 v[116:117], v[98:101], off
	global_store_dwordx4 v[116:117], v[102:105], off offset:256
	s_nop 0
	v_lshlrev_b64 v[100:101], 11, v[114:115]
	v_lshl_add_u64 v[100:101], s[48:49], 0, v[100:101]
	v_or_b32_e32 v98, 48, v148
	v_lshl_add_u64 v[100:101], v[100:101], 0, s[10:11]
	v_ashrrev_i32_e32 v99, 31, v98
	v_lshl_add_u64 v[100:101], v[100:101], 0, v[138:139]
	v_fmamk_f32 v104, v233, 0x3a800000, v155
	v_rsq_f32_e32 v104, v104
	s_nop 0
	v_mul_f32_e32 v105, 0x3e38aa3b, v104
	v_cndmask_b32_e64 v104, v104, v105, s[6:7]
	v_pk_mul_f32 v[96:97], v[96:97], v[104:105] op_sel_hi:[1,0]
	v_pk_mul_f32 v[94:95], v[94:95], v[104:105] op_sel_hi:[1,0]
	v_pk_mul_f32 v[92:93], v[92:93], v[104:105] op_sel_hi:[1,0]
	v_pk_mul_f32 v[90:91], v[90:91], v[104:105] op_sel_hi:[1,0]
	v_pk_mul_f32 v[88:89], v[88:89], v[104:105] op_sel_hi:[1,0]
	v_pk_mul_f32 v[86:87], v[86:87], v[104:105] op_sel_hi:[1,0]
	v_pk_mul_f32 v[106:107], v[84:85], v[104:105] op_sel_hi:[1,0]
	v_pk_mul_f32 v[104:105], v[82:83], v[104:105] op_sel_hi:[1,0]
	v_cvt_pk_bf16_f32 v82, v94, v95
	v_cvt_pk_bf16_f32 v83, v96, v97
	v_cvt_pk_bf16_f32 v84, v90, v91
	v_cvt_pk_bf16_f32 v85, v92, v93
	v_cvt_pk_bf16_f32 v86, v86, v87
	v_cvt_pk_bf16_f32 v87, v88, v89
	v_cvt_pk_bf16_f32 v88, v104, v105
	v_cvt_pk_bf16_f32 v89, v106, v107
	global_store_dwordx4 v[100:101], v[82:85], off
	global_store_dwordx4 v[100:101], v[86:89], off offset:256
	s_nop 0
	v_lshlrev_b64 v[84:85], 11, v[98:99]
	v_lshl_add_u64 v[84:85], s[48:49], 0, v[84:85]
	v_add_u32_e32 v82, 0x80, v148
	v_lshl_add_u64 v[84:85], v[84:85], 0, s[10:11]
	v_ashrrev_i32_e32 v83, 31, v82
	v_lshl_add_u64 v[84:85], v[84:85], 0, v[138:139]
	v_fmamk_f32 v88, v234, 0x3a800000, v155
	v_rsq_f32_e32 v88, v88
	s_nop 0
	v_mul_f32_e32 v89, 0x3e38aa3b, v88
	v_cndmask_b32_e64 v88, v88, v89, s[6:7]
	v_pk_mul_f32 v[80:81], v[80:81], v[88:89] op_sel_hi:[1,0]
	v_pk_mul_f32 v[78:79], v[78:79], v[88:89] op_sel_hi:[1,0]
	v_pk_mul_f32 v[76:77], v[76:77], v[88:89] op_sel_hi:[1,0]
	v_pk_mul_f32 v[74:75], v[74:75], v[88:89] op_sel_hi:[1,0]
	v_pk_mul_f32 v[72:73], v[72:73], v[88:89] op_sel_hi:[1,0]
	v_pk_mul_f32 v[70:71], v[70:71], v[88:89] op_sel_hi:[1,0]
	v_pk_mul_f32 v[90:91], v[68:69], v[88:89] op_sel_hi:[1,0]
	v_pk_mul_f32 v[88:89], v[66:67], v[88:89] op_sel_hi:[1,0]
	v_cvt_pk_bf16_f32 v66, v78, v79
	v_cvt_pk_bf16_f32 v67, v80, v81
	v_cvt_pk_bf16_f32 v68, v74, v75
	v_cvt_pk_bf16_f32 v69, v76, v77
	v_cvt_pk_bf16_f32 v70, v70, v71
	v_cvt_pk_bf16_f32 v71, v72, v73
	v_cvt_pk_bf16_f32 v72, v88, v89
	v_cvt_pk_bf16_f32 v73, v90, v91
	global_store_dwordx4 v[84:85], v[66:69], off
	global_store_dwordx4 v[84:85], v[70:73], off offset:256
	s_nop 0
	v_lshlrev_b64 v[68:69], 11, v[82:83]
	v_lshl_add_u64 v[68:69], s[48:49], 0, v[68:69]
	v_add_u32_e32 v66, 0x90, v148
	v_lshl_add_u64 v[68:69], v[68:69], 0, s[10:11]
	v_ashrrev_i32_e32 v67, 31, v66
	v_lshl_add_u64 v[68:69], v[68:69], 0, v[138:139]
	v_fmamk_f32 v72, v235, 0x3a800000, v155
	v_rsq_f32_e32 v72, v72
	s_nop 0
	v_mul_f32_e32 v73, 0x3e38aa3b, v72
	v_cndmask_b32_e64 v72, v72, v73, s[6:7]
	v_pk_mul_f32 v[64:65], v[64:65], v[72:73] op_sel_hi:[1,0]
	v_pk_mul_f32 v[62:63], v[62:63], v[72:73] op_sel_hi:[1,0]
	v_pk_mul_f32 v[60:61], v[60:61], v[72:73] op_sel_hi:[1,0]
	v_pk_mul_f32 v[58:59], v[58:59], v[72:73] op_sel_hi:[1,0]
	v_pk_mul_f32 v[56:57], v[56:57], v[72:73] op_sel_hi:[1,0]
	v_pk_mul_f32 v[54:55], v[54:55], v[72:73] op_sel_hi:[1,0]
	v_pk_mul_f32 v[74:75], v[52:53], v[72:73] op_sel_hi:[1,0]
	v_pk_mul_f32 v[72:73], v[50:51], v[72:73] op_sel_hi:[1,0]
	v_cvt_pk_bf16_f32 v50, v62, v63
	v_cvt_pk_bf16_f32 v51, v64, v65
	v_cvt_pk_bf16_f32 v52, v58, v59
	v_cvt_pk_bf16_f32 v53, v60, v61
	v_cvt_pk_bf16_f32 v54, v54, v55
	v_cvt_pk_bf16_f32 v55, v56, v57
	v_cvt_pk_bf16_f32 v56, v72, v73
	v_cvt_pk_bf16_f32 v57, v74, v75
	global_store_dwordx4 v[68:69], v[50:53], off
	global_store_dwordx4 v[68:69], v[54:57], off offset:256
	s_nop 0
	v_lshlrev_b64 v[52:53], 11, v[66:67]
	v_lshl_add_u64 v[52:53], s[48:49], 0, v[52:53]
	v_add_u32_e32 v50, 0xa0, v148
	v_lshl_add_u64 v[52:53], v[52:53], 0, s[10:11]
	v_ashrrev_i32_e32 v51, 31, v50
	v_lshl_add_u64 v[52:53], v[52:53], 0, v[138:139]
	v_fmamk_f32 v56, v236, 0x3a800000, v155
	v_rsq_f32_e32 v56, v56
	s_nop 0
	v_mul_f32_e32 v57, 0x3e38aa3b, v56
	v_cndmask_b32_e64 v56, v56, v57, s[6:7]
	v_pk_mul_f32 v[48:49], v[48:49], v[56:57] op_sel_hi:[1,0]
	v_pk_mul_f32 v[46:47], v[46:47], v[56:57] op_sel_hi:[1,0]
	v_pk_mul_f32 v[44:45], v[44:45], v[56:57] op_sel_hi:[1,0]
	v_pk_mul_f32 v[42:43], v[42:43], v[56:57] op_sel_hi:[1,0]
	v_pk_mul_f32 v[40:41], v[40:41], v[56:57] op_sel_hi:[1,0]
	v_pk_mul_f32 v[38:39], v[38:39], v[56:57] op_sel_hi:[1,0]
	v_pk_mul_f32 v[58:59], v[36:37], v[56:57] op_sel_hi:[1,0]
	v_pk_mul_f32 v[56:57], v[34:35], v[56:57] op_sel_hi:[1,0]
	v_cvt_pk_bf16_f32 v34, v46, v47
	v_cvt_pk_bf16_f32 v35, v48, v49
	v_cvt_pk_bf16_f32 v36, v42, v43
	v_cvt_pk_bf16_f32 v37, v44, v45
	v_cvt_pk_bf16_f32 v38, v38, v39
	v_cvt_pk_bf16_f32 v39, v40, v41
	v_cvt_pk_bf16_f32 v40, v56, v57
	v_cvt_pk_bf16_f32 v41, v58, v59
	global_store_dwordx4 v[52:53], v[34:37], off
	global_store_dwordx4 v[52:53], v[38:41], off offset:256
	s_nop 0
	v_lshlrev_b64 v[36:37], 11, v[50:51]
	v_lshl_add_u64 v[36:37], s[48:49], 0, v[36:37]
	v_add_u32_e32 v34, 0xb0, v148
	v_lshl_add_u64 v[36:37], v[36:37], 0, s[10:11]
	v_ashrrev_i32_e32 v35, 31, v34
	v_lshl_add_u64 v[36:37], v[36:37], 0, v[138:139]
	v_fmamk_f32 v40, v237, 0x3a800000, v155
	v_rsq_f32_e32 v40, v40
	s_nop 0
	v_mul_f32_e32 v41, 0x3e38aa3b, v40
	v_cndmask_b32_e64 v40, v40, v41, s[6:7]
	v_pk_mul_f32 v[32:33], v[32:33], v[40:41] op_sel_hi:[1,0]
	v_pk_mul_f32 v[30:31], v[30:31], v[40:41] op_sel_hi:[1,0]
	v_pk_mul_f32 v[28:29], v[28:29], v[40:41] op_sel_hi:[1,0]
	v_pk_mul_f32 v[26:27], v[26:27], v[40:41] op_sel_hi:[1,0]
	v_pk_mul_f32 v[24:25], v[24:25], v[40:41] op_sel_hi:[1,0]
	v_pk_mul_f32 v[22:23], v[22:23], v[40:41] op_sel_hi:[1,0]
	v_pk_mul_f32 v[42:43], v[20:21], v[40:41] op_sel_hi:[1,0]
	v_pk_mul_f32 v[40:41], v[18:19], v[40:41] op_sel_hi:[1,0]
	v_cvt_pk_bf16_f32 v18, v30, v31
	v_cvt_pk_bf16_f32 v19, v32, v33
	v_cvt_pk_bf16_f32 v20, v26, v27
	v_cvt_pk_bf16_f32 v21, v28, v29
	v_cvt_pk_bf16_f32 v22, v22, v23
	v_cvt_pk_bf16_f32 v23, v24, v25
	v_cvt_pk_bf16_f32 v24, v40, v41
	v_cvt_pk_bf16_f32 v25, v42, v43
	global_store_dwordx4 v[36:37], v[18:21], off
	global_store_dwordx4 v[36:37], v[22:25], off offset:256
	s_nop 0
	v_lshlrev_b64 v[18:19], 11, v[34:35]
	v_lshl_add_u64 v[18:19], s[48:49], 0, v[18:19]
	v_lshl_add_u64 v[18:19], v[18:19], 0, s[10:11]
	v_lshl_add_u64 v[18:19], v[18:19], 0, v[138:139]
	v_fmamk_f32 v20, v238, 0x3a800000, v155
	v_rsq_f32_e32 v20, v20
	s_nop 0
	v_mul_f32_e32 v21, 0x3e38aa3b, v20
	v_cndmask_b32_e64 v20, v20, v21, s[6:7]
	v_pk_mul_f32 v[16:17], v[16:17], v[20:21] op_sel_hi:[1,0]
	v_pk_mul_f32 v[14:15], v[14:15], v[20:21] op_sel_hi:[1,0]
	v_pk_mul_f32 v[12:13], v[12:13], v[20:21] op_sel_hi:[1,0]
	v_pk_mul_f32 v[10:11], v[10:11], v[20:21] op_sel_hi:[1,0]
	v_pk_mul_f32 v[8:9], v[8:9], v[20:21] op_sel_hi:[1,0]
	v_pk_mul_f32 v[6:7], v[6:7], v[20:21] op_sel_hi:[1,0]
	v_pk_mul_f32 v[22:23], v[4:5], v[20:21] op_sel_hi:[1,0]
	v_pk_mul_f32 v[20:21], v[2:3], v[20:21] op_sel_hi:[1,0]
	v_cvt_pk_bf16_f32 v2, v14, v15
	v_cvt_pk_bf16_f32 v3, v16, v17
	v_cvt_pk_bf16_f32 v4, v10, v11
	v_cvt_pk_bf16_f32 v5, v12, v13
	v_cvt_pk_bf16_f32 v6, v6, v7
	v_cvt_pk_bf16_f32 v7, v8, v9
	v_cvt_pk_bf16_f32 v8, v20, v21
	v_cvt_pk_bf16_f32 v9, v22, v23
	global_store_dwordx4 v[18:19], v[2:5], off
	global_store_dwordx4 v[18:19], v[6:9], off offset:256
	s_cbranch_vccnz .LBB0_348
	s_andn2_b64 vcc, exec, s[12:13]
	s_cbranch_vccnz .LBB0_347
	s_branch .LBB0_347

.LBB0_726:
	s_andn2_b64 vcc, exec, s[14:15]
	s_cbranch_vccnz .LBB0_762
	v_ashrrev_i32_e32 v3, 31, v10
	v_lshrrev_b32_e32 v3, 26, v3
	v_add_u32_e32 v3, v10, v3
	v_ashrrev_i32_e32 v11, 6, v3
	v_bfe_i32 v3, v10, 27, 1
	v_lshlrev_b32_e32 v2, 4, v10
	v_lshrrev_b32_e32 v3, 22, v3
	v_add_u32_e32 v3, v2, v3
	v_and_b32_e32 v3, 0xfffffc00, v3
	v_sub_u32_e32 v3, v2, v3
	v_lshrrev_b32_e32 v4, 4, v3
	v_bitop3_b32 v3, v4, v3, 32 bitop3:0x6c
	v_ashrrev_i32_e32 v5, 31, v3
	v_lshrrev_b32_e32 v5, 26, v5
	v_add_u32_e32 v5, v3, v5
	v_lshlrev_b32_e32 v4, 3, v11
	v_ashrrev_i32_e32 v12, 6, v5
	v_and_b32_e32 v5, 0xc0, v5
	v_and_b32_e32 v4, -16, v4
	v_sub_u32_e32 v3, v3, v5
	v_mov_b32_e32 v5, 1
	v_add_u32_e32 v4, v12, v4
	v_ashrrev_i16_sdwa v3, v5, sext(v3) dst_sel:DWORD dst_unused:UNUSED_PAD src0_sel:DWORD src1_sel:BYTE_0
	s_waitcnt lgkmcnt(0)
	s_add_u32 s3, s10, 0xa400000
	v_lshlrev_b32_e32 v6, 5, v11
	v_bfe_i32 v13, v3, 0, 16
	v_lshlrev_b32_e32 v3, 1, v4
	v_lshrrev_b32_e32 v7, 2, v4
	v_and_b32_e32 v8, 3, v12
	s_mov_b32 s10, 0x1fffe0
	v_and_b32_e32 v6, 32, v6
	v_and_b32_e32 v3, 24, v3
	v_and_b32_e32 v7, 4, v7
	v_and_or_b32 v8, v4, s10, v8
	v_or3_b32 v3, v8, v7, v3
	v_add_lshl_u32 v6, v6, v13, 1
	v_add_u32_e32 v2, 0x2000, v2
	v_lshl_add_u32 v196, v3, 11, v6
	v_ashrrev_i32_e32 v3, 31, v2
	v_lshrrev_b32_e32 v3, 22, v3
	v_add_u32_e32 v3, v2, v3
	v_ashrrev_i32_e32 v14, 10, v3
	v_mul_i32_i24_e32 v3, 0x400, v14
	v_sub_u32_e32 v2, v2, v3
	v_lshrrev_b32_e32 v3, 4, v2
	v_bitop3_b32 v2, v3, v2, 32 bitop3:0x6c
	v_lshl_add_u32 v194, v4, 11, v6
	v_ashrrev_i32_e32 v4, 31, v2
	v_lshrrev_b32_e32 v4, 26, v4
	v_add_u32_e32 v4, v2, v4
	s_addc_u32 s23, s11, 0
	v_lshlrev_b32_e32 v3, 3, v14
	v_ashrrev_i32_e32 v15, 6, v4
	v_and_b32_e32 v4, 0xc0, v4
	s_add_u32 s29, s12, 0x4c00000
	v_and_b32_e32 v3, -16, v3
	v_sub_u32_e32 v2, v2, v4
	s_addc_u32 s31, s13, 0
	v_add_u32_e32 v3, v15, v3
	v_ashrrev_i16_sdwa v2, v5, sext(v2) dst_sel:DWORD dst_unused:UNUSED_PAD src0_sel:DWORD src1_sel:BYTE_0
	v_and_b32_e32 v5, 3, v15
	s_ashr_i32 s16, s24, 6
	s_ashr_i32 s49, s48, 31
	s_ashr_i32 s51, s50, 31
	s_ashr_i32 s25, s24, 8
	v_and_or_b32 v5, v3, s10, v5
	s_lshl_b32 s58, s16, 10
	s_lshl_b64 s[10:11], s[48:49], 19
	s_lshl_b64 s[12:13], s[50:51], 19
	s_add_u32 s54, s29, s12
	v_lshlrev_b32_e32 v6, 5, v14
	v_bfe_i32 v16, v2, 0, 16
	v_lshlrev_b32_e32 v2, 1, v3
	v_lshrrev_b32_e32 v4, 2, v3
	s_addc_u32 s55, s31, s13
	s_add_i32 s59, s58, 0
	v_and_b32_e32 v6, 32, v6
	v_and_b32_e32 v2, 24, v2
	v_and_b32_e32 v4, 4, v4
	s_add_i32 m0, s59, 0x10000
	v_or3_b32 v2, v5, v4, v2
	v_add_lshl_u32 v4, v6, v16, 1
	global_load_lds_dwordx4 v196, s[54:55]
	s_add_i32 m0, s59, 0x12000
	v_lshl_add_u32 v200, v2, 11, v4
	s_add_u32 s12, s54, 0x40000
	global_load_lds_dwordx4 v200, s[54:55]
	s_addc_u32 s13, s55, 0
	s_add_i32 m0, s59, 0x14000
	v_lshl_add_u32 v198, v3, 11, v4
	global_load_lds_dwordx4 v196, s[12:13]
	s_add_i32 m0, s59, 0x16000
	s_add_u32 s52, s3, s10
	s_addc_u32 s53, s23, s11
	s_add_i32 s60, s59, 0x2000
	global_load_lds_dwordx4 v200, s[12:13]
	s_mov_b32 m0, s59
	s_add_u32 s10, s52, 0x40000
	global_load_lds_dwordx4 v194, s[52:53]
	s_mov_b32 m0, s60
	s_addc_u32 s11, s53, 0
	s_add_i32 s61, s59, 0x4000
	global_load_lds_dwordx4 v198, s[52:53]
	s_mov_b32 m0, s61
	s_add_i32 s62, s59, 0x6000
	global_load_lds_dwordx4 v194, s[10:11]
	s_mov_b32 m0, s62
	v_mov_b32_e32 v203, 0
	global_load_lds_dwordx4 v198, s[10:11]
	v_mov_b32_e32 v197, v203
	v_mov_b32_e32 v201, v203
	v_mov_b32_e32 v195, v203
	v_mov_b32_e32 v199, v203
	s_cmp_eq_u32 s25, 1
	s_mov_b32 s63, 0
	v_lshl_add_u64 v[8:9], s[54:55], 0, v[196:197]
	v_lshl_add_u64 v[6:7], s[54:55], 0, v[200:201]
	v_lshl_add_u64 v[2:3], s[52:53], 0, v[194:195]
	s_cselect_b64 s[10:11], -1, 0
	s_cmp_lg_u32 s25, 1
	v_lshl_add_u64 v[4:5], s[52:53], 0, v[198:199]
	s_cbranch_scc1 .LBB0_729
.LBB0_729:
	s_add_u32 s12, s4, 0x6400000
	s_addc_u32 s13, s5, 0
	s_add_u32 s14, s6, 0x40000
	s_addc_u32 s15, s7, 0
	s_lshl_b32 s4, s16, 5
	s_mov_b64 s[16:17], 0x80
	s_and_b32 s7, s4, 0x60
	s_add_i32 m0, s59, 0x18000
	v_lshl_add_u64 v[8:9], v[8:9], 0, s[16:17]
	s_lshl_b32 s6, s25, 13
	s_lshl_b32 s26, s7, 7
	s_waitcnt vmcnt(2)
	s_barrier
	global_load_lds_dwordx4 v[8:9], off
	v_lshl_add_u64 v[6:7], v[6:7], 0, s[16:17]
	s_add_i32 m0, s59, 0x1a000
	s_add_i32 s64, s59, 0x8000
	s_add_i32 s65, s59, 0xa000
	global_load_lds_dwordx4 v[6:7], off
	v_lshl_add_u64 v[2:3], v[2:3], 0, s[16:17]
	s_mov_b32 m0, s64
	s_add_u32 s4, s54, 0x40080
	global_load_lds_dwordx4 v[2:3], off
	v_lshl_add_u64 v[2:3], v[4:5], 0, s[16:17]
	s_mov_b32 m0, s65
	s_addc_u32 s5, s55, 0
	global_load_lds_dwordx4 v[2:3], off
	s_add_i32 m0, s59, 0x1c000
	v_lshl_add_u64 v[2:3], s[4:5], 0, v[196:197]
	global_load_lds_dwordx4 v[2:3], off
	v_lshl_add_u64 v[2:3], s[4:5], 0, v[200:201]
	s_add_i32 m0, s59, 0x1e000
	s_cmpk_lt_u32 s24, 0x100
	global_load_lds_dwordx4 v[2:3], off
	v_bfe_u32 v3, v10, 4, 2
	v_and_b32_e32 v2, 15, v10
	v_lshlrev_b32_e32 v4, 4, v3
	v_lshl_or_b32 v243, s25, 6, v2
	v_lshl_or_b32 v2, v2, 6, v4
	v_lshlrev_b32_e32 v4, 2, v10
	v_and_b32_e32 v4, 32, v4
	v_bitop3_b32 v5, v2, s6, v4 bitop3:0xde
	v_bitop3_b32 v244, v2, s26, v4 bitop3:0xde
	v_lshl_or_b32 v2, v3, 3, s7
	v_cmp_eq_u32_e64 s[4:5], 0, v3
	v_lshlrev_b32_e32 v3, 14, v11
	v_and_b32_e32 v3, 0xffff8000, v3
	v_lshl_add_u32 v3, v12, 11, v3
	v_and_b32_e32 v4, 1, v11
	v_lshl_or_b32 v3, v4, 6, v3
	v_lshl_add_u32 v206, v13, 1, v3
	v_lshlrev_b32_e32 v3, 14, v14
	v_and_b32_e32 v3, 0xffff8000, v3
	v_lshl_add_u32 v3, v15, 11, v3
	v_and_b32_e32 v4, 1, v14
	s_waitcnt vmcnt(6)
	v_lshl_or_b32 v3, v4, 6, v3
	s_cselect_b64 s[24:25], -1, 0
	v_lshlrev_b32_e32 v202, 1, v2
	v_lshl_add_u32 v208, v16, 1, v3
	s_add_i32 s69, 0, 0x10000
	s_add_i32 s70, 0, 0x14000
	v_mbcnt_lo_u32_b32 v3, -1, 0
	s_ashr_i32 s66, s38, 31
	s_mov_b32 s67, s38
	s_ashr_i32 s68, s2, 31
	v_lshl_add_u64 v[204:205], s[12:13], 0, v[202:203]
	v_mov_b32_e32 v207, v203
	v_mov_b32_e32 v209, v203
	v_add_u32_e32 v245, s69, v244
	v_add_u32_e32 v246, s70, v244
	v_add_u32_e32 v247, 0, v5
	v_mbcnt_hi_u32_b32 v248, -1, v3
	v_lshlrev_b32_e32 v202, 1, v2
	s_barrier
	s_branch .LBB0_732

.LBB0_738:
	s_ashr_i32 s43, s42, 31
	s_lshl_b64 s[44:45], s[42:43], 19
	s_add_u32 s44, s3, s44
	s_addc_u32 s45, s23, s45
	s_and_b64 s[46:47], s[6:7], exec
	s_cselect_b32 s43, s45, s53
	s_cselect_b32 s49, s44, s52
	s_ashr_i32 s27, s26, 31
	s_lshl_b64 s[46:47], s[26:27], 19
	s_add_u32 s46, s29, s46
	s_addc_u32 s47, s31, s47
	s_and_b64 s[56:57], s[6:7], exec
	s_cselect_b32 s27, s47, s55
	s_cselect_b32 s51, s46, s54
	s_add_u32 s52, s52, 0x40080
	s_addc_u32 s53, s53, 0
	s_add_u32 s71, s54, 0x100
	v_mov_b32_e32 v2, 0
	s_addc_u32 s72, s55, 0
	s_mov_b32 s73, -2
	v_mov_b32_e32 v3, v2
	v_mov_b32_e32 v4, v2
	v_mov_b32_e32 v5, v2
	v_mov_b32_e32 v6, v2
	v_mov_b32_e32 v7, v2
	v_mov_b32_e32 v8, v2
	v_mov_b32_e32 v9, v2
	v_mov_b32_e32 v18, v2
	v_mov_b32_e32 v19, v2
	v_mov_b32_e32 v20, v2
	v_mov_b32_e32 v21, v2
	v_mov_b32_e32 v22, v2
	v_mov_b32_e32 v23, v2
	v_mov_b32_e32 v24, v2
	v_mov_b32_e32 v25, v2
	v_mov_b32_e32 v34, v2
	v_mov_b32_e32 v35, v2
	v_mov_b32_e32 v36, v2
	v_mov_b32_e32 v37, v2
	v_mov_b32_e32 v38, v2
	v_mov_b32_e32 v39, v2
	v_mov_b32_e32 v40, v2
	v_mov_b32_e32 v41, v2
	v_mov_b32_e32 v50, v2
	v_mov_b32_e32 v51, v2
	v_mov_b32_e32 v52, v2
	v_mov_b32_e32 v53, v2
	v_mov_b32_e32 v54, v2
	v_mov_b32_e32 v55, v2
	v_mov_b32_e32 v56, v2
	v_mov_b32_e32 v57, v2
	v_mov_b32_e32 v10, v2
	v_mov_b32_e32 v11, v2
	v_mov_b32_e32 v12, v2
	v_mov_b32_e32 v13, v2
	v_mov_b32_e32 v14, v2
	v_mov_b32_e32 v15, v2
	v_mov_b32_e32 v16, v2
	v_mov_b32_e32 v17, v2
	v_mov_b32_e32 v26, v2
	v_mov_b32_e32 v27, v2
	v_mov_b32_e32 v28, v2
	v_mov_b32_e32 v29, v2
	v_mov_b32_e32 v30, v2
	v_mov_b32_e32 v31, v2
	v_mov_b32_e32 v32, v2
	v_mov_b32_e32 v33, v2
	v_mov_b32_e32 v42, v2
	v_mov_b32_e32 v43, v2
	v_mov_b32_e32 v44, v2
	v_mov_b32_e32 v45, v2
	v_mov_b32_e32 v46, v2
	v_mov_b32_e32 v47, v2
	v_mov_b32_e32 v48, v2
	v_mov_b32_e32 v49, v2
	v_mov_b32_e32 v58, v2
	v_mov_b32_e32 v59, v2
	v_mov_b32_e32 v60, v2
	v_mov_b32_e32 v61, v2
	v_mov_b32_e32 v62, v2
	v_mov_b32_e32 v63, v2
	v_mov_b32_e32 v64, v2
	v_mov_b32_e32 v65, v2
	v_mov_b32_e32 v66, v2
	v_mov_b32_e32 v67, v2
	v_mov_b32_e32 v68, v2
	v_mov_b32_e32 v69, v2
	v_mov_b32_e32 v70, v2
	v_mov_b32_e32 v71, v2
	v_mov_b32_e32 v72, v2
	v_mov_b32_e32 v73, v2
	s_waitcnt vmcnt(0)
	v_mov_b32_e32 v82, v2
	v_mov_b32_e32 v83, v2
	v_mov_b32_e32 v84, v2
	v_mov_b32_e32 v85, v2
	v_mov_b32_e32 v86, v2
	v_mov_b32_e32 v87, v2
	v_mov_b32_e32 v88, v2
	v_mov_b32_e32 v89, v2
	v_mov_b32_e32 v98, v2
	v_mov_b32_e32 v99, v2
	v_mov_b32_e32 v100, v2
	v_mov_b32_e32 v101, v2
	v_mov_b32_e32 v102, v2
	v_mov_b32_e32 v103, v2
	v_mov_b32_e32 v104, v2
	v_mov_b32_e32 v105, v2
	v_mov_b32_e32 v114, v2
	v_mov_b32_e32 v115, v2
	v_mov_b32_e32 v116, v2
	v_mov_b32_e32 v117, v2
	v_mov_b32_e32 v118, v2
	v_mov_b32_e32 v119, v2
	v_mov_b32_e32 v120, v2
	v_mov_b32_e32 v121, v2
	v_mov_b32_e32 v74, v2
	v_mov_b32_e32 v75, v2
	v_mov_b32_e32 v76, v2
	v_mov_b32_e32 v77, v2
	v_mov_b32_e32 v78, v2
	v_mov_b32_e32 v79, v2
	v_mov_b32_e32 v80, v2
	v_mov_b32_e32 v81, v2
	v_mov_b32_e32 v90, v2
	v_mov_b32_e32 v91, v2
	v_mov_b32_e32 v92, v2
	v_mov_b32_e32 v93, v2
	v_mov_b32_e32 v94, v2
	v_mov_b32_e32 v95, v2
	v_mov_b32_e32 v96, v2
	v_mov_b32_e32 v97, v2
	v_mov_b32_e32 v106, v2
	v_mov_b32_e32 v107, v2
	v_mov_b32_e32 v108, v2
	v_mov_b32_e32 v109, v2
	v_mov_b32_e32 v110, v2
	v_mov_b32_e32 v111, v2
	v_mov_b32_e32 v112, v2
	v_mov_b32_e32 v113, v2
	v_mov_b32_e32 v150, v2
	v_mov_b32_e32 v151, v2
	v_mov_b32_e32 v152, v2
	v_mov_b32_e32 v153, v2
	v_mov_b32_e32 v154, v2
	v_mov_b32_e32 v155, v2
	v_mov_b32_e32 v156, v2
	v_mov_b32_e32 v157, v2
	s_cmp_eq_u64 s[24:25], 0
	s_cbranch_scc1 .Lhb_B_p5
.LBB0_739:
	ds_read_b128 v[122:125], v245
	ds_read_b128 v[126:129], v245 offset:1024
	ds_read_b128 v[130:133], v245 offset:2048
	ds_read_b128 v[134:137], v245 offset:3072
	ds_read_b128 v[138:141], v246
	ds_read_b128 v[142:145], v246 offset:1024
	ds_read_b128 v[146:149], v246 offset:2048
	ds_read_b128 v[158:161], v246 offset:3072
	s_add_u32 s54, s52, 0xfffc0080
	s_addc_u32 s55, s53, -1
	s_cmp_eq_u32 s73, 12
	s_cselect_b32 s57, s43, s55
	s_cselect_b32 s56, s49, s54
	s_cselect_b32 s55, s27, s72
	s_cselect_b32 s54, s51, s71
	v_lshl_add_u64 v[210:211], s[52:53], 0, v[206:207]
	s_add_i32 m0, s59, 0xc000
	ds_read_b128 v[162:165], v247
	ds_read_b128 v[166:169], v247 offset:1024
	ds_read_b128 v[170:173], v247 offset:2048
	ds_read_b128 v[174:177], v247 offset:3072
	ds_read_b128 v[178:181], v247 offset:4096
	ds_read_b128 v[182:185], v247 offset:5120
	ds_read_b128 v[186:189], v247 offset:6144
	ds_read_b128 v[190:193], v247 offset:7168
	global_load_lds_dwordx4 v[210:211], off
	v_lshl_add_u64 v[210:211], s[52:53], 0, v[208:209]
	s_add_i32 m0, s59, 0xe000
	s_nop 0
	global_load_lds_dwordx4 v[210:211], off
	s_waitcnt vmcnt(8)
	s_waitcnt lgkmcnt(0)
	s_setprio 1
	v_mfma_f32_16x16x32_bf16 v[154:157], v[122:125], v[162:165], v[154:157]
	v_mfma_f32_16x16x32_bf16 v[150:153], v[130:133], v[162:165], v[150:153]
	v_mfma_f32_16x16x32_bf16 v[110:113], v[122:125], v[170:173], v[110:113]
	v_mfma_f32_16x16x32_bf16 v[106:109], v[130:133], v[170:173], v[106:109]
	v_mfma_f32_16x16x32_bf16 v[94:97], v[122:125], v[178:181], v[94:97]
	v_mfma_f32_16x16x32_bf16 v[90:93], v[130:133], v[178:181], v[90:93]
	v_mfma_f32_16x16x32_bf16 v[78:81], v[122:125], v[186:189], v[78:81]
	v_mfma_f32_16x16x32_bf16 v[74:77], v[130:133], v[186:189], v[74:77]
	v_mfma_f32_16x16x32_bf16 v[154:157], v[126:129], v[166:169], v[154:157]
	v_mfma_f32_16x16x32_bf16 v[150:153], v[134:137], v[166:169], v[150:153]
	v_mfma_f32_16x16x32_bf16 v[110:113], v[126:129], v[174:177], v[110:113]
	v_mfma_f32_16x16x32_bf16 v[106:109], v[134:137], v[174:177], v[106:109]
	v_mfma_f32_16x16x32_bf16 v[94:97], v[126:129], v[182:185], v[94:97]
	v_mfma_f32_16x16x32_bf16 v[90:93], v[134:137], v[182:185], v[90:93]
	v_mfma_f32_16x16x32_bf16 v[78:81], v[126:129], v[190:193], v[78:81]
	v_mfma_f32_16x16x32_bf16 v[74:77], v[134:137], v[190:193], v[74:77]
	s_setprio 0
	s_setprio 1
	v_mfma_f32_16x16x32_bf16 v[118:121], v[138:141], v[162:165], v[118:121]
	v_mfma_f32_16x16x32_bf16 v[114:117], v[146:149], v[162:165], v[114:117]
	v_mfma_f32_16x16x32_bf16 v[102:105], v[138:141], v[170:173], v[102:105]
	v_mfma_f32_16x16x32_bf16 v[98:101], v[146:149], v[170:173], v[98:101]
	v_mfma_f32_16x16x32_bf16 v[86:89], v[138:141], v[178:181], v[86:89]
	v_mfma_f32_16x16x32_bf16 v[82:85], v[146:149], v[178:181], v[82:85]
	v_mfma_f32_16x16x32_bf16 v[70:73], v[138:141], v[186:189], v[70:73]
	v_mfma_f32_16x16x32_bf16 v[66:69], v[146:149], v[186:189], v[66:69]
	v_mfma_f32_16x16x32_bf16 v[118:121], v[142:145], v[166:169], v[118:121]
	v_mfma_f32_16x16x32_bf16 v[114:117], v[158:161], v[166:169], v[114:117]
	v_mfma_f32_16x16x32_bf16 v[102:105], v[142:145], v[174:177], v[102:105]
	v_mfma_f32_16x16x32_bf16 v[98:101], v[158:161], v[174:177], v[98:101]
	v_mfma_f32_16x16x32_bf16 v[86:89], v[142:145], v[182:185], v[86:89]
	v_mfma_f32_16x16x32_bf16 v[82:85], v[158:161], v[182:185], v[82:85]
	v_mfma_f32_16x16x32_bf16 v[70:73], v[142:145], v[190:193], v[70:73]
	v_mfma_f32_16x16x32_bf16 v[66:69], v[158:161], v[190:193], v[66:69]
	s_setprio 0
	s_barrier
	s_add_i32 s74, s69, s58
	v_lshl_add_u64 v[210:211], s[54:55], 0, v[196:197]
	s_mov_b32 m0, s74
	ds_read_b128 v[162:165], v247 offset:16384
	ds_read_b128 v[166:169], v247 offset:17408
	ds_read_b128 v[170:173], v247 offset:18432
	ds_read_b128 v[174:177], v247 offset:19456
	ds_read_b128 v[178:181], v247 offset:20480
	ds_read_b128 v[182:185], v247 offset:21504
	ds_read_b128 v[186:189], v247 offset:22528
	ds_read_b128 v[190:193], v247 offset:23552
	global_load_lds_dwordx4 v[210:211], off
	s_add_i32 m0, s74, 0x2000
	s_add_u32 s74, s54, 0x40000
	v_lshl_add_u64 v[212:213], s[54:55], 0, v[200:201]
	s_addc_u32 s75, s55, 0
	s_add_i32 s76, s70, s58
	global_load_lds_dwordx4 v[212:213], off
	v_lshl_add_u64 v[214:215], s[74:75], 0, v[196:197]
	s_mov_b32 m0, s76
	v_lshl_add_u64 v[216:217], s[56:57], 0, v[198:199]
	global_load_lds_dwordx4 v[214:215], off
	v_lshl_add_u64 v[214:215], s[74:75], 0, v[200:201]
	s_add_i32 m0, s76, 0x2000
	s_nop 0
	global_load_lds_dwordx4 v[214:215], off
	v_lshl_add_u64 v[214:215], s[56:57], 0, v[194:195]
	s_mov_b32 m0, s59
	s_nop 0
	global_load_lds_dwordx4 v[214:215], off
	s_mov_b32 m0, s60
	s_nop 0
	global_load_lds_dwordx4 v[216:217], off
	s_waitcnt vmcnt(8)
	s_waitcnt lgkmcnt(0)
	s_setprio 1
	v_mfma_f32_16x16x32_bf16 v[62:65], v[122:125], v[162:165], v[62:65]
	v_mfma_f32_16x16x32_bf16 v[58:61], v[130:133], v[162:165], v[58:61]
	v_mfma_f32_16x16x32_bf16 v[46:49], v[122:125], v[170:173], v[46:49]
	v_mfma_f32_16x16x32_bf16 v[42:45], v[130:133], v[170:173], v[42:45]
	v_mfma_f32_16x16x32_bf16 v[30:33], v[122:125], v[178:181], v[30:33]
	v_mfma_f32_16x16x32_bf16 v[26:29], v[130:133], v[178:181], v[26:29]
	v_mfma_f32_16x16x32_bf16 v[14:17], v[122:125], v[186:189], v[14:17]
	v_mfma_f32_16x16x32_bf16 v[10:13], v[130:133], v[186:189], v[10:13]
	v_mfma_f32_16x16x32_bf16 v[62:65], v[126:129], v[166:169], v[62:65]
	v_mfma_f32_16x16x32_bf16 v[58:61], v[134:137], v[166:169], v[58:61]
	v_mfma_f32_16x16x32_bf16 v[46:49], v[126:129], v[174:177], v[46:49]
	v_mfma_f32_16x16x32_bf16 v[42:45], v[134:137], v[174:177], v[42:45]
	v_mfma_f32_16x16x32_bf16 v[30:33], v[126:129], v[182:185], v[30:33]
	v_mfma_f32_16x16x32_bf16 v[26:29], v[134:137], v[182:185], v[26:29]
	v_mfma_f32_16x16x32_bf16 v[14:17], v[126:129], v[190:193], v[14:17]
	v_mfma_f32_16x16x32_bf16 v[10:13], v[134:137], v[190:193], v[10:13]
	s_setprio 0
	s_setprio 1
	v_mfma_f32_16x16x32_bf16 v[54:57], v[138:141], v[162:165], v[54:57]
	v_mfma_f32_16x16x32_bf16 v[50:53], v[146:149], v[162:165], v[50:53]
	v_mfma_f32_16x16x32_bf16 v[38:41], v[138:141], v[170:173], v[38:41]
	v_mfma_f32_16x16x32_bf16 v[34:37], v[146:149], v[170:173], v[34:37]
	v_mfma_f32_16x16x32_bf16 v[22:25], v[138:141], v[178:181], v[22:25]
	v_mfma_f32_16x16x32_bf16 v[18:21], v[146:149], v[178:181], v[18:21]
	v_mfma_f32_16x16x32_bf16 v[6:9], v[138:141], v[186:189], v[6:9]
	v_mfma_f32_16x16x32_bf16 v[2:5], v[146:149], v[186:189], v[2:5]
	v_mfma_f32_16x16x32_bf16 v[54:57], v[142:145], v[166:169], v[54:57]
	v_mfma_f32_16x16x32_bf16 v[50:53], v[158:161], v[166:169], v[50:53]
	v_mfma_f32_16x16x32_bf16 v[38:41], v[142:145], v[174:177], v[38:41]
	v_mfma_f32_16x16x32_bf16 v[34:37], v[158:161], v[174:177], v[34:37]
	v_mfma_f32_16x16x32_bf16 v[22:25], v[142:145], v[182:185], v[22:25]
	v_mfma_f32_16x16x32_bf16 v[18:21], v[158:161], v[182:185], v[18:21]
	v_mfma_f32_16x16x32_bf16 v[6:9], v[142:145], v[190:193], v[6:9]
	v_mfma_f32_16x16x32_bf16 v[2:5], v[158:161], v[190:193], v[2:5]
	s_setprio 0
	s_barrier
	s_add_i32 s74, 0, 0x18000
	s_add_i32 s75, 0, 0x1c000
	v_add_u32_e32 v134, s74, v244
	v_add_u32_e32 v158, s75, v244
	ds_read_b128 v[122:125], v134
	ds_read_b128 v[126:129], v134 offset:1024
	ds_read_b128 v[130:133], v134 offset:2048
	ds_read_b128 v[134:137], v134 offset:3072
	ds_read_b128 v[138:141], v158
	ds_read_b128 v[142:145], v158 offset:1024
	ds_read_b128 v[146:149], v158 offset:2048
	ds_read_b128 v[158:161], v158 offset:3072
	s_add_u32 s56, s56, 0x40000
	s_addc_u32 s57, s57, 0
	s_mov_b32 m0, s61
	v_lshl_add_u64 v[218:219], s[56:57], 0, v[194:195]
	ds_read_b128 v[162:165], v247 offset:32768
	ds_read_b128 v[166:169], v247 offset:33792
	ds_read_b128 v[170:173], v247 offset:34816
	ds_read_b128 v[174:177], v247 offset:35840
	ds_read_b128 v[178:181], v247 offset:36864
	ds_read_b128 v[182:185], v247 offset:37888
	ds_read_b128 v[186:189], v247 offset:38912
	ds_read_b128 v[190:193], v247 offset:39936
	global_load_lds_dwordx4 v[218:219], off
	v_lshl_add_u64 v[218:219], s[56:57], 0, v[198:199]
	s_mov_b32 m0, s62
	s_nop 0
	global_load_lds_dwordx4 v[218:219], off
	s_waitcnt vmcnt(8)
	s_waitcnt lgkmcnt(0)
	s_setprio 1
	v_mfma_f32_16x16x32_bf16 v[154:157], v[122:125], v[162:165], v[154:157]
	v_mfma_f32_16x16x32_bf16 v[150:153], v[130:133], v[162:165], v[150:153]
	v_mfma_f32_16x16x32_bf16 v[110:113], v[122:125], v[170:173], v[110:113]
	v_mfma_f32_16x16x32_bf16 v[106:109], v[130:133], v[170:173], v[106:109]
	v_mfma_f32_16x16x32_bf16 v[94:97], v[122:125], v[178:181], v[94:97]
	v_mfma_f32_16x16x32_bf16 v[90:93], v[130:133], v[178:181], v[90:93]
	v_mfma_f32_16x16x32_bf16 v[78:81], v[122:125], v[186:189], v[78:81]
	v_mfma_f32_16x16x32_bf16 v[74:77], v[130:133], v[186:189], v[74:77]
	v_mfma_f32_16x16x32_bf16 v[154:157], v[126:129], v[166:169], v[154:157]
	v_mfma_f32_16x16x32_bf16 v[150:153], v[134:137], v[166:169], v[150:153]
	v_mfma_f32_16x16x32_bf16 v[110:113], v[126:129], v[174:177], v[110:113]
	v_mfma_f32_16x16x32_bf16 v[106:109], v[134:137], v[174:177], v[106:109]
	v_mfma_f32_16x16x32_bf16 v[94:97], v[126:129], v[182:185], v[94:97]
	v_mfma_f32_16x16x32_bf16 v[90:93], v[134:137], v[182:185], v[90:93]
	v_mfma_f32_16x16x32_bf16 v[78:81], v[126:129], v[190:193], v[78:81]
	v_mfma_f32_16x16x32_bf16 v[74:77], v[134:137], v[190:193], v[74:77]
	s_setprio 0
	s_setprio 1
	v_mfma_f32_16x16x32_bf16 v[118:121], v[138:141], v[162:165], v[118:121]
	v_mfma_f32_16x16x32_bf16 v[114:117], v[146:149], v[162:165], v[114:117]
	v_mfma_f32_16x16x32_bf16 v[102:105], v[138:141], v[170:173], v[102:105]
	v_mfma_f32_16x16x32_bf16 v[98:101], v[146:149], v[170:173], v[98:101]
	v_mfma_f32_16x16x32_bf16 v[86:89], v[138:141], v[178:181], v[86:89]
	v_mfma_f32_16x16x32_bf16 v[82:85], v[146:149], v[178:181], v[82:85]
	v_mfma_f32_16x16x32_bf16 v[70:73], v[138:141], v[186:189], v[70:73]
	v_mfma_f32_16x16x32_bf16 v[66:69], v[146:149], v[186:189], v[66:69]
	v_mfma_f32_16x16x32_bf16 v[118:121], v[142:145], v[166:169], v[118:121]
	v_mfma_f32_16x16x32_bf16 v[114:117], v[158:161], v[166:169], v[114:117]
	v_mfma_f32_16x16x32_bf16 v[102:105], v[142:145], v[174:177], v[102:105]
	v_mfma_f32_16x16x32_bf16 v[98:101], v[158:161], v[174:177], v[98:101]
	v_mfma_f32_16x16x32_bf16 v[86:89], v[142:145], v[182:185], v[86:89]
	v_mfma_f32_16x16x32_bf16 v[82:85], v[158:161], v[182:185], v[82:85]
	v_mfma_f32_16x16x32_bf16 v[70:73], v[142:145], v[190:193], v[70:73]
	v_mfma_f32_16x16x32_bf16 v[66:69], v[158:161], v[190:193], v[66:69]
	s_setprio 0
	s_barrier
	s_add_i32 s56, s74, s58
	v_lshl_add_u64 v[210:211], v[210:211], 0, s[16:17]
	s_mov_b32 m0, s56
	ds_read_b128 v[162:165], v247 offset:49152
	ds_read_b128 v[166:169], v247 offset:50176
	ds_read_b128 v[170:173], v247 offset:51200
	ds_read_b128 v[174:177], v247 offset:52224
	ds_read_b128 v[178:181], v247 offset:53248
	ds_read_b128 v[182:185], v247 offset:54272
	ds_read_b128 v[186:189], v247 offset:55296
	ds_read_b128 v[190:193], v247 offset:56320
	global_load_lds_dwordx4 v[210:211], off
	s_add_i32 m0, s56, 0x2000
	s_add_u32 s54, s54, 0x40080
	v_lshl_add_u64 v[210:211], v[212:213], 0, s[16:17]
	s_addc_u32 s55, s55, 0
	s_add_i32 s56, s75, s58
	global_load_lds_dwordx4 v[210:211], off
	v_lshl_add_u64 v[210:211], s[54:55], 0, v[196:197]
	s_mov_b32 m0, s56
	s_nop 0
	global_load_lds_dwordx4 v[210:211], off
	v_lshl_add_u64 v[210:211], s[54:55], 0, v[200:201]
	s_add_i32 m0, s56, 0x2000
	s_nop 0
	global_load_lds_dwordx4 v[210:211], off
	v_lshl_add_u64 v[210:211], v[214:215], 0, s[16:17]
	s_mov_b32 m0, s64
	s_nop 0
	global_load_lds_dwordx4 v[210:211], off
	v_lshl_add_u64 v[210:211], v[216:217], 0, s[16:17]
	s_mov_b32 m0, s65
	s_nop 0
	global_load_lds_dwordx4 v[210:211], off
	s_waitcnt vmcnt(8)
	s_waitcnt lgkmcnt(0)
	s_setprio 1
	v_mfma_f32_16x16x32_bf16 v[62:65], v[122:125], v[162:165], v[62:65]
	v_mfma_f32_16x16x32_bf16 v[58:61], v[130:133], v[162:165], v[58:61]
	v_mfma_f32_16x16x32_bf16 v[46:49], v[122:125], v[170:173], v[46:49]
	v_mfma_f32_16x16x32_bf16 v[42:45], v[130:133], v[170:173], v[42:45]
	v_mfma_f32_16x16x32_bf16 v[30:33], v[122:125], v[178:181], v[30:33]
	v_mfma_f32_16x16x32_bf16 v[26:29], v[130:133], v[178:181], v[26:29]
	v_mfma_f32_16x16x32_bf16 v[14:17], v[122:125], v[186:189], v[14:17]
	v_mfma_f32_16x16x32_bf16 v[10:13], v[130:133], v[186:189], v[10:13]
	v_mfma_f32_16x16x32_bf16 v[62:65], v[126:129], v[166:169], v[62:65]
	v_mfma_f32_16x16x32_bf16 v[58:61], v[134:137], v[166:169], v[58:61]
	v_mfma_f32_16x16x32_bf16 v[46:49], v[126:129], v[174:177], v[46:49]
	v_mfma_f32_16x16x32_bf16 v[42:45], v[134:137], v[174:177], v[42:45]
	v_mfma_f32_16x16x32_bf16 v[30:33], v[126:129], v[182:185], v[30:33]
	v_mfma_f32_16x16x32_bf16 v[26:29], v[134:137], v[182:185], v[26:29]
	v_mfma_f32_16x16x32_bf16 v[14:17], v[126:129], v[190:193], v[14:17]
	v_mfma_f32_16x16x32_bf16 v[10:13], v[134:137], v[190:193], v[10:13]
	s_setprio 0
	s_setprio 1
	v_mfma_f32_16x16x32_bf16 v[54:57], v[138:141], v[162:165], v[54:57]
	v_mfma_f32_16x16x32_bf16 v[50:53], v[146:149], v[162:165], v[50:53]
	v_mfma_f32_16x16x32_bf16 v[38:41], v[138:141], v[170:173], v[38:41]
	v_mfma_f32_16x16x32_bf16 v[34:37], v[146:149], v[170:173], v[34:37]
	v_mfma_f32_16x16x32_bf16 v[22:25], v[138:141], v[178:181], v[22:25]
	v_mfma_f32_16x16x32_bf16 v[18:21], v[146:149], v[178:181], v[18:21]
	v_mfma_f32_16x16x32_bf16 v[6:9], v[138:141], v[186:189], v[6:9]
	v_mfma_f32_16x16x32_bf16 v[2:5], v[146:149], v[186:189], v[2:5]
	v_mfma_f32_16x16x32_bf16 v[54:57], v[142:145], v[166:169], v[54:57]
	v_mfma_f32_16x16x32_bf16 v[50:53], v[158:161], v[166:169], v[50:53]
	v_mfma_f32_16x16x32_bf16 v[38:41], v[142:145], v[174:177], v[38:41]
	v_mfma_f32_16x16x32_bf16 v[34:37], v[158:161], v[174:177], v[34:37]
	v_mfma_f32_16x16x32_bf16 v[22:25], v[142:145], v[182:185], v[22:25]
	v_mfma_f32_16x16x32_bf16 v[18:21], v[158:161], v[182:185], v[18:21]
	v_mfma_f32_16x16x32_bf16 v[6:9], v[142:145], v[190:193], v[6:9]
	v_mfma_f32_16x16x32_bf16 v[2:5], v[158:161], v[190:193], v[2:5]
	s_setprio 0
	s_barrier
	s_add_i32 s73, s73, 2
	s_add_u32 s52, s52, 0x100
	s_addc_u32 s53, s53, 0
	s_add_u32 s71, s71, 0x100
	s_addc_u32 s72, s72, 0
	s_cmp_gt_u32 s73, 13
	s_cbranch_scc0 .LBB0_739
	s_branch .Lhb_exit_p5
.Lhb_B_p5:
	ds_read_b128 v[122:125], v245
	ds_read_b128 v[126:129], v245 offset:1024
	ds_read_b128 v[130:133], v245 offset:2048
	ds_read_b128 v[134:137], v245 offset:3072
	ds_read_b128 v[138:141], v246
	ds_read_b128 v[142:145], v246 offset:1024
	ds_read_b128 v[146:149], v246 offset:2048
	ds_read_b128 v[158:161], v246 offset:3072
	s_add_u32 s54, s52, 0xfffc0080
	s_addc_u32 s55, s53, -1
	s_cmp_eq_u32 s73, 12
	s_cselect_b32 s57, s43, s55
	s_cselect_b32 s56, s49, s54
	s_cselect_b32 s55, s27, s72
	s_cselect_b32 s54, s51, s71
	v_lshl_add_u64 v[210:211], s[52:53], 0, v[206:207]
	s_add_i32 m0, s59, 0xc000
	ds_read_b128 v[162:165], v247
	ds_read_b128 v[166:169], v247 offset:1024
	ds_read_b128 v[170:173], v247 offset:2048
	ds_read_b128 v[174:177], v247 offset:3072
	ds_read_b128 v[178:181], v247 offset:4096
	ds_read_b128 v[182:185], v247 offset:5120
	ds_read_b128 v[186:189], v247 offset:6144
	ds_read_b128 v[190:193], v247 offset:7168
	global_load_lds_dwordx4 v[210:211], off
	v_lshl_add_u64 v[210:211], s[52:53], 0, v[208:209]
	s_add_i32 m0, s59, 0xe000
	s_nop 0
	global_load_lds_dwordx4 v[210:211], off
	s_waitcnt vmcnt(8)
	s_waitcnt lgkmcnt(0)
	s_setprio 1
	s_barrier
	v_mfma_f32_16x16x32_bf16 v[154:157], v[122:125], v[162:165], v[154:157]
	v_mfma_f32_16x16x32_bf16 v[150:153], v[130:133], v[162:165], v[150:153]
	v_mfma_f32_16x16x32_bf16 v[110:113], v[122:125], v[170:173], v[110:113]
	v_mfma_f32_16x16x32_bf16 v[106:109], v[130:133], v[170:173], v[106:109]
	v_mfma_f32_16x16x32_bf16 v[94:97], v[122:125], v[178:181], v[94:97]
	v_mfma_f32_16x16x32_bf16 v[90:93], v[130:133], v[178:181], v[90:93]
	v_mfma_f32_16x16x32_bf16 v[78:81], v[122:125], v[186:189], v[78:81]
	v_mfma_f32_16x16x32_bf16 v[74:77], v[130:133], v[186:189], v[74:77]
	v_mfma_f32_16x16x32_bf16 v[154:157], v[126:129], v[166:169], v[154:157]
	v_mfma_f32_16x16x32_bf16 v[150:153], v[134:137], v[166:169], v[150:153]
	v_mfma_f32_16x16x32_bf16 v[110:113], v[126:129], v[174:177], v[110:113]
	v_mfma_f32_16x16x32_bf16 v[106:109], v[134:137], v[174:177], v[106:109]
	v_mfma_f32_16x16x32_bf16 v[94:97], v[126:129], v[182:185], v[94:97]
	v_mfma_f32_16x16x32_bf16 v[90:93], v[134:137], v[182:185], v[90:93]
	v_mfma_f32_16x16x32_bf16 v[78:81], v[126:129], v[190:193], v[78:81]
	v_mfma_f32_16x16x32_bf16 v[74:77], v[134:137], v[190:193], v[74:77]
	s_setprio 0
	s_setprio 1
	v_mfma_f32_16x16x32_bf16 v[118:121], v[138:141], v[162:165], v[118:121]
	v_mfma_f32_16x16x32_bf16 v[114:117], v[146:149], v[162:165], v[114:117]
	v_mfma_f32_16x16x32_bf16 v[102:105], v[138:141], v[170:173], v[102:105]
	v_mfma_f32_16x16x32_bf16 v[98:101], v[146:149], v[170:173], v[98:101]
	v_mfma_f32_16x16x32_bf16 v[86:89], v[138:141], v[178:181], v[86:89]
	v_mfma_f32_16x16x32_bf16 v[82:85], v[146:149], v[178:181], v[82:85]
	v_mfma_f32_16x16x32_bf16 v[70:73], v[138:141], v[186:189], v[70:73]
	v_mfma_f32_16x16x32_bf16 v[66:69], v[146:149], v[186:189], v[66:69]
	v_mfma_f32_16x16x32_bf16 v[118:121], v[142:145], v[166:169], v[118:121]
	v_mfma_f32_16x16x32_bf16 v[114:117], v[158:161], v[166:169], v[114:117]
	v_mfma_f32_16x16x32_bf16 v[102:105], v[142:145], v[174:177], v[102:105]
	v_mfma_f32_16x16x32_bf16 v[98:101], v[158:161], v[174:177], v[98:101]
	v_mfma_f32_16x16x32_bf16 v[86:89], v[142:145], v[182:185], v[86:89]
	v_mfma_f32_16x16x32_bf16 v[82:85], v[158:161], v[182:185], v[82:85]
	v_mfma_f32_16x16x32_bf16 v[70:73], v[142:145], v[190:193], v[70:73]
	v_mfma_f32_16x16x32_bf16 v[66:69], v[158:161], v[190:193], v[66:69]
	s_setprio 0
	s_add_i32 s74, s69, s58
	v_lshl_add_u64 v[210:211], s[54:55], 0, v[196:197]
	s_mov_b32 m0, s74
	ds_read_b128 v[162:165], v247 offset:16384
	ds_read_b128 v[166:169], v247 offset:17408
	ds_read_b128 v[170:173], v247 offset:18432
	ds_read_b128 v[174:177], v247 offset:19456
	ds_read_b128 v[178:181], v247 offset:20480
	ds_read_b128 v[182:185], v247 offset:21504
	ds_read_b128 v[186:189], v247 offset:22528
	ds_read_b128 v[190:193], v247 offset:23552
	global_load_lds_dwordx4 v[210:211], off
	s_add_i32 m0, s74, 0x2000
	s_add_u32 s74, s54, 0x40000
	v_lshl_add_u64 v[212:213], s[54:55], 0, v[200:201]
	s_addc_u32 s75, s55, 0
	s_add_i32 s76, s70, s58
	global_load_lds_dwordx4 v[212:213], off
	v_lshl_add_u64 v[214:215], s[74:75], 0, v[196:197]
	s_mov_b32 m0, s76
	v_lshl_add_u64 v[216:217], s[56:57], 0, v[198:199]
	global_load_lds_dwordx4 v[214:215], off
	v_lshl_add_u64 v[214:215], s[74:75], 0, v[200:201]
	s_add_i32 m0, s76, 0x2000
	s_nop 0
	global_load_lds_dwordx4 v[214:215], off
	v_lshl_add_u64 v[214:215], s[56:57], 0, v[194:195]
	s_mov_b32 m0, s59
	s_nop 0
	global_load_lds_dwordx4 v[214:215], off
	s_mov_b32 m0, s60
	s_nop 0
	global_load_lds_dwordx4 v[216:217], off
	s_waitcnt vmcnt(8)
	s_waitcnt lgkmcnt(0)
	s_setprio 1
	s_barrier
	v_mfma_f32_16x16x32_bf16 v[62:65], v[122:125], v[162:165], v[62:65]
	v_mfma_f32_16x16x32_bf16 v[58:61], v[130:133], v[162:165], v[58:61]
	v_mfma_f32_16x16x32_bf16 v[46:49], v[122:125], v[170:173], v[46:49]
	v_mfma_f32_16x16x32_bf16 v[42:45], v[130:133], v[170:173], v[42:45]
	v_mfma_f32_16x16x32_bf16 v[30:33], v[122:125], v[178:181], v[30:33]
	v_mfma_f32_16x16x32_bf16 v[26:29], v[130:133], v[178:181], v[26:29]
	v_mfma_f32_16x16x32_bf16 v[14:17], v[122:125], v[186:189], v[14:17]
	v_mfma_f32_16x16x32_bf16 v[10:13], v[130:133], v[186:189], v[10:13]
	v_mfma_f32_16x16x32_bf16 v[62:65], v[126:129], v[166:169], v[62:65]
	v_mfma_f32_16x16x32_bf16 v[58:61], v[134:137], v[166:169], v[58:61]
	v_mfma_f32_16x16x32_bf16 v[46:49], v[126:129], v[174:177], v[46:49]
	v_mfma_f32_16x16x32_bf16 v[42:45], v[134:137], v[174:177], v[42:45]
	v_mfma_f32_16x16x32_bf16 v[30:33], v[126:129], v[182:185], v[30:33]
	v_mfma_f32_16x16x32_bf16 v[26:29], v[134:137], v[182:185], v[26:29]
	v_mfma_f32_16x16x32_bf16 v[14:17], v[126:129], v[190:193], v[14:17]
	v_mfma_f32_16x16x32_bf16 v[10:13], v[134:137], v[190:193], v[10:13]
	s_setprio 0
	s_setprio 1
	v_mfma_f32_16x16x32_bf16 v[54:57], v[138:141], v[162:165], v[54:57]
	v_mfma_f32_16x16x32_bf16 v[50:53], v[146:149], v[162:165], v[50:53]
	v_mfma_f32_16x16x32_bf16 v[38:41], v[138:141], v[170:173], v[38:41]
	v_mfma_f32_16x16x32_bf16 v[34:37], v[146:149], v[170:173], v[34:37]
	v_mfma_f32_16x16x32_bf16 v[22:25], v[138:141], v[178:181], v[22:25]
	v_mfma_f32_16x16x32_bf16 v[18:21], v[146:149], v[178:181], v[18:21]
	v_mfma_f32_16x16x32_bf16 v[6:9], v[138:141], v[186:189], v[6:9]
	v_mfma_f32_16x16x32_bf16 v[2:5], v[146:149], v[186:189], v[2:5]
	v_mfma_f32_16x16x32_bf16 v[54:57], v[142:145], v[166:169], v[54:57]
	v_mfma_f32_16x16x32_bf16 v[50:53], v[158:161], v[166:169], v[50:53]
	v_mfma_f32_16x16x32_bf16 v[38:41], v[142:145], v[174:177], v[38:41]
	v_mfma_f32_16x16x32_bf16 v[34:37], v[158:161], v[174:177], v[34:37]
	v_mfma_f32_16x16x32_bf16 v[22:25], v[142:145], v[182:185], v[22:25]
	v_mfma_f32_16x16x32_bf16 v[18:21], v[158:161], v[182:185], v[18:21]
	v_mfma_f32_16x16x32_bf16 v[6:9], v[142:145], v[190:193], v[6:9]
	v_mfma_f32_16x16x32_bf16 v[2:5], v[158:161], v[190:193], v[2:5]
	s_setprio 0
	s_add_i32 s74, 0, 0x18000
	s_add_i32 s75, 0, 0x1c000
	v_add_u32_e32 v134, s74, v244
	v_add_u32_e32 v158, s75, v244
	ds_read_b128 v[122:125], v134
	ds_read_b128 v[126:129], v134 offset:1024
	ds_read_b128 v[130:133], v134 offset:2048
	ds_read_b128 v[134:137], v134 offset:3072
	ds_read_b128 v[138:141], v158
	ds_read_b128 v[142:145], v158 offset:1024
	ds_read_b128 v[146:149], v158 offset:2048
	ds_read_b128 v[158:161], v158 offset:3072
	s_add_u32 s56, s56, 0x40000
	s_addc_u32 s57, s57, 0
	s_mov_b32 m0, s61
	v_lshl_add_u64 v[218:219], s[56:57], 0, v[194:195]
	ds_read_b128 v[162:165], v247 offset:32768
	ds_read_b128 v[166:169], v247 offset:33792
	ds_read_b128 v[170:173], v247 offset:34816
	ds_read_b128 v[174:177], v247 offset:35840
	ds_read_b128 v[178:181], v247 offset:36864
	ds_read_b128 v[182:185], v247 offset:37888
	ds_read_b128 v[186:189], v247 offset:38912
	ds_read_b128 v[190:193], v247 offset:39936
	global_load_lds_dwordx4 v[218:219], off
	v_lshl_add_u64 v[218:219], s[56:57], 0, v[198:199]
	s_mov_b32 m0, s62
	s_nop 0
	global_load_lds_dwordx4 v[218:219], off
	s_waitcnt vmcnt(8)
	s_waitcnt lgkmcnt(0)
	s_setprio 1
	s_barrier
	v_mfma_f32_16x16x32_bf16 v[154:157], v[122:125], v[162:165], v[154:157]
	v_mfma_f32_16x16x32_bf16 v[150:153], v[130:133], v[162:165], v[150:153]
	v_mfma_f32_16x16x32_bf16 v[110:113], v[122:125], v[170:173], v[110:113]
	v_mfma_f32_16x16x32_bf16 v[106:109], v[130:133], v[170:173], v[106:109]
	v_mfma_f32_16x16x32_bf16 v[94:97], v[122:125], v[178:181], v[94:97]
	v_mfma_f32_16x16x32_bf16 v[90:93], v[130:133], v[178:181], v[90:93]
	v_mfma_f32_16x16x32_bf16 v[78:81], v[122:125], v[186:189], v[78:81]
	v_mfma_f32_16x16x32_bf16 v[74:77], v[130:133], v[186:189], v[74:77]
	v_mfma_f32_16x16x32_bf16 v[154:157], v[126:129], v[166:169], v[154:157]
	v_mfma_f32_16x16x32_bf16 v[150:153], v[134:137], v[166:169], v[150:153]
	v_mfma_f32_16x16x32_bf16 v[110:113], v[126:129], v[174:177], v[110:113]
	v_mfma_f32_16x16x32_bf16 v[106:109], v[134:137], v[174:177], v[106:109]
	v_mfma_f32_16x16x32_bf16 v[94:97], v[126:129], v[182:185], v[94:97]
	v_mfma_f32_16x16x32_bf16 v[90:93], v[134:137], v[182:185], v[90:93]
	v_mfma_f32_16x16x32_bf16 v[78:81], v[126:129], v[190:193], v[78:81]
	v_mfma_f32_16x16x32_bf16 v[74:77], v[134:137], v[190:193], v[74:77]
	s_setprio 0
	s_setprio 1
	v_mfma_f32_16x16x32_bf16 v[118:121], v[138:141], v[162:165], v[118:121]
	v_mfma_f32_16x16x32_bf16 v[114:117], v[146:149], v[162:165], v[114:117]
	v_mfma_f32_16x16x32_bf16 v[102:105], v[138:141], v[170:173], v[102:105]
	v_mfma_f32_16x16x32_bf16 v[98:101], v[146:149], v[170:173], v[98:101]
	v_mfma_f32_16x16x32_bf16 v[86:89], v[138:141], v[178:181], v[86:89]
	v_mfma_f32_16x16x32_bf16 v[82:85], v[146:149], v[178:181], v[82:85]
	v_mfma_f32_16x16x32_bf16 v[70:73], v[138:141], v[186:189], v[70:73]
	v_mfma_f32_16x16x32_bf16 v[66:69], v[146:149], v[186:189], v[66:69]
	v_mfma_f32_16x16x32_bf16 v[118:121], v[142:145], v[166:169], v[118:121]
	v_mfma_f32_16x16x32_bf16 v[114:117], v[158:161], v[166:169], v[114:117]
	v_mfma_f32_16x16x32_bf16 v[102:105], v[142:145], v[174:177], v[102:105]
	v_mfma_f32_16x16x32_bf16 v[98:101], v[158:161], v[174:177], v[98:101]
	v_mfma_f32_16x16x32_bf16 v[86:89], v[142:145], v[182:185], v[86:89]
	v_mfma_f32_16x16x32_bf16 v[82:85], v[158:161], v[182:185], v[82:85]
	v_mfma_f32_16x16x32_bf16 v[70:73], v[142:145], v[190:193], v[70:73]
	v_mfma_f32_16x16x32_bf16 v[66:69], v[158:161], v[190:193], v[66:69]
	s_setprio 0
	s_add_i32 s56, s74, s58
	v_lshl_add_u64 v[210:211], v[210:211], 0, s[16:17]
	s_mov_b32 m0, s56
	ds_read_b128 v[162:165], v247 offset:49152
	ds_read_b128 v[166:169], v247 offset:50176
	ds_read_b128 v[170:173], v247 offset:51200
	ds_read_b128 v[174:177], v247 offset:52224
	ds_read_b128 v[178:181], v247 offset:53248
	ds_read_b128 v[182:185], v247 offset:54272
	ds_read_b128 v[186:189], v247 offset:55296
	ds_read_b128 v[190:193], v247 offset:56320
	global_load_lds_dwordx4 v[210:211], off
	s_add_i32 m0, s56, 0x2000
	s_add_u32 s54, s54, 0x40080
	v_lshl_add_u64 v[210:211], v[212:213], 0, s[16:17]
	s_addc_u32 s55, s55, 0
	s_add_i32 s56, s75, s58
	global_load_lds_dwordx4 v[210:211], off
	v_lshl_add_u64 v[210:211], s[54:55], 0, v[196:197]
	s_mov_b32 m0, s56
	s_nop 0
	global_load_lds_dwordx4 v[210:211], off
	v_lshl_add_u64 v[210:211], s[54:55], 0, v[200:201]
	s_add_i32 m0, s56, 0x2000
	s_nop 0
	global_load_lds_dwordx4 v[210:211], off
	v_lshl_add_u64 v[210:211], v[214:215], 0, s[16:17]
	s_mov_b32 m0, s64
	s_nop 0
	global_load_lds_dwordx4 v[210:211], off
	v_lshl_add_u64 v[210:211], v[216:217], 0, s[16:17]
	s_mov_b32 m0, s65
	s_nop 0
	global_load_lds_dwordx4 v[210:211], off
	s_waitcnt vmcnt(8)
	s_waitcnt lgkmcnt(0)
	s_setprio 1
	s_barrier
	v_mfma_f32_16x16x32_bf16 v[62:65], v[122:125], v[162:165], v[62:65]
	v_mfma_f32_16x16x32_bf16 v[58:61], v[130:133], v[162:165], v[58:61]
	v_mfma_f32_16x16x32_bf16 v[46:49], v[122:125], v[170:173], v[46:49]
	v_mfma_f32_16x16x32_bf16 v[42:45], v[130:133], v[170:173], v[42:45]
	v_mfma_f32_16x16x32_bf16 v[30:33], v[122:125], v[178:181], v[30:33]
	v_mfma_f32_16x16x32_bf16 v[26:29], v[130:133], v[178:181], v[26:29]
	v_mfma_f32_16x16x32_bf16 v[14:17], v[122:125], v[186:189], v[14:17]
	v_mfma_f32_16x16x32_bf16 v[10:13], v[130:133], v[186:189], v[10:13]
	v_mfma_f32_16x16x32_bf16 v[62:65], v[126:129], v[166:169], v[62:65]
	v_mfma_f32_16x16x32_bf16 v[58:61], v[134:137], v[166:169], v[58:61]
	v_mfma_f32_16x16x32_bf16 v[46:49], v[126:129], v[174:177], v[46:49]
	v_mfma_f32_16x16x32_bf16 v[42:45], v[134:137], v[174:177], v[42:45]
	v_mfma_f32_16x16x32_bf16 v[30:33], v[126:129], v[182:185], v[30:33]
	v_mfma_f32_16x16x32_bf16 v[26:29], v[134:137], v[182:185], v[26:29]
	v_mfma_f32_16x16x32_bf16 v[14:17], v[126:129], v[190:193], v[14:17]
	v_mfma_f32_16x16x32_bf16 v[10:13], v[134:137], v[190:193], v[10:13]
	s_setprio 0
	s_setprio 1
	v_mfma_f32_16x16x32_bf16 v[54:57], v[138:141], v[162:165], v[54:57]
	v_mfma_f32_16x16x32_bf16 v[50:53], v[146:149], v[162:165], v[50:53]
	v_mfma_f32_16x16x32_bf16 v[38:41], v[138:141], v[170:173], v[38:41]
	v_mfma_f32_16x16x32_bf16 v[34:37], v[146:149], v[170:173], v[34:37]
	v_mfma_f32_16x16x32_bf16 v[22:25], v[138:141], v[178:181], v[22:25]
	v_mfma_f32_16x16x32_bf16 v[18:21], v[146:149], v[178:181], v[18:21]
	v_mfma_f32_16x16x32_bf16 v[6:9], v[138:141], v[186:189], v[6:9]
	v_mfma_f32_16x16x32_bf16 v[2:5], v[146:149], v[186:189], v[2:5]
	v_mfma_f32_16x16x32_bf16 v[54:57], v[142:145], v[166:169], v[54:57]
	v_mfma_f32_16x16x32_bf16 v[50:53], v[158:161], v[166:169], v[50:53]
	v_mfma_f32_16x16x32_bf16 v[38:41], v[142:145], v[174:177], v[38:41]
	v_mfma_f32_16x16x32_bf16 v[34:37], v[158:161], v[174:177], v[34:37]
	v_mfma_f32_16x16x32_bf16 v[22:25], v[142:145], v[182:185], v[22:25]
	v_mfma_f32_16x16x32_bf16 v[18:21], v[158:161], v[182:185], v[18:21]
	v_mfma_f32_16x16x32_bf16 v[6:9], v[142:145], v[190:193], v[6:9]
	v_mfma_f32_16x16x32_bf16 v[2:5], v[158:161], v[190:193], v[2:5]
	s_setprio 0
	s_add_i32 s73, s73, 2
	s_add_u32 s52, s52, 0x100
	s_addc_u32 s53, s53, 0
	s_add_u32 s71, s71, 0x100
	s_addc_u32 s72, s72, 0
	s_cmp_gt_u32 s73, 13
	s_cbranch_scc0 .Lhb_B_p5

.LBB0_758:
	s_or_b64 exec, exec, s[48:49]
	s_andn2_b64 vcc, exec, s[6:7]
	s_mov_b64 s[6:7], -1
	s_cbranch_vccnz .LBB0_731
	s_andn2_b64 vcc, exec, s[10:11]
	s_cbranch_vccnz .LBB0_730
	s_branch .LBB0_730

.LBB0_829:
.LBB0_830:
	s_cmp_lt_i32 s20, 7
	s_cselect_b64 s[6:7], -1, 0
	s_and_b64 s[6:7], s[6:7], s[4:5]
	s_andn2_b64 vcc, exec, s[6:7]
	s_cbranch_vccnz .LBB0_847
	s_mov_b64 s[4:5], s[0:1]
	s_mov_b64 s[8:9], s[0:1]
	s_mov_b64 s[10:11], s[0:1]
	s_mov_b64 s[12:13], s[0:1]
	v_mov_b32_e32 v10, v1
	s_cmpk_gt_i32 s2, 0xaff
	v_readfirstlane_b32 s17, v10
	s_cbranch_scc1 .LBB0_847
	v_lshlrev_b32_e32 v2, 4, v10
	v_add_u32_e32 v3, 0x2000, v2
	v_ashrrev_i32_e32 v4, 31, v3
	v_lshrrev_b32_e32 v4, 22, v4
	v_add_u32_e32 v4, v3, v4
	v_ashrrev_i32_e32 v11, 10, v4
	v_mul_i32_i24_e32 v4, 0x400, v11
	v_sub_u32_e32 v3, v3, v4
	v_lshrrev_b32_e32 v4, 4, v3
	v_bitop3_b32 v3, v4, v3, 32 bitop3:0x6c
	v_ashrrev_i32_e32 v4, 31, v3
	v_lshrrev_b32_e32 v4, 26, v4
	v_add_u32_e32 v4, v3, v4
	v_lshlrev_b32_e32 v5, 3, v11
	v_ashrrev_i32_e32 v12, 6, v4
	v_and_b32_e32 v5, -16, v5
	v_add_u32_e32 v5, v12, v5
	s_load_dwordx2 s[14:15], s[10:11], 0xa8
	s_load_dwordx2 s[24:25], s[12:13], 0xa8
	v_and_b32_e32 v6, 3, v12
	s_mov_b32 s10, 0x1fffe0
	v_lshrrev_b32_e32 v7, 2, v5
	v_lshlrev_b32_e32 v8, 1, v5
	v_and_b32_e32 v4, 0xc0, v4
	v_and_or_b32 v6, v5, s10, v6
	v_and_b32_e32 v7, 4, v7
	v_and_b32_e32 v8, 24, v8
	v_sub_u32_e32 v3, v3, v4
	v_mov_b32_e32 v4, 1
	v_or3_b32 v6, v6, v7, v8
	v_lshlrev_b32_e32 v7, 5, v11
	v_ashrrev_i16_sdwa v3, v4, sext(v3) dst_sel:DWORD dst_unused:UNUSED_PAD src0_sel:DWORD src1_sel:BYTE_0
	v_and_b32_e32 v7, 32, v7
	v_bfe_i32 v13, v3, 0, 16
	v_add_lshl_u32 v3, v7, v13, 1
	v_lshl_add_u32 v130, v6, 11, v3
	v_lshl_add_u32 v132, v5, 11, v3
	v_bfe_i32 v3, v10, 27, 1
	v_lshrrev_b32_e32 v3, 22, v3
	v_add_u32_e32 v3, v2, v3
	v_and_b32_e32 v3, 0xfffffc00, v3
	v_sub_u32_e32 v2, v2, v3
	v_lshrrev_b32_e32 v3, 4, v2
	v_ashrrev_i32_e32 v5, 31, v10
	v_bitop3_b32 v2, v3, v2, 32 bitop3:0x6c
	v_lshrrev_b32_e32 v5, 26, v5
	v_ashrrev_i32_e32 v3, 31, v2
	v_add_u32_e32 v5, v10, v5
	s_waitcnt lgkmcnt(0)
	s_add_u32 s3, s14, 0x6400000
	v_lshrrev_b32_e32 v3, 26, v3
	v_ashrrev_i32_e32 v15, 6, v5
	s_addc_u32 s23, s15, 0
	v_add_u32_e32 v3, v2, v3
	v_lshlrev_b32_e32 v5, 3, v15
	s_add_u32 s29, s24, 0xf00000
	v_ashrrev_i32_e32 v14, 6, v3
	v_and_b32_e32 v5, -16, v5
	s_addc_u32 s31, s25, 0
	v_add_u32_e32 v5, v14, v5
	v_and_b32_e32 v6, 3, v14
	s_ashr_i32 s55, s2, 31
	v_and_or_b32 v6, v5, s10, v6
	s_lshr_b32 s10, s55, 29
	s_add_i32 s10, s2, s10
	s_ashr_i32 s14, s17, 6
	s_ashr_i32 s11, s10, 3
	s_and_b32 s10, s10, -8
	s_ashr_i32 s24, s17, 8
	s_lshl_b32 s54, s14, 10
	s_sub_i32 s10, s2, s10
	s_cmp_lt_i32 s10, 0
	s_movk_i32 s56, 0x161
	s_cselect_b32 s12, s56, 0x160
	s_mul_i32 s10, s10, s12
	s_add_i32 s10, s10, s11
	s_mul_hi_i32 s11, s10, 0x2e8ba2e9
	s_lshr_b32 s12, s11, 31
	s_ashr_i32 s11, s11, 5
	s_add_i32 s11, s11, s12
	s_lshl_b32 s12, s11, 3
	s_mulk_i32 s11, 0xb0
	s_sub_i32 s10, s10, s11
	s_sext_i32_i16 s11, s10
	s_bfe_u32 s11, s11, 0x3001c
	s_add_i32 s11, s10, s11
	s_sext_i32_i16 s13, s11
	s_and_b32 s11, s11, 0xfff8
	s_sub_i32 s10, s10, s11
	s_sext_i32_i16 s10, s10
	v_lshrrev_b32_e32 v7, 2, v5
	v_lshlrev_b32_e32 v8, 1, v5
	v_and_b32_e32 v3, 0xc0, v3
	s_lshr_b32 s16, s13, 3
	s_add_i32 s46, s12, s10
	v_and_b32_e32 v7, 4, v7
	v_and_b32_e32 v8, 24, v8
	v_sub_u32_e32 v2, v2, v3
	s_ashr_i32 s47, s46, 31
	s_bfe_i64 s[12:13], s[16:17], 0x100000
	v_or3_b32 v6, v6, v7, v8
	v_lshlrev_b32_e32 v7, 5, v15
	v_ashrrev_i16_sdwa v2, v4, sext(v2) dst_sel:DWORD dst_unused:UNUSED_PAD src0_sel:DWORD src1_sel:BYTE_0
	s_lshl_b64 s[10:11], s[46:47], 19
	s_lshl_b64 s[12:13], s[12:13], 19
	v_and_b32_e32 v7, 32, v7
	v_bfe_i32 v16, v2, 0, 16
	s_add_u32 s50, s29, s12
	v_add_lshl_u32 v2, v7, v16, 1
	s_addc_u32 s51, s31, s13
	s_add_i32 s57, s54, 0
	v_lshl_add_u32 v134, v6, 11, v2
	s_add_i32 m0, s57, 0x10000
	v_lshl_add_u32 v136, v5, 11, v2
	global_load_lds_dwordx4 v134, s[50:51]
	s_add_i32 m0, s57, 0x12000
	s_add_u32 s12, s50, 0x40000
	global_load_lds_dwordx4 v130, s[50:51]
	s_addc_u32 s13, s51, 0
	s_add_i32 m0, s57, 0x14000
	v_mov_b32_e32 v139, 0
	global_load_lds_dwordx4 v134, s[12:13]
	s_add_i32 m0, s57, 0x16000
	s_add_u32 s48, s3, s10
	s_addc_u32 s49, s23, s11
	s_add_i32 s58, s57, 0x2000
	global_load_lds_dwordx4 v130, s[12:13]
	s_mov_b32 m0, s57
	s_add_u32 s10, s48, 0x40000
	global_load_lds_dwordx4 v136, s[48:49]
	s_mov_b32 m0, s58
	s_addc_u32 s11, s49, 0
	s_add_i32 s59, s57, 0x4000
	global_load_lds_dwordx4 v132, s[48:49]
	s_mov_b32 m0, s59
	s_add_i32 s60, s57, 0x6000
	global_load_lds_dwordx4 v136, s[10:11]
	s_mov_b32 m0, s60
	v_mov_b32_e32 v135, v139
	global_load_lds_dwordx4 v132, s[10:11]
	s_load_dwordx2 s[10:11], s[4:5], 0xa8
	s_nop 0
	s_load_dwordx2 s[4:5], s[8:9], 0xa8
	v_mov_b32_e32 v131, v139
	v_mov_b32_e32 v137, v139
	v_mov_b32_e32 v133, v139
	s_cmp_eq_u32 s24, 1
	s_mov_b32 s61, 0
	v_lshl_add_u64 v[8:9], s[50:51], 0, v[134:135]
	v_lshl_add_u64 v[6:7], s[50:51], 0, v[130:131]
	v_lshl_add_u64 v[2:3], s[48:49], 0, v[136:137]
	s_cselect_b64 s[8:9], -1, 0
	s_cmp_lg_u32 s24, 1
	v_lshl_add_u64 v[4:5], s[48:49], 0, v[132:133]
	s_cbranch_scc1 .LBB0_834
.LBB0_834:
	s_waitcnt lgkmcnt(0)
	s_add_u32 s10, s10, 0x40000
	s_addc_u32 s11, s11, 0
	s_add_u32 s12, s4, 0xa400000
	s_addc_u32 s13, s5, 0
	s_lshl_b32 s4, s14, 5
	s_mov_b64 s[14:15], 0x80
	s_and_b32 s26, s4, 0x60
	s_add_i32 m0, s57, 0x18000
	v_lshl_add_u64 v[8:9], v[8:9], 0, s[14:15]
	s_lshl_b32 s25, s24, 13
	s_lshl_b32 s27, s26, 7
	s_waitcnt vmcnt(2)
	s_barrier
	global_load_lds_dwordx4 v[8:9], off
	v_lshl_add_u64 v[6:7], v[6:7], 0, s[14:15]
	s_add_i32 m0, s57, 0x1a000
	s_add_i32 s62, s57, 0x8000
	s_add_i32 s63, s57, 0xa000
	global_load_lds_dwordx4 v[6:7], off
	v_lshl_add_u64 v[2:3], v[2:3], 0, s[14:15]
	s_mov_b32 m0, s62
	s_add_u32 s4, s50, 0x40080
	global_load_lds_dwordx4 v[2:3], off
	v_lshl_add_u64 v[2:3], v[4:5], 0, s[14:15]
	s_mov_b32 m0, s63
	s_addc_u32 s5, s51, 0
	global_load_lds_dwordx4 v[2:3], off
	s_add_i32 m0, s57, 0x1c000
	v_lshl_add_u64 v[2:3], s[4:5], 0, v[134:135]
	global_load_lds_dwordx4 v[2:3], off
	v_lshl_add_u64 v[2:3], s[4:5], 0, v[130:131]
	s_add_i32 m0, s57, 0x1e000
	s_cmpk_lt_u32 s17, 0x100
	global_load_lds_dwordx4 v[2:3], off
	v_lshrrev_b32_e32 v3, 1, v10
	v_and_b32_e32 v3, 24, v3
	v_and_b32_e32 v2, 15, v10
	v_lshlrev_b32_e32 v4, 1, v3
	v_lshl_or_b32 v150, s24, 6, v2
	v_lshl_or_b32 v2, v2, 6, v4
	v_lshlrev_b32_e32 v4, 2, v10
	v_and_b32_e32 v4, 32, v4
	v_bitop3_b32 v5, v2, s25, v4 bitop3:0xde
	v_bitop3_b32 v151, v2, s27, v4 bitop3:0xde
	v_or_b32_e32 v2, s26, v3
	v_lshlrev_b32_e32 v3, 14, v15
	v_and_b32_e32 v3, 0xffff8000, v3
	v_lshl_add_u32 v3, v14, 11, v3
	v_and_b32_e32 v4, 1, v15
	v_lshl_or_b32 v3, v4, 6, v3
	v_lshl_add_u32 v140, v16, 1, v3
	v_lshlrev_b32_e32 v3, 14, v11
	v_and_b32_e32 v3, 0xffff8000, v3
	s_waitcnt vmcnt(6)
	v_lshl_add_u32 v3, v12, 11, v3
	v_and_b32_e32 v4, 1, v11
	s_sext_i32_i16 s47, s16
	s_cselect_b64 s[16:17], -1, 0
	v_lshl_or_b32 v3, v4, 6, v3
	s_add_i32 s66, 0, 0x10000
	s_add_i32 s67, 0, 0x14000
	v_or_b32_e32 v152, 16, v150
	v_or_b32_e32 v153, 32, v150
	v_or_b32_e32 v154, 48, v150
	s_ashr_i32 s64, s38, 31
	s_mov_b32 s65, s38
	v_mov_b32_e32 v141, v139
	v_lshl_add_u32 v142, v13, 1, v3
	v_mov_b32_e32 v143, v139
	v_mov_b64_e32 v[144:145], 0xb00
	v_mov_b64_e32 v[146:147], 0xaff
	v_add_u32_e32 v155, s66, v151
	v_add_u32_e32 v156, s67, v151
	v_add_u32_e32 v157, 0, v5
	v_mov_b32_e32 v158, 0x358637bd
	s_movk_i32 s68, 0x1600
	v_lshlrev_b32_e32 v138, 1, v2
	s_barrier
	s_branch .LBB0_837

.LBB0_839:
	s_ashr_i32 s27, s26, 31
	s_lshl_b64 s[42:43], s[26:27], 19
	s_add_u32 s42, s3, s42
	s_addc_u32 s43, s23, s43
	s_and_b64 s[44:45], s[4:5], exec
	s_cselect_b32 s27, s43, s49
	s_cselect_b32 s69, s42, s48
	s_ashr_i32 s25, s24, 31
	s_lshl_b64 s[44:45], s[24:25], 19
	s_add_u32 s44, s29, s44
	s_addc_u32 s45, s31, s45
	s_and_b64 s[52:53], s[4:5], exec
	s_cselect_b32 s25, s45, s51
	s_cselect_b32 s70, s44, s50
	s_add_u32 s48, s48, 0x40080
	s_addc_u32 s49, s49, 0
	s_add_u32 s71, s50, 0x100
	v_mov_b32_e32 v2, 0
	s_addc_u32 s72, s51, 0
	s_mov_b32 s73, -2
	v_mov_b32_e32 v3, v2
	v_mov_b32_e32 v4, v2
	v_mov_b32_e32 v5, v2
	v_mov_b32_e32 v14, v2
	v_mov_b32_e32 v15, v2
	v_mov_b32_e32 v16, v2
	v_mov_b32_e32 v17, v2
	v_mov_b32_e32 v22, v2
	v_mov_b32_e32 v23, v2
	v_mov_b32_e32 v24, v2
	v_mov_b32_e32 v25, v2
	v_mov_b32_e32 v30, v2
	v_mov_b32_e32 v31, v2
	v_mov_b32_e32 v32, v2
	v_mov_b32_e32 v33, v2
	v_mov_b32_e32 v38, v2
	v_mov_b32_e32 v39, v2
	v_mov_b32_e32 v40, v2
	v_mov_b32_e32 v41, v2
	v_mov_b32_e32 v46, v2
	v_mov_b32_e32 v47, v2
	v_mov_b32_e32 v48, v2
	v_mov_b32_e32 v49, v2
	v_mov_b32_e32 v54, v2
	v_mov_b32_e32 v55, v2
	v_mov_b32_e32 v56, v2
	v_mov_b32_e32 v57, v2
	v_mov_b32_e32 v62, v2
	v_mov_b32_e32 v63, v2
	v_mov_b32_e32 v64, v2
	v_mov_b32_e32 v65, v2
	v_mov_b32_e32 v6, v2
	v_mov_b32_e32 v7, v2
	v_mov_b32_e32 v8, v2
	v_mov_b32_e32 v9, v2
	v_mov_b32_e32 v10, v2
	v_mov_b32_e32 v11, v2
	v_mov_b32_e32 v12, v2
	v_mov_b32_e32 v13, v2
	v_mov_b32_e32 v18, v2
	v_mov_b32_e32 v19, v2
	v_mov_b32_e32 v20, v2
	v_mov_b32_e32 v21, v2
	v_mov_b32_e32 v26, v2
	v_mov_b32_e32 v27, v2
	v_mov_b32_e32 v28, v2
	v_mov_b32_e32 v29, v2
	v_mov_b32_e32 v34, v2
	v_mov_b32_e32 v35, v2
	v_mov_b32_e32 v36, v2
	v_mov_b32_e32 v37, v2
	v_mov_b32_e32 v42, v2
	v_mov_b32_e32 v43, v2
	v_mov_b32_e32 v44, v2
	v_mov_b32_e32 v45, v2
	v_mov_b32_e32 v50, v2
	v_mov_b32_e32 v51, v2
	v_mov_b32_e32 v52, v2
	v_mov_b32_e32 v53, v2
	v_mov_b32_e32 v58, v2
	v_mov_b32_e32 v59, v2
	v_mov_b32_e32 v60, v2
	v_mov_b32_e32 v61, v2
	v_mov_b32_e32 v70, v2
	v_mov_b32_e32 v71, v2
	v_mov_b32_e32 v72, v2
	v_mov_b32_e32 v73, v2
	v_mov_b32_e32 v78, v2
	v_mov_b32_e32 v79, v2
	v_mov_b32_e32 v80, v2
	v_mov_b32_e32 v81, v2
	s_waitcnt vmcnt(0)
	v_mov_b32_e32 v86, v2
	v_mov_b32_e32 v87, v2
	v_mov_b32_e32 v88, v2
	v_mov_b32_e32 v89, v2
	v_mov_b32_e32 v94, v2
	v_mov_b32_e32 v95, v2
	v_mov_b32_e32 v96, v2
	v_mov_b32_e32 v97, v2
	v_mov_b32_e32 v102, v2
	v_mov_b32_e32 v103, v2
	v_mov_b32_e32 v104, v2
	v_mov_b32_e32 v105, v2
	v_mov_b32_e32 v110, v2
	v_mov_b32_e32 v111, v2
	v_mov_b32_e32 v112, v2
	v_mov_b32_e32 v113, v2
	v_mov_b32_e32 v122, v2
	v_mov_b32_e32 v123, v2
	v_mov_b32_e32 v124, v2
	v_mov_b32_e32 v125, v2
	v_mov_b32_e32 v126, v2
	v_mov_b32_e32 v127, v2
	v_mov_b32_e32 v128, v2
	v_mov_b32_e32 v129, v2
	v_mov_b32_e32 v66, v2
	v_mov_b32_e32 v67, v2
	v_mov_b32_e32 v68, v2
	v_mov_b32_e32 v69, v2
	v_mov_b32_e32 v74, v2
	v_mov_b32_e32 v75, v2
	v_mov_b32_e32 v76, v2
	v_mov_b32_e32 v77, v2
	v_mov_b32_e32 v82, v2
	v_mov_b32_e32 v83, v2
	v_mov_b32_e32 v84, v2
	v_mov_b32_e32 v85, v2
	v_mov_b32_e32 v90, v2
	v_mov_b32_e32 v91, v2
	v_mov_b32_e32 v92, v2
	v_mov_b32_e32 v93, v2
	v_mov_b32_e32 v98, v2
	v_mov_b32_e32 v99, v2
	v_mov_b32_e32 v100, v2
	v_mov_b32_e32 v101, v2
	v_mov_b32_e32 v106, v2
	v_mov_b32_e32 v107, v2
	v_mov_b32_e32 v108, v2
	v_mov_b32_e32 v109, v2
	v_mov_b32_e32 v114, v2
	v_mov_b32_e32 v115, v2
	v_mov_b32_e32 v116, v2
	v_mov_b32_e32 v117, v2
	v_mov_b32_e32 v118, v2
	v_mov_b32_e32 v119, v2
	v_mov_b32_e32 v120, v2
	v_mov_b32_e32 v121, v2
	s_cmp_eq_u64 s[16:17], 0
	s_cbranch_scc1 .Lhb_B_p6

.LBB0_922:
	s_andn2_b64 vcc, exec, s[14:15]
	s_cbranch_vccnz .LBB0_962
	v_ashrrev_i32_e32 v3, 31, v10
	v_lshrrev_b32_e32 v3, 26, v3
	v_add_u32_e32 v3, v10, v3
	v_ashrrev_i32_e32 v11, 6, v3
	v_bfe_i32 v3, v10, 27, 1
	v_lshlrev_b32_e32 v2, 4, v10
	v_lshrrev_b32_e32 v3, 22, v3
	v_add_u32_e32 v3, v2, v3
	v_and_b32_e32 v3, 0xfffffc00, v3
	v_sub_u32_e32 v3, v2, v3
	v_lshrrev_b32_e32 v4, 4, v3
	v_bitop3_b32 v3, v4, v3, 32 bitop3:0x6c
	v_ashrrev_i32_e32 v5, 31, v3
	v_lshrrev_b32_e32 v5, 26, v5
	v_lshlrev_b32_e32 v4, 3, v11
	v_add_u32_e32 v5, v3, v5
	s_waitcnt lgkmcnt(0)
	s_add_u32 s3, s8, 0xa400000
	v_and_b32_e32 v4, -16, v4
	v_ashrrev_i32_e32 v13, 6, v5
	v_and_b32_e32 v5, 0xc0, v5
	s_addc_u32 s23, s9, 0
	v_add_u32_e32 v4, v13, v4
	v_lshlrev_b32_e32 v6, 5, v11
	v_sub_u32_e32 v3, v3, v5
	v_mov_b32_e32 v5, 1
	s_add_u32 s29, s12, 0x3580000
	v_and_b32_e32 v12, 32, v6
	v_ashrrev_i16_sdwa v3, v5, sext(v3) dst_sel:DWORD dst_unused:UNUSED_PAD src0_sel:DWORD src1_sel:BYTE_0
	v_lshlrev_b32_e32 v6, 1, v4
	v_lshrrev_b32_e32 v7, 2, v4
	v_and_b32_e32 v8, 3, v13
	s_mov_b32 s12, 0xffffe0
	v_bfe_i32 v14, v3, 0, 16
	v_and_b32_e32 v6, 24, v6
	v_and_b32_e32 v7, 4, v7
	v_and_or_b32 v8, v4, s12, v8
	s_movk_i32 s9, 0xb00
	v_add_u32_e32 v3, v12, v14
	v_or3_b32 v6, v8, v7, v6
	v_mul_lo_u32 v4, v4, s9
	v_add_lshl_u32 v194, v3, v4, 1
	v_mul_u32_u24_e32 v4, 0xb00, v6
	v_add_u32_e32 v2, 0x2000, v2
	v_add_lshl_u32 v196, v4, v3, 1
	v_ashrrev_i32_e32 v3, 31, v2
	v_lshrrev_b32_e32 v3, 22, v3
	v_add_u32_e32 v3, v2, v3
	v_ashrrev_i32_e32 v15, 10, v3
	v_mul_i32_i24_e32 v3, 0x400, v15
	v_sub_u32_e32 v2, v2, v3
	v_lshrrev_b32_e32 v3, 4, v2
	v_bitop3_b32 v2, v3, v2, 32 bitop3:0x6c
	v_ashrrev_i32_e32 v4, 31, v2
	v_lshrrev_b32_e32 v4, 26, v4
	v_lshlrev_b32_e32 v3, 3, v15
	v_add_u32_e32 v4, v2, v4
	s_addc_u32 s31, s13, 0
	v_and_b32_e32 v3, -16, v3
	v_ashrrev_i32_e32 v16, 6, v4
	v_lshlrev_b32_e32 v6, 5, v15
	v_and_b32_e32 v4, 0xc0, v4
	s_ashr_i32 s24, s26, 6
	s_ashr_i32 s8, s26, 8
	v_add_u32_e32 v3, v16, v3
	v_and_b32_e32 v17, 32, v6
	v_sub_u32_e32 v2, v2, v4
	v_and_b32_e32 v6, 3, v16
	s_lshl_b32 s52, s24, 10
	s_mul_i32 s13, s68, 0x160000
	v_ashrrev_i16_sdwa v2, v5, sext(v2) dst_sel:DWORD dst_unused:UNUSED_PAD src0_sel:DWORD src1_sel:BYTE_0
	v_lshlrev_b32_e32 v4, 1, v3
	v_lshrrev_b32_e32 v5, 2, v3
	v_and_or_b32 v6, v3, s12, v6
	s_mul_hi_i32 s12, s68, 0x160000
	s_add_u32 s46, s29, s13
	v_bfe_i32 v18, v2, 0, 16
	v_and_b32_e32 v4, 24, v4
	v_and_b32_e32 v5, 4, v5
	s_addc_u32 s47, s31, s12
	s_add_i32 s53, s52, 0
	v_add_u32_e32 v2, v17, v18
	v_or3_b32 v4, v6, v5, v4
	v_mul_lo_u32 v3, v3, s9
	s_add_i32 m0, s53, 0x10000
	v_add_lshl_u32 v198, v2, v3, 1
	v_mul_u32_u24_e32 v3, 0xb00, v4
	global_load_lds_dwordx4 v196, s[46:47]
	s_add_i32 m0, s53, 0x12000
	v_add_lshl_u32 v200, v3, v2, 1
	s_add_u32 s12, s46, 0xb0000
	global_load_lds_dwordx4 v200, s[46:47]
	s_addc_u32 s13, s47, 0
	s_add_i32 m0, s53, 0x14000
	s_mul_i32 s15, s67, 0x160000
	global_load_lds_dwordx4 v196, s[12:13]
	s_add_i32 m0, s53, 0x16000
	s_mul_hi_i32 s14, s67, 0x160000
	s_add_u32 s44, s3, s15
	s_addc_u32 s45, s23, s14
	s_add_i32 s54, s53, 0x2000
	global_load_lds_dwordx4 v200, s[12:13]
	s_mov_b32 m0, s53
	s_add_u32 s12, s44, 0xb0000
	global_load_lds_dwordx4 v194, s[44:45]
	s_mov_b32 m0, s54
	s_addc_u32 s13, s45, 0
	s_add_i32 s55, s53, 0x4000
	global_load_lds_dwordx4 v198, s[44:45]
	s_mov_b32 m0, s55
	s_add_i32 s56, s53, 0x6000
	global_load_lds_dwordx4 v194, s[12:13]
	s_mov_b32 m0, s56
	v_mov_b32_e32 v203, 0
	global_load_lds_dwordx4 v198, s[12:13]
	v_mov_b32_e32 v197, v203
	v_mov_b32_e32 v201, v203
	v_mov_b32_e32 v195, v203
	v_mov_b32_e32 v199, v203
	s_cmp_eq_u32 s8, 1
	s_mov_b32 s57, 0
	v_lshl_add_u64 v[8:9], s[46:47], 0, v[196:197]
	v_lshl_add_u64 v[6:7], s[46:47], 0, v[200:201]
	v_lshl_add_u64 v[2:3], s[44:45], 0, v[194:195]
	s_cselect_b64 s[12:13], -1, 0
	s_cmp_lg_u32 s8, 1
	v_lshl_add_u64 v[4:5], s[44:45], 0, v[198:199]
	s_cbranch_scc1 .LBB0_925
.LBB0_925:
	s_add_u32 s14, s4, 0x6400000
	s_addc_u32 s15, s5, 0
	s_add_u32 s16, s6, 0x60000
	s_addc_u32 s17, s7, 0
	s_lshl_b32 s4, s24, 5
	s_mov_b64 s[24:25], 0x80
	s_and_b32 s42, s4, 0x60
	s_add_i32 m0, s53, 0x18000
	v_lshl_add_u64 v[8:9], v[8:9], 0, s[24:25]
	s_lshl_b32 s6, s8, 13
	s_lshl_b32 s7, s42, 7
	s_waitcnt vmcnt(2)
	s_barrier
	global_load_lds_dwordx4 v[8:9], off
	v_lshl_add_u64 v[6:7], v[6:7], 0, s[24:25]
	s_add_i32 m0, s53, 0x1a000
	s_add_i32 s58, s53, 0x8000
	s_add_i32 s59, s53, 0xa000
	global_load_lds_dwordx4 v[6:7], off
	v_lshl_add_u64 v[2:3], v[2:3], 0, s[24:25]
	s_mov_b32 m0, s58
	s_add_u32 s4, s46, 0xb0080
	global_load_lds_dwordx4 v[2:3], off
	v_lshl_add_u64 v[2:3], v[4:5], 0, s[24:25]
	s_mov_b32 m0, s59
	s_addc_u32 s5, s47, 0
	global_load_lds_dwordx4 v[2:3], off
	s_add_i32 m0, s53, 0x1c000
	v_lshl_add_u64 v[2:3], s[4:5], 0, v[196:197]
	global_load_lds_dwordx4 v[2:3], off
	v_lshl_add_u64 v[2:3], s[4:5], 0, v[200:201]
	s_add_i32 m0, s53, 0x1e000
	s_cmpk_lt_u32 s26, 0x100
	global_load_lds_dwordx4 v[2:3], off
	v_bfe_u32 v3, v10, 4, 2
	v_and_b32_e32 v2, 15, v10
	v_lshlrev_b32_e32 v4, 4, v3
	v_lshl_or_b32 v243, s8, 6, v2
	v_lshl_or_b32 v2, v2, 6, v4
	v_lshlrev_b32_e32 v4, 2, v10
	v_and_b32_e32 v4, 32, v4
	v_bitop3_b32 v6, v2, s6, v4 bitop3:0xde
	v_bitop3_b32 v244, v2, s7, v4 bitop3:0xde
	v_lshl_or_b32 v2, v3, 3, s42
	v_cmp_eq_u32_e64 s[4:5], 0, v3
	v_lshrrev_b32_e32 v3, 1, v11
	v_mul_lo_u32 v4, v13, s9
	s_mov_b32 s8, 0xb000
	v_mad_u64_u32 v[4:5], s[42:43], v3, s8, v[4:5]
	v_lshlrev_b32_e32 v202, 1, v2
	v_or_b32_e32 v3, v4, v12
	v_lshl_add_u64 v[204:205], s[14:15], 0, v[202:203]
	v_add_lshl_u32 v202, v3, v14, 1
	v_lshrrev_b32_e32 v3, 1, v15
	v_mul_lo_u32 v4, v16, s9
	v_mad_u64_u32 v[4:5], s[8:9], v3, s8, v[4:5]
	s_mov_b64 s[6:7], 0xb0080
	s_waitcnt vmcnt(6)
	v_or_b32_e32 v3, v4, v17
	s_cselect_b64 s[26:27], -1, 0
	v_lshl_add_u64 v[206:207], v[202:203], 0, s[6:7]
	v_add_lshl_u32 v202, v3, v18, 1
	s_add_i32 s63, 0, 0x10000
	s_add_i32 s64, 0, 0x14000
	v_mbcnt_lo_u32_b32 v3, -1, 0
	s_ashr_i32 s60, s38, 31
	s_mov_b32 s61, s38
	s_ashr_i32 s62, s2, 31
	v_lshl_add_u64 v[208:209], v[202:203], 0, s[6:7]
	v_add_u32_e32 v245, s63, v244
	v_add_u32_e32 v246, s64, v244
	v_add_u32_e32 v247, 0, v6
	v_mbcnt_hi_u32_b32 v248, -1, v3
	v_lshlrev_b32_e32 v202, 1, v2
	s_barrier
	s_branch .LBB0_928

.LBB0_938:
	s_add_u32 s69, s46, 0x100
	v_mov_b32_e32 v2, 0
	s_addc_u32 s70, s47, 0
	s_mov_b32 s71, -2
	v_mov_b32_e32 v3, v2
	v_mov_b32_e32 v4, v2
	v_mov_b32_e32 v5, v2
	v_mov_b32_e32 v6, v2
	v_mov_b32_e32 v7, v2
	v_mov_b32_e32 v8, v2
	v_mov_b32_e32 v9, v2
	v_mov_b32_e32 v18, v2
	v_mov_b32_e32 v19, v2
	v_mov_b32_e32 v20, v2
	v_mov_b32_e32 v21, v2
	v_mov_b32_e32 v22, v2
	v_mov_b32_e32 v23, v2
	v_mov_b32_e32 v24, v2
	v_mov_b32_e32 v25, v2
	v_mov_b32_e32 v34, v2
	v_mov_b32_e32 v35, v2
	v_mov_b32_e32 v36, v2
	v_mov_b32_e32 v37, v2
	v_mov_b32_e32 v38, v2
	v_mov_b32_e32 v39, v2
	v_mov_b32_e32 v40, v2
	v_mov_b32_e32 v41, v2
	v_mov_b32_e32 v50, v2
	v_mov_b32_e32 v51, v2
	v_mov_b32_e32 v52, v2
	v_mov_b32_e32 v53, v2
	v_mov_b32_e32 v54, v2
	v_mov_b32_e32 v55, v2
	v_mov_b32_e32 v56, v2
	v_mov_b32_e32 v57, v2
	v_mov_b32_e32 v10, v2
	v_mov_b32_e32 v11, v2
	v_mov_b32_e32 v12, v2
	v_mov_b32_e32 v13, v2
	v_mov_b32_e32 v14, v2
	v_mov_b32_e32 v15, v2
	v_mov_b32_e32 v16, v2
	v_mov_b32_e32 v17, v2
	v_mov_b32_e32 v26, v2
	v_mov_b32_e32 v27, v2
	v_mov_b32_e32 v28, v2
	v_mov_b32_e32 v29, v2
	v_mov_b32_e32 v30, v2
	v_mov_b32_e32 v31, v2
	v_mov_b32_e32 v32, v2
	v_mov_b32_e32 v33, v2
	v_mov_b32_e32 v42, v2
	v_mov_b32_e32 v43, v2
	v_mov_b32_e32 v44, v2
	v_mov_b32_e32 v45, v2
	v_mov_b32_e32 v46, v2
	v_mov_b32_e32 v47, v2
	v_mov_b32_e32 v48, v2
	v_mov_b32_e32 v49, v2
	v_mov_b32_e32 v58, v2
	v_mov_b32_e32 v59, v2
	v_mov_b32_e32 v60, v2
	v_mov_b32_e32 v61, v2
	v_mov_b32_e32 v62, v2
	v_mov_b32_e32 v63, v2
	v_mov_b32_e32 v64, v2
	v_mov_b32_e32 v65, v2
	v_mov_b32_e32 v66, v2
	v_mov_b32_e32 v67, v2
	v_mov_b32_e32 v68, v2
	v_mov_b32_e32 v69, v2
	v_mov_b32_e32 v70, v2
	v_mov_b32_e32 v71, v2
	v_mov_b32_e32 v72, v2
	v_mov_b32_e32 v73, v2
	s_waitcnt vmcnt(0)
	v_mov_b32_e32 v82, v2
	v_mov_b32_e32 v83, v2
	v_mov_b32_e32 v84, v2
	v_mov_b32_e32 v85, v2
	v_mov_b32_e32 v86, v2
	v_mov_b32_e32 v87, v2
	v_mov_b32_e32 v88, v2
	v_mov_b32_e32 v89, v2
	v_mov_b32_e32 v98, v2
	v_mov_b32_e32 v99, v2
	v_mov_b32_e32 v100, v2
	v_mov_b32_e32 v101, v2
	v_mov_b32_e32 v102, v2
	v_mov_b32_e32 v103, v2
	v_mov_b32_e32 v104, v2
	v_mov_b32_e32 v105, v2
	v_mov_b32_e32 v114, v2
	v_mov_b32_e32 v115, v2
	v_mov_b32_e32 v116, v2
	v_mov_b32_e32 v117, v2
	v_mov_b32_e32 v118, v2
	v_mov_b32_e32 v119, v2
	v_mov_b32_e32 v120, v2
	v_mov_b32_e32 v121, v2
	v_mov_b32_e32 v74, v2
	v_mov_b32_e32 v75, v2
	v_mov_b32_e32 v76, v2
	v_mov_b32_e32 v77, v2
	v_mov_b32_e32 v78, v2
	v_mov_b32_e32 v79, v2
	v_mov_b32_e32 v80, v2
	v_mov_b32_e32 v81, v2
	v_mov_b32_e32 v90, v2
	v_mov_b32_e32 v91, v2
	v_mov_b32_e32 v92, v2
	v_mov_b32_e32 v93, v2
	v_mov_b32_e32 v94, v2
	v_mov_b32_e32 v95, v2
	v_mov_b32_e32 v96, v2
	v_mov_b32_e32 v97, v2
	v_mov_b32_e32 v106, v2
	v_mov_b32_e32 v107, v2
	v_mov_b32_e32 v108, v2
	v_mov_b32_e32 v109, v2
	v_mov_b32_e32 v110, v2
	v_mov_b32_e32 v111, v2
	v_mov_b32_e32 v112, v2
	v_mov_b32_e32 v113, v2
	v_mov_b32_e32 v150, v2
	v_mov_b32_e32 v151, v2
	v_mov_b32_e32 v152, v2
	v_mov_b32_e32 v153, v2
	v_mov_b32_e32 v154, v2
	v_mov_b32_e32 v155, v2
	v_mov_b32_e32 v156, v2
	v_mov_b32_e32 v157, v2
	s_cmp_eq_u64 s[26:27], 0
	s_cbranch_scc1 .Lhb_B_p7

.Lhb_exit_p7:
	s_and_b64 vcc, exec, s[26:27]
	s_cbranch_vccz .LBB0_942
.LBB0_942:
	s_lshl_b32 s44, s68, 8
	v_lshl_add_u32 v238, s67, 8, v243
	s_ashr_i32 s45, s44, 31
	s_lshl_b64 s[46:47], s[44:45], 1
	v_ashrrev_i32_e32 v239, 31, v238
	v_lshl_add_u64 v[126:127], v[204:205], 0, s[46:47]
	v_lshlrev_b64 v[240:241], 11, v[238:239]
	v_lshl_add_u64 v[122:123], v[126:127], 0, v[240:241]
	global_load_dwordx4 v[190:193], v[122:123], off
	global_load_dwordx4 v[186:189], v[122:123], off offset:256
	v_or_b32_e32 v234, 16, v238
	v_ashrrev_i32_e32 v235, 31, v234
	v_or_b32_e32 v230, 32, v238
	v_lshlrev_b64 v[236:237], 11, v[234:235]
	v_ashrrev_i32_e32 v231, 31, v230
	v_or_b32_e32 v226, 48, v238
	v_lshl_add_u64 v[122:123], v[126:127], 0, v[236:237]
	v_lshlrev_b64 v[232:233], 11, v[230:231]
	v_ashrrev_i32_e32 v227, 31, v226
	v_add_u32_e32 v222, 0x80, v238
	global_load_dwordx4 v[182:185], v[122:123], off
	global_load_dwordx4 v[178:181], v[122:123], off offset:256
	v_lshl_add_u64 v[122:123], v[126:127], 0, v[232:233]
	v_lshlrev_b64 v[228:229], 11, v[226:227]
	v_ashrrev_i32_e32 v223, 31, v222
	v_add_u32_e32 v218, 0x90, v238
	global_load_dwordx4 v[174:177], v[122:123], off
	global_load_dwordx4 v[170:173], v[122:123], off offset:256
	v_lshl_add_u64 v[122:123], v[126:127], 0, v[228:229]
	v_lshlrev_b64 v[224:225], 11, v[222:223]
	v_ashrrev_i32_e32 v219, 31, v218
	v_add_u32_e32 v212, 0xa0, v238
	v_add_u32_e32 v210, 0xb0, v238
	global_load_dwordx4 v[166:169], v[122:123], off
	global_load_dwordx4 v[162:165], v[122:123], off offset:256
	v_lshl_add_u64 v[122:123], v[126:127], 0, v[224:225]
	v_lshlrev_b64 v[220:221], 11, v[218:219]
	v_ashrrev_i32_e32 v213, 31, v212
	v_ashrrev_i32_e32 v211, 31, v210
	global_load_dwordx4 v[158:161], v[122:123], off
	global_load_dwordx4 v[146:149], v[122:123], off offset:256
	v_lshl_add_u64 v[122:123], v[126:127], 0, v[220:221]
	v_lshlrev_b64 v[216:217], 11, v[212:213]
	v_lshlrev_b64 v[214:215], 11, v[210:211]
	global_load_dwordx4 v[142:145], v[122:123], off
	global_load_dwordx4 v[138:141], v[122:123], off offset:256
	v_lshl_add_u64 v[122:123], v[126:127], 0, v[216:217]
	v_lshl_add_u64 v[126:127], v[126:127], 0, v[214:215]
	global_load_dwordx4 v[130:133], v[122:123], off
	s_nop 0
	global_load_dwordx4 v[122:125], v[122:123], off offset:256
	s_nop 0
	global_load_dwordx4 v[134:137], v[126:127], off
	s_nop 0
	global_load_dwordx4 v[126:129], v[126:127], off offset:256
	v_lshl_add_u64 v[240:241], s[14:15], 0, v[240:241]
	v_lshl_add_u64 v[240:241], v[240:241], 0, s[46:47]
	v_lshl_add_u64 v[240:241], v[240:241], 0, v[202:203]
	v_and_b32_e32 v250, 64, v248
	v_xor_b32_e32 v249, 16, v248
	v_add_u32_e32 v250, 64, v250
	v_cmp_lt_i32_e32 vcc, v249, v250
	v_xor_b32_e32 v251, 32, v248
	s_waitcnt vmcnt(0)
	v_lshlrev_b32_e32 v252, 16, v190
	v_and_b32_e32 v253, 0xffff0000, v190
	v_lshlrev_b32_e32 v190, 16, v191
	v_and_b32_e32 v191, 0xffff0000, v191
	v_lshlrev_b32_e32 v254, 16, v192
	v_and_b32_e32 v255, 0xffff0000, v192
	v_lshlrev_b32_e32 v192, 16, v193
	v_and_b32_e32 v193, 0xffff0000, v193
	v_pk_fma_f32 v[156:157], v[156:157], 0.5, v[190:191] op_sel_hi:[1,0,1]
	v_pk_fma_f32 v[154:155], v[154:155], 0.5, v[252:253] op_sel_hi:[1,0,1]
	v_pk_fma_f32 v[190:191], v[152:153], 0.5, v[192:193] op_sel_hi:[1,0,1]
	v_pk_fma_f32 v[192:193], v[150:151], 0.5, v[254:255] op_sel_hi:[1,0,1]
	v_cvt_pk_bf16_f32 v150, v154, v155
	v_cvt_pk_bf16_f32 v151, v156, v157
	v_cvt_pk_bf16_f32 v152, v192, v193
	v_cvt_pk_bf16_f32 v153, v190, v191
	global_store_dwordx4 v[240:241], v[150:153], off
	v_cndmask_b32_e32 v249, v248, v249, vcc
	v_lshlrev_b32_e32 v249, 2, v249
	v_mul_f32_e32 v150, v155, v155
	v_mul_f32_e32 v151, v157, v157
	v_fmac_f32_e32 v150, v154, v154
	v_fmac_f32_e32 v151, v156, v156
	v_add_f32_e32 v150, v150, v151
	v_mul_f32_e32 v151, v193, v193
	v_mul_f32_e32 v152, v191, v191
	v_fmac_f32_e32 v151, v192, v192
	v_fmac_f32_e32 v152, v190, v190
	v_add_f32_e32 v151, v151, v152
	v_add_f32_e32 v190, v150, v151
	v_lshlrev_b32_e32 v150, 16, v186
	v_and_b32_e32 v151, 0xffff0000, v186
	v_lshlrev_b32_e32 v152, 16, v187
	v_and_b32_e32 v153, 0xffff0000, v187
	v_lshlrev_b32_e32 v154, 16, v188
	v_and_b32_e32 v155, 0xffff0000, v188
	v_lshlrev_b32_e32 v156, 16, v189
	v_and_b32_e32 v157, 0xffff0000, v189
	v_pk_fma_f32 v[120:121], v[120:121], 0.5, v[152:153] op_sel_hi:[1,0,1]
	v_pk_fma_f32 v[118:119], v[118:119], 0.5, v[150:151] op_sel_hi:[1,0,1]
	v_pk_fma_f32 v[150:151], v[116:117], 0.5, v[156:157] op_sel_hi:[1,0,1]
	v_pk_fma_f32 v[152:153], v[114:115], 0.5, v[154:155] op_sel_hi:[1,0,1]
	v_cvt_pk_bf16_f32 v114, v118, v119
	v_cvt_pk_bf16_f32 v115, v120, v121
	v_cvt_pk_bf16_f32 v116, v152, v153
	v_cvt_pk_bf16_f32 v117, v150, v151
	global_store_dwordx4 v[240:241], v[114:117], off offset:256
	v_cmp_lt_i32_e32 vcc, v251, v250
	s_nop 0
	v_mul_f32_e32 v114, v119, v119
	v_mul_f32_e32 v115, v121, v121
	v_fmac_f32_e32 v114, v118, v118
	v_fmac_f32_e32 v115, v120, v120
	v_add_f32_e32 v114, v114, v115
	v_mul_f32_e32 v115, v153, v153
	v_mul_f32_e32 v116, v151, v151
	v_fmac_f32_e32 v115, v152, v152
	v_fmac_f32_e32 v116, v150, v150
	v_add_f32_e32 v115, v115, v116
	v_add_f32_e32 v114, v114, v115
	v_add_f32_e32 v114, v190, v114
	ds_bpermute_b32 v115, v249, v114
	v_cndmask_b32_e32 v250, v248, v251, vcc
	v_lshlrev_b32_e32 v250, 2, v250
	s_waitcnt lgkmcnt(0)
	v_add_f32_e32 v114, v114, v115
	ds_bpermute_b32 v115, v250, v114
	s_and_saveexec_b64 s[46:47], s[4:5]
	s_cbranch_execz .LBB0_944
	v_lshl_add_u64 v[116:117], v[238:239], 2, s[16:17]
	s_waitcnt lgkmcnt(0)
	v_add_f32_e32 v114, v114, v115
	global_atomic_add_f32 v[116:117], v114, off

.LBB0_1037:
	s_load_dwordx2 s[48:49], s[14:15], 0xa8
	s_load_dwordx2 s[50:51], s[16:17], 0xa8
	s_andn2_b64 vcc, exec, s[44:45]
	s_cbranch_vccnz .LBB0_1121
	v_ashrrev_i32_e32 v3, 31, v10
	v_lshrrev_b32_e32 v3, 26, v3
	v_add_u32_e32 v3, v10, v3
	v_ashrrev_i32_e32 v11, 6, v3
	v_bfe_i32 v3, v10, 27, 1
	v_lshlrev_b32_e32 v2, 4, v10
	v_lshrrev_b32_e32 v3, 22, v3
	v_add_u32_e32 v3, v2, v3
	v_and_b32_e32 v3, 0xfffffc00, v3
	v_sub_u32_e32 v3, v2, v3
	v_lshrrev_b32_e32 v4, 4, v3
	v_bitop3_b32 v3, v4, v3, 32 bitop3:0x6c
	v_ashrrev_i32_e32 v5, 31, v3
	v_lshrrev_b32_e32 v5, 26, v5
	v_add_u32_e32 v5, v3, v5
	v_lshlrev_b32_e32 v4, 3, v11
	v_ashrrev_i32_e32 v12, 6, v5
	v_and_b32_e32 v5, 0xc0, v5
	v_and_b32_e32 v4, -16, v4
	v_sub_u32_e32 v3, v3, v5
	v_mov_b32_e32 v5, 1
	v_add_u32_e32 v4, v12, v4
	v_ashrrev_i16_sdwa v3, v5, sext(v3) dst_sel:DWORD dst_unused:UNUSED_PAD src0_sel:DWORD src1_sel:BYTE_0
	v_lshlrev_b32_e32 v6, 5, v11
	v_bfe_i32 v13, v3, 0, 16
	v_lshlrev_b32_e32 v3, 1, v4
	v_lshrrev_b32_e32 v7, 2, v4
	v_and_b32_e32 v8, 3, v12
	s_mov_b32 s9, 0x1fffe0
	v_and_b32_e32 v6, 32, v6
	v_and_b32_e32 v3, 24, v3
	v_and_b32_e32 v7, 4, v7
	v_and_or_b32 v8, v4, s9, v8
	v_or3_b32 v3, v8, v7, v3
	v_add_lshl_u32 v6, v6, v13, 1
	v_add_u32_e32 v2, 0x2000, v2
	v_lshl_add_u32 v132, v3, 11, v6
	v_ashrrev_i32_e32 v3, 31, v2
	v_lshrrev_b32_e32 v3, 22, v3
	v_add_u32_e32 v3, v2, v3
	v_ashrrev_i32_e32 v14, 10, v3
	v_mul_i32_i24_e32 v3, 0x400, v14
	v_sub_u32_e32 v2, v2, v3
	v_lshrrev_b32_e32 v3, 4, v2
	v_bitop3_b32 v2, v3, v2, 32 bitop3:0x6c
	v_lshl_add_u32 v130, v4, 11, v6
	v_ashrrev_i32_e32 v4, 31, v2
	v_lshrrev_b32_e32 v4, 26, v4
	v_add_u32_e32 v4, v2, v4
	s_waitcnt lgkmcnt(0)
	s_add_u32 s3, s24, 0x6400000
	v_lshlrev_b32_e32 v3, 3, v14
	v_ashrrev_i32_e32 v15, 6, v4
	v_and_b32_e32 v4, 0xc0, v4
	s_addc_u32 s23, s25, 0
	v_and_b32_e32 v3, -16, v3
	v_sub_u32_e32 v2, v2, v4
	s_add_u32 s29, s42, 0x4e00000
	v_add_u32_e32 v3, v15, v3
	v_ashrrev_i16_sdwa v2, v5, sext(v2) dst_sel:DWORD dst_unused:UNUSED_PAD src0_sel:DWORD src1_sel:BYTE_0
	v_and_b32_e32 v5, 3, v15
	s_addc_u32 s31, s43, 0
	s_ashr_i32 s42, s46, 6
	v_and_or_b32 v5, v3, s9, v5
	s_ashr_i32 s11, s10, 31
	s_ashr_i32 s9, s8, 31
	s_ashr_i32 s44, s46, 8
	s_lshl_b32 s62, s42, 10
	s_lshl_b64 s[14:15], s[10:11], 19
	s_lshl_b64 s[16:17], s[8:9], 19
	s_add_u32 s58, s29, s16
	v_lshlrev_b32_e32 v6, 5, v14
	v_bfe_i32 v16, v2, 0, 16
	v_lshlrev_b32_e32 v2, 1, v3
	v_lshrrev_b32_e32 v4, 2, v3
	s_addc_u32 s59, s31, s17
	s_add_i32 s63, s62, 0
	v_and_b32_e32 v6, 32, v6
	v_and_b32_e32 v2, 24, v2
	v_and_b32_e32 v4, 4, v4
	s_add_i32 m0, s63, 0x10000
	v_or3_b32 v2, v5, v4, v2
	v_add_lshl_u32 v4, v6, v16, 1
	global_load_lds_dwordx4 v132, s[58:59]
	s_add_i32 m0, s63, 0x12000
	v_lshl_add_u32 v136, v2, 11, v4
	s_add_u32 s16, s58, 0x40000
	global_load_lds_dwordx4 v136, s[58:59]
	s_addc_u32 s17, s59, 0
	s_add_i32 m0, s63, 0x14000
	v_lshl_add_u32 v134, v3, 11, v4
	global_load_lds_dwordx4 v132, s[16:17]
	s_add_i32 m0, s63, 0x16000
	s_add_u32 s56, s3, s14
	s_addc_u32 s57, s23, s15
	s_add_i32 s64, s63, 0x2000
	global_load_lds_dwordx4 v136, s[16:17]
	s_mov_b32 m0, s63
	s_add_u32 s14, s56, 0x40000
	global_load_lds_dwordx4 v130, s[56:57]
	s_mov_b32 m0, s64
	s_addc_u32 s15, s57, 0
	s_add_i32 s65, s63, 0x4000
	global_load_lds_dwordx4 v134, s[56:57]
	s_mov_b32 m0, s65
	s_add_i32 s66, s63, 0x6000
	global_load_lds_dwordx4 v130, s[14:15]
	s_mov_b32 m0, s66
	v_mov_b32_e32 v133, 0
	global_load_lds_dwordx4 v134, s[14:15]
	v_mov_b32_e32 v137, v133
	v_mov_b32_e32 v131, v133
	v_mov_b32_e32 v135, v133
	s_cmp_eq_u32 s44, 1
	s_mov_b32 s67, 0
	v_lshl_add_u64 v[8:9], s[58:59], 0, v[132:133]
	v_lshl_add_u64 v[6:7], s[58:59], 0, v[136:137]
	v_lshl_add_u64 v[2:3], s[56:57], 0, v[130:131]
	s_cselect_b64 s[14:15], -1, 0
	s_cmp_lg_u32 s44, 1
	v_lshl_add_u64 v[4:5], s[56:57], 0, v[134:135]
	s_cbranch_scc1 .LBB0_1040
.LBB0_1040:
	s_add_u32 s16, s4, 0x60000
	s_addc_u32 s17, s5, 0
	s_add_u32 s24, s6, 0x80000
	s_addc_u32 s25, s7, 0
	s_add_u32 s26, s26, 0x200000
	s_addc_u32 s27, s27, 0
	s_and_b32 s9, s42, 3
	s_mov_b64 s[42:43], 0x80
	s_add_i32 m0, s63, 0x18000
	v_lshl_add_u64 v[8:9], v[8:9], 0, s[42:43]
	s_lshl_b32 s6, s44, 13
	s_lshl_b32 s7, s9, 12
	s_waitcnt vmcnt(2)
	s_barrier
	global_load_lds_dwordx4 v[8:9], off
	v_lshl_add_u64 v[6:7], v[6:7], 0, s[42:43]
	s_add_i32 m0, s63, 0x1a000
	s_add_i32 s68, s63, 0x8000
	s_add_i32 s69, s63, 0xa000
	global_load_lds_dwordx4 v[6:7], off
	v_lshl_add_u64 v[2:3], v[2:3], 0, s[42:43]
	s_mov_b32 m0, s68
	s_add_u32 s4, s58, 0x40080
	global_load_lds_dwordx4 v[2:3], off
	v_lshl_add_u64 v[2:3], v[4:5], 0, s[42:43]
	s_mov_b32 m0, s69
	s_addc_u32 s5, s59, 0
	global_load_lds_dwordx4 v[2:3], off
	s_add_i32 m0, s63, 0x1c000
	v_lshl_add_u64 v[2:3], s[4:5], 0, v[132:133]
	global_load_lds_dwordx4 v[2:3], off
	v_lshl_add_u64 v[2:3], s[4:5], 0, v[136:137]
	s_add_i32 m0, s63, 0x1e000
	v_bfe_u32 v4, v10, 4, 2
	global_load_lds_dwordx4 v[2:3], off
	v_and_b32_e32 v3, 15, v10
	v_lshlrev_b32_e32 v2, 4, v4
	v_lshlrev_b32_e32 v5, 2, v10
	v_lshl_or_b32 v153, s44, 6, v3
	v_lshl_or_b32 v3, v3, 6, v2
	v_and_b32_e32 v5, 32, v5
	v_bitop3_b32 v6, v3, s6, v5 bitop3:0xde
	v_bitop3_b32 v155, v3, s7, v5 bitop3:0xde
	v_mov_b32_e32 v3, v133
	v_lshlrev_b32_e32 v154, 3, v4
	v_cmp_eq_u32_e64 s[4:5], 0, v4
	v_lshl_add_u64 v[4:5], s[50:51], 0, v[2:3]
	s_mov_b64 s[6:7], 0x1f400000
	v_lshl_or_b32 v2, s9, 6, v2
	v_lshl_add_u64 v[138:139], v[4:5], 0, s[6:7]
	v_lshl_add_u64 v[2:3], s[48:49], 0, v[2:3]
	s_mov_b64 s[6:7], 0x1e400000
	v_lshl_add_u64 v[140:141], v[2:3], 0, s[6:7]
	v_lshlrev_b32_e32 v2, 14, v11
	v_and_b32_e32 v2, 0xffff8000, v2
	v_lshl_add_u32 v2, v12, 11, v2
	v_and_b32_e32 v3, 1, v11
	v_lshl_or_b32 v2, v3, 6, v2
	v_lshl_add_u32 v142, v13, 1, v2
	v_lshlrev_b32_e32 v2, 14, v14
	v_and_b32_e32 v2, 0xffff8000, v2
	s_cmpk_lt_u32 s46, 0x100
	v_lshl_add_u32 v2, v15, 11, v2
	v_and_b32_e32 v3, 1, v14
	s_waitcnt vmcnt(6)
	s_cselect_b64 s[44:45], -1, 0
	s_cmp_eq_u32 s9, 0
	v_lshl_or_b32 v2, v3, 6, v2
	s_cselect_b64 s[46:47], -1, 0
	v_lshl_add_u32 v144, v16, 1, v2
	s_add_i32 s73, 0, 0x10000
	s_add_i32 s74, 0, 0x14000
	v_mbcnt_lo_u32_b32 v2, -1, 0
	s_ashr_i32 s70, s38, 31
	s_mov_b32 s71, s38
	s_ashr_i32 s72, s2, 31
	v_mov_b32_e32 v143, v133
	v_mov_b32_e32 v145, v133
	v_mov_b64_e32 v[146:147], 0x100
	v_mov_b64_e32 v[148:149], 0xff
	v_add_u32_e32 v156, s73, v155
	v_add_u32_e32 v157, s74, v155
	v_add_u32_e32 v158, 0, v6
	v_mov_b32_e32 v159, 0x358637bd
	s_mov_b32 s75, 0xf9e0
	s_mov_b32 s76, 0xfbe0
	s_mov_b32 s77, 0xfde0
	s_mov_b32 s78, 0xffe0
	v_mbcnt_hi_u32_b32 v160, -1, v2
	s_barrier
	s_branch .LBB0_1043

.LBB0_1049:
	s_ashr_i32 s51, s50, 31
	s_lshl_b64 s[52:53], s[50:51], 19
	s_add_u32 s52, s3, s52
	s_addc_u32 s53, s23, s53
	s_and_b64 s[54:55], s[6:7], exec
	s_cselect_b32 s9, s53, s57
	s_cselect_b32 s11, s52, s56
	s_ashr_i32 s49, s48, 31
	s_lshl_b64 s[54:55], s[48:49], 19
	s_add_u32 s54, s29, s54
	s_addc_u32 s55, s31, s55
	s_and_b64 s[60:61], s[6:7], exec
	s_cselect_b32 s49, s55, s59
	s_cselect_b32 s51, s54, s58
	s_add_u32 s56, s56, 0x40080
	s_addc_u32 s57, s57, 0
	s_add_u32 s79, s58, 0x100
	v_mov_b32_e32 v2, 0
	s_addc_u32 s80, s59, 0
	s_mov_b32 s81, -2
	s_waitcnt lgkmcnt(0)
	v_mov_b32_e32 v3, v2
	v_mov_b32_e32 v4, v2
	v_mov_b32_e32 v5, v2
	v_mov_b32_e32 v6, v2
	v_mov_b32_e32 v7, v2
	v_mov_b32_e32 v8, v2
	v_mov_b32_e32 v9, v2
	v_mov_b32_e32 v18, v2
	v_mov_b32_e32 v19, v2
	v_mov_b32_e32 v20, v2
	v_mov_b32_e32 v21, v2
	v_mov_b32_e32 v22, v2
	v_mov_b32_e32 v23, v2
	v_mov_b32_e32 v24, v2
	v_mov_b32_e32 v25, v2
	v_mov_b32_e32 v34, v2
	v_mov_b32_e32 v35, v2
	v_mov_b32_e32 v36, v2
	v_mov_b32_e32 v37, v2
	v_mov_b32_e32 v38, v2
	v_mov_b32_e32 v39, v2
	v_mov_b32_e32 v40, v2
	v_mov_b32_e32 v41, v2
	v_mov_b32_e32 v50, v2
	v_mov_b32_e32 v51, v2
	v_mov_b32_e32 v52, v2
	v_mov_b32_e32 v53, v2
	v_mov_b32_e32 v54, v2
	v_mov_b32_e32 v55, v2
	v_mov_b32_e32 v56, v2
	v_mov_b32_e32 v57, v2
	v_mov_b32_e32 v10, v2
	v_mov_b32_e32 v11, v2
	v_mov_b32_e32 v12, v2
	v_mov_b32_e32 v13, v2
	v_mov_b32_e32 v14, v2
	v_mov_b32_e32 v15, v2
	v_mov_b32_e32 v16, v2
	v_mov_b32_e32 v17, v2
	v_mov_b32_e32 v26, v2
	v_mov_b32_e32 v27, v2
	v_mov_b32_e32 v28, v2
	v_mov_b32_e32 v29, v2
	v_mov_b32_e32 v30, v2
	v_mov_b32_e32 v31, v2
	v_mov_b32_e32 v32, v2
	v_mov_b32_e32 v33, v2
	v_mov_b32_e32 v42, v2
	v_mov_b32_e32 v43, v2
	v_mov_b32_e32 v44, v2
	v_mov_b32_e32 v45, v2
	v_mov_b32_e32 v46, v2
	v_mov_b32_e32 v47, v2
	v_mov_b32_e32 v48, v2
	v_mov_b32_e32 v49, v2
	v_mov_b32_e32 v58, v2
	v_mov_b32_e32 v59, v2
	v_mov_b32_e32 v60, v2
	v_mov_b32_e32 v61, v2
	v_mov_b32_e32 v62, v2
	v_mov_b32_e32 v63, v2
	v_mov_b32_e32 v64, v2
	v_mov_b32_e32 v65, v2
	v_mov_b32_e32 v66, v2
	v_mov_b32_e32 v67, v2
	v_mov_b32_e32 v68, v2
	v_mov_b32_e32 v69, v2
	v_mov_b32_e32 v70, v2
	v_mov_b32_e32 v71, v2
	v_mov_b32_e32 v72, v2
	v_mov_b32_e32 v73, v2
	s_waitcnt vmcnt(0)
	v_mov_b32_e32 v82, v2
	v_mov_b32_e32 v83, v2
	v_mov_b32_e32 v84, v2
	v_mov_b32_e32 v85, v2
	v_mov_b32_e32 v86, v2
	v_mov_b32_e32 v87, v2
	v_mov_b32_e32 v88, v2
	v_mov_b32_e32 v89, v2
	v_mov_b32_e32 v98, v2
	v_mov_b32_e32 v99, v2
	v_mov_b32_e32 v100, v2
	v_mov_b32_e32 v101, v2
	v_mov_b32_e32 v102, v2
	v_mov_b32_e32 v103, v2
	v_mov_b32_e32 v104, v2
	v_mov_b32_e32 v105, v2
	v_mov_b32_e32 v114, v2
	v_mov_b32_e32 v115, v2
	v_mov_b32_e32 v116, v2
	v_mov_b32_e32 v117, v2
	v_mov_b32_e32 v118, v2
	v_mov_b32_e32 v119, v2
	v_mov_b32_e32 v120, v2
	v_mov_b32_e32 v121, v2
	v_mov_b32_e32 v74, v2
	v_mov_b32_e32 v75, v2
	v_mov_b32_e32 v76, v2
	v_mov_b32_e32 v77, v2
	v_mov_b32_e32 v78, v2
	v_mov_b32_e32 v79, v2
	v_mov_b32_e32 v80, v2
	v_mov_b32_e32 v81, v2
	v_mov_b32_e32 v90, v2
	v_mov_b32_e32 v91, v2
	v_mov_b32_e32 v92, v2
	v_mov_b32_e32 v93, v2
	v_mov_b32_e32 v94, v2
	v_mov_b32_e32 v95, v2
	v_mov_b32_e32 v96, v2
	v_mov_b32_e32 v97, v2
	v_mov_b32_e32 v106, v2
	v_mov_b32_e32 v107, v2
	v_mov_b32_e32 v108, v2
	v_mov_b32_e32 v109, v2
	v_mov_b32_e32 v110, v2
	v_mov_b32_e32 v111, v2
	v_mov_b32_e32 v112, v2
	v_mov_b32_e32 v113, v2
	v_mov_b32_e32 v122, v2
	v_mov_b32_e32 v123, v2
	v_mov_b32_e32 v124, v2
	v_mov_b32_e32 v125, v2
	v_mov_b32_e32 v126, v2
	v_mov_b32_e32 v127, v2
	v_mov_b32_e32 v128, v2
	v_mov_b32_e32 v129, v2
	s_cmp_eq_u64 s[44:45], 0
	s_cbranch_scc1 .Lhb_B_p8a
.LBB0_1050:
	ds_read_b128 v[162:165], v156
	ds_read_b128 v[166:169], v156 offset:1024
	ds_read_b128 v[170:173], v156 offset:2048
	ds_read_b128 v[174:177], v156 offset:3072
	ds_read_b128 v[178:181], v157
	ds_read_b128 v[182:185], v157 offset:1024
	ds_read_b128 v[186:189], v157 offset:2048
	ds_read_b128 v[190:193], v157 offset:3072
	s_add_u32 s58, s56, 0xfffc0080
	s_addc_u32 s59, s57, -1
	s_cmp_eq_u32 s81, 12
	s_cselect_b32 s61, s9, s59
	s_cselect_b32 s60, s11, s58
	s_cselect_b32 s59, s49, s80
	s_cselect_b32 s58, s51, s79
	v_lshl_add_u64 v[150:151], s[56:57], 0, v[142:143]
	s_add_i32 m0, s63, 0xc000
	ds_read_b128 v[194:197], v158
	ds_read_b128 v[198:201], v158 offset:1024
	ds_read_b128 v[202:205], v158 offset:2048
	ds_read_b128 v[206:209], v158 offset:3072
	ds_read_b128 v[210:213], v158 offset:4096
	ds_read_b128 v[214:217], v158 offset:5120
	ds_read_b128 v[218:221], v158 offset:6144
	ds_read_b128 v[222:225], v158 offset:7168
	global_load_lds_dwordx4 v[150:151], off
	v_lshl_add_u64 v[150:151], s[56:57], 0, v[144:145]
	s_add_i32 m0, s63, 0xe000
	s_nop 0
	global_load_lds_dwordx4 v[150:151], off
	s_waitcnt vmcnt(8)
	s_waitcnt lgkmcnt(0)
	s_setprio 1
	v_mfma_f32_16x16x32_bf16 v[126:129], v[162:165], v[194:197], v[126:129]
	v_mfma_f32_16x16x32_bf16 v[122:125], v[170:173], v[194:197], v[122:125]
	v_mfma_f32_16x16x32_bf16 v[110:113], v[162:165], v[202:205], v[110:113]
	v_mfma_f32_16x16x32_bf16 v[106:109], v[170:173], v[202:205], v[106:109]
	v_mfma_f32_16x16x32_bf16 v[94:97], v[162:165], v[210:213], v[94:97]
	v_mfma_f32_16x16x32_bf16 v[90:93], v[170:173], v[210:213], v[90:93]
	v_mfma_f32_16x16x32_bf16 v[78:81], v[162:165], v[218:221], v[78:81]
	v_mfma_f32_16x16x32_bf16 v[74:77], v[170:173], v[218:221], v[74:77]
	v_mfma_f32_16x16x32_bf16 v[126:129], v[166:169], v[198:201], v[126:129]
	v_mfma_f32_16x16x32_bf16 v[122:125], v[174:177], v[198:201], v[122:125]
	v_mfma_f32_16x16x32_bf16 v[110:113], v[166:169], v[206:209], v[110:113]
	v_mfma_f32_16x16x32_bf16 v[106:109], v[174:177], v[206:209], v[106:109]
	v_mfma_f32_16x16x32_bf16 v[94:97], v[166:169], v[214:217], v[94:97]
	v_mfma_f32_16x16x32_bf16 v[90:93], v[174:177], v[214:217], v[90:93]
	v_mfma_f32_16x16x32_bf16 v[78:81], v[166:169], v[222:225], v[78:81]
	v_mfma_f32_16x16x32_bf16 v[74:77], v[174:177], v[222:225], v[74:77]
	s_setprio 0
	s_setprio 1
	v_mfma_f32_16x16x32_bf16 v[118:121], v[178:181], v[194:197], v[118:121]
	v_mfma_f32_16x16x32_bf16 v[114:117], v[186:189], v[194:197], v[114:117]
	v_mfma_f32_16x16x32_bf16 v[102:105], v[178:181], v[202:205], v[102:105]
	v_mfma_f32_16x16x32_bf16 v[98:101], v[186:189], v[202:205], v[98:101]
	v_mfma_f32_16x16x32_bf16 v[86:89], v[178:181], v[210:213], v[86:89]
	v_mfma_f32_16x16x32_bf16 v[82:85], v[186:189], v[210:213], v[82:85]
	v_mfma_f32_16x16x32_bf16 v[70:73], v[178:181], v[218:221], v[70:73]
	v_mfma_f32_16x16x32_bf16 v[66:69], v[186:189], v[218:221], v[66:69]
	v_mfma_f32_16x16x32_bf16 v[118:121], v[182:185], v[198:201], v[118:121]
	v_mfma_f32_16x16x32_bf16 v[114:117], v[190:193], v[198:201], v[114:117]
	v_mfma_f32_16x16x32_bf16 v[102:105], v[182:185], v[206:209], v[102:105]
	v_mfma_f32_16x16x32_bf16 v[98:101], v[190:193], v[206:209], v[98:101]
	v_mfma_f32_16x16x32_bf16 v[86:89], v[182:185], v[214:217], v[86:89]
	v_mfma_f32_16x16x32_bf16 v[82:85], v[190:193], v[214:217], v[82:85]
	v_mfma_f32_16x16x32_bf16 v[70:73], v[182:185], v[222:225], v[70:73]
	v_mfma_f32_16x16x32_bf16 v[66:69], v[190:193], v[222:225], v[66:69]
	s_setprio 0
	s_barrier
	s_add_i32 s82, s73, s62
	v_lshl_add_u64 v[150:151], s[58:59], 0, v[132:133]
	s_mov_b32 m0, s82
	ds_read_b128 v[194:197], v158 offset:16384
	ds_read_b128 v[198:201], v158 offset:17408
	ds_read_b128 v[202:205], v158 offset:18432
	ds_read_b128 v[206:209], v158 offset:19456
	ds_read_b128 v[210:213], v158 offset:20480
	ds_read_b128 v[214:217], v158 offset:21504
	ds_read_b128 v[218:221], v158 offset:22528
	ds_read_b128 v[222:225], v158 offset:23552
	global_load_lds_dwordx4 v[150:151], off
	s_add_i32 m0, s82, 0x2000
	s_add_u32 s82, s58, 0x40000
	v_lshl_add_u64 v[226:227], s[58:59], 0, v[136:137]
	s_addc_u32 s83, s59, 0
	s_add_i32 s84, s74, s62
	global_load_lds_dwordx4 v[226:227], off
	v_lshl_add_u64 v[228:229], s[82:83], 0, v[132:133]
	s_mov_b32 m0, s84
	v_lshl_add_u64 v[230:231], s[60:61], 0, v[134:135]
	global_load_lds_dwordx4 v[228:229], off
	v_lshl_add_u64 v[228:229], s[82:83], 0, v[136:137]
	s_add_i32 m0, s84, 0x2000
	s_nop 0
	global_load_lds_dwordx4 v[228:229], off
	v_lshl_add_u64 v[228:229], s[60:61], 0, v[130:131]
	s_mov_b32 m0, s63
	s_nop 0
	global_load_lds_dwordx4 v[228:229], off
	s_mov_b32 m0, s64
	s_nop 0
	global_load_lds_dwordx4 v[230:231], off
	s_waitcnt vmcnt(8)
	s_waitcnt lgkmcnt(0)
	s_setprio 1
	v_mfma_f32_16x16x32_bf16 v[62:65], v[162:165], v[194:197], v[62:65]
	v_mfma_f32_16x16x32_bf16 v[58:61], v[170:173], v[194:197], v[58:61]
	v_mfma_f32_16x16x32_bf16 v[46:49], v[162:165], v[202:205], v[46:49]
	v_mfma_f32_16x16x32_bf16 v[42:45], v[170:173], v[202:205], v[42:45]
	v_mfma_f32_16x16x32_bf16 v[30:33], v[162:165], v[210:213], v[30:33]
	v_mfma_f32_16x16x32_bf16 v[26:29], v[170:173], v[210:213], v[26:29]
	v_mfma_f32_16x16x32_bf16 v[14:17], v[162:165], v[218:221], v[14:17]
	v_mfma_f32_16x16x32_bf16 v[10:13], v[170:173], v[218:221], v[10:13]
	v_mfma_f32_16x16x32_bf16 v[62:65], v[166:169], v[198:201], v[62:65]
	v_mfma_f32_16x16x32_bf16 v[58:61], v[174:177], v[198:201], v[58:61]
	v_mfma_f32_16x16x32_bf16 v[46:49], v[166:169], v[206:209], v[46:49]
	v_mfma_f32_16x16x32_bf16 v[42:45], v[174:177], v[206:209], v[42:45]
	v_mfma_f32_16x16x32_bf16 v[30:33], v[166:169], v[214:217], v[30:33]
	v_mfma_f32_16x16x32_bf16 v[26:29], v[174:177], v[214:217], v[26:29]
	v_mfma_f32_16x16x32_bf16 v[14:17], v[166:169], v[222:225], v[14:17]
	v_mfma_f32_16x16x32_bf16 v[10:13], v[174:177], v[222:225], v[10:13]
	s_setprio 0
	s_setprio 1
	v_mfma_f32_16x16x32_bf16 v[54:57], v[178:181], v[194:197], v[54:57]
	v_mfma_f32_16x16x32_bf16 v[50:53], v[186:189], v[194:197], v[50:53]
	v_mfma_f32_16x16x32_bf16 v[38:41], v[178:181], v[202:205], v[38:41]
	v_mfma_f32_16x16x32_bf16 v[34:37], v[186:189], v[202:205], v[34:37]
	v_mfma_f32_16x16x32_bf16 v[22:25], v[178:181], v[210:213], v[22:25]
	v_mfma_f32_16x16x32_bf16 v[18:21], v[186:189], v[210:213], v[18:21]
	v_mfma_f32_16x16x32_bf16 v[6:9], v[178:181], v[218:221], v[6:9]
	v_mfma_f32_16x16x32_bf16 v[2:5], v[186:189], v[218:221], v[2:5]
	v_mfma_f32_16x16x32_bf16 v[54:57], v[182:185], v[198:201], v[54:57]
	v_mfma_f32_16x16x32_bf16 v[50:53], v[190:193], v[198:201], v[50:53]
	v_mfma_f32_16x16x32_bf16 v[38:41], v[182:185], v[206:209], v[38:41]
	v_mfma_f32_16x16x32_bf16 v[34:37], v[190:193], v[206:209], v[34:37]
	v_mfma_f32_16x16x32_bf16 v[22:25], v[182:185], v[214:217], v[22:25]
	v_mfma_f32_16x16x32_bf16 v[18:21], v[190:193], v[214:217], v[18:21]
	v_mfma_f32_16x16x32_bf16 v[6:9], v[182:185], v[222:225], v[6:9]
	v_mfma_f32_16x16x32_bf16 v[2:5], v[190:193], v[222:225], v[2:5]
	s_setprio 0
	s_barrier
	s_add_i32 s82, 0, 0x18000
	v_add_u32_e32 v152, s82, v155
	s_add_i32 s83, 0, 0x1c000
	ds_read_b128 v[162:165], v152
	ds_read_b128 v[166:169], v152 offset:1024
	ds_read_b128 v[170:173], v152 offset:2048
	ds_read_b128 v[174:177], v152 offset:3072
	v_add_u32_e32 v152, s83, v155
	ds_read_b128 v[178:181], v152
	ds_read_b128 v[182:185], v152 offset:1024
	ds_read_b128 v[186:189], v152 offset:2048
	ds_read_b128 v[190:193], v152 offset:3072
	s_add_u32 s60, s60, 0x40000
	s_addc_u32 s61, s61, 0
	s_mov_b32 m0, s65
	v_lshl_add_u64 v[232:233], s[60:61], 0, v[130:131]
	ds_read_b128 v[194:197], v158 offset:32768
	ds_read_b128 v[198:201], v158 offset:33792
	ds_read_b128 v[202:205], v158 offset:34816
	ds_read_b128 v[206:209], v158 offset:35840
	ds_read_b128 v[210:213], v158 offset:36864
	ds_read_b128 v[214:217], v158 offset:37888
	ds_read_b128 v[218:221], v158 offset:38912
	ds_read_b128 v[222:225], v158 offset:39936
	global_load_lds_dwordx4 v[232:233], off
	v_lshl_add_u64 v[232:233], s[60:61], 0, v[134:135]
	s_mov_b32 m0, s66
	s_nop 0
	global_load_lds_dwordx4 v[232:233], off
	s_waitcnt vmcnt(8)
	s_waitcnt lgkmcnt(0)
	s_setprio 1
	v_mfma_f32_16x16x32_bf16 v[126:129], v[162:165], v[194:197], v[126:129]
	v_mfma_f32_16x16x32_bf16 v[122:125], v[170:173], v[194:197], v[122:125]
	v_mfma_f32_16x16x32_bf16 v[110:113], v[162:165], v[202:205], v[110:113]
	v_mfma_f32_16x16x32_bf16 v[106:109], v[170:173], v[202:205], v[106:109]
	v_mfma_f32_16x16x32_bf16 v[94:97], v[162:165], v[210:213], v[94:97]
	v_mfma_f32_16x16x32_bf16 v[90:93], v[170:173], v[210:213], v[90:93]
	v_mfma_f32_16x16x32_bf16 v[78:81], v[162:165], v[218:221], v[78:81]
	v_mfma_f32_16x16x32_bf16 v[74:77], v[170:173], v[218:221], v[74:77]
	v_mfma_f32_16x16x32_bf16 v[126:129], v[166:169], v[198:201], v[126:129]
	v_mfma_f32_16x16x32_bf16 v[122:125], v[174:177], v[198:201], v[122:125]
	v_mfma_f32_16x16x32_bf16 v[110:113], v[166:169], v[206:209], v[110:113]
	v_mfma_f32_16x16x32_bf16 v[106:109], v[174:177], v[206:209], v[106:109]
	v_mfma_f32_16x16x32_bf16 v[94:97], v[166:169], v[214:217], v[94:97]
	v_mfma_f32_16x16x32_bf16 v[90:93], v[174:177], v[214:217], v[90:93]
	v_mfma_f32_16x16x32_bf16 v[78:81], v[166:169], v[222:225], v[78:81]
	v_mfma_f32_16x16x32_bf16 v[74:77], v[174:177], v[222:225], v[74:77]
	s_setprio 0
	s_setprio 1
	v_mfma_f32_16x16x32_bf16 v[118:121], v[178:181], v[194:197], v[118:121]
	v_mfma_f32_16x16x32_bf16 v[114:117], v[186:189], v[194:197], v[114:117]
	v_mfma_f32_16x16x32_bf16 v[102:105], v[178:181], v[202:205], v[102:105]
	v_mfma_f32_16x16x32_bf16 v[98:101], v[186:189], v[202:205], v[98:101]
	v_mfma_f32_16x16x32_bf16 v[86:89], v[178:181], v[210:213], v[86:89]
	v_mfma_f32_16x16x32_bf16 v[82:85], v[186:189], v[210:213], v[82:85]
	v_mfma_f32_16x16x32_bf16 v[70:73], v[178:181], v[218:221], v[70:73]
	v_mfma_f32_16x16x32_bf16 v[66:69], v[186:189], v[218:221], v[66:69]
	v_mfma_f32_16x16x32_bf16 v[118:121], v[182:185], v[198:201], v[118:121]
	v_mfma_f32_16x16x32_bf16 v[114:117], v[190:193], v[198:201], v[114:117]
	v_mfma_f32_16x16x32_bf16 v[102:105], v[182:185], v[206:209], v[102:105]
	v_mfma_f32_16x16x32_bf16 v[98:101], v[190:193], v[206:209], v[98:101]
	v_mfma_f32_16x16x32_bf16 v[86:89], v[182:185], v[214:217], v[86:89]
	v_mfma_f32_16x16x32_bf16 v[82:85], v[190:193], v[214:217], v[82:85]
	v_mfma_f32_16x16x32_bf16 v[70:73], v[182:185], v[222:225], v[70:73]
	v_mfma_f32_16x16x32_bf16 v[66:69], v[190:193], v[222:225], v[66:69]
	s_setprio 0
	s_barrier
	s_add_i32 s60, s82, s62
	v_lshl_add_u64 v[150:151], v[150:151], 0, s[42:43]
	s_mov_b32 m0, s60
	ds_read_b128 v[194:197], v158 offset:49152
	ds_read_b128 v[198:201], v158 offset:50176
	ds_read_b128 v[202:205], v158 offset:51200
	ds_read_b128 v[206:209], v158 offset:52224
	ds_read_b128 v[210:213], v158 offset:53248
	ds_read_b128 v[214:217], v158 offset:54272
	ds_read_b128 v[218:221], v158 offset:55296
	ds_read_b128 v[222:225], v158 offset:56320
	global_load_lds_dwordx4 v[150:151], off
	s_add_i32 m0, s60, 0x2000
	s_add_u32 s58, s58, 0x40080
	v_lshl_add_u64 v[150:151], v[226:227], 0, s[42:43]
	s_addc_u32 s59, s59, 0
	s_add_i32 s60, s83, s62
	global_load_lds_dwordx4 v[150:151], off
	v_lshl_add_u64 v[150:151], s[58:59], 0, v[132:133]
	s_mov_b32 m0, s60
	s_nop 0
	global_load_lds_dwordx4 v[150:151], off
	v_lshl_add_u64 v[150:151], s[58:59], 0, v[136:137]
	s_add_i32 m0, s60, 0x2000
	s_nop 0
	global_load_lds_dwordx4 v[150:151], off
	v_lshl_add_u64 v[150:151], v[228:229], 0, s[42:43]
	s_mov_b32 m0, s68
	s_nop 0
	global_load_lds_dwordx4 v[150:151], off
	v_lshl_add_u64 v[150:151], v[230:231], 0, s[42:43]
	s_mov_b32 m0, s69
	s_nop 0
	global_load_lds_dwordx4 v[150:151], off
	s_waitcnt vmcnt(8)
	s_waitcnt lgkmcnt(0)
	s_setprio 1
	v_mfma_f32_16x16x32_bf16 v[62:65], v[162:165], v[194:197], v[62:65]
	v_mfma_f32_16x16x32_bf16 v[58:61], v[170:173], v[194:197], v[58:61]
	v_mfma_f32_16x16x32_bf16 v[46:49], v[162:165], v[202:205], v[46:49]
	v_mfma_f32_16x16x32_bf16 v[42:45], v[170:173], v[202:205], v[42:45]
	v_mfma_f32_16x16x32_bf16 v[30:33], v[162:165], v[210:213], v[30:33]
	v_mfma_f32_16x16x32_bf16 v[26:29], v[170:173], v[210:213], v[26:29]
	v_mfma_f32_16x16x32_bf16 v[14:17], v[162:165], v[218:221], v[14:17]
	v_mfma_f32_16x16x32_bf16 v[10:13], v[170:173], v[218:221], v[10:13]
	v_mfma_f32_16x16x32_bf16 v[62:65], v[166:169], v[198:201], v[62:65]
	v_mfma_f32_16x16x32_bf16 v[58:61], v[174:177], v[198:201], v[58:61]
	v_mfma_f32_16x16x32_bf16 v[46:49], v[166:169], v[206:209], v[46:49]
	v_mfma_f32_16x16x32_bf16 v[42:45], v[174:177], v[206:209], v[42:45]
	v_mfma_f32_16x16x32_bf16 v[30:33], v[166:169], v[214:217], v[30:33]
	v_mfma_f32_16x16x32_bf16 v[26:29], v[174:177], v[214:217], v[26:29]
	v_mfma_f32_16x16x32_bf16 v[14:17], v[166:169], v[222:225], v[14:17]
	v_mfma_f32_16x16x32_bf16 v[10:13], v[174:177], v[222:225], v[10:13]
	s_setprio 0
	s_setprio 1
	v_mfma_f32_16x16x32_bf16 v[54:57], v[178:181], v[194:197], v[54:57]
	v_mfma_f32_16x16x32_bf16 v[50:53], v[186:189], v[194:197], v[50:53]
	v_mfma_f32_16x16x32_bf16 v[38:41], v[178:181], v[202:205], v[38:41]
	v_mfma_f32_16x16x32_bf16 v[34:37], v[186:189], v[202:205], v[34:37]
	v_mfma_f32_16x16x32_bf16 v[22:25], v[178:181], v[210:213], v[22:25]
	v_mfma_f32_16x16x32_bf16 v[18:21], v[186:189], v[210:213], v[18:21]
	v_mfma_f32_16x16x32_bf16 v[6:9], v[178:181], v[218:221], v[6:9]
	v_mfma_f32_16x16x32_bf16 v[2:5], v[186:189], v[218:221], v[2:5]
	v_mfma_f32_16x16x32_bf16 v[54:57], v[182:185], v[198:201], v[54:57]
	v_mfma_f32_16x16x32_bf16 v[50:53], v[190:193], v[198:201], v[50:53]
	v_mfma_f32_16x16x32_bf16 v[38:41], v[182:185], v[206:209], v[38:41]
	v_mfma_f32_16x16x32_bf16 v[34:37], v[190:193], v[206:209], v[34:37]
	v_mfma_f32_16x16x32_bf16 v[22:25], v[182:185], v[214:217], v[22:25]
	v_mfma_f32_16x16x32_bf16 v[18:21], v[190:193], v[214:217], v[18:21]
	v_mfma_f32_16x16x32_bf16 v[6:9], v[182:185], v[222:225], v[6:9]
	v_mfma_f32_16x16x32_bf16 v[2:5], v[190:193], v[222:225], v[2:5]
	s_setprio 0
	s_barrier
	s_add_i32 s81, s81, 2
	s_add_u32 s56, s56, 0x100
	s_addc_u32 s57, s57, 0
	s_add_u32 s79, s79, 0x100
	s_addc_u32 s80, s80, 0
	s_cmp_gt_u32 s81, 13
	s_cbranch_scc0 .LBB0_1050
	s_branch .Lhb_exit_p8a
.Lhb_B_p8a:
	ds_read_b128 v[162:165], v156
	ds_read_b128 v[166:169], v156 offset:1024
	ds_read_b128 v[170:173], v156 offset:2048
	ds_read_b128 v[174:177], v156 offset:3072
	ds_read_b128 v[178:181], v157
	ds_read_b128 v[182:185], v157 offset:1024
	ds_read_b128 v[186:189], v157 offset:2048
	ds_read_b128 v[190:193], v157 offset:3072
	s_add_u32 s58, s56, 0xfffc0080
	s_addc_u32 s59, s57, -1
	s_cmp_eq_u32 s81, 12
	s_cselect_b32 s61, s9, s59
	s_cselect_b32 s60, s11, s58
	s_cselect_b32 s59, s49, s80
	s_cselect_b32 s58, s51, s79
	v_lshl_add_u64 v[150:151], s[56:57], 0, v[142:143]
	s_add_i32 m0, s63, 0xc000
	ds_read_b128 v[194:197], v158
	ds_read_b128 v[198:201], v158 offset:1024
	ds_read_b128 v[202:205], v158 offset:2048
	ds_read_b128 v[206:209], v158 offset:3072
	ds_read_b128 v[210:213], v158 offset:4096
	ds_read_b128 v[214:217], v158 offset:5120
	ds_read_b128 v[218:221], v158 offset:6144
	ds_read_b128 v[222:225], v158 offset:7168
	global_load_lds_dwordx4 v[150:151], off
	v_lshl_add_u64 v[150:151], s[56:57], 0, v[144:145]
	s_add_i32 m0, s63, 0xe000
	s_nop 0
	global_load_lds_dwordx4 v[150:151], off
	s_waitcnt vmcnt(8)
	s_waitcnt lgkmcnt(0)
	s_setprio 1
	s_barrier
	v_mfma_f32_16x16x32_bf16 v[126:129], v[162:165], v[194:197], v[126:129]
	v_mfma_f32_16x16x32_bf16 v[122:125], v[170:173], v[194:197], v[122:125]
	v_mfma_f32_16x16x32_bf16 v[110:113], v[162:165], v[202:205], v[110:113]
	v_mfma_f32_16x16x32_bf16 v[106:109], v[170:173], v[202:205], v[106:109]
	v_mfma_f32_16x16x32_bf16 v[94:97], v[162:165], v[210:213], v[94:97]
	v_mfma_f32_16x16x32_bf16 v[90:93], v[170:173], v[210:213], v[90:93]
	v_mfma_f32_16x16x32_bf16 v[78:81], v[162:165], v[218:221], v[78:81]
	v_mfma_f32_16x16x32_bf16 v[74:77], v[170:173], v[218:221], v[74:77]
	v_mfma_f32_16x16x32_bf16 v[126:129], v[166:169], v[198:201], v[126:129]
	v_mfma_f32_16x16x32_bf16 v[122:125], v[174:177], v[198:201], v[122:125]
	v_mfma_f32_16x16x32_bf16 v[110:113], v[166:169], v[206:209], v[110:113]
	v_mfma_f32_16x16x32_bf16 v[106:109], v[174:177], v[206:209], v[106:109]
	v_mfma_f32_16x16x32_bf16 v[94:97], v[166:169], v[214:217], v[94:97]
	v_mfma_f32_16x16x32_bf16 v[90:93], v[174:177], v[214:217], v[90:93]
	v_mfma_f32_16x16x32_bf16 v[78:81], v[166:169], v[222:225], v[78:81]
	v_mfma_f32_16x16x32_bf16 v[74:77], v[174:177], v[222:225], v[74:77]
	s_setprio 0
	s_setprio 1
	v_mfma_f32_16x16x32_bf16 v[118:121], v[178:181], v[194:197], v[118:121]
	v_mfma_f32_16x16x32_bf16 v[114:117], v[186:189], v[194:197], v[114:117]
	v_mfma_f32_16x16x32_bf16 v[102:105], v[178:181], v[202:205], v[102:105]
	v_mfma_f32_16x16x32_bf16 v[98:101], v[186:189], v[202:205], v[98:101]
	v_mfma_f32_16x16x32_bf16 v[86:89], v[178:181], v[210:213], v[86:89]
	v_mfma_f32_16x16x32_bf16 v[82:85], v[186:189], v[210:213], v[82:85]
	v_mfma_f32_16x16x32_bf16 v[70:73], v[178:181], v[218:221], v[70:73]
	v_mfma_f32_16x16x32_bf16 v[66:69], v[186:189], v[218:221], v[66:69]
	v_mfma_f32_16x16x32_bf16 v[118:121], v[182:185], v[198:201], v[118:121]
	v_mfma_f32_16x16x32_bf16 v[114:117], v[190:193], v[198:201], v[114:117]
	v_mfma_f32_16x16x32_bf16 v[102:105], v[182:185], v[206:209], v[102:105]
	v_mfma_f32_16x16x32_bf16 v[98:101], v[190:193], v[206:209], v[98:101]
	v_mfma_f32_16x16x32_bf16 v[86:89], v[182:185], v[214:217], v[86:89]
	v_mfma_f32_16x16x32_bf16 v[82:85], v[190:193], v[214:217], v[82:85]
	v_mfma_f32_16x16x32_bf16 v[70:73], v[182:185], v[222:225], v[70:73]
	v_mfma_f32_16x16x32_bf16 v[66:69], v[190:193], v[222:225], v[66:69]
	s_setprio 0
	s_add_i32 s82, s73, s62
	v_lshl_add_u64 v[150:151], s[58:59], 0, v[132:133]
	s_mov_b32 m0, s82
	ds_read_b128 v[194:197], v158 offset:16384
	ds_read_b128 v[198:201], v158 offset:17408
	ds_read_b128 v[202:205], v158 offset:18432
	ds_read_b128 v[206:209], v158 offset:19456
	ds_read_b128 v[210:213], v158 offset:20480
	ds_read_b128 v[214:217], v158 offset:21504
	ds_read_b128 v[218:221], v158 offset:22528
	ds_read_b128 v[222:225], v158 offset:23552
	global_load_lds_dwordx4 v[150:151], off
	s_add_i32 m0, s82, 0x2000
	s_add_u32 s82, s58, 0x40000
	v_lshl_add_u64 v[226:227], s[58:59], 0, v[136:137]
	s_addc_u32 s83, s59, 0
	s_add_i32 s84, s74, s62
	global_load_lds_dwordx4 v[226:227], off
	v_lshl_add_u64 v[228:229], s[82:83], 0, v[132:133]
	s_mov_b32 m0, s84
	v_lshl_add_u64 v[230:231], s[60:61], 0, v[134:135]
	global_load_lds_dwordx4 v[228:229], off
	v_lshl_add_u64 v[228:229], s[82:83], 0, v[136:137]
	s_add_i32 m0, s84, 0x2000
	s_nop 0
	global_load_lds_dwordx4 v[228:229], off
	v_lshl_add_u64 v[228:229], s[60:61], 0, v[130:131]
	s_mov_b32 m0, s63
	s_nop 0
	global_load_lds_dwordx4 v[228:229], off
	s_mov_b32 m0, s64
	s_nop 0
	global_load_lds_dwordx4 v[230:231], off
	s_waitcnt vmcnt(8)
	s_waitcnt lgkmcnt(0)
	s_setprio 1
	s_barrier
	v_mfma_f32_16x16x32_bf16 v[62:65], v[162:165], v[194:197], v[62:65]
	v_mfma_f32_16x16x32_bf16 v[58:61], v[170:173], v[194:197], v[58:61]
	v_mfma_f32_16x16x32_bf16 v[46:49], v[162:165], v[202:205], v[46:49]
	v_mfma_f32_16x16x32_bf16 v[42:45], v[170:173], v[202:205], v[42:45]
	v_mfma_f32_16x16x32_bf16 v[30:33], v[162:165], v[210:213], v[30:33]
	v_mfma_f32_16x16x32_bf16 v[26:29], v[170:173], v[210:213], v[26:29]
	v_mfma_f32_16x16x32_bf16 v[14:17], v[162:165], v[218:221], v[14:17]
	v_mfma_f32_16x16x32_bf16 v[10:13], v[170:173], v[218:221], v[10:13]
	v_mfma_f32_16x16x32_bf16 v[62:65], v[166:169], v[198:201], v[62:65]
	v_mfma_f32_16x16x32_bf16 v[58:61], v[174:177], v[198:201], v[58:61]
	v_mfma_f32_16x16x32_bf16 v[46:49], v[166:169], v[206:209], v[46:49]
	v_mfma_f32_16x16x32_bf16 v[42:45], v[174:177], v[206:209], v[42:45]
	v_mfma_f32_16x16x32_bf16 v[30:33], v[166:169], v[214:217], v[30:33]
	v_mfma_f32_16x16x32_bf16 v[26:29], v[174:177], v[214:217], v[26:29]
	v_mfma_f32_16x16x32_bf16 v[14:17], v[166:169], v[222:225], v[14:17]
	v_mfma_f32_16x16x32_bf16 v[10:13], v[174:177], v[222:225], v[10:13]
	s_setprio 0
	s_setprio 1
	v_mfma_f32_16x16x32_bf16 v[54:57], v[178:181], v[194:197], v[54:57]
	v_mfma_f32_16x16x32_bf16 v[50:53], v[186:189], v[194:197], v[50:53]
	v_mfma_f32_16x16x32_bf16 v[38:41], v[178:181], v[202:205], v[38:41]
	v_mfma_f32_16x16x32_bf16 v[34:37], v[186:189], v[202:205], v[34:37]
	v_mfma_f32_16x16x32_bf16 v[22:25], v[178:181], v[210:213], v[22:25]
	v_mfma_f32_16x16x32_bf16 v[18:21], v[186:189], v[210:213], v[18:21]
	v_mfma_f32_16x16x32_bf16 v[6:9], v[178:181], v[218:221], v[6:9]
	v_mfma_f32_16x16x32_bf16 v[2:5], v[186:189], v[218:221], v[2:5]
	v_mfma_f32_16x16x32_bf16 v[54:57], v[182:185], v[198:201], v[54:57]
	v_mfma_f32_16x16x32_bf16 v[50:53], v[190:193], v[198:201], v[50:53]
	v_mfma_f32_16x16x32_bf16 v[38:41], v[182:185], v[206:209], v[38:41]
	v_mfma_f32_16x16x32_bf16 v[34:37], v[190:193], v[206:209], v[34:37]
	v_mfma_f32_16x16x32_bf16 v[22:25], v[182:185], v[214:217], v[22:25]
	v_mfma_f32_16x16x32_bf16 v[18:21], v[190:193], v[214:217], v[18:21]
	v_mfma_f32_16x16x32_bf16 v[6:9], v[182:185], v[222:225], v[6:9]
	v_mfma_f32_16x16x32_bf16 v[2:5], v[190:193], v[222:225], v[2:5]
	s_setprio 0
	s_add_i32 s82, 0, 0x18000
	v_add_u32_e32 v152, s82, v155
	s_add_i32 s83, 0, 0x1c000
	ds_read_b128 v[162:165], v152
	ds_read_b128 v[166:169], v152 offset:1024
	ds_read_b128 v[170:173], v152 offset:2048
	ds_read_b128 v[174:177], v152 offset:3072
	v_add_u32_e32 v152, s83, v155
	ds_read_b128 v[178:181], v152
	ds_read_b128 v[182:185], v152 offset:1024
	ds_read_b128 v[186:189], v152 offset:2048
	ds_read_b128 v[190:193], v152 offset:3072
	s_add_u32 s60, s60, 0x40000
	s_addc_u32 s61, s61, 0
	s_mov_b32 m0, s65
	v_lshl_add_u64 v[232:233], s[60:61], 0, v[130:131]
	ds_read_b128 v[194:197], v158 offset:32768
	ds_read_b128 v[198:201], v158 offset:33792
	ds_read_b128 v[202:205], v158 offset:34816
	ds_read_b128 v[206:209], v158 offset:35840
	ds_read_b128 v[210:213], v158 offset:36864
	ds_read_b128 v[214:217], v158 offset:37888
	ds_read_b128 v[218:221], v158 offset:38912
	ds_read_b128 v[222:225], v158 offset:39936
	global_load_lds_dwordx4 v[232:233], off
	v_lshl_add_u64 v[232:233], s[60:61], 0, v[134:135]
	s_mov_b32 m0, s66
	s_nop 0
	global_load_lds_dwordx4 v[232:233], off
	s_waitcnt vmcnt(8)
	s_waitcnt lgkmcnt(0)
	s_setprio 1
	s_barrier
	v_mfma_f32_16x16x32_bf16 v[126:129], v[162:165], v[194:197], v[126:129]
	v_mfma_f32_16x16x32_bf16 v[122:125], v[170:173], v[194:197], v[122:125]
	v_mfma_f32_16x16x32_bf16 v[110:113], v[162:165], v[202:205], v[110:113]
	v_mfma_f32_16x16x32_bf16 v[106:109], v[170:173], v[202:205], v[106:109]
	v_mfma_f32_16x16x32_bf16 v[94:97], v[162:165], v[210:213], v[94:97]
	v_mfma_f32_16x16x32_bf16 v[90:93], v[170:173], v[210:213], v[90:93]
	v_mfma_f32_16x16x32_bf16 v[78:81], v[162:165], v[218:221], v[78:81]
	v_mfma_f32_16x16x32_bf16 v[74:77], v[170:173], v[218:221], v[74:77]
	v_mfma_f32_16x16x32_bf16 v[126:129], v[166:169], v[198:201], v[126:129]
	v_mfma_f32_16x16x32_bf16 v[122:125], v[174:177], v[198:201], v[122:125]
	v_mfma_f32_16x16x32_bf16 v[110:113], v[166:169], v[206:209], v[110:113]
	v_mfma_f32_16x16x32_bf16 v[106:109], v[174:177], v[206:209], v[106:109]
	v_mfma_f32_16x16x32_bf16 v[94:97], v[166:169], v[214:217], v[94:97]
	v_mfma_f32_16x16x32_bf16 v[90:93], v[174:177], v[214:217], v[90:93]
	v_mfma_f32_16x16x32_bf16 v[78:81], v[166:169], v[222:225], v[78:81]
	v_mfma_f32_16x16x32_bf16 v[74:77], v[174:177], v[222:225], v[74:77]
	s_setprio 0
	s_setprio 1
	v_mfma_f32_16x16x32_bf16 v[118:121], v[178:181], v[194:197], v[118:121]
	v_mfma_f32_16x16x32_bf16 v[114:117], v[186:189], v[194:197], v[114:117]
	v_mfma_f32_16x16x32_bf16 v[102:105], v[178:181], v[202:205], v[102:105]
	v_mfma_f32_16x16x32_bf16 v[98:101], v[186:189], v[202:205], v[98:101]
	v_mfma_f32_16x16x32_bf16 v[86:89], v[178:181], v[210:213], v[86:89]
	v_mfma_f32_16x16x32_bf16 v[82:85], v[186:189], v[210:213], v[82:85]
	v_mfma_f32_16x16x32_bf16 v[70:73], v[178:181], v[218:221], v[70:73]
	v_mfma_f32_16x16x32_bf16 v[66:69], v[186:189], v[218:221], v[66:69]
	v_mfma_f32_16x16x32_bf16 v[118:121], v[182:185], v[198:201], v[118:121]
	v_mfma_f32_16x16x32_bf16 v[114:117], v[190:193], v[198:201], v[114:117]
	v_mfma_f32_16x16x32_bf16 v[102:105], v[182:185], v[206:209], v[102:105]
	v_mfma_f32_16x16x32_bf16 v[98:101], v[190:193], v[206:209], v[98:101]
	v_mfma_f32_16x16x32_bf16 v[86:89], v[182:185], v[214:217], v[86:89]
	v_mfma_f32_16x16x32_bf16 v[82:85], v[190:193], v[214:217], v[82:85]
	v_mfma_f32_16x16x32_bf16 v[70:73], v[182:185], v[222:225], v[70:73]
	v_mfma_f32_16x16x32_bf16 v[66:69], v[190:193], v[222:225], v[66:69]
	s_setprio 0
	s_add_i32 s60, s82, s62
	v_lshl_add_u64 v[150:151], v[150:151], 0, s[42:43]
	s_mov_b32 m0, s60
	ds_read_b128 v[194:197], v158 offset:49152
	ds_read_b128 v[198:201], v158 offset:50176
	ds_read_b128 v[202:205], v158 offset:51200
	ds_read_b128 v[206:209], v158 offset:52224
	ds_read_b128 v[210:213], v158 offset:53248
	ds_read_b128 v[214:217], v158 offset:54272
	ds_read_b128 v[218:221], v158 offset:55296
	ds_read_b128 v[222:225], v158 offset:56320
	global_load_lds_dwordx4 v[150:151], off
	s_add_i32 m0, s60, 0x2000
	s_add_u32 s58, s58, 0x40080
	v_lshl_add_u64 v[150:151], v[226:227], 0, s[42:43]
	s_addc_u32 s59, s59, 0
	s_add_i32 s60, s83, s62
	global_load_lds_dwordx4 v[150:151], off
	v_lshl_add_u64 v[150:151], s[58:59], 0, v[132:133]
	s_mov_b32 m0, s60
	s_nop 0
	global_load_lds_dwordx4 v[150:151], off
	v_lshl_add_u64 v[150:151], s[58:59], 0, v[136:137]
	s_add_i32 m0, s60, 0x2000
	s_nop 0
	global_load_lds_dwordx4 v[150:151], off
	v_lshl_add_u64 v[150:151], v[228:229], 0, s[42:43]
	s_mov_b32 m0, s68
	s_nop 0
	global_load_lds_dwordx4 v[150:151], off
	v_lshl_add_u64 v[150:151], v[230:231], 0, s[42:43]
	s_mov_b32 m0, s69
	s_nop 0
	global_load_lds_dwordx4 v[150:151], off
	s_waitcnt vmcnt(8)
	s_waitcnt lgkmcnt(0)
	s_setprio 1
	s_barrier
	v_mfma_f32_16x16x32_bf16 v[62:65], v[162:165], v[194:197], v[62:65]
	v_mfma_f32_16x16x32_bf16 v[58:61], v[170:173], v[194:197], v[58:61]
	v_mfma_f32_16x16x32_bf16 v[46:49], v[162:165], v[202:205], v[46:49]
	v_mfma_f32_16x16x32_bf16 v[42:45], v[170:173], v[202:205], v[42:45]
	v_mfma_f32_16x16x32_bf16 v[30:33], v[162:165], v[210:213], v[30:33]
	v_mfma_f32_16x16x32_bf16 v[26:29], v[170:173], v[210:213], v[26:29]
	v_mfma_f32_16x16x32_bf16 v[14:17], v[162:165], v[218:221], v[14:17]
	v_mfma_f32_16x16x32_bf16 v[10:13], v[170:173], v[218:221], v[10:13]
	v_mfma_f32_16x16x32_bf16 v[62:65], v[166:169], v[198:201], v[62:65]
	v_mfma_f32_16x16x32_bf16 v[58:61], v[174:177], v[198:201], v[58:61]
	v_mfma_f32_16x16x32_bf16 v[46:49], v[166:169], v[206:209], v[46:49]
	v_mfma_f32_16x16x32_bf16 v[42:45], v[174:177], v[206:209], v[42:45]
	v_mfma_f32_16x16x32_bf16 v[30:33], v[166:169], v[214:217], v[30:33]
	v_mfma_f32_16x16x32_bf16 v[26:29], v[174:177], v[214:217], v[26:29]
	v_mfma_f32_16x16x32_bf16 v[14:17], v[166:169], v[222:225], v[14:17]
	v_mfma_f32_16x16x32_bf16 v[10:13], v[174:177], v[222:225], v[10:13]
	s_setprio 0
	s_setprio 1
	v_mfma_f32_16x16x32_bf16 v[54:57], v[178:181], v[194:197], v[54:57]
	v_mfma_f32_16x16x32_bf16 v[50:53], v[186:189], v[194:197], v[50:53]
	v_mfma_f32_16x16x32_bf16 v[38:41], v[178:181], v[202:205], v[38:41]
	v_mfma_f32_16x16x32_bf16 v[34:37], v[186:189], v[202:205], v[34:37]
	v_mfma_f32_16x16x32_bf16 v[22:25], v[178:181], v[210:213], v[22:25]
	v_mfma_f32_16x16x32_bf16 v[18:21], v[186:189], v[210:213], v[18:21]
	v_mfma_f32_16x16x32_bf16 v[6:9], v[178:181], v[218:221], v[6:9]
	v_mfma_f32_16x16x32_bf16 v[2:5], v[186:189], v[218:221], v[2:5]
	v_mfma_f32_16x16x32_bf16 v[54:57], v[182:185], v[198:201], v[54:57]
	v_mfma_f32_16x16x32_bf16 v[50:53], v[190:193], v[198:201], v[50:53]
	v_mfma_f32_16x16x32_bf16 v[38:41], v[182:185], v[206:209], v[38:41]
	v_mfma_f32_16x16x32_bf16 v[34:37], v[190:193], v[206:209], v[34:37]
	v_mfma_f32_16x16x32_bf16 v[22:25], v[182:185], v[214:217], v[22:25]
	v_mfma_f32_16x16x32_bf16 v[18:21], v[190:193], v[214:217], v[18:21]
	v_mfma_f32_16x16x32_bf16 v[6:9], v[182:185], v[222:225], v[6:9]
	v_mfma_f32_16x16x32_bf16 v[2:5], v[190:193], v[222:225], v[2:5]
	s_setprio 0
	s_add_i32 s81, s81, 2
	s_add_u32 s56, s56, 0x100
	s_addc_u32 s57, s57, 0
	s_add_u32 s79, s79, 0x100
	s_addc_u32 s80, s80, 0
	s_cmp_gt_u32 s81, 13
	s_cbranch_scc0 .Lhb_B_p8a
.Lhb_exit_p8a:
	s_and_b64 vcc, exec, s[44:45]
	s_cbranch_vccz .LBB0_1053

.LBB0_1118:
	s_andn2_b64 vcc, exec, s[14:15]
	s_cbranch_vccnz .LBB0_1041
	s_branch .LBB0_1041

.LBB0_1121:
	s_waitcnt lgkmcnt(0)
	s_mov_b64 s[4:5], s[0:1]
	s_mov_b64 s[6:7], s[0:1]
	s_mov_b64 s[8:9], s[0:1]
	s_mov_b64 s[10:11], s[0:1]
	v_mov_b32_e32 v10, v1
	s_cmpk_gt_i32 s2, 0xaff
	v_readfirstlane_b32 s17, v10
	s_cbranch_scc1 .LBB0_1137
	v_lshlrev_b32_e32 v2, 4, v10
	v_add_u32_e32 v3, 0x2000, v2
	v_ashrrev_i32_e32 v4, 31, v3
	v_lshrrev_b32_e32 v4, 22, v4
	v_add_u32_e32 v4, v3, v4
	v_ashrrev_i32_e32 v11, 10, v4
	v_mul_i32_i24_e32 v4, 0x400, v11
	v_sub_u32_e32 v3, v3, v4
	v_lshrrev_b32_e32 v4, 4, v3
	v_bitop3_b32 v3, v4, v3, 32 bitop3:0x6c
	v_ashrrev_i32_e32 v4, 31, v3
	v_lshrrev_b32_e32 v4, 26, v4
	v_add_u32_e32 v4, v3, v4
	v_lshlrev_b32_e32 v5, 3, v11
	v_ashrrev_i32_e32 v12, 6, v4
	v_and_b32_e32 v5, -16, v5
	v_add_u32_e32 v5, v12, v5
	s_load_dwordx2 s[14:15], s[8:9], 0xa8
	s_load_dwordx2 s[24:25], s[10:11], 0xa8
	v_and_b32_e32 v6, 3, v12
	s_mov_b32 s8, 0x1fffe0
	v_lshrrev_b32_e32 v7, 2, v5
	v_lshlrev_b32_e32 v8, 1, v5
	v_and_b32_e32 v4, 0xc0, v4
	v_and_or_b32 v6, v5, s8, v6
	v_and_b32_e32 v7, 4, v7
	v_and_b32_e32 v8, 24, v8
	v_sub_u32_e32 v3, v3, v4
	v_mov_b32_e32 v4, 1
	v_or3_b32 v6, v6, v7, v8
	v_lshlrev_b32_e32 v7, 5, v11
	v_ashrrev_i16_sdwa v3, v4, sext(v3) dst_sel:DWORD dst_unused:UNUSED_PAD src0_sel:DWORD src1_sel:BYTE_0
	v_and_b32_e32 v7, 32, v7
	v_bfe_i32 v13, v3, 0, 16
	v_add_lshl_u32 v3, v7, v13, 1
	v_lshl_add_u32 v130, v6, 11, v3
	v_lshl_add_u32 v132, v5, 11, v3
	v_bfe_i32 v3, v10, 27, 1
	v_lshrrev_b32_e32 v3, 22, v3
	v_add_u32_e32 v3, v2, v3
	v_and_b32_e32 v3, 0xfffffc00, v3
	v_sub_u32_e32 v2, v2, v3
	v_lshrrev_b32_e32 v3, 4, v2
	v_ashrrev_i32_e32 v5, 31, v10
	v_bitop3_b32 v2, v3, v2, 32 bitop3:0x6c
	v_lshrrev_b32_e32 v5, 26, v5
	v_ashrrev_i32_e32 v3, 31, v2
	v_add_u32_e32 v5, v10, v5
	s_waitcnt lgkmcnt(0)
	s_add_u32 s3, s14, 0x6400000
	v_lshrrev_b32_e32 v3, 26, v3
	v_ashrrev_i32_e32 v15, 6, v5
	s_addc_u32 s23, s15, 0
	v_add_u32_e32 v3, v2, v3
	v_lshlrev_b32_e32 v5, 3, v15
	s_add_u32 s29, s24, 0x1a00000
	v_ashrrev_i32_e32 v14, 6, v3
	v_and_b32_e32 v5, -16, v5
	s_addc_u32 s31, s25, 0
	v_add_u32_e32 v5, v14, v5
	v_and_b32_e32 v6, 3, v14
	s_ashr_i32 s55, s2, 31
	v_and_or_b32 v6, v5, s8, v6
	s_lshr_b32 s8, s55, 29
	s_add_i32 s8, s2, s8
	s_ashr_i32 s14, s17, 6
	s_ashr_i32 s9, s8, 3
	s_and_b32 s8, s8, -8
	s_ashr_i32 s24, s17, 8
	s_lshl_b32 s54, s14, 10
	s_sub_i32 s8, s2, s8
	s_cmp_lt_i32 s8, 0
	s_movk_i32 s56, 0x161
	s_cselect_b32 s10, s56, 0x160
	s_mul_i32 s8, s8, s10
	s_add_i32 s8, s8, s9
	s_mul_hi_i32 s9, s8, 0x2e8ba2e9
	s_lshr_b32 s10, s9, 31
	s_ashr_i32 s9, s9, 5
	s_add_i32 s9, s9, s10
	s_lshl_b32 s10, s9, 3
	s_mulk_i32 s9, 0xb0
	s_sub_i32 s8, s8, s9
	s_sext_i32_i16 s9, s8
	s_bfe_u32 s9, s9, 0x3001c
	s_add_i32 s9, s8, s9
	s_sext_i32_i16 s11, s9
	s_and_b32 s9, s9, 0xfff8
	s_sub_i32 s8, s8, s9
	s_sext_i32_i16 s8, s8
	v_lshrrev_b32_e32 v7, 2, v5
	v_lshlrev_b32_e32 v8, 1, v5
	v_and_b32_e32 v3, 0xc0, v3
	s_lshr_b32 s16, s11, 3
	s_add_i32 s46, s10, s8
	v_and_b32_e32 v7, 4, v7
	v_and_b32_e32 v8, 24, v8
	v_sub_u32_e32 v2, v2, v3
	s_ashr_i32 s47, s46, 31
	s_bfe_i64 s[10:11], s[16:17], 0x100000
	v_or3_b32 v6, v6, v7, v8
	v_lshlrev_b32_e32 v7, 5, v15
	v_ashrrev_i16_sdwa v2, v4, sext(v2) dst_sel:DWORD dst_unused:UNUSED_PAD src0_sel:DWORD src1_sel:BYTE_0
	s_lshl_b64 s[8:9], s[46:47], 19
	s_lshl_b64 s[10:11], s[10:11], 19
	v_and_b32_e32 v7, 32, v7
	v_bfe_i32 v16, v2, 0, 16
	s_add_u32 s50, s29, s10
	v_add_lshl_u32 v2, v7, v16, 1
	s_addc_u32 s51, s31, s11
	s_add_i32 s57, s54, 0
	v_lshl_add_u32 v134, v6, 11, v2
	s_add_i32 m0, s57, 0x10000
	v_lshl_add_u32 v136, v5, 11, v2
	global_load_lds_dwordx4 v134, s[50:51]
	s_add_i32 m0, s57, 0x12000
	s_add_u32 s10, s50, 0x40000
	global_load_lds_dwordx4 v130, s[50:51]
	s_addc_u32 s11, s51, 0
	s_add_i32 m0, s57, 0x14000
	v_mov_b32_e32 v139, 0
	global_load_lds_dwordx4 v134, s[10:11]
	s_add_i32 m0, s57, 0x16000
	s_add_u32 s48, s3, s8
	s_addc_u32 s49, s23, s9
	s_add_i32 s58, s57, 0x2000
	global_load_lds_dwordx4 v130, s[10:11]
	s_mov_b32 m0, s57
	s_add_u32 s8, s48, 0x40000
	global_load_lds_dwordx4 v136, s[48:49]
	s_mov_b32 m0, s58
	s_addc_u32 s9, s49, 0
	s_add_i32 s59, s57, 0x4000
	global_load_lds_dwordx4 v132, s[48:49]
	s_mov_b32 m0, s59
	s_add_i32 s60, s57, 0x6000
	global_load_lds_dwordx4 v136, s[8:9]
	s_mov_b32 m0, s60
	v_mov_b32_e32 v135, v139
	global_load_lds_dwordx4 v132, s[8:9]
	s_load_dwordx2 s[8:9], s[4:5], 0xa8
	s_nop 0
	s_load_dwordx2 s[4:5], s[6:7], 0xa8
	v_mov_b32_e32 v131, v139
	v_mov_b32_e32 v137, v139
	v_mov_b32_e32 v133, v139
	s_cmp_eq_u32 s24, 1
	s_mov_b32 s61, 0
	v_lshl_add_u64 v[8:9], s[50:51], 0, v[134:135]
	v_lshl_add_u64 v[6:7], s[50:51], 0, v[130:131]
	v_lshl_add_u64 v[2:3], s[48:49], 0, v[136:137]
	s_cselect_b64 s[6:7], -1, 0
	s_cmp_lg_u32 s24, 1
	v_lshl_add_u64 v[4:5], s[48:49], 0, v[132:133]
	s_cbranch_scc1 .LBB0_1124
.LBB0_1124:
	s_waitcnt lgkmcnt(0)
	s_add_u32 s8, s8, 0x60000
	s_addc_u32 s9, s9, 0
	s_add_u32 s10, s4, 0xa400000
	s_addc_u32 s11, s5, 0
	s_lshl_b32 s4, s14, 5
	s_mov_b64 s[14:15], 0x80
	s_and_b32 s26, s4, 0x60
	s_add_i32 m0, s57, 0x18000
	v_lshl_add_u64 v[8:9], v[8:9], 0, s[14:15]
	s_lshl_b32 s25, s24, 13
	s_lshl_b32 s27, s26, 7
	s_waitcnt vmcnt(2)
	s_barrier
	global_load_lds_dwordx4 v[8:9], off
	v_lshl_add_u64 v[6:7], v[6:7], 0, s[14:15]
	s_add_i32 m0, s57, 0x1a000
	s_add_i32 s62, s57, 0x8000
	s_add_i32 s63, s57, 0xa000
	global_load_lds_dwordx4 v[6:7], off
	v_lshl_add_u64 v[2:3], v[2:3], 0, s[14:15]
	s_mov_b32 m0, s62
	s_add_u32 s4, s50, 0x40080
	global_load_lds_dwordx4 v[2:3], off
	v_lshl_add_u64 v[2:3], v[4:5], 0, s[14:15]
	s_mov_b32 m0, s63
	s_addc_u32 s5, s51, 0
	global_load_lds_dwordx4 v[2:3], off
	s_add_i32 m0, s57, 0x1c000
	v_lshl_add_u64 v[2:3], s[4:5], 0, v[134:135]
	global_load_lds_dwordx4 v[2:3], off
	v_lshl_add_u64 v[2:3], s[4:5], 0, v[130:131]
	s_add_i32 m0, s57, 0x1e000
	s_cmpk_lt_u32 s17, 0x100
	global_load_lds_dwordx4 v[2:3], off
	v_lshrrev_b32_e32 v3, 1, v10
	v_and_b32_e32 v3, 24, v3
	v_and_b32_e32 v2, 15, v10
	v_lshlrev_b32_e32 v4, 1, v3
	v_lshl_or_b32 v150, s24, 6, v2
	v_lshl_or_b32 v2, v2, 6, v4
	v_lshlrev_b32_e32 v4, 2, v10
	v_and_b32_e32 v4, 32, v4
	v_bitop3_b32 v5, v2, s25, v4 bitop3:0xde
	v_bitop3_b32 v151, v2, s27, v4 bitop3:0xde
	v_or_b32_e32 v2, s26, v3
	v_lshlrev_b32_e32 v3, 14, v15
	v_and_b32_e32 v3, 0xffff8000, v3
	v_lshl_add_u32 v3, v14, 11, v3
	v_and_b32_e32 v4, 1, v15
	v_lshl_or_b32 v3, v4, 6, v3
	v_lshl_add_u32 v140, v16, 1, v3
	v_lshlrev_b32_e32 v3, 14, v11
	v_and_b32_e32 v3, 0xffff8000, v3
	s_waitcnt vmcnt(6)
	v_lshl_add_u32 v3, v12, 11, v3
	v_and_b32_e32 v4, 1, v11
	s_sext_i32_i16 s47, s16
	s_cselect_b64 s[16:17], -1, 0
	v_lshl_or_b32 v3, v4, 6, v3
	s_add_i32 s66, 0, 0x10000
	s_add_i32 s67, 0, 0x14000
	v_or_b32_e32 v152, 16, v150
	v_or_b32_e32 v153, 32, v150
	v_or_b32_e32 v154, 48, v150
	s_ashr_i32 s64, s38, 31
	s_mov_b32 s65, s38
	v_mov_b32_e32 v141, v139
	v_lshl_add_u32 v142, v13, 1, v3
	v_mov_b32_e32 v143, v139
	v_mov_b64_e32 v[144:145], 0xb00
	v_mov_b64_e32 v[146:147], 0xaff
	v_add_u32_e32 v155, s66, v151
	v_add_u32_e32 v156, s67, v151
	v_add_u32_e32 v157, 0, v5
	v_mov_b32_e32 v158, 0x358637bd
	s_movk_i32 s68, 0x1600
	v_lshlrev_b32_e32 v138, 1, v2
	s_barrier
	s_branch .LBB0_1127

.LBB0_1236:
	s_andn2_b64 vcc, exec, s[14:15]
	s_cbranch_vccnz .LBB0_1276
	v_ashrrev_i32_e32 v3, 31, v10
	v_lshrrev_b32_e32 v3, 26, v3
	v_add_u32_e32 v3, v10, v3
	v_ashrrev_i32_e32 v11, 6, v3
	v_bfe_i32 v3, v10, 27, 1
	v_lshlrev_b32_e32 v2, 4, v10
	v_lshrrev_b32_e32 v3, 22, v3
	v_add_u32_e32 v3, v2, v3
	v_and_b32_e32 v3, 0xfffffc00, v3
	v_sub_u32_e32 v3, v2, v3
	v_lshrrev_b32_e32 v4, 4, v3
	v_bitop3_b32 v3, v4, v3, 32 bitop3:0x6c
	v_ashrrev_i32_e32 v5, 31, v3
	v_lshrrev_b32_e32 v5, 26, v5
	v_lshlrev_b32_e32 v4, 3, v11
	v_add_u32_e32 v5, v3, v5
	s_waitcnt lgkmcnt(0)
	s_add_u32 s3, s8, 0xa400000
	v_and_b32_e32 v4, -16, v4
	v_ashrrev_i32_e32 v13, 6, v5
	v_and_b32_e32 v5, 0xc0, v5
	s_addc_u32 s23, s9, 0
	v_add_u32_e32 v4, v13, v4
	v_lshlrev_b32_e32 v6, 5, v11
	v_sub_u32_e32 v3, v3, v5
	v_mov_b32_e32 v5, 1
	s_add_u32 s29, s12, 0x3b00000
	v_and_b32_e32 v12, 32, v6
	v_ashrrev_i16_sdwa v3, v5, sext(v3) dst_sel:DWORD dst_unused:UNUSED_PAD src0_sel:DWORD src1_sel:BYTE_0
	v_lshlrev_b32_e32 v6, 1, v4
	v_lshrrev_b32_e32 v7, 2, v4
	v_and_b32_e32 v8, 3, v13
	s_mov_b32 s12, 0xffffe0
	v_bfe_i32 v14, v3, 0, 16
	v_and_b32_e32 v6, 24, v6
	v_and_b32_e32 v7, 4, v7
	v_and_or_b32 v8, v4, s12, v8
	s_movk_i32 s9, 0xb00
	v_add_u32_e32 v3, v12, v14
	v_or3_b32 v6, v8, v7, v6
	v_mul_lo_u32 v4, v4, s9
	v_add_lshl_u32 v194, v3, v4, 1
	v_mul_u32_u24_e32 v4, 0xb00, v6
	v_add_u32_e32 v2, 0x2000, v2
	v_add_lshl_u32 v196, v4, v3, 1
	v_ashrrev_i32_e32 v3, 31, v2
	v_lshrrev_b32_e32 v3, 22, v3
	v_add_u32_e32 v3, v2, v3
	v_ashrrev_i32_e32 v15, 10, v3
	v_mul_i32_i24_e32 v3, 0x400, v15
	v_sub_u32_e32 v2, v2, v3
	v_lshrrev_b32_e32 v3, 4, v2
	v_bitop3_b32 v2, v3, v2, 32 bitop3:0x6c
	v_ashrrev_i32_e32 v4, 31, v2
	v_lshrrev_b32_e32 v4, 26, v4
	v_lshlrev_b32_e32 v3, 3, v15
	v_add_u32_e32 v4, v2, v4
	s_addc_u32 s31, s13, 0
	v_and_b32_e32 v3, -16, v3
	v_ashrrev_i32_e32 v16, 6, v4
	v_lshlrev_b32_e32 v6, 5, v15
	v_and_b32_e32 v4, 0xc0, v4
	s_ashr_i32 s24, s26, 6
	s_ashr_i32 s8, s26, 8
	v_add_u32_e32 v3, v16, v3
	v_and_b32_e32 v17, 32, v6
	v_sub_u32_e32 v2, v2, v4
	v_and_b32_e32 v6, 3, v16
	s_lshl_b32 s52, s24, 10
	s_mul_i32 s13, s68, 0x160000
	v_ashrrev_i16_sdwa v2, v5, sext(v2) dst_sel:DWORD dst_unused:UNUSED_PAD src0_sel:DWORD src1_sel:BYTE_0
	v_lshlrev_b32_e32 v4, 1, v3
	v_lshrrev_b32_e32 v5, 2, v3
	v_and_or_b32 v6, v3, s12, v6
	s_mul_hi_i32 s12, s68, 0x160000
	s_add_u32 s46, s29, s13
	v_bfe_i32 v18, v2, 0, 16
	v_and_b32_e32 v4, 24, v4
	v_and_b32_e32 v5, 4, v5
	s_addc_u32 s47, s31, s12
	s_add_i32 s53, s52, 0
	v_add_u32_e32 v2, v17, v18
	v_or3_b32 v4, v6, v5, v4
	v_mul_lo_u32 v3, v3, s9
	s_add_i32 m0, s53, 0x10000
	v_add_lshl_u32 v198, v2, v3, 1
	v_mul_u32_u24_e32 v3, 0xb00, v4
	global_load_lds_dwordx4 v196, s[46:47]
	s_add_i32 m0, s53, 0x12000
	v_add_lshl_u32 v200, v3, v2, 1
	s_add_u32 s12, s46, 0xb0000
	global_load_lds_dwordx4 v200, s[46:47]
	s_addc_u32 s13, s47, 0
	s_add_i32 m0, s53, 0x14000
	s_mul_i32 s15, s67, 0x160000
	global_load_lds_dwordx4 v196, s[12:13]
	s_add_i32 m0, s53, 0x16000
	s_mul_hi_i32 s14, s67, 0x160000
	s_add_u32 s44, s3, s15
	s_addc_u32 s45, s23, s14
	s_add_i32 s54, s53, 0x2000
	global_load_lds_dwordx4 v200, s[12:13]
	s_mov_b32 m0, s53
	s_add_u32 s12, s44, 0xb0000
	global_load_lds_dwordx4 v194, s[44:45]
	s_mov_b32 m0, s54
	s_addc_u32 s13, s45, 0
	s_add_i32 s55, s53, 0x4000
	global_load_lds_dwordx4 v198, s[44:45]
	s_mov_b32 m0, s55
	s_add_i32 s56, s53, 0x6000
	global_load_lds_dwordx4 v194, s[12:13]
	s_mov_b32 m0, s56
	v_mov_b32_e32 v203, 0
	global_load_lds_dwordx4 v198, s[12:13]
	v_mov_b32_e32 v197, v203
	v_mov_b32_e32 v201, v203
	v_mov_b32_e32 v195, v203
	v_mov_b32_e32 v199, v203
	s_cmp_eq_u32 s8, 1
	s_mov_b32 s57, 0
	v_lshl_add_u64 v[8:9], s[46:47], 0, v[196:197]
	v_lshl_add_u64 v[6:7], s[46:47], 0, v[200:201]
	v_lshl_add_u64 v[2:3], s[44:45], 0, v[194:195]
	s_cselect_b64 s[12:13], -1, 0
	s_cmp_lg_u32 s8, 1
	v_lshl_add_u64 v[4:5], s[44:45], 0, v[198:199]
	s_cbranch_scc1 .LBB0_1239
.LBB0_1239:
	s_add_u32 s14, s4, 0x6400000
	s_addc_u32 s15, s5, 0
	s_add_u32 s16, s6, 0xa0000
	s_addc_u32 s17, s7, 0
	s_lshl_b32 s4, s24, 5
	s_mov_b64 s[24:25], 0x80
	s_and_b32 s42, s4, 0x60
	s_add_i32 m0, s53, 0x18000
	v_lshl_add_u64 v[8:9], v[8:9], 0, s[24:25]
	s_lshl_b32 s6, s8, 13
	s_lshl_b32 s7, s42, 7
	s_waitcnt vmcnt(2)
	s_barrier
	global_load_lds_dwordx4 v[8:9], off
	v_lshl_add_u64 v[6:7], v[6:7], 0, s[24:25]
	s_add_i32 m0, s53, 0x1a000
	s_add_i32 s58, s53, 0x8000
	s_add_i32 s59, s53, 0xa000
	global_load_lds_dwordx4 v[6:7], off
	v_lshl_add_u64 v[2:3], v[2:3], 0, s[24:25]
	s_mov_b32 m0, s58
	s_add_u32 s4, s46, 0xb0080
	global_load_lds_dwordx4 v[2:3], off
	v_lshl_add_u64 v[2:3], v[4:5], 0, s[24:25]
	s_mov_b32 m0, s59
	s_addc_u32 s5, s47, 0
	global_load_lds_dwordx4 v[2:3], off
	s_add_i32 m0, s53, 0x1c000
	v_lshl_add_u64 v[2:3], s[4:5], 0, v[196:197]
	global_load_lds_dwordx4 v[2:3], off
	v_lshl_add_u64 v[2:3], s[4:5], 0, v[200:201]
	s_add_i32 m0, s53, 0x1e000
	s_cmpk_lt_u32 s26, 0x100
	global_load_lds_dwordx4 v[2:3], off
	v_bfe_u32 v3, v10, 4, 2
	v_and_b32_e32 v2, 15, v10
	v_lshlrev_b32_e32 v4, 4, v3
	v_lshl_or_b32 v243, s8, 6, v2
	v_lshl_or_b32 v2, v2, 6, v4
	v_lshlrev_b32_e32 v4, 2, v10
	v_and_b32_e32 v4, 32, v4
	v_bitop3_b32 v6, v2, s6, v4 bitop3:0xde
	v_bitop3_b32 v244, v2, s7, v4 bitop3:0xde
	v_lshl_or_b32 v2, v3, 3, s42
	v_cmp_eq_u32_e64 s[4:5], 0, v3
	v_lshrrev_b32_e32 v3, 1, v11
	v_mul_lo_u32 v4, v13, s9
	s_mov_b32 s8, 0xb000
	v_mad_u64_u32 v[4:5], s[42:43], v3, s8, v[4:5]
	v_lshlrev_b32_e32 v202, 1, v2
	v_or_b32_e32 v3, v4, v12
	v_lshl_add_u64 v[204:205], s[14:15], 0, v[202:203]
	v_add_lshl_u32 v202, v3, v14, 1
	v_lshrrev_b32_e32 v3, 1, v15
	v_mul_lo_u32 v4, v16, s9
	v_mad_u64_u32 v[4:5], s[8:9], v3, s8, v[4:5]
	s_mov_b64 s[6:7], 0xb0080
	s_waitcnt vmcnt(6)
	v_or_b32_e32 v3, v4, v17
	s_cselect_b64 s[26:27], -1, 0
	v_lshl_add_u64 v[206:207], v[202:203], 0, s[6:7]
	v_add_lshl_u32 v202, v3, v18, 1
	s_add_i32 s63, 0, 0x10000
	s_add_i32 s64, 0, 0x14000
	v_mbcnt_lo_u32_b32 v3, -1, 0
	s_ashr_i32 s60, s38, 31
	s_mov_b32 s61, s38
	s_ashr_i32 s62, s2, 31
	v_lshl_add_u64 v[208:209], v[202:203], 0, s[6:7]
	v_add_u32_e32 v245, s63, v244
	v_add_u32_e32 v246, s64, v244
	v_add_u32_e32 v247, 0, v6
	v_mbcnt_hi_u32_b32 v248, -1, v3
	v_lshlrev_b32_e32 v202, 1, v2
	s_barrier
	s_branch .LBB0_1242

.Lhb_exit_p9:
	s_and_b64 vcc, exec, s[26:27]
	s_cbranch_vccz .LBB0_1256
.LBB0_1256:
	s_lshl_b32 s44, s68, 8
	v_lshl_add_u32 v238, s67, 8, v243
	s_ashr_i32 s45, s44, 31
	s_lshl_b64 s[46:47], s[44:45], 1
	v_ashrrev_i32_e32 v239, 31, v238
	v_lshl_add_u64 v[126:127], v[204:205], 0, s[46:47]
	v_lshlrev_b64 v[240:241], 11, v[238:239]
	v_lshl_add_u64 v[122:123], v[126:127], 0, v[240:241]
	global_load_dwordx4 v[190:193], v[122:123], off
	global_load_dwordx4 v[186:189], v[122:123], off offset:256
	v_or_b32_e32 v234, 16, v238
	v_ashrrev_i32_e32 v235, 31, v234
	v_or_b32_e32 v230, 32, v238
	v_lshlrev_b64 v[236:237], 11, v[234:235]
	v_ashrrev_i32_e32 v231, 31, v230
	v_or_b32_e32 v226, 48, v238
	v_lshl_add_u64 v[122:123], v[126:127], 0, v[236:237]
	v_lshlrev_b64 v[232:233], 11, v[230:231]
	v_ashrrev_i32_e32 v227, 31, v226
	v_add_u32_e32 v222, 0x80, v238
	global_load_dwordx4 v[182:185], v[122:123], off
	global_load_dwordx4 v[178:181], v[122:123], off offset:256
	v_lshl_add_u64 v[122:123], v[126:127], 0, v[232:233]
	v_lshlrev_b64 v[228:229], 11, v[226:227]
	v_ashrrev_i32_e32 v223, 31, v222
	v_add_u32_e32 v218, 0x90, v238
	global_load_dwordx4 v[174:177], v[122:123], off
	global_load_dwordx4 v[170:173], v[122:123], off offset:256
	v_lshl_add_u64 v[122:123], v[126:127], 0, v[228:229]
	v_lshlrev_b64 v[224:225], 11, v[222:223]
	v_ashrrev_i32_e32 v219, 31, v218
	v_add_u32_e32 v212, 0xa0, v238
	v_add_u32_e32 v210, 0xb0, v238
	global_load_dwordx4 v[166:169], v[122:123], off
	global_load_dwordx4 v[162:165], v[122:123], off offset:256
	v_lshl_add_u64 v[122:123], v[126:127], 0, v[224:225]
	v_lshlrev_b64 v[220:221], 11, v[218:219]
	v_ashrrev_i32_e32 v213, 31, v212
	v_ashrrev_i32_e32 v211, 31, v210
	global_load_dwordx4 v[158:161], v[122:123], off
	global_load_dwordx4 v[146:149], v[122:123], off offset:256
	v_lshl_add_u64 v[122:123], v[126:127], 0, v[220:221]
	v_lshlrev_b64 v[216:217], 11, v[212:213]
	v_lshlrev_b64 v[214:215], 11, v[210:211]
	global_load_dwordx4 v[142:145], v[122:123], off
	global_load_dwordx4 v[138:141], v[122:123], off offset:256
	v_lshl_add_u64 v[122:123], v[126:127], 0, v[216:217]
	v_lshl_add_u64 v[126:127], v[126:127], 0, v[214:215]
	global_load_dwordx4 v[130:133], v[122:123], off
	s_nop 0
	global_load_dwordx4 v[122:125], v[122:123], off offset:256
	s_nop 0
	global_load_dwordx4 v[134:137], v[126:127], off
	s_nop 0
	global_load_dwordx4 v[126:129], v[126:127], off offset:256
	v_lshl_add_u64 v[240:241], s[14:15], 0, v[240:241]
	v_lshl_add_u64 v[240:241], v[240:241], 0, s[46:47]
	v_lshl_add_u64 v[240:241], v[240:241], 0, v[202:203]
	v_and_b32_e32 v250, 64, v248
	v_xor_b32_e32 v249, 16, v248
	v_add_u32_e32 v250, 64, v250
	v_cmp_lt_i32_e32 vcc, v249, v250
	v_xor_b32_e32 v251, 32, v248
	s_waitcnt vmcnt(0)
	v_lshlrev_b32_e32 v252, 16, v190
	v_and_b32_e32 v253, 0xffff0000, v190
	v_lshlrev_b32_e32 v190, 16, v191
	v_and_b32_e32 v191, 0xffff0000, v191
	v_lshlrev_b32_e32 v254, 16, v192
	v_and_b32_e32 v255, 0xffff0000, v192
	v_lshlrev_b32_e32 v192, 16, v193
	v_and_b32_e32 v193, 0xffff0000, v193
	v_pk_fma_f32 v[156:157], v[156:157], 0.5, v[190:191] op_sel_hi:[1,0,1]
	v_pk_fma_f32 v[154:155], v[154:155], 0.5, v[252:253] op_sel_hi:[1,0,1]
	v_pk_fma_f32 v[190:191], v[152:153], 0.5, v[192:193] op_sel_hi:[1,0,1]
	v_pk_fma_f32 v[192:193], v[150:151], 0.5, v[254:255] op_sel_hi:[1,0,1]
	v_cvt_pk_bf16_f32 v150, v154, v155
	v_cvt_pk_bf16_f32 v151, v156, v157
	v_cvt_pk_bf16_f32 v152, v192, v193
	v_cvt_pk_bf16_f32 v153, v190, v191
	global_store_dwordx4 v[240:241], v[150:153], off
	v_cndmask_b32_e32 v249, v248, v249, vcc
	v_lshlrev_b32_e32 v249, 2, v249
	v_mul_f32_e32 v150, v155, v155
	v_mul_f32_e32 v151, v157, v157
	v_fmac_f32_e32 v150, v154, v154
	v_fmac_f32_e32 v151, v156, v156
	v_add_f32_e32 v150, v150, v151
	v_mul_f32_e32 v151, v193, v193
	v_mul_f32_e32 v152, v191, v191
	v_fmac_f32_e32 v151, v192, v192
	v_fmac_f32_e32 v152, v190, v190
	v_add_f32_e32 v151, v151, v152
	v_add_f32_e32 v190, v150, v151
	v_lshlrev_b32_e32 v150, 16, v186
	v_and_b32_e32 v151, 0xffff0000, v186
	v_lshlrev_b32_e32 v152, 16, v187
	v_and_b32_e32 v153, 0xffff0000, v187
	v_lshlrev_b32_e32 v154, 16, v188
	v_and_b32_e32 v155, 0xffff0000, v188
	v_lshlrev_b32_e32 v156, 16, v189
	v_and_b32_e32 v157, 0xffff0000, v189
	v_pk_fma_f32 v[120:121], v[120:121], 0.5, v[152:153] op_sel_hi:[1,0,1]
	v_pk_fma_f32 v[118:119], v[118:119], 0.5, v[150:151] op_sel_hi:[1,0,1]
	v_pk_fma_f32 v[150:151], v[116:117], 0.5, v[156:157] op_sel_hi:[1,0,1]
	v_pk_fma_f32 v[152:153], v[114:115], 0.5, v[154:155] op_sel_hi:[1,0,1]
	v_cvt_pk_bf16_f32 v114, v118, v119
	v_cvt_pk_bf16_f32 v115, v120, v121
	v_cvt_pk_bf16_f32 v116, v152, v153
	v_cvt_pk_bf16_f32 v117, v150, v151
	global_store_dwordx4 v[240:241], v[114:117], off offset:256
	v_cmp_lt_i32_e32 vcc, v251, v250
	s_nop 0
	v_mul_f32_e32 v114, v119, v119
	v_mul_f32_e32 v115, v121, v121
	v_fmac_f32_e32 v114, v118, v118
	v_fmac_f32_e32 v115, v120, v120
	v_add_f32_e32 v114, v114, v115
	v_mul_f32_e32 v115, v153, v153
	v_mul_f32_e32 v116, v151, v151
	v_fmac_f32_e32 v115, v152, v152
	v_fmac_f32_e32 v116, v150, v150
	v_add_f32_e32 v115, v115, v116
	v_add_f32_e32 v114, v114, v115
	v_add_f32_e32 v114, v190, v114
	ds_bpermute_b32 v115, v249, v114
	v_cndmask_b32_e32 v250, v248, v251, vcc
	v_lshlrev_b32_e32 v250, 2, v250
	s_waitcnt lgkmcnt(0)
	v_add_f32_e32 v114, v114, v115
	ds_bpermute_b32 v115, v250, v114
	s_and_saveexec_b64 s[46:47], s[4:5]
	s_cbranch_execz .LBB0_1258
	v_lshl_add_u64 v[116:117], v[238:239], 2, s[16:17]
	s_waitcnt lgkmcnt(0)
	v_add_f32_e32 v114, v114, v115
	global_atomic_add_f32 v[116:117], v114, off

.LBB0_1349:
	v_ashrrev_i32_e32 v3, 31, v10
	v_lshrrev_b32_e32 v3, 26, v3
	v_add_u32_e32 v3, v10, v3
	v_ashrrev_i32_e32 v11, 6, v3
	v_bfe_i32 v3, v10, 27, 1
	v_lshlrev_b32_e32 v2, 4, v10
	v_lshrrev_b32_e32 v3, 22, v3
	v_add_u32_e32 v3, v2, v3
	v_and_b32_e32 v3, 0xfffffc00, v3
	v_sub_u32_e32 v3, v2, v3
	v_lshrrev_b32_e32 v4, 4, v3
	v_bitop3_b32 v3, v4, v3, 32 bitop3:0x6c
	v_ashrrev_i32_e32 v5, 31, v3
	v_lshrrev_b32_e32 v5, 26, v5
	v_add_u32_e32 v5, v3, v5
	v_lshlrev_b32_e32 v4, 3, v11
	v_ashrrev_i32_e32 v12, 6, v5
	v_and_b32_e32 v5, 0xc0, v5
	v_and_b32_e32 v4, -16, v4
	v_sub_u32_e32 v3, v3, v5
	v_mov_b32_e32 v5, 1
	v_add_u32_e32 v4, v12, v4
	v_ashrrev_i16_sdwa v3, v5, sext(v3) dst_sel:DWORD dst_unused:UNUSED_PAD src0_sel:DWORD src1_sel:BYTE_0
	s_load_dwordx2 s[16:17], s[12:13], 0xa8
	s_load_dwordx2 s[24:25], s[14:15], 0xa8
	v_lshlrev_b32_e32 v6, 5, v11
	v_bfe_i32 v13, v3, 0, 16
	v_lshlrev_b32_e32 v3, 1, v4
	v_lshrrev_b32_e32 v7, 2, v4
	v_and_b32_e32 v8, 3, v12
	s_mov_b32 s12, 0x1fffe0
	v_and_b32_e32 v6, 32, v6
	v_and_b32_e32 v3, 24, v3
	v_and_b32_e32 v7, 4, v7
	v_and_or_b32 v8, v4, s12, v8
	v_or3_b32 v3, v8, v7, v3
	v_add_lshl_u32 v6, v6, v13, 1
	v_add_u32_e32 v2, 0x2000, v2
	v_lshl_add_u32 v132, v3, 11, v6
	v_ashrrev_i32_e32 v3, 31, v2
	v_lshrrev_b32_e32 v3, 22, v3
	v_add_u32_e32 v3, v2, v3
	v_ashrrev_i32_e32 v14, 10, v3
	v_mul_i32_i24_e32 v3, 0x400, v14
	v_sub_u32_e32 v2, v2, v3
	v_lshrrev_b32_e32 v3, 4, v2
	v_bitop3_b32 v2, v3, v2, 32 bitop3:0x6c
	v_lshl_add_u32 v130, v4, 11, v6
	v_ashrrev_i32_e32 v4, 31, v2
	v_lshrrev_b32_e32 v4, 26, v4
	s_waitcnt lgkmcnt(0)
	s_add_u32 s3, s16, 0x6400000
	v_add_u32_e32 v4, v2, v4
	s_addc_u32 s23, s17, 0
	v_lshlrev_b32_e32 v3, 3, v14
	v_ashrrev_i32_e32 v15, 6, v4
	v_and_b32_e32 v4, 0xc0, v4
	s_add_u32 s29, s24, 0x5000000
	v_and_b32_e32 v3, -16, v3
	v_sub_u32_e32 v2, v2, v4
	s_addc_u32 s31, s25, 0
	v_add_u32_e32 v3, v15, v3
	v_ashrrev_i16_sdwa v2, v5, sext(v2) dst_sel:DWORD dst_unused:UNUSED_PAD src0_sel:DWORD src1_sel:BYTE_0
	v_and_b32_e32 v5, 3, v15
	s_ashr_i32 s24, s26, 6
	s_ashr_i32 s53, s52, 31
	s_ashr_i32 s51, s50, 31
	s_ashr_i32 s27, s26, 8
	v_and_or_b32 v5, v3, s12, v5
	s_lshl_b32 s60, s24, 10
	s_lshl_b64 s[12:13], s[52:53], 19
	s_lshl_b64 s[14:15], s[50:51], 19
	s_add_u32 s56, s29, s14
	v_lshlrev_b32_e32 v6, 5, v14
	v_bfe_i32 v16, v2, 0, 16
	v_lshlrev_b32_e32 v2, 1, v3
	v_lshrrev_b32_e32 v4, 2, v3
	s_addc_u32 s57, s31, s15
	s_add_i32 s61, s60, 0
	v_and_b32_e32 v6, 32, v6
	v_and_b32_e32 v2, 24, v2
	v_and_b32_e32 v4, 4, v4
	s_add_i32 m0, s61, 0x10000
	v_or3_b32 v2, v5, v4, v2
	v_add_lshl_u32 v4, v6, v16, 1
	global_load_lds_dwordx4 v132, s[56:57]
	s_add_i32 m0, s61, 0x12000
	v_lshl_add_u32 v136, v2, 11, v4
	s_add_u32 s14, s56, 0x40000
	global_load_lds_dwordx4 v136, s[56:57]
	s_addc_u32 s15, s57, 0
	s_add_i32 m0, s61, 0x14000
	v_lshl_add_u32 v134, v3, 11, v4
	global_load_lds_dwordx4 v132, s[14:15]
	s_add_i32 m0, s61, 0x16000
	s_add_u32 s54, s3, s12
	s_addc_u32 s55, s23, s13
	s_add_i32 s62, s61, 0x2000
	global_load_lds_dwordx4 v136, s[14:15]
	s_mov_b32 m0, s61
	s_add_u32 s12, s54, 0x40000
	global_load_lds_dwordx4 v130, s[54:55]
	s_mov_b32 m0, s62
	s_addc_u32 s13, s55, 0
	s_add_i32 s63, s61, 0x4000
	global_load_lds_dwordx4 v134, s[54:55]
	s_mov_b32 m0, s63
	s_add_i32 s64, s61, 0x6000
	global_load_lds_dwordx4 v130, s[12:13]
	s_mov_b32 m0, s64
	v_mov_b32_e32 v139, 0
	global_load_lds_dwordx4 v134, s[12:13]
	s_load_dwordx2 s[12:13], s[4:5], 0xa8
	s_nop 0
	s_load_dwordx2 s[6:7], s[6:7], 0xa8
	s_nop 0
	s_load_dwordx2 s[4:5], s[10:11], 0xa8
	v_mov_b32_e32 v133, v139
	v_mov_b32_e32 v137, v139
	v_mov_b32_e32 v131, v139
	v_mov_b32_e32 v135, v139
	s_cmp_eq_u32 s27, 1
	s_mov_b32 s65, 0
	v_lshl_add_u64 v[8:9], s[56:57], 0, v[132:133]
	v_lshl_add_u64 v[6:7], s[56:57], 0, v[136:137]
	v_lshl_add_u64 v[2:3], s[54:55], 0, v[130:131]
	s_cselect_b64 s[10:11], -1, 0
	s_cmp_lg_u32 s27, 1
	v_lshl_add_u64 v[4:5], s[54:55], 0, v[134:135]
	s_cbranch_scc1 .LBB0_1351
.LBB0_1351:
	s_waitcnt lgkmcnt(0)
	s_add_u32 s12, s12, 0xa0000
	s_addc_u32 s13, s13, 0
	s_add_u32 s14, s6, 0x10400000
	s_addc_u32 s15, s7, 0
	s_add_u32 s16, s4, 0xc0000
	s_addc_u32 s17, s5, 0
	s_lshl_b32 s4, s24, 5
	s_mov_b64 s[24:25], 0x80
	s_and_b32 s7, s4, 0x60
	s_add_i32 m0, s61, 0x18000
	v_lshl_add_u64 v[8:9], v[8:9], 0, s[24:25]
	s_lshl_b32 s6, s27, 13
	s_lshl_b32 s42, s7, 7
	s_waitcnt vmcnt(2)
	s_barrier
	global_load_lds_dwordx4 v[8:9], off
	v_lshl_add_u64 v[6:7], v[6:7], 0, s[24:25]
	s_add_i32 m0, s61, 0x1a000
	s_add_i32 s66, s61, 0x8000
	s_add_i32 s67, s61, 0xa000
	global_load_lds_dwordx4 v[6:7], off
	v_lshl_add_u64 v[2:3], v[2:3], 0, s[24:25]
	s_mov_b32 m0, s66
	s_add_u32 s4, s56, 0x40080
	global_load_lds_dwordx4 v[2:3], off
	v_lshl_add_u64 v[2:3], v[4:5], 0, s[24:25]
	s_mov_b32 m0, s67
	s_addc_u32 s5, s57, 0
	global_load_lds_dwordx4 v[2:3], off
	s_add_i32 m0, s61, 0x1c000
	v_lshl_add_u64 v[2:3], s[4:5], 0, v[132:133]
	global_load_lds_dwordx4 v[2:3], off
	v_lshl_add_u64 v[2:3], s[4:5], 0, v[136:137]
	s_add_i32 m0, s61, 0x1e000
	s_cmpk_lt_u32 s26, 0x100
	global_load_lds_dwordx4 v[2:3], off
	v_bfe_u32 v3, v10, 4, 2
	v_and_b32_e32 v2, 15, v10
	v_lshlrev_b32_e32 v4, 4, v3
	v_lshl_or_b32 v150, s27, 6, v2
	v_lshl_or_b32 v2, v2, 6, v4
	v_lshlrev_b32_e32 v4, 2, v10
	v_and_b32_e32 v4, 32, v4
	v_bitop3_b32 v5, v2, s6, v4 bitop3:0xde
	v_bitop3_b32 v151, v2, s42, v4 bitop3:0xde
	v_lshl_or_b32 v2, v3, 3, s7
	v_cmp_eq_u32_e64 s[4:5], 0, v3
	v_lshlrev_b32_e32 v3, 14, v11
	v_and_b32_e32 v3, 0xffff8000, v3
	v_lshl_add_u32 v3, v12, 11, v3
	v_and_b32_e32 v4, 1, v11
	v_lshl_or_b32 v3, v4, 6, v3
	v_lshl_add_u32 v140, v13, 1, v3
	v_lshlrev_b32_e32 v3, 14, v14
	v_and_b32_e32 v3, 0xffff8000, v3
	v_lshl_add_u32 v3, v15, 11, v3
	v_and_b32_e32 v4, 1, v14
	s_waitcnt vmcnt(6)
	v_lshl_or_b32 v3, v4, 6, v3
	s_cselect_b64 s[26:27], -1, 0
	v_lshl_add_u32 v142, v16, 1, v3
	s_add_i32 s71, 0, 0x10000
	s_add_i32 s72, 0, 0x14000
	v_mbcnt_lo_u32_b32 v3, -1, 0
	s_ashr_i32 s68, s38, 31
	s_mov_b32 s69, s38
	s_ashr_i32 s70, s2, 31
	v_mov_b32_e32 v141, v139
	v_mov_b32_e32 v143, v139
	v_mov_b64_e32 v[144:145], 0x180
	v_mov_b64_e32 v[146:147], 0x17f
	v_add_u32_e32 v152, s71, v151
	v_add_u32_e32 v153, s72, v151
	v_add_u32_e32 v154, 0, v5
	v_mbcnt_hi_u32_b32 v155, -1, v3
	v_mov_b32_e32 v156, 0x358637bd
	s_movk_i32 s73, 0x600
	v_lshlrev_b32_e32 v138, 1, v2
	s_barrier
	s_branch .LBB0_1354

.LBB0_1356:
	s_ashr_i32 s45, s44, 31
	s_lshl_b64 s[46:47], s[44:45], 19
	s_add_u32 s46, s3, s46
	s_addc_u32 s47, s23, s47
	s_and_b64 s[48:49], s[6:7], exec
	s_cselect_b32 s45, s47, s55
	s_cselect_b32 s51, s46, s54
	s_ashr_i32 s43, s42, 31
	s_lshl_b64 s[48:49], s[42:43], 19
	s_add_u32 s48, s29, s48
	s_addc_u32 s49, s31, s49
	s_and_b64 s[58:59], s[6:7], exec
	s_cselect_b32 s43, s49, s57
	s_cselect_b32 s53, s48, s56
	s_add_u32 s54, s54, 0x40080
	s_addc_u32 s55, s55, 0
	s_add_u32 s74, s56, 0x100
	v_mov_b32_e32 v2, 0
	s_addc_u32 s75, s57, 0
	s_mov_b32 s76, -2
	s_waitcnt lgkmcnt(0)
	v_mov_b32_e32 v3, v2
	v_mov_b32_e32 v4, v2
	v_mov_b32_e32 v5, v2
	v_mov_b32_e32 v6, v2
	v_mov_b32_e32 v7, v2
	v_mov_b32_e32 v8, v2
	v_mov_b32_e32 v9, v2
	v_mov_b32_e32 v18, v2
	v_mov_b32_e32 v19, v2
	v_mov_b32_e32 v20, v2
	v_mov_b32_e32 v21, v2
	v_mov_b32_e32 v22, v2
	v_mov_b32_e32 v23, v2
	v_mov_b32_e32 v24, v2
	v_mov_b32_e32 v25, v2
	v_mov_b32_e32 v34, v2
	v_mov_b32_e32 v35, v2
	v_mov_b32_e32 v36, v2
	v_mov_b32_e32 v37, v2
	v_mov_b32_e32 v38, v2
	v_mov_b32_e32 v39, v2
	v_mov_b32_e32 v40, v2
	v_mov_b32_e32 v41, v2
	v_mov_b32_e32 v50, v2
	v_mov_b32_e32 v51, v2
	v_mov_b32_e32 v52, v2
	v_mov_b32_e32 v53, v2
	v_mov_b32_e32 v54, v2
	v_mov_b32_e32 v55, v2
	v_mov_b32_e32 v56, v2
	v_mov_b32_e32 v57, v2
	v_mov_b32_e32 v10, v2
	v_mov_b32_e32 v11, v2
	v_mov_b32_e32 v12, v2
	v_mov_b32_e32 v13, v2
	v_mov_b32_e32 v14, v2
	v_mov_b32_e32 v15, v2
	v_mov_b32_e32 v16, v2
	v_mov_b32_e32 v17, v2
	v_mov_b32_e32 v26, v2
	v_mov_b32_e32 v27, v2
	v_mov_b32_e32 v28, v2
	v_mov_b32_e32 v29, v2
	v_mov_b32_e32 v30, v2
	v_mov_b32_e32 v31, v2
	v_mov_b32_e32 v32, v2
	v_mov_b32_e32 v33, v2
	v_mov_b32_e32 v42, v2
	v_mov_b32_e32 v43, v2
	v_mov_b32_e32 v44, v2
	v_mov_b32_e32 v45, v2
	v_mov_b32_e32 v46, v2
	v_mov_b32_e32 v47, v2
	v_mov_b32_e32 v48, v2
	v_mov_b32_e32 v49, v2
	v_mov_b32_e32 v58, v2
	v_mov_b32_e32 v59, v2
	v_mov_b32_e32 v60, v2
	v_mov_b32_e32 v61, v2
	v_mov_b32_e32 v62, v2
	v_mov_b32_e32 v63, v2
	v_mov_b32_e32 v64, v2
	v_mov_b32_e32 v65, v2
	v_mov_b32_e32 v66, v2
	v_mov_b32_e32 v67, v2
	v_mov_b32_e32 v68, v2
	v_mov_b32_e32 v69, v2
	v_mov_b32_e32 v70, v2
	v_mov_b32_e32 v71, v2
	v_mov_b32_e32 v72, v2
	v_mov_b32_e32 v73, v2
	s_waitcnt vmcnt(0)
	v_mov_b32_e32 v82, v2
	v_mov_b32_e32 v83, v2
	v_mov_b32_e32 v84, v2
	v_mov_b32_e32 v85, v2
	v_mov_b32_e32 v86, v2
	v_mov_b32_e32 v87, v2
	v_mov_b32_e32 v88, v2
	v_mov_b32_e32 v89, v2
	v_mov_b32_e32 v98, v2
	v_mov_b32_e32 v99, v2
	v_mov_b32_e32 v100, v2
	v_mov_b32_e32 v101, v2
	v_mov_b32_e32 v102, v2
	v_mov_b32_e32 v103, v2
	v_mov_b32_e32 v104, v2
	v_mov_b32_e32 v105, v2
	v_mov_b32_e32 v114, v2
	v_mov_b32_e32 v115, v2
	v_mov_b32_e32 v116, v2
	v_mov_b32_e32 v117, v2
	v_mov_b32_e32 v118, v2
	v_mov_b32_e32 v119, v2
	v_mov_b32_e32 v120, v2
	v_mov_b32_e32 v121, v2
	v_mov_b32_e32 v74, v2
	v_mov_b32_e32 v75, v2
	v_mov_b32_e32 v76, v2
	v_mov_b32_e32 v77, v2
	v_mov_b32_e32 v78, v2
	v_mov_b32_e32 v79, v2
	v_mov_b32_e32 v80, v2
	v_mov_b32_e32 v81, v2
	v_mov_b32_e32 v90, v2
	v_mov_b32_e32 v91, v2
	v_mov_b32_e32 v92, v2
	v_mov_b32_e32 v93, v2
	v_mov_b32_e32 v94, v2
	v_mov_b32_e32 v95, v2
	v_mov_b32_e32 v96, v2
	v_mov_b32_e32 v97, v2
	v_mov_b32_e32 v106, v2
	v_mov_b32_e32 v107, v2
	v_mov_b32_e32 v108, v2
	v_mov_b32_e32 v109, v2
	v_mov_b32_e32 v110, v2
	v_mov_b32_e32 v111, v2
	v_mov_b32_e32 v112, v2
	v_mov_b32_e32 v113, v2
	v_mov_b32_e32 v122, v2
	v_mov_b32_e32 v123, v2
	v_mov_b32_e32 v124, v2
	v_mov_b32_e32 v125, v2
	v_mov_b32_e32 v126, v2
	v_mov_b32_e32 v127, v2
	v_mov_b32_e32 v128, v2
	v_mov_b32_e32 v129, v2
	s_cmp_eq_u64 s[26:27], 0
	s_cbranch_scc1 .Lhb_B_p10
.LBB0_1357:
	ds_read_b128 v[158:161], v152
	ds_read_b128 v[162:165], v152 offset:1024
	ds_read_b128 v[166:169], v152 offset:2048
	ds_read_b128 v[170:173], v152 offset:3072
	ds_read_b128 v[174:177], v153
	ds_read_b128 v[178:181], v153 offset:1024
	ds_read_b128 v[182:185], v153 offset:2048
	ds_read_b128 v[186:189], v153 offset:3072
	s_add_u32 s56, s54, 0xfffc0080
	s_addc_u32 s57, s55, -1
	s_cmp_eq_u32 s76, 12
	s_cselect_b32 s59, s45, s57
	s_cselect_b32 s58, s51, s56
	s_cselect_b32 s57, s43, s75
	s_cselect_b32 s56, s53, s74
	v_lshl_add_u64 v[148:149], s[54:55], 0, v[140:141]
	s_add_i32 m0, s61, 0xc000
	ds_read_b128 v[190:193], v154
	ds_read_b128 v[194:197], v154 offset:1024
	ds_read_b128 v[198:201], v154 offset:2048
	ds_read_b128 v[202:205], v154 offset:3072
	ds_read_b128 v[206:209], v154 offset:4096
	ds_read_b128 v[210:213], v154 offset:5120
	ds_read_b128 v[214:217], v154 offset:6144
	ds_read_b128 v[218:221], v154 offset:7168
	global_load_lds_dwordx4 v[148:149], off
	v_lshl_add_u64 v[148:149], s[54:55], 0, v[142:143]
	s_add_i32 m0, s61, 0xe000
	s_nop 0
	global_load_lds_dwordx4 v[148:149], off
	s_waitcnt vmcnt(8)
	s_waitcnt lgkmcnt(0)
	s_setprio 1
	v_mfma_f32_16x16x32_bf16 v[126:129], v[158:161], v[190:193], v[126:129]
	v_mfma_f32_16x16x32_bf16 v[122:125], v[166:169], v[190:193], v[122:125]
	v_mfma_f32_16x16x32_bf16 v[110:113], v[158:161], v[198:201], v[110:113]
	v_mfma_f32_16x16x32_bf16 v[106:109], v[166:169], v[198:201], v[106:109]
	v_mfma_f32_16x16x32_bf16 v[94:97], v[158:161], v[206:209], v[94:97]
	v_mfma_f32_16x16x32_bf16 v[90:93], v[166:169], v[206:209], v[90:93]
	v_mfma_f32_16x16x32_bf16 v[78:81], v[158:161], v[214:217], v[78:81]
	v_mfma_f32_16x16x32_bf16 v[74:77], v[166:169], v[214:217], v[74:77]
	v_mfma_f32_16x16x32_bf16 v[126:129], v[162:165], v[194:197], v[126:129]
	v_mfma_f32_16x16x32_bf16 v[122:125], v[170:173], v[194:197], v[122:125]
	v_mfma_f32_16x16x32_bf16 v[110:113], v[162:165], v[202:205], v[110:113]
	v_mfma_f32_16x16x32_bf16 v[106:109], v[170:173], v[202:205], v[106:109]
	v_mfma_f32_16x16x32_bf16 v[94:97], v[162:165], v[210:213], v[94:97]
	v_mfma_f32_16x16x32_bf16 v[90:93], v[170:173], v[210:213], v[90:93]
	v_mfma_f32_16x16x32_bf16 v[78:81], v[162:165], v[218:221], v[78:81]
	v_mfma_f32_16x16x32_bf16 v[74:77], v[170:173], v[218:221], v[74:77]
	s_setprio 0
	s_setprio 1
	v_mfma_f32_16x16x32_bf16 v[118:121], v[174:177], v[190:193], v[118:121]
	v_mfma_f32_16x16x32_bf16 v[114:117], v[182:185], v[190:193], v[114:117]
	v_mfma_f32_16x16x32_bf16 v[102:105], v[174:177], v[198:201], v[102:105]
	v_mfma_f32_16x16x32_bf16 v[98:101], v[182:185], v[198:201], v[98:101]
	v_mfma_f32_16x16x32_bf16 v[86:89], v[174:177], v[206:209], v[86:89]
	v_mfma_f32_16x16x32_bf16 v[82:85], v[182:185], v[206:209], v[82:85]
	v_mfma_f32_16x16x32_bf16 v[70:73], v[174:177], v[214:217], v[70:73]
	v_mfma_f32_16x16x32_bf16 v[66:69], v[182:185], v[214:217], v[66:69]
	v_mfma_f32_16x16x32_bf16 v[118:121], v[178:181], v[194:197], v[118:121]
	v_mfma_f32_16x16x32_bf16 v[114:117], v[186:189], v[194:197], v[114:117]
	v_mfma_f32_16x16x32_bf16 v[102:105], v[178:181], v[202:205], v[102:105]
	v_mfma_f32_16x16x32_bf16 v[98:101], v[186:189], v[202:205], v[98:101]
	v_mfma_f32_16x16x32_bf16 v[86:89], v[178:181], v[210:213], v[86:89]
	v_mfma_f32_16x16x32_bf16 v[82:85], v[186:189], v[210:213], v[82:85]
	v_mfma_f32_16x16x32_bf16 v[70:73], v[178:181], v[218:221], v[70:73]
	v_mfma_f32_16x16x32_bf16 v[66:69], v[186:189], v[218:221], v[66:69]
	s_setprio 0
	s_barrier
	s_add_i32 s77, s71, s60
	v_lshl_add_u64 v[148:149], s[56:57], 0, v[132:133]
	s_mov_b32 m0, s77
	ds_read_b128 v[190:193], v154 offset:16384
	ds_read_b128 v[194:197], v154 offset:17408
	ds_read_b128 v[198:201], v154 offset:18432
	ds_read_b128 v[202:205], v154 offset:19456
	ds_read_b128 v[206:209], v154 offset:20480
	ds_read_b128 v[210:213], v154 offset:21504
	ds_read_b128 v[214:217], v154 offset:22528
	ds_read_b128 v[218:221], v154 offset:23552
	global_load_lds_dwordx4 v[148:149], off
	s_add_i32 m0, s77, 0x2000
	s_add_u32 s78, s56, 0x40000
	v_lshl_add_u64 v[222:223], s[56:57], 0, v[136:137]
	s_addc_u32 s79, s57, 0
	s_add_i32 s77, s72, s60
	global_load_lds_dwordx4 v[222:223], off
	v_lshl_add_u64 v[224:225], s[78:79], 0, v[132:133]
	s_mov_b32 m0, s77
	v_lshl_add_u64 v[226:227], s[58:59], 0, v[134:135]
	global_load_lds_dwordx4 v[224:225], off
	v_lshl_add_u64 v[224:225], s[78:79], 0, v[136:137]
	s_add_i32 m0, s77, 0x2000
	s_nop 0
	global_load_lds_dwordx4 v[224:225], off
	v_lshl_add_u64 v[224:225], s[58:59], 0, v[130:131]
	s_mov_b32 m0, s61
	s_nop 0
	global_load_lds_dwordx4 v[224:225], off
	s_mov_b32 m0, s62
	s_nop 0
	global_load_lds_dwordx4 v[226:227], off
	s_waitcnt vmcnt(8)
	s_waitcnt lgkmcnt(0)
	s_setprio 1
	v_mfma_f32_16x16x32_bf16 v[62:65], v[158:161], v[190:193], v[62:65]
	v_mfma_f32_16x16x32_bf16 v[58:61], v[166:169], v[190:193], v[58:61]
	v_mfma_f32_16x16x32_bf16 v[46:49], v[158:161], v[198:201], v[46:49]
	v_mfma_f32_16x16x32_bf16 v[42:45], v[166:169], v[198:201], v[42:45]
	v_mfma_f32_16x16x32_bf16 v[30:33], v[158:161], v[206:209], v[30:33]
	v_mfma_f32_16x16x32_bf16 v[26:29], v[166:169], v[206:209], v[26:29]
	v_mfma_f32_16x16x32_bf16 v[14:17], v[158:161], v[214:217], v[14:17]
	v_mfma_f32_16x16x32_bf16 v[10:13], v[166:169], v[214:217], v[10:13]
	v_mfma_f32_16x16x32_bf16 v[62:65], v[162:165], v[194:197], v[62:65]
	v_mfma_f32_16x16x32_bf16 v[58:61], v[170:173], v[194:197], v[58:61]
	v_mfma_f32_16x16x32_bf16 v[46:49], v[162:165], v[202:205], v[46:49]
	v_mfma_f32_16x16x32_bf16 v[42:45], v[170:173], v[202:205], v[42:45]
	v_mfma_f32_16x16x32_bf16 v[30:33], v[162:165], v[210:213], v[30:33]
	v_mfma_f32_16x16x32_bf16 v[26:29], v[170:173], v[210:213], v[26:29]
	v_mfma_f32_16x16x32_bf16 v[14:17], v[162:165], v[218:221], v[14:17]
	v_mfma_f32_16x16x32_bf16 v[10:13], v[170:173], v[218:221], v[10:13]
	s_setprio 0
	s_setprio 1
	v_mfma_f32_16x16x32_bf16 v[54:57], v[174:177], v[190:193], v[54:57]
	v_mfma_f32_16x16x32_bf16 v[50:53], v[182:185], v[190:193], v[50:53]
	v_mfma_f32_16x16x32_bf16 v[38:41], v[174:177], v[198:201], v[38:41]
	v_mfma_f32_16x16x32_bf16 v[34:37], v[182:185], v[198:201], v[34:37]
	v_mfma_f32_16x16x32_bf16 v[22:25], v[174:177], v[206:209], v[22:25]
	v_mfma_f32_16x16x32_bf16 v[18:21], v[182:185], v[206:209], v[18:21]
	v_mfma_f32_16x16x32_bf16 v[6:9], v[174:177], v[214:217], v[6:9]
	v_mfma_f32_16x16x32_bf16 v[2:5], v[182:185], v[214:217], v[2:5]
	v_mfma_f32_16x16x32_bf16 v[54:57], v[178:181], v[194:197], v[54:57]
	v_mfma_f32_16x16x32_bf16 v[50:53], v[186:189], v[194:197], v[50:53]
	v_mfma_f32_16x16x32_bf16 v[38:41], v[178:181], v[202:205], v[38:41]
	v_mfma_f32_16x16x32_bf16 v[34:37], v[186:189], v[202:205], v[34:37]
	v_mfma_f32_16x16x32_bf16 v[22:25], v[178:181], v[210:213], v[22:25]
	v_mfma_f32_16x16x32_bf16 v[18:21], v[186:189], v[210:213], v[18:21]
	v_mfma_f32_16x16x32_bf16 v[6:9], v[178:181], v[218:221], v[6:9]
	v_mfma_f32_16x16x32_bf16 v[2:5], v[186:189], v[218:221], v[2:5]
	s_setprio 0
	s_barrier
	s_add_i32 s77, 0, 0x18000
	v_add_u32_e32 v157, s77, v151
	s_add_i32 s78, 0, 0x1c000
	ds_read_b128 v[158:161], v157
	ds_read_b128 v[162:165], v157 offset:1024
	ds_read_b128 v[166:169], v157 offset:2048
	ds_read_b128 v[170:173], v157 offset:3072
	v_add_u32_e32 v157, s78, v151
	ds_read_b128 v[174:177], v157
	ds_read_b128 v[178:181], v157 offset:1024
	ds_read_b128 v[182:185], v157 offset:2048
	ds_read_b128 v[186:189], v157 offset:3072
	s_add_u32 s58, s58, 0x40000
	s_addc_u32 s59, s59, 0
	s_mov_b32 m0, s63
	v_lshl_add_u64 v[228:229], s[58:59], 0, v[130:131]
	ds_read_b128 v[190:193], v154 offset:32768
	ds_read_b128 v[194:197], v154 offset:33792
	ds_read_b128 v[198:201], v154 offset:34816
	ds_read_b128 v[202:205], v154 offset:35840
	ds_read_b128 v[206:209], v154 offset:36864
	ds_read_b128 v[210:213], v154 offset:37888
	ds_read_b128 v[214:217], v154 offset:38912
	ds_read_b128 v[218:221], v154 offset:39936
	global_load_lds_dwordx4 v[228:229], off
	v_lshl_add_u64 v[228:229], s[58:59], 0, v[134:135]
	s_mov_b32 m0, s64
	s_nop 0
	global_load_lds_dwordx4 v[228:229], off
	s_waitcnt vmcnt(8)
	s_waitcnt lgkmcnt(0)
	s_setprio 1
	v_mfma_f32_16x16x32_bf16 v[126:129], v[158:161], v[190:193], v[126:129]
	v_mfma_f32_16x16x32_bf16 v[122:125], v[166:169], v[190:193], v[122:125]
	v_mfma_f32_16x16x32_bf16 v[110:113], v[158:161], v[198:201], v[110:113]
	v_mfma_f32_16x16x32_bf16 v[106:109], v[166:169], v[198:201], v[106:109]
	v_mfma_f32_16x16x32_bf16 v[94:97], v[158:161], v[206:209], v[94:97]
	v_mfma_f32_16x16x32_bf16 v[90:93], v[166:169], v[206:209], v[90:93]
	v_mfma_f32_16x16x32_bf16 v[78:81], v[158:161], v[214:217], v[78:81]
	v_mfma_f32_16x16x32_bf16 v[74:77], v[166:169], v[214:217], v[74:77]
	v_mfma_f32_16x16x32_bf16 v[126:129], v[162:165], v[194:197], v[126:129]
	v_mfma_f32_16x16x32_bf16 v[122:125], v[170:173], v[194:197], v[122:125]
	v_mfma_f32_16x16x32_bf16 v[110:113], v[162:165], v[202:205], v[110:113]
	v_mfma_f32_16x16x32_bf16 v[106:109], v[170:173], v[202:205], v[106:109]
	v_mfma_f32_16x16x32_bf16 v[94:97], v[162:165], v[210:213], v[94:97]
	v_mfma_f32_16x16x32_bf16 v[90:93], v[170:173], v[210:213], v[90:93]
	v_mfma_f32_16x16x32_bf16 v[78:81], v[162:165], v[218:221], v[78:81]
	v_mfma_f32_16x16x32_bf16 v[74:77], v[170:173], v[218:221], v[74:77]
	s_setprio 0
	s_setprio 1
	v_mfma_f32_16x16x32_bf16 v[118:121], v[174:177], v[190:193], v[118:121]
	v_mfma_f32_16x16x32_bf16 v[114:117], v[182:185], v[190:193], v[114:117]
	v_mfma_f32_16x16x32_bf16 v[102:105], v[174:177], v[198:201], v[102:105]
	v_mfma_f32_16x16x32_bf16 v[98:101], v[182:185], v[198:201], v[98:101]
	v_mfma_f32_16x16x32_bf16 v[86:89], v[174:177], v[206:209], v[86:89]
	v_mfma_f32_16x16x32_bf16 v[82:85], v[182:185], v[206:209], v[82:85]
	v_mfma_f32_16x16x32_bf16 v[70:73], v[174:177], v[214:217], v[70:73]
	v_mfma_f32_16x16x32_bf16 v[66:69], v[182:185], v[214:217], v[66:69]
	v_mfma_f32_16x16x32_bf16 v[118:121], v[178:181], v[194:197], v[118:121]
	v_mfma_f32_16x16x32_bf16 v[114:117], v[186:189], v[194:197], v[114:117]
	v_mfma_f32_16x16x32_bf16 v[102:105], v[178:181], v[202:205], v[102:105]
	v_mfma_f32_16x16x32_bf16 v[98:101], v[186:189], v[202:205], v[98:101]
	v_mfma_f32_16x16x32_bf16 v[86:89], v[178:181], v[210:213], v[86:89]
	v_mfma_f32_16x16x32_bf16 v[82:85], v[186:189], v[210:213], v[82:85]
	v_mfma_f32_16x16x32_bf16 v[70:73], v[178:181], v[218:221], v[70:73]
	v_mfma_f32_16x16x32_bf16 v[66:69], v[186:189], v[218:221], v[66:69]
	s_setprio 0
	s_barrier
	s_add_i32 s58, s77, s60
	v_lshl_add_u64 v[148:149], v[148:149], 0, s[24:25]
	s_mov_b32 m0, s58
	ds_read_b128 v[190:193], v154 offset:49152
	ds_read_b128 v[194:197], v154 offset:50176
	ds_read_b128 v[198:201], v154 offset:51200
	ds_read_b128 v[202:205], v154 offset:52224
	ds_read_b128 v[206:209], v154 offset:53248
	ds_read_b128 v[210:213], v154 offset:54272
	ds_read_b128 v[214:217], v154 offset:55296
	ds_read_b128 v[218:221], v154 offset:56320
	global_load_lds_dwordx4 v[148:149], off
	s_add_i32 m0, s58, 0x2000
	s_add_u32 s56, s56, 0x40080
	v_lshl_add_u64 v[148:149], v[222:223], 0, s[24:25]
	s_addc_u32 s57, s57, 0
	s_add_i32 s58, s78, s60
	global_load_lds_dwordx4 v[148:149], off
	v_lshl_add_u64 v[148:149], s[56:57], 0, v[132:133]
	s_mov_b32 m0, s58
	s_nop 0
	global_load_lds_dwordx4 v[148:149], off
	v_lshl_add_u64 v[148:149], s[56:57], 0, v[136:137]
	s_add_i32 m0, s58, 0x2000
	s_nop 0
	global_load_lds_dwordx4 v[148:149], off
	v_lshl_add_u64 v[148:149], v[224:225], 0, s[24:25]
	s_mov_b32 m0, s66
	s_nop 0
	global_load_lds_dwordx4 v[148:149], off
	v_lshl_add_u64 v[148:149], v[226:227], 0, s[24:25]
	s_mov_b32 m0, s67
	s_nop 0
	global_load_lds_dwordx4 v[148:149], off
	s_waitcnt vmcnt(8)
	s_waitcnt lgkmcnt(0)
	s_setprio 1
	v_mfma_f32_16x16x32_bf16 v[62:65], v[158:161], v[190:193], v[62:65]
	v_mfma_f32_16x16x32_bf16 v[58:61], v[166:169], v[190:193], v[58:61]
	v_mfma_f32_16x16x32_bf16 v[46:49], v[158:161], v[198:201], v[46:49]
	v_mfma_f32_16x16x32_bf16 v[42:45], v[166:169], v[198:201], v[42:45]
	v_mfma_f32_16x16x32_bf16 v[30:33], v[158:161], v[206:209], v[30:33]
	v_mfma_f32_16x16x32_bf16 v[26:29], v[166:169], v[206:209], v[26:29]
	v_mfma_f32_16x16x32_bf16 v[14:17], v[158:161], v[214:217], v[14:17]
	v_mfma_f32_16x16x32_bf16 v[10:13], v[166:169], v[214:217], v[10:13]
	v_mfma_f32_16x16x32_bf16 v[62:65], v[162:165], v[194:197], v[62:65]
	v_mfma_f32_16x16x32_bf16 v[58:61], v[170:173], v[194:197], v[58:61]
	v_mfma_f32_16x16x32_bf16 v[46:49], v[162:165], v[202:205], v[46:49]
	v_mfma_f32_16x16x32_bf16 v[42:45], v[170:173], v[202:205], v[42:45]
	v_mfma_f32_16x16x32_bf16 v[30:33], v[162:165], v[210:213], v[30:33]
	v_mfma_f32_16x16x32_bf16 v[26:29], v[170:173], v[210:213], v[26:29]
	v_mfma_f32_16x16x32_bf16 v[14:17], v[162:165], v[218:221], v[14:17]
	v_mfma_f32_16x16x32_bf16 v[10:13], v[170:173], v[218:221], v[10:13]
	s_setprio 0
	s_setprio 1
	v_mfma_f32_16x16x32_bf16 v[54:57], v[174:177], v[190:193], v[54:57]
	v_mfma_f32_16x16x32_bf16 v[50:53], v[182:185], v[190:193], v[50:53]
	v_mfma_f32_16x16x32_bf16 v[38:41], v[174:177], v[198:201], v[38:41]
	v_mfma_f32_16x16x32_bf16 v[34:37], v[182:185], v[198:201], v[34:37]
	v_mfma_f32_16x16x32_bf16 v[22:25], v[174:177], v[206:209], v[22:25]
	v_mfma_f32_16x16x32_bf16 v[18:21], v[182:185], v[206:209], v[18:21]
	v_mfma_f32_16x16x32_bf16 v[6:9], v[174:177], v[214:217], v[6:9]
	v_mfma_f32_16x16x32_bf16 v[2:5], v[182:185], v[214:217], v[2:5]
	v_mfma_f32_16x16x32_bf16 v[54:57], v[178:181], v[194:197], v[54:57]
	v_mfma_f32_16x16x32_bf16 v[50:53], v[186:189], v[194:197], v[50:53]
	v_mfma_f32_16x16x32_bf16 v[38:41], v[178:181], v[202:205], v[38:41]
	v_mfma_f32_16x16x32_bf16 v[34:37], v[186:189], v[202:205], v[34:37]
	v_mfma_f32_16x16x32_bf16 v[22:25], v[178:181], v[210:213], v[22:25]
	v_mfma_f32_16x16x32_bf16 v[18:21], v[186:189], v[210:213], v[18:21]
	v_mfma_f32_16x16x32_bf16 v[6:9], v[178:181], v[218:221], v[6:9]
	v_mfma_f32_16x16x32_bf16 v[2:5], v[186:189], v[218:221], v[2:5]
	s_setprio 0
	s_barrier
	s_add_i32 s76, s76, 2
	s_add_u32 s54, s54, 0x100
	s_addc_u32 s55, s55, 0
	s_add_u32 s74, s74, 0x100
	s_addc_u32 s75, s75, 0
	s_cmp_gt_u32 s76, 13
	s_cbranch_scc0 .LBB0_1357
	s_branch .Lhb_exit_p10
.Lhb_B_p10:
	ds_read_b128 v[158:161], v152
	ds_read_b128 v[162:165], v152 offset:1024
	ds_read_b128 v[166:169], v152 offset:2048
	ds_read_b128 v[170:173], v152 offset:3072
	ds_read_b128 v[174:177], v153
	ds_read_b128 v[178:181], v153 offset:1024
	ds_read_b128 v[182:185], v153 offset:2048
	ds_read_b128 v[186:189], v153 offset:3072
	s_add_u32 s56, s54, 0xfffc0080
	s_addc_u32 s57, s55, -1
	s_cmp_eq_u32 s76, 12
	s_cselect_b32 s59, s45, s57
	s_cselect_b32 s58, s51, s56
	s_cselect_b32 s57, s43, s75
	s_cselect_b32 s56, s53, s74
	v_lshl_add_u64 v[148:149], s[54:55], 0, v[140:141]
	s_add_i32 m0, s61, 0xc000
	ds_read_b128 v[190:193], v154
	ds_read_b128 v[194:197], v154 offset:1024
	ds_read_b128 v[198:201], v154 offset:2048
	ds_read_b128 v[202:205], v154 offset:3072
	ds_read_b128 v[206:209], v154 offset:4096
	ds_read_b128 v[210:213], v154 offset:5120
	ds_read_b128 v[214:217], v154 offset:6144
	ds_read_b128 v[218:221], v154 offset:7168
	global_load_lds_dwordx4 v[148:149], off
	v_lshl_add_u64 v[148:149], s[54:55], 0, v[142:143]
	s_add_i32 m0, s61, 0xe000
	s_nop 0
	global_load_lds_dwordx4 v[148:149], off
	s_waitcnt vmcnt(8)
	s_waitcnt lgkmcnt(0)
	s_setprio 1
	s_barrier
	v_mfma_f32_16x16x32_bf16 v[126:129], v[158:161], v[190:193], v[126:129]
	v_mfma_f32_16x16x32_bf16 v[122:125], v[166:169], v[190:193], v[122:125]
	v_mfma_f32_16x16x32_bf16 v[110:113], v[158:161], v[198:201], v[110:113]
	v_mfma_f32_16x16x32_bf16 v[106:109], v[166:169], v[198:201], v[106:109]
	v_mfma_f32_16x16x32_bf16 v[94:97], v[158:161], v[206:209], v[94:97]
	v_mfma_f32_16x16x32_bf16 v[90:93], v[166:169], v[206:209], v[90:93]
	v_mfma_f32_16x16x32_bf16 v[78:81], v[158:161], v[214:217], v[78:81]
	v_mfma_f32_16x16x32_bf16 v[74:77], v[166:169], v[214:217], v[74:77]
	v_mfma_f32_16x16x32_bf16 v[126:129], v[162:165], v[194:197], v[126:129]
	v_mfma_f32_16x16x32_bf16 v[122:125], v[170:173], v[194:197], v[122:125]
	v_mfma_f32_16x16x32_bf16 v[110:113], v[162:165], v[202:205], v[110:113]
	v_mfma_f32_16x16x32_bf16 v[106:109], v[170:173], v[202:205], v[106:109]
	v_mfma_f32_16x16x32_bf16 v[94:97], v[162:165], v[210:213], v[94:97]
	v_mfma_f32_16x16x32_bf16 v[90:93], v[170:173], v[210:213], v[90:93]
	v_mfma_f32_16x16x32_bf16 v[78:81], v[162:165], v[218:221], v[78:81]
	v_mfma_f32_16x16x32_bf16 v[74:77], v[170:173], v[218:221], v[74:77]
	s_setprio 0
	s_setprio 1
	v_mfma_f32_16x16x32_bf16 v[118:121], v[174:177], v[190:193], v[118:121]
	v_mfma_f32_16x16x32_bf16 v[114:117], v[182:185], v[190:193], v[114:117]
	v_mfma_f32_16x16x32_bf16 v[102:105], v[174:177], v[198:201], v[102:105]
	v_mfma_f32_16x16x32_bf16 v[98:101], v[182:185], v[198:201], v[98:101]
	v_mfma_f32_16x16x32_bf16 v[86:89], v[174:177], v[206:209], v[86:89]
	v_mfma_f32_16x16x32_bf16 v[82:85], v[182:185], v[206:209], v[82:85]
	v_mfma_f32_16x16x32_bf16 v[70:73], v[174:177], v[214:217], v[70:73]
	v_mfma_f32_16x16x32_bf16 v[66:69], v[182:185], v[214:217], v[66:69]
	v_mfma_f32_16x16x32_bf16 v[118:121], v[178:181], v[194:197], v[118:121]
	v_mfma_f32_16x16x32_bf16 v[114:117], v[186:189], v[194:197], v[114:117]
	v_mfma_f32_16x16x32_bf16 v[102:105], v[178:181], v[202:205], v[102:105]
	v_mfma_f32_16x16x32_bf16 v[98:101], v[186:189], v[202:205], v[98:101]
	v_mfma_f32_16x16x32_bf16 v[86:89], v[178:181], v[210:213], v[86:89]
	v_mfma_f32_16x16x32_bf16 v[82:85], v[186:189], v[210:213], v[82:85]
	v_mfma_f32_16x16x32_bf16 v[70:73], v[178:181], v[218:221], v[70:73]
	v_mfma_f32_16x16x32_bf16 v[66:69], v[186:189], v[218:221], v[66:69]
	s_setprio 0
	s_add_i32 s77, s71, s60
	v_lshl_add_u64 v[148:149], s[56:57], 0, v[132:133]
	s_mov_b32 m0, s77
	ds_read_b128 v[190:193], v154 offset:16384
	ds_read_b128 v[194:197], v154 offset:17408
	ds_read_b128 v[198:201], v154 offset:18432
	ds_read_b128 v[202:205], v154 offset:19456
	ds_read_b128 v[206:209], v154 offset:20480
	ds_read_b128 v[210:213], v154 offset:21504
	ds_read_b128 v[214:217], v154 offset:22528
	ds_read_b128 v[218:221], v154 offset:23552
	global_load_lds_dwordx4 v[148:149], off
	s_add_i32 m0, s77, 0x2000
	s_add_u32 s78, s56, 0x40000
	v_lshl_add_u64 v[222:223], s[56:57], 0, v[136:137]
	s_addc_u32 s79, s57, 0
	s_add_i32 s77, s72, s60
	global_load_lds_dwordx4 v[222:223], off
	v_lshl_add_u64 v[224:225], s[78:79], 0, v[132:133]
	s_mov_b32 m0, s77
	v_lshl_add_u64 v[226:227], s[58:59], 0, v[134:135]
	global_load_lds_dwordx4 v[224:225], off
	v_lshl_add_u64 v[224:225], s[78:79], 0, v[136:137]
	s_add_i32 m0, s77, 0x2000
	s_nop 0
	global_load_lds_dwordx4 v[224:225], off
	v_lshl_add_u64 v[224:225], s[58:59], 0, v[130:131]
	s_mov_b32 m0, s61
	s_nop 0
	global_load_lds_dwordx4 v[224:225], off
	s_mov_b32 m0, s62
	s_nop 0
	global_load_lds_dwordx4 v[226:227], off
	s_waitcnt vmcnt(8)
	s_waitcnt lgkmcnt(0)
	s_setprio 1
	s_barrier
	v_mfma_f32_16x16x32_bf16 v[62:65], v[158:161], v[190:193], v[62:65]
	v_mfma_f32_16x16x32_bf16 v[58:61], v[166:169], v[190:193], v[58:61]
	v_mfma_f32_16x16x32_bf16 v[46:49], v[158:161], v[198:201], v[46:49]
	v_mfma_f32_16x16x32_bf16 v[42:45], v[166:169], v[198:201], v[42:45]
	v_mfma_f32_16x16x32_bf16 v[30:33], v[158:161], v[206:209], v[30:33]
	v_mfma_f32_16x16x32_bf16 v[26:29], v[166:169], v[206:209], v[26:29]
	v_mfma_f32_16x16x32_bf16 v[14:17], v[158:161], v[214:217], v[14:17]
	v_mfma_f32_16x16x32_bf16 v[10:13], v[166:169], v[214:217], v[10:13]
	v_mfma_f32_16x16x32_bf16 v[62:65], v[162:165], v[194:197], v[62:65]
	v_mfma_f32_16x16x32_bf16 v[58:61], v[170:173], v[194:197], v[58:61]
	v_mfma_f32_16x16x32_bf16 v[46:49], v[162:165], v[202:205], v[46:49]
	v_mfma_f32_16x16x32_bf16 v[42:45], v[170:173], v[202:205], v[42:45]
	v_mfma_f32_16x16x32_bf16 v[30:33], v[162:165], v[210:213], v[30:33]
	v_mfma_f32_16x16x32_bf16 v[26:29], v[170:173], v[210:213], v[26:29]
	v_mfma_f32_16x16x32_bf16 v[14:17], v[162:165], v[218:221], v[14:17]
	v_mfma_f32_16x16x32_bf16 v[10:13], v[170:173], v[218:221], v[10:13]
	s_setprio 0
	s_setprio 1
	v_mfma_f32_16x16x32_bf16 v[54:57], v[174:177], v[190:193], v[54:57]
	v_mfma_f32_16x16x32_bf16 v[50:53], v[182:185], v[190:193], v[50:53]
	v_mfma_f32_16x16x32_bf16 v[38:41], v[174:177], v[198:201], v[38:41]
	v_mfma_f32_16x16x32_bf16 v[34:37], v[182:185], v[198:201], v[34:37]
	v_mfma_f32_16x16x32_bf16 v[22:25], v[174:177], v[206:209], v[22:25]
	v_mfma_f32_16x16x32_bf16 v[18:21], v[182:185], v[206:209], v[18:21]
	v_mfma_f32_16x16x32_bf16 v[6:9], v[174:177], v[214:217], v[6:9]
	v_mfma_f32_16x16x32_bf16 v[2:5], v[182:185], v[214:217], v[2:5]
	v_mfma_f32_16x16x32_bf16 v[54:57], v[178:181], v[194:197], v[54:57]
	v_mfma_f32_16x16x32_bf16 v[50:53], v[186:189], v[194:197], v[50:53]
	v_mfma_f32_16x16x32_bf16 v[38:41], v[178:181], v[202:205], v[38:41]
	v_mfma_f32_16x16x32_bf16 v[34:37], v[186:189], v[202:205], v[34:37]
	v_mfma_f32_16x16x32_bf16 v[22:25], v[178:181], v[210:213], v[22:25]
	v_mfma_f32_16x16x32_bf16 v[18:21], v[186:189], v[210:213], v[18:21]
	v_mfma_f32_16x16x32_bf16 v[6:9], v[178:181], v[218:221], v[6:9]
	v_mfma_f32_16x16x32_bf16 v[2:5], v[186:189], v[218:221], v[2:5]
	s_setprio 0
	s_add_i32 s77, 0, 0x18000
	v_add_u32_e32 v157, s77, v151
	s_add_i32 s78, 0, 0x1c000
	ds_read_b128 v[158:161], v157
	ds_read_b128 v[162:165], v157 offset:1024
	ds_read_b128 v[166:169], v157 offset:2048
	ds_read_b128 v[170:173], v157 offset:3072
	v_add_u32_e32 v157, s78, v151
	ds_read_b128 v[174:177], v157
	ds_read_b128 v[178:181], v157 offset:1024
	ds_read_b128 v[182:185], v157 offset:2048
	ds_read_b128 v[186:189], v157 offset:3072
	s_add_u32 s58, s58, 0x40000
	s_addc_u32 s59, s59, 0
	s_mov_b32 m0, s63
	v_lshl_add_u64 v[228:229], s[58:59], 0, v[130:131]
	ds_read_b128 v[190:193], v154 offset:32768
	ds_read_b128 v[194:197], v154 offset:33792
	ds_read_b128 v[198:201], v154 offset:34816
	ds_read_b128 v[202:205], v154 offset:35840
	ds_read_b128 v[206:209], v154 offset:36864
	ds_read_b128 v[210:213], v154 offset:37888
	ds_read_b128 v[214:217], v154 offset:38912
	ds_read_b128 v[218:221], v154 offset:39936
	global_load_lds_dwordx4 v[228:229], off
	v_lshl_add_u64 v[228:229], s[58:59], 0, v[134:135]
	s_mov_b32 m0, s64
	s_nop 0
	global_load_lds_dwordx4 v[228:229], off
	s_waitcnt vmcnt(8)
	s_waitcnt lgkmcnt(0)
	s_setprio 1
	s_barrier
	v_mfma_f32_16x16x32_bf16 v[126:129], v[158:161], v[190:193], v[126:129]
	v_mfma_f32_16x16x32_bf16 v[122:125], v[166:169], v[190:193], v[122:125]
	v_mfma_f32_16x16x32_bf16 v[110:113], v[158:161], v[198:201], v[110:113]
	v_mfma_f32_16x16x32_bf16 v[106:109], v[166:169], v[198:201], v[106:109]
	v_mfma_f32_16x16x32_bf16 v[94:97], v[158:161], v[206:209], v[94:97]
	v_mfma_f32_16x16x32_bf16 v[90:93], v[166:169], v[206:209], v[90:93]
	v_mfma_f32_16x16x32_bf16 v[78:81], v[158:161], v[214:217], v[78:81]
	v_mfma_f32_16x16x32_bf16 v[74:77], v[166:169], v[214:217], v[74:77]
	v_mfma_f32_16x16x32_bf16 v[126:129], v[162:165], v[194:197], v[126:129]
	v_mfma_f32_16x16x32_bf16 v[122:125], v[170:173], v[194:197], v[122:125]
	v_mfma_f32_16x16x32_bf16 v[110:113], v[162:165], v[202:205], v[110:113]
	v_mfma_f32_16x16x32_bf16 v[106:109], v[170:173], v[202:205], v[106:109]
	v_mfma_f32_16x16x32_bf16 v[94:97], v[162:165], v[210:213], v[94:97]
	v_mfma_f32_16x16x32_bf16 v[90:93], v[170:173], v[210:213], v[90:93]
	v_mfma_f32_16x16x32_bf16 v[78:81], v[162:165], v[218:221], v[78:81]
	v_mfma_f32_16x16x32_bf16 v[74:77], v[170:173], v[218:221], v[74:77]
	s_setprio 0
	s_setprio 1
	v_mfma_f32_16x16x32_bf16 v[118:121], v[174:177], v[190:193], v[118:121]
	v_mfma_f32_16x16x32_bf16 v[114:117], v[182:185], v[190:193], v[114:117]
	v_mfma_f32_16x16x32_bf16 v[102:105], v[174:177], v[198:201], v[102:105]
	v_mfma_f32_16x16x32_bf16 v[98:101], v[182:185], v[198:201], v[98:101]
	v_mfma_f32_16x16x32_bf16 v[86:89], v[174:177], v[206:209], v[86:89]
	v_mfma_f32_16x16x32_bf16 v[82:85], v[182:185], v[206:209], v[82:85]
	v_mfma_f32_16x16x32_bf16 v[70:73], v[174:177], v[214:217], v[70:73]
	v_mfma_f32_16x16x32_bf16 v[66:69], v[182:185], v[214:217], v[66:69]
	v_mfma_f32_16x16x32_bf16 v[118:121], v[178:181], v[194:197], v[118:121]
	v_mfma_f32_16x16x32_bf16 v[114:117], v[186:189], v[194:197], v[114:117]
	v_mfma_f32_16x16x32_bf16 v[102:105], v[178:181], v[202:205], v[102:105]
	v_mfma_f32_16x16x32_bf16 v[98:101], v[186:189], v[202:205], v[98:101]
	v_mfma_f32_16x16x32_bf16 v[86:89], v[178:181], v[210:213], v[86:89]
	v_mfma_f32_16x16x32_bf16 v[82:85], v[186:189], v[210:213], v[82:85]
	v_mfma_f32_16x16x32_bf16 v[70:73], v[178:181], v[218:221], v[70:73]
	v_mfma_f32_16x16x32_bf16 v[66:69], v[186:189], v[218:221], v[66:69]
	s_setprio 0
	s_add_i32 s58, s77, s60
	v_lshl_add_u64 v[148:149], v[148:149], 0, s[24:25]
	s_mov_b32 m0, s58
	ds_read_b128 v[190:193], v154 offset:49152
	ds_read_b128 v[194:197], v154 offset:50176
	ds_read_b128 v[198:201], v154 offset:51200
	ds_read_b128 v[202:205], v154 offset:52224
	ds_read_b128 v[206:209], v154 offset:53248
	ds_read_b128 v[210:213], v154 offset:54272
	ds_read_b128 v[214:217], v154 offset:55296
	ds_read_b128 v[218:221], v154 offset:56320
	global_load_lds_dwordx4 v[148:149], off
	s_add_i32 m0, s58, 0x2000
	s_add_u32 s56, s56, 0x40080
	v_lshl_add_u64 v[148:149], v[222:223], 0, s[24:25]
	s_addc_u32 s57, s57, 0
	s_add_i32 s58, s78, s60
	global_load_lds_dwordx4 v[148:149], off
	v_lshl_add_u64 v[148:149], s[56:57], 0, v[132:133]
	s_mov_b32 m0, s58
	s_nop 0
	global_load_lds_dwordx4 v[148:149], off
	v_lshl_add_u64 v[148:149], s[56:57], 0, v[136:137]
	s_add_i32 m0, s58, 0x2000
	s_nop 0
	global_load_lds_dwordx4 v[148:149], off
	v_lshl_add_u64 v[148:149], v[224:225], 0, s[24:25]
	s_mov_b32 m0, s66
	s_nop 0
	global_load_lds_dwordx4 v[148:149], off
	v_lshl_add_u64 v[148:149], v[226:227], 0, s[24:25]
	s_mov_b32 m0, s67
	s_nop 0
	global_load_lds_dwordx4 v[148:149], off
	s_waitcnt vmcnt(8)
	s_waitcnt lgkmcnt(0)
	s_setprio 1
	s_barrier
	v_mfma_f32_16x16x32_bf16 v[62:65], v[158:161], v[190:193], v[62:65]
	v_mfma_f32_16x16x32_bf16 v[58:61], v[166:169], v[190:193], v[58:61]
	v_mfma_f32_16x16x32_bf16 v[46:49], v[158:161], v[198:201], v[46:49]
	v_mfma_f32_16x16x32_bf16 v[42:45], v[166:169], v[198:201], v[42:45]
	v_mfma_f32_16x16x32_bf16 v[30:33], v[158:161], v[206:209], v[30:33]
	v_mfma_f32_16x16x32_bf16 v[26:29], v[166:169], v[206:209], v[26:29]
	v_mfma_f32_16x16x32_bf16 v[14:17], v[158:161], v[214:217], v[14:17]
	v_mfma_f32_16x16x32_bf16 v[10:13], v[166:169], v[214:217], v[10:13]
	v_mfma_f32_16x16x32_bf16 v[62:65], v[162:165], v[194:197], v[62:65]
	v_mfma_f32_16x16x32_bf16 v[58:61], v[170:173], v[194:197], v[58:61]
	v_mfma_f32_16x16x32_bf16 v[46:49], v[162:165], v[202:205], v[46:49]
	v_mfma_f32_16x16x32_bf16 v[42:45], v[170:173], v[202:205], v[42:45]
	v_mfma_f32_16x16x32_bf16 v[30:33], v[162:165], v[210:213], v[30:33]
	v_mfma_f32_16x16x32_bf16 v[26:29], v[170:173], v[210:213], v[26:29]
	v_mfma_f32_16x16x32_bf16 v[14:17], v[162:165], v[218:221], v[14:17]
	v_mfma_f32_16x16x32_bf16 v[10:13], v[170:173], v[218:221], v[10:13]
	s_setprio 0
	s_setprio 1
	v_mfma_f32_16x16x32_bf16 v[54:57], v[174:177], v[190:193], v[54:57]
	v_mfma_f32_16x16x32_bf16 v[50:53], v[182:185], v[190:193], v[50:53]
	v_mfma_f32_16x16x32_bf16 v[38:41], v[174:177], v[198:201], v[38:41]
	v_mfma_f32_16x16x32_bf16 v[34:37], v[182:185], v[198:201], v[34:37]
	v_mfma_f32_16x16x32_bf16 v[22:25], v[174:177], v[206:209], v[22:25]
	v_mfma_f32_16x16x32_bf16 v[18:21], v[182:185], v[206:209], v[18:21]
	v_mfma_f32_16x16x32_bf16 v[6:9], v[174:177], v[214:217], v[6:9]
	v_mfma_f32_16x16x32_bf16 v[2:5], v[182:185], v[214:217], v[2:5]
	v_mfma_f32_16x16x32_bf16 v[54:57], v[178:181], v[194:197], v[54:57]
	v_mfma_f32_16x16x32_bf16 v[50:53], v[186:189], v[194:197], v[50:53]
	v_mfma_f32_16x16x32_bf16 v[38:41], v[178:181], v[202:205], v[38:41]
	v_mfma_f32_16x16x32_bf16 v[34:37], v[186:189], v[202:205], v[34:37]
	v_mfma_f32_16x16x32_bf16 v[22:25], v[178:181], v[210:213], v[22:25]
	v_mfma_f32_16x16x32_bf16 v[18:21], v[186:189], v[210:213], v[18:21]
	v_mfma_f32_16x16x32_bf16 v[6:9], v[178:181], v[218:221], v[6:9]
	v_mfma_f32_16x16x32_bf16 v[2:5], v[186:189], v[218:221], v[2:5]
	s_setprio 0
	s_add_i32 s76, s76, 2
	s_add_u32 s54, s54, 0x100
	s_addc_u32 s55, s55, 0
	s_add_u32 s74, s74, 0x100
	s_addc_u32 s75, s75, 0
	s_cmp_gt_u32 s76, 13
	s_cbranch_scc0 .Lhb_B_p10
.Lhb_exit_p10:
	s_and_b64 vcc, exec, s[26:27]
	s_cbranch_vccz .LBB0_1360
.LBB0_1360:
	v_lshl_add_u32 v148, s52, 8, v150
	v_ashrrev_i32_e32 v149, 31, v148
	v_lshl_add_u64 v[158:159], v[148:149], 2, s[12:13]
	global_load_dword v232, v[158:159], off offset:64
	global_load_dword v233, v[158:159], off offset:128
	global_load_dword v234, v[158:159], off offset:192
	global_load_dword v235, v[158:159], off offset:512
	global_load_dword v236, v[158:159], off offset:576
	global_load_dword v237, v[158:159], off offset:640
	global_load_dword v238, v[158:159], off offset:704
	global_load_dword v157, v[158:159], off
	v_and_b32_e32 v160, 64, v155
	v_xor_b32_e32 v162, 16, v155
	v_add_u32_e32 v164, 64, v160
	v_mov_b64_e32 v[158:159], s[14:15]
	v_cmp_lt_i32_e32 vcc, v162, v164
	v_mad_i64_i32 v[160:161], s[52:53], v148, s73, v[158:159]
	s_nop 0
	v_cndmask_b32_e32 v158, v155, v162, vcc
	v_xor_b32_e32 v163, 32, v155
	v_cmp_lt_i32_e32 vcc, v163, v164
	v_lshlrev_b32_e32 v158, 2, v158
	s_lshl_b32 s50, s50, 8
	s_ashr_i32 s51, s50, 31
	s_waitcnt vmcnt(0)
	v_fmamk_f32 v157, v157, 0x3a800000, v156
	v_rsq_f32_e32 v162, v157
	v_cndmask_b32_e32 v157, v155, v163, vcc
	v_lshlrev_b32_e32 v157, 2, v157
	v_pk_mul_f32 v[128:129], v[128:129], v[162:163] op_sel_hi:[1,0]
	v_pk_mul_f32 v[126:127], v[126:127], v[162:163] op_sel_hi:[1,0]
	v_pk_mul_f32 v[124:125], v[124:125], v[162:163] op_sel_hi:[1,0]
	v_pk_mul_f32 v[122:123], v[122:123], v[162:163] op_sel_hi:[1,0]
	v_pk_mul_f32 v[120:121], v[120:121], v[162:163] op_sel_hi:[1,0]
	v_pk_mul_f32 v[118:119], v[118:119], v[162:163] op_sel_hi:[1,0]
	v_pk_mul_f32 v[164:165], v[116:117], v[162:163] op_sel_hi:[1,0]
	v_pk_mul_f32 v[162:163], v[114:115], v[162:163] op_sel_hi:[1,0]
	v_mul_f32_e32 v159, v127, v127
	v_mul_f32_e32 v166, v129, v129
	v_mul_f32_e32 v167, v123, v123
	v_mul_f32_e32 v168, v125, v125
	v_cvt_pk_bf16_f32 v114, v126, v127
	v_cvt_pk_bf16_f32 v115, v128, v129
	v_cvt_pk_bf16_f32 v116, v122, v123
	v_cvt_pk_bf16_f32 v117, v124, v125
	v_mul_f32_e32 v123, v119, v119
	v_mul_f32_e32 v125, v121, v121
	v_mul_f32_e32 v127, v163, v163
	v_mul_f32_e32 v129, v165, v165
	v_fmac_f32_e32 v159, v126, v126
	v_fmac_f32_e32 v166, v128, v128
	v_fmac_f32_e32 v167, v122, v122
	v_fmac_f32_e32 v168, v124, v124
	v_fmac_f32_e32 v123, v118, v118
	v_fmac_f32_e32 v125, v120, v120
	v_fmac_f32_e32 v127, v162, v162
	v_fmac_f32_e32 v129, v164, v164
	v_add_f32_e32 v122, v159, v166
	v_add_f32_e32 v124, v167, v168
	v_add_f32_e32 v123, v123, v125
	v_add_f32_e32 v125, v127, v129
	v_add_f32_e32 v122, v122, v124
	v_add_f32_e32 v123, v123, v125
	v_add_f32_e32 v124, v122, v123
	ds_bpermute_b32 v125, v158, v124
	v_lshl_add_u64 v[122:123], s[50:51], 1, v[160:161]
	v_lshl_add_u64 v[122:123], v[122:123], 0, v[138:139]
	global_store_dwordx4 v[122:123], v[114:117], off
	s_waitcnt lgkmcnt(0)
	s_nop 0
	v_add_f32_e32 v114, v124, v125
	ds_bpermute_b32 v115, v157, v114
	v_cvt_pk_bf16_f32 v116, v118, v119
	v_cvt_pk_bf16_f32 v117, v120, v121
	v_cvt_pk_bf16_f32 v118, v162, v163
	v_cvt_pk_bf16_f32 v119, v164, v165
	global_store_dwordx4 v[122:123], v[116:119], off offset:256
	s_and_saveexec_b64 s[52:53], s[4:5]
	s_cbranch_execz .LBB0_1362
	v_lshl_add_u64 v[116:117], v[148:149], 2, s[16:17]
	s_waitcnt lgkmcnt(0)
	v_add_f32_e32 v114, v114, v115
	global_atomic_add_f32 v[116:117], v114, off

.LBB0_1376:
	s_or_b64 exec, exec, s[50:51]
	s_andn2_b64 vcc, exec, s[6:7]
	s_mov_b64 s[6:7], -1
	s_cbranch_vccnz .LBB0_1353
	s_andn2_b64 vcc, exec, s[10:11]
	s_cbranch_vccnz .LBB0_1352
	s_branch .LBB0_1352

.LBB0_1473:
	s_andn2_b64 vcc, exec, s[24:25]
	s_cbranch_vccnz .LBB0_1525
	s_waitcnt lgkmcnt(0)
	v_ashrrev_i32_e32 v3, 31, v10
	v_lshrrev_b32_e32 v3, 26, v3
	v_add_u32_e32 v3, v10, v3
	v_ashrrev_i32_e32 v11, 6, v3
	v_bfe_i32 v3, v10, 27, 1
	v_lshlrev_b32_e32 v2, 4, v10
	v_lshrrev_b32_e32 v3, 22, v3
	v_add_u32_e32 v3, v2, v3
	v_and_b32_e32 v3, 0xfffffc00, v3
	v_sub_u32_e32 v3, v2, v3
	v_lshrrev_b32_e32 v4, 4, v3
	v_bitop3_b32 v3, v4, v3, 32 bitop3:0x6c
	v_ashrrev_i32_e32 v5, 31, v3
	v_lshrrev_b32_e32 v5, 26, v5
	v_lshlrev_b32_e32 v4, 3, v11
	v_add_u32_e32 v5, v3, v5
	v_and_b32_e32 v4, -16, v4
	v_ashrrev_i32_e32 v13, 6, v5
	v_and_b32_e32 v5, 0xc0, v5
	v_add_u32_e32 v4, v13, v4
	v_lshlrev_b32_e32 v6, 5, v11
	v_sub_u32_e32 v3, v3, v5
	v_mov_b32_e32 v5, 1
	s_load_dwordx2 s[24:25], s[14:15], 0xa8
	s_load_dwordx2 s[26:27], s[16:17], 0xa8
	v_and_b32_e32 v12, 32, v6
	v_ashrrev_i16_sdwa v3, v5, sext(v3) dst_sel:DWORD dst_unused:UNUSED_PAD src0_sel:DWORD src1_sel:BYTE_0
	v_lshlrev_b32_e32 v6, 1, v4
	v_lshrrev_b32_e32 v7, 2, v4
	v_and_b32_e32 v8, 3, v13
	s_mov_b32 s14, 0xffffe0
	v_bfe_i32 v14, v3, 0, 16
	v_and_b32_e32 v6, 24, v6
	v_and_b32_e32 v7, 4, v7
	v_and_or_b32 v8, v4, s14, v8
	s_movk_i32 s46, 0x300
	v_add_u32_e32 v3, v12, v14
	v_or3_b32 v6, v8, v7, v6
	v_mul_lo_u32 v4, v4, s46
	v_add_lshl_u32 v130, v3, v4, 1
	v_mul_u32_u24_e32 v4, 0x300, v6
	v_add_u32_e32 v2, 0x2000, v2
	v_add_lshl_u32 v132, v4, v3, 1
	v_ashrrev_i32_e32 v3, 31, v2
	v_lshrrev_b32_e32 v3, 22, v3
	v_add_u32_e32 v3, v2, v3
	v_ashrrev_i32_e32 v15, 10, v3
	v_mul_i32_i24_e32 v3, 0x400, v15
	v_sub_u32_e32 v2, v2, v3
	v_lshrrev_b32_e32 v3, 4, v2
	v_bitop3_b32 v2, v3, v2, 32 bitop3:0x6c
	s_waitcnt lgkmcnt(0)
	s_add_u32 s3, s24, 0x10400000
	v_ashrrev_i32_e32 v4, 31, v2
	s_addc_u32 s23, s25, 0
	v_lshrrev_b32_e32 v4, 26, v4
	s_add_u32 s29, s26, 0x5180000
	v_lshlrev_b32_e32 v3, 3, v15
	v_add_u32_e32 v4, v2, v4
	s_addc_u32 s31, s27, 0
	s_ashr_i32 s42, s44, 6
	v_and_b32_e32 v3, -16, v3
	v_ashrrev_i32_e32 v16, 6, v4
	v_lshlrev_b32_e32 v6, 5, v15
	v_and_b32_e32 v4, 0xc0, v4
	v_add_u32_e32 v3, v16, v3
	v_and_b32_e32 v17, 32, v6
	v_sub_u32_e32 v2, v2, v4
	v_and_b32_e32 v6, 3, v16
	s_ashr_i32 s45, s44, 8
	s_lshl_b32 s56, s42, 10
	s_mul_i32 s15, s77, 0x60000
	v_ashrrev_i16_sdwa v2, v5, sext(v2) dst_sel:DWORD dst_unused:UNUSED_PAD src0_sel:DWORD src1_sel:BYTE_0
	v_lshlrev_b32_e32 v4, 1, v3
	v_lshrrev_b32_e32 v5, 2, v3
	v_and_or_b32 v6, v3, s14, v6
	s_mul_hi_i32 s14, s77, 0x60000
	s_add_u32 s52, s29, s15
	v_bfe_i32 v18, v2, 0, 16
	v_and_b32_e32 v4, 24, v4
	v_and_b32_e32 v5, 4, v5
	s_addc_u32 s53, s31, s14
	s_add_i32 s57, s56, 0
	v_add_u32_e32 v2, v17, v18
	v_or3_b32 v4, v6, v5, v4
	v_mul_lo_u32 v3, v3, s46
	s_add_i32 m0, s57, 0x10000
	v_add_lshl_u32 v134, v2, v3, 1
	v_mul_u32_u24_e32 v3, 0x300, v4
	global_load_lds_dwordx4 v132, s[52:53]
	s_add_i32 m0, s57, 0x12000
	v_add_lshl_u32 v136, v3, v2, 1
	s_add_u32 s14, s52, 0x30000
	global_load_lds_dwordx4 v136, s[52:53]
	s_addc_u32 s15, s53, 0
	s_add_i32 m0, s57, 0x14000
	s_mul_i32 s17, s78, 0x60000
	global_load_lds_dwordx4 v132, s[14:15]
	s_add_i32 m0, s57, 0x16000
	s_mul_hi_i32 s16, s78, 0x60000
	s_add_u32 s50, s3, s17
	s_addc_u32 s51, s23, s16
	s_add_i32 s58, s57, 0x2000
	global_load_lds_dwordx4 v136, s[14:15]
	s_mov_b32 m0, s57
	s_add_u32 s14, s50, 0x30000
	global_load_lds_dwordx4 v130, s[50:51]
	s_mov_b32 m0, s58
	s_addc_u32 s15, s51, 0
	s_add_i32 s59, s57, 0x4000
	global_load_lds_dwordx4 v134, s[50:51]
	s_mov_b32 m0, s59
	s_add_i32 s60, s57, 0x6000
	global_load_lds_dwordx4 v130, s[14:15]
	s_mov_b32 m0, s60
	v_mov_b32_e32 v139, 0
	global_load_lds_dwordx4 v134, s[14:15]
	s_load_dwordx2 s[14:15], s[4:5], 0xa8
	s_load_dwordx2 s[16:17], s[6:7], 0xa8
	s_nop 0
	s_load_dwordx2 s[6:7], s[10:11], 0xa8
	s_load_dwordx2 s[4:5], s[12:13], 0xa8
	v_mov_b32_e32 v133, v139
	v_mov_b32_e32 v137, v139
	v_mov_b32_e32 v131, v139
	v_mov_b32_e32 v135, v139
	s_cmp_eq_u32 s45, 1
	s_mov_b32 s11, 0
	v_lshl_add_u64 v[8:9], s[52:53], 0, v[132:133]
	v_lshl_add_u64 v[6:7], s[52:53], 0, v[136:137]
	v_lshl_add_u64 v[2:3], s[50:51], 0, v[130:131]
	s_cselect_b64 s[12:13], -1, 0
	s_cmp_lg_u32 s45, 1
	v_lshl_add_u64 v[4:5], s[50:51], 0, v[134:135]
	s_cbranch_scc1 .LBB0_1476
.LBB0_1476:
	s_waitcnt lgkmcnt(0)
	s_add_u32 s14, s14, 0xc0000
	s_addc_u32 s15, s15, 0
	s_add_u32 s16, s16, 0xa400000
	s_addc_u32 s17, s17, 0
	s_add_u32 s24, s6, 0xe400000
	s_addc_u32 s25, s7, 0
	s_add_u32 s26, s4, 0x200000
	s_addc_u32 s27, s5, 0
	s_and_b32 s6, s42, 3
	s_mov_b64 s[42:43], 0x80
	s_add_i32 m0, s57, 0x18000
	v_lshl_add_u64 v[8:9], v[8:9], 0, s[42:43]
	s_lshl_b32 s7, s45, 13
	s_lshl_b32 s10, s6, 12
	s_waitcnt vmcnt(2)
	s_barrier
	global_load_lds_dwordx4 v[8:9], off
	v_lshl_add_u64 v[6:7], v[6:7], 0, s[42:43]
	s_add_i32 m0, s57, 0x1a000
	s_add_i32 s61, s57, 0x8000
	s_add_i32 s62, s57, 0xa000
	global_load_lds_dwordx4 v[6:7], off
	v_lshl_add_u64 v[2:3], v[2:3], 0, s[42:43]
	s_mov_b32 m0, s61
	s_add_u32 s4, s52, 0x30080
	global_load_lds_dwordx4 v[2:3], off
	v_lshl_add_u64 v[2:3], v[4:5], 0, s[42:43]
	s_mov_b32 m0, s62
	s_addc_u32 s5, s53, 0
	global_load_lds_dwordx4 v[2:3], off
	s_add_i32 m0, s57, 0x1c000
	v_lshl_add_u64 v[2:3], s[4:5], 0, v[132:133]
	global_load_lds_dwordx4 v[2:3], off
	v_lshl_add_u64 v[2:3], s[4:5], 0, v[136:137]
	s_add_i32 m0, s57, 0x1e000
	s_cmpk_lt_u32 s44, 0x100
	global_load_lds_dwordx4 v[2:3], off
	v_lshrrev_b32_e32 v3, 1, v10
	v_and_b32_e32 v140, 24, v3
	v_and_b32_e32 v2, 15, v10
	v_lshlrev_b32_e32 v3, 1, v140
	v_lshl_or_b32 v141, s45, 6, v2
	v_lshl_or_b32 v2, v2, 6, v3
	v_lshlrev_b32_e32 v3, 2, v10
	v_and_b32_e32 v3, 32, v3
	v_bitop3_b32 v4, v2, s7, v3 bitop3:0xde
	v_bitop3_b32 v143, v2, s10, v3 bitop3:0xde
	s_cselect_b64 s[44:45], -1, 0
	v_lshl_or_b32 v142, s6, 5, v140
	s_lshl_b32 s6, s6, 6
	v_lshrrev_b32_e32 v3, 1, v11
	v_mul_lo_u32 v2, v13, s46
	s_movk_i32 s10, 0x3000
	s_or_b32 s63, s6, 0xfffffc00
	v_mad_u64_u32 v[2:3], s[6:7], v3, s10, v[2:3]
	v_or_b32_e32 v2, v2, v12
	v_add_lshl_u32 v138, v2, v14, 1
	v_lshrrev_b32_e32 v3, 1, v15
	v_mul_lo_u32 v2, v16, s46
	v_mad_u64_u32 v[2:3], s[6:7], v3, s10, v[2:3]
	s_mov_b64 s[4:5], 0x30080
	s_waitcnt vmcnt(6)
	v_or_b32_e32 v2, v2, v17
	v_lshl_add_u64 v[144:145], v[138:139], 0, s[4:5]
	v_add_lshl_u32 v138, v2, v18, 1
	s_add_i32 s68, 0, 0x10000
	s_add_i32 s69, 0, 0x14000
	s_ashr_i32 s64, s38, 31
	s_mov_b32 s65, s38
	s_ashr_i32 s66, s2, 31
	v_lshl_add_u64 v[146:147], v[138:139], 0, s[4:5]
	v_mov_b64_e32 v[148:149], 0x300
	v_mov_b64_e32 v[150:151], 0x2ff
	s_movk_i32 s67, 0x61
	v_add_u32_e32 v157, s68, v143
	v_add_u32_e32 v158, s69, v143
	v_add_u32_e32 v159, 0, v4
	v_mov_b32_e32 v160, 0x358637bd
	s_mov_b32 s70, 0xf9e0
	s_mov_b32 s71, 0xfbe0
	s_mov_b32 s72, 0xfde0
	s_mov_b32 s73, 0xffe0
	s_mov_b32 s74, 0
	s_barrier
	s_branch .LBB0_1479

.LBB0_1485:
	s_add_u32 s10, s52, 0x100
	v_mov_b32_e32 v2, 0
	s_addc_u32 s79, s53, 0
	s_mov_b32 s80, -2
	v_mov_b32_e32 v3, v2
	v_mov_b32_e32 v4, v2
	v_mov_b32_e32 v5, v2
	v_mov_b32_e32 v6, v2
	v_mov_b32_e32 v7, v2
	v_mov_b32_e32 v8, v2
	v_mov_b32_e32 v9, v2
	v_mov_b32_e32 v18, v2
	v_mov_b32_e32 v19, v2
	v_mov_b32_e32 v20, v2
	v_mov_b32_e32 v21, v2
	v_mov_b32_e32 v22, v2
	v_mov_b32_e32 v23, v2
	v_mov_b32_e32 v24, v2
	v_mov_b32_e32 v25, v2
	v_mov_b32_e32 v34, v2
	v_mov_b32_e32 v35, v2
	v_mov_b32_e32 v36, v2
	v_mov_b32_e32 v37, v2
	v_mov_b32_e32 v38, v2
	v_mov_b32_e32 v39, v2
	v_mov_b32_e32 v40, v2
	v_mov_b32_e32 v41, v2
	v_mov_b32_e32 v50, v2
	v_mov_b32_e32 v51, v2
	v_mov_b32_e32 v52, v2
	v_mov_b32_e32 v53, v2
	v_mov_b32_e32 v54, v2
	v_mov_b32_e32 v55, v2
	v_mov_b32_e32 v56, v2
	v_mov_b32_e32 v57, v2
	v_mov_b32_e32 v10, v2
	v_mov_b32_e32 v11, v2
	v_mov_b32_e32 v12, v2
	v_mov_b32_e32 v13, v2
	v_mov_b32_e32 v14, v2
	v_mov_b32_e32 v15, v2
	v_mov_b32_e32 v16, v2
	v_mov_b32_e32 v17, v2
	v_mov_b32_e32 v26, v2
	v_mov_b32_e32 v27, v2
	v_mov_b32_e32 v28, v2
	v_mov_b32_e32 v29, v2
	v_mov_b32_e32 v30, v2
	v_mov_b32_e32 v31, v2
	v_mov_b32_e32 v32, v2
	v_mov_b32_e32 v33, v2
	v_mov_b32_e32 v42, v2
	v_mov_b32_e32 v43, v2
	v_mov_b32_e32 v44, v2
	v_mov_b32_e32 v45, v2
	v_mov_b32_e32 v46, v2
	v_mov_b32_e32 v47, v2
	v_mov_b32_e32 v48, v2
	v_mov_b32_e32 v49, v2
	v_mov_b32_e32 v58, v2
	v_mov_b32_e32 v59, v2
	v_mov_b32_e32 v60, v2
	v_mov_b32_e32 v61, v2
	v_mov_b32_e32 v62, v2
	v_mov_b32_e32 v63, v2
	v_mov_b32_e32 v64, v2
	v_mov_b32_e32 v65, v2
	v_mov_b32_e32 v66, v2
	v_mov_b32_e32 v67, v2
	v_mov_b32_e32 v68, v2
	v_mov_b32_e32 v69, v2
	v_mov_b32_e32 v70, v2
	v_mov_b32_e32 v71, v2
	v_mov_b32_e32 v72, v2
	v_mov_b32_e32 v73, v2
	s_waitcnt vmcnt(0)
	v_mov_b32_e32 v82, v2
	v_mov_b32_e32 v83, v2
	v_mov_b32_e32 v84, v2
	v_mov_b32_e32 v85, v2
	v_mov_b32_e32 v86, v2
	v_mov_b32_e32 v87, v2
	v_mov_b32_e32 v88, v2
	v_mov_b32_e32 v89, v2
	v_mov_b32_e32 v98, v2
	v_mov_b32_e32 v99, v2
	v_mov_b32_e32 v100, v2
	v_mov_b32_e32 v101, v2
	v_mov_b32_e32 v102, v2
	v_mov_b32_e32 v103, v2
	v_mov_b32_e32 v104, v2
	v_mov_b32_e32 v105, v2
	v_mov_b32_e32 v114, v2
	v_mov_b32_e32 v115, v2
	v_mov_b32_e32 v116, v2
	v_mov_b32_e32 v117, v2
	v_mov_b32_e32 v118, v2
	v_mov_b32_e32 v119, v2
	v_mov_b32_e32 v120, v2
	v_mov_b32_e32 v121, v2
	v_mov_b32_e32 v74, v2
	v_mov_b32_e32 v75, v2
	v_mov_b32_e32 v76, v2
	v_mov_b32_e32 v77, v2
	v_mov_b32_e32 v78, v2
	v_mov_b32_e32 v79, v2
	v_mov_b32_e32 v80, v2
	v_mov_b32_e32 v81, v2
	v_mov_b32_e32 v90, v2
	v_mov_b32_e32 v91, v2
	v_mov_b32_e32 v92, v2
	v_mov_b32_e32 v93, v2
	v_mov_b32_e32 v94, v2
	v_mov_b32_e32 v95, v2
	v_mov_b32_e32 v96, v2
	v_mov_b32_e32 v97, v2
	v_mov_b32_e32 v106, v2
	v_mov_b32_e32 v107, v2
	v_mov_b32_e32 v108, v2
	v_mov_b32_e32 v109, v2
	v_mov_b32_e32 v110, v2
	v_mov_b32_e32 v111, v2
	v_mov_b32_e32 v112, v2
	v_mov_b32_e32 v113, v2
	v_mov_b32_e32 v122, v2
	v_mov_b32_e32 v123, v2
	v_mov_b32_e32 v124, v2
	v_mov_b32_e32 v125, v2
	v_mov_b32_e32 v126, v2
	v_mov_b32_e32 v127, v2
	v_mov_b32_e32 v128, v2
	v_mov_b32_e32 v129, v2
	s_cmp_eq_u64 s[44:45], 0
	s_cbranch_scc1 .Lhb_B_p11
.LBB0_1486:
	ds_read_b128 v[152:155], v157
	ds_read_b128 v[162:165], v157 offset:1024
	ds_read_b128 v[166:169], v157 offset:2048
	ds_read_b128 v[170:173], v157 offset:3072
	ds_read_b128 v[174:177], v158
	ds_read_b128 v[178:181], v158 offset:1024
	ds_read_b128 v[182:185], v158 offset:2048
	ds_read_b128 v[186:189], v158 offset:3072
	s_add_u32 s6, s50, 0x100
	s_addc_u32 s7, s51, 0
	s_cmp_eq_u32 s80, 8
	s_cselect_b32 s55, s47, s7
	s_cselect_b32 s54, s46, s6
	s_cselect_b32 s53, s49, s79
	s_cselect_b32 s52, s48, s10
	v_lshl_add_u64 v[222:223], s[50:51], 0, v[144:145]
	s_add_i32 m0, s57, 0xc000
	ds_read_b128 v[190:193], v159
	ds_read_b128 v[194:197], v159 offset:1024
	ds_read_b128 v[198:201], v159 offset:2048
	ds_read_b128 v[202:205], v159 offset:3072
	ds_read_b128 v[206:209], v159 offset:4096
	ds_read_b128 v[210:213], v159 offset:5120
	ds_read_b128 v[214:217], v159 offset:6144
	ds_read_b128 v[218:221], v159 offset:7168
	global_load_lds_dwordx4 v[222:223], off
	v_lshl_add_u64 v[222:223], s[50:51], 0, v[146:147]
	s_add_i32 m0, s57, 0xe000
	s_nop 0
	global_load_lds_dwordx4 v[222:223], off
	s_waitcnt vmcnt(8)
	s_waitcnt lgkmcnt(0)
	s_setprio 1
	v_mfma_f32_16x16x32_bf16 v[126:129], v[152:155], v[190:193], v[126:129]
	v_mfma_f32_16x16x32_bf16 v[122:125], v[166:169], v[190:193], v[122:125]
	v_mfma_f32_16x16x32_bf16 v[110:113], v[152:155], v[198:201], v[110:113]
	v_mfma_f32_16x16x32_bf16 v[106:109], v[166:169], v[198:201], v[106:109]
	v_mfma_f32_16x16x32_bf16 v[94:97], v[152:155], v[206:209], v[94:97]
	v_mfma_f32_16x16x32_bf16 v[90:93], v[166:169], v[206:209], v[90:93]
	v_mfma_f32_16x16x32_bf16 v[78:81], v[152:155], v[214:217], v[78:81]
	v_mfma_f32_16x16x32_bf16 v[74:77], v[166:169], v[214:217], v[74:77]
	v_mfma_f32_16x16x32_bf16 v[126:129], v[162:165], v[194:197], v[126:129]
	v_mfma_f32_16x16x32_bf16 v[122:125], v[170:173], v[194:197], v[122:125]
	v_mfma_f32_16x16x32_bf16 v[110:113], v[162:165], v[202:205], v[110:113]
	v_mfma_f32_16x16x32_bf16 v[106:109], v[170:173], v[202:205], v[106:109]
	v_mfma_f32_16x16x32_bf16 v[94:97], v[162:165], v[210:213], v[94:97]
	v_mfma_f32_16x16x32_bf16 v[90:93], v[170:173], v[210:213], v[90:93]
	v_mfma_f32_16x16x32_bf16 v[78:81], v[162:165], v[218:221], v[78:81]
	v_mfma_f32_16x16x32_bf16 v[74:77], v[170:173], v[218:221], v[74:77]
	s_setprio 0
	s_setprio 1
	v_mfma_f32_16x16x32_bf16 v[118:121], v[174:177], v[190:193], v[118:121]
	v_mfma_f32_16x16x32_bf16 v[114:117], v[182:185], v[190:193], v[114:117]
	v_mfma_f32_16x16x32_bf16 v[102:105], v[174:177], v[198:201], v[102:105]
	v_mfma_f32_16x16x32_bf16 v[98:101], v[182:185], v[198:201], v[98:101]
	v_mfma_f32_16x16x32_bf16 v[86:89], v[174:177], v[206:209], v[86:89]
	v_mfma_f32_16x16x32_bf16 v[82:85], v[182:185], v[206:209], v[82:85]
	v_mfma_f32_16x16x32_bf16 v[70:73], v[174:177], v[214:217], v[70:73]
	v_mfma_f32_16x16x32_bf16 v[66:69], v[182:185], v[214:217], v[66:69]
	v_mfma_f32_16x16x32_bf16 v[118:121], v[178:181], v[194:197], v[118:121]
	v_mfma_f32_16x16x32_bf16 v[114:117], v[186:189], v[194:197], v[114:117]
	v_mfma_f32_16x16x32_bf16 v[102:105], v[178:181], v[202:205], v[102:105]
	v_mfma_f32_16x16x32_bf16 v[98:101], v[186:189], v[202:205], v[98:101]
	v_mfma_f32_16x16x32_bf16 v[86:89], v[178:181], v[210:213], v[86:89]
	v_mfma_f32_16x16x32_bf16 v[82:85], v[186:189], v[210:213], v[82:85]
	v_mfma_f32_16x16x32_bf16 v[70:73], v[178:181], v[218:221], v[70:73]
	v_mfma_f32_16x16x32_bf16 v[66:69], v[186:189], v[218:221], v[66:69]
	s_setprio 0
	s_barrier
	s_add_i32 s50, s68, s56
	v_lshl_add_u64 v[222:223], s[52:53], 0, v[132:133]
	s_mov_b32 m0, s50
	ds_read_b128 v[190:193], v159 offset:16384
	ds_read_b128 v[194:197], v159 offset:17408
	ds_read_b128 v[198:201], v159 offset:18432
	ds_read_b128 v[202:205], v159 offset:19456
	ds_read_b128 v[206:209], v159 offset:20480
	ds_read_b128 v[210:213], v159 offset:21504
	ds_read_b128 v[214:217], v159 offset:22528
	ds_read_b128 v[218:221], v159 offset:23552
	global_load_lds_dwordx4 v[222:223], off
	s_add_i32 m0, s50, 0x2000
	s_add_u32 s50, s52, 0x30000
	v_lshl_add_u64 v[224:225], s[52:53], 0, v[136:137]
	s_addc_u32 s51, s53, 0
	s_add_i32 s81, s69, s56
	global_load_lds_dwordx4 v[224:225], off
	v_lshl_add_u64 v[226:227], s[50:51], 0, v[132:133]
	s_mov_b32 m0, s81
	v_lshl_add_u64 v[228:229], s[54:55], 0, v[134:135]
	global_load_lds_dwordx4 v[226:227], off
	v_lshl_add_u64 v[226:227], s[50:51], 0, v[136:137]
	s_add_i32 m0, s81, 0x2000
	s_nop 0
	global_load_lds_dwordx4 v[226:227], off
	v_lshl_add_u64 v[226:227], s[54:55], 0, v[130:131]
	s_mov_b32 m0, s57
	s_nop 0
	global_load_lds_dwordx4 v[226:227], off
	s_mov_b32 m0, s58
	s_nop 0
	global_load_lds_dwordx4 v[228:229], off
	s_waitcnt vmcnt(8)
	s_waitcnt lgkmcnt(0)
	s_setprio 1
	v_mfma_f32_16x16x32_bf16 v[62:65], v[152:155], v[190:193], v[62:65]
	v_mfma_f32_16x16x32_bf16 v[58:61], v[166:169], v[190:193], v[58:61]
	v_mfma_f32_16x16x32_bf16 v[46:49], v[152:155], v[198:201], v[46:49]
	v_mfma_f32_16x16x32_bf16 v[42:45], v[166:169], v[198:201], v[42:45]
	v_mfma_f32_16x16x32_bf16 v[30:33], v[152:155], v[206:209], v[30:33]
	v_mfma_f32_16x16x32_bf16 v[26:29], v[166:169], v[206:209], v[26:29]
	v_mfma_f32_16x16x32_bf16 v[14:17], v[152:155], v[214:217], v[14:17]
	v_mfma_f32_16x16x32_bf16 v[10:13], v[166:169], v[214:217], v[10:13]
	v_mfma_f32_16x16x32_bf16 v[62:65], v[162:165], v[194:197], v[62:65]
	v_mfma_f32_16x16x32_bf16 v[58:61], v[170:173], v[194:197], v[58:61]
	v_mfma_f32_16x16x32_bf16 v[46:49], v[162:165], v[202:205], v[46:49]
	v_mfma_f32_16x16x32_bf16 v[42:45], v[170:173], v[202:205], v[42:45]
	v_mfma_f32_16x16x32_bf16 v[30:33], v[162:165], v[210:213], v[30:33]
	v_mfma_f32_16x16x32_bf16 v[26:29], v[170:173], v[210:213], v[26:29]
	v_mfma_f32_16x16x32_bf16 v[14:17], v[162:165], v[218:221], v[14:17]
	v_mfma_f32_16x16x32_bf16 v[10:13], v[170:173], v[218:221], v[10:13]
	s_setprio 0
	s_setprio 1
	v_mfma_f32_16x16x32_bf16 v[54:57], v[174:177], v[190:193], v[54:57]
	v_mfma_f32_16x16x32_bf16 v[50:53], v[182:185], v[190:193], v[50:53]
	v_mfma_f32_16x16x32_bf16 v[38:41], v[174:177], v[198:201], v[38:41]
	v_mfma_f32_16x16x32_bf16 v[34:37], v[182:185], v[198:201], v[34:37]
	v_mfma_f32_16x16x32_bf16 v[22:25], v[174:177], v[206:209], v[22:25]
	v_mfma_f32_16x16x32_bf16 v[18:21], v[182:185], v[206:209], v[18:21]
	v_mfma_f32_16x16x32_bf16 v[6:9], v[174:177], v[214:217], v[6:9]
	v_mfma_f32_16x16x32_bf16 v[2:5], v[182:185], v[214:217], v[2:5]
	v_mfma_f32_16x16x32_bf16 v[54:57], v[178:181], v[194:197], v[54:57]
	v_mfma_f32_16x16x32_bf16 v[50:53], v[186:189], v[194:197], v[50:53]
	v_mfma_f32_16x16x32_bf16 v[38:41], v[178:181], v[202:205], v[38:41]
	v_mfma_f32_16x16x32_bf16 v[34:37], v[186:189], v[202:205], v[34:37]
	v_mfma_f32_16x16x32_bf16 v[22:25], v[178:181], v[210:213], v[22:25]
	v_mfma_f32_16x16x32_bf16 v[18:21], v[186:189], v[210:213], v[18:21]
	v_mfma_f32_16x16x32_bf16 v[6:9], v[178:181], v[218:221], v[6:9]
	v_mfma_f32_16x16x32_bf16 v[2:5], v[186:189], v[218:221], v[2:5]
	s_setprio 0
	s_barrier
	s_add_i32 s81, 0, 0x18000
	v_add_u32_e32 v138, s81, v143
	s_add_i32 s82, 0, 0x1c000
	ds_read_b128 v[152:155], v138
	ds_read_b128 v[162:165], v138 offset:1024
	ds_read_b128 v[166:169], v138 offset:2048
	ds_read_b128 v[170:173], v138 offset:3072
	v_add_u32_e32 v138, s82, v143
	ds_read_b128 v[174:177], v138
	ds_read_b128 v[178:181], v138 offset:1024
	ds_read_b128 v[182:185], v138 offset:2048
	ds_read_b128 v[186:189], v138 offset:3072
	s_add_u32 s50, s54, 0x30000
	s_addc_u32 s51, s55, 0
	s_mov_b32 m0, s59
	v_lshl_add_u64 v[230:231], s[50:51], 0, v[130:131]
	ds_read_b128 v[190:193], v159 offset:32768
	ds_read_b128 v[194:197], v159 offset:33792
	ds_read_b128 v[198:201], v159 offset:34816
	ds_read_b128 v[202:205], v159 offset:35840
	ds_read_b128 v[206:209], v159 offset:36864
	ds_read_b128 v[210:213], v159 offset:37888
	ds_read_b128 v[214:217], v159 offset:38912
	ds_read_b128 v[218:221], v159 offset:39936
	global_load_lds_dwordx4 v[230:231], off
	v_lshl_add_u64 v[230:231], s[50:51], 0, v[134:135]
	s_mov_b32 m0, s60
	s_nop 0
	global_load_lds_dwordx4 v[230:231], off
	s_waitcnt vmcnt(8)
	s_waitcnt lgkmcnt(0)
	s_setprio 1
	v_mfma_f32_16x16x32_bf16 v[126:129], v[152:155], v[190:193], v[126:129]
	v_mfma_f32_16x16x32_bf16 v[122:125], v[166:169], v[190:193], v[122:125]
	v_mfma_f32_16x16x32_bf16 v[110:113], v[152:155], v[198:201], v[110:113]
	v_mfma_f32_16x16x32_bf16 v[106:109], v[166:169], v[198:201], v[106:109]
	v_mfma_f32_16x16x32_bf16 v[94:97], v[152:155], v[206:209], v[94:97]
	v_mfma_f32_16x16x32_bf16 v[90:93], v[166:169], v[206:209], v[90:93]
	v_mfma_f32_16x16x32_bf16 v[78:81], v[152:155], v[214:217], v[78:81]
	v_mfma_f32_16x16x32_bf16 v[74:77], v[166:169], v[214:217], v[74:77]
	v_mfma_f32_16x16x32_bf16 v[126:129], v[162:165], v[194:197], v[126:129]
	v_mfma_f32_16x16x32_bf16 v[122:125], v[170:173], v[194:197], v[122:125]
	v_mfma_f32_16x16x32_bf16 v[110:113], v[162:165], v[202:205], v[110:113]
	v_mfma_f32_16x16x32_bf16 v[106:109], v[170:173], v[202:205], v[106:109]
	v_mfma_f32_16x16x32_bf16 v[94:97], v[162:165], v[210:213], v[94:97]
	v_mfma_f32_16x16x32_bf16 v[90:93], v[170:173], v[210:213], v[90:93]
	v_mfma_f32_16x16x32_bf16 v[78:81], v[162:165], v[218:221], v[78:81]
	v_mfma_f32_16x16x32_bf16 v[74:77], v[170:173], v[218:221], v[74:77]
	s_setprio 0
	s_setprio 1
	v_mfma_f32_16x16x32_bf16 v[118:121], v[174:177], v[190:193], v[118:121]
	v_mfma_f32_16x16x32_bf16 v[114:117], v[182:185], v[190:193], v[114:117]
	v_mfma_f32_16x16x32_bf16 v[102:105], v[174:177], v[198:201], v[102:105]
	v_mfma_f32_16x16x32_bf16 v[98:101], v[182:185], v[198:201], v[98:101]
	v_mfma_f32_16x16x32_bf16 v[86:89], v[174:177], v[206:209], v[86:89]
	v_mfma_f32_16x16x32_bf16 v[82:85], v[182:185], v[206:209], v[82:85]
	v_mfma_f32_16x16x32_bf16 v[70:73], v[174:177], v[214:217], v[70:73]
	v_mfma_f32_16x16x32_bf16 v[66:69], v[182:185], v[214:217], v[66:69]
	v_mfma_f32_16x16x32_bf16 v[118:121], v[178:181], v[194:197], v[118:121]
	v_mfma_f32_16x16x32_bf16 v[114:117], v[186:189], v[194:197], v[114:117]
	v_mfma_f32_16x16x32_bf16 v[102:105], v[178:181], v[202:205], v[102:105]
	v_mfma_f32_16x16x32_bf16 v[98:101], v[186:189], v[202:205], v[98:101]
	v_mfma_f32_16x16x32_bf16 v[86:89], v[178:181], v[210:213], v[86:89]
	v_mfma_f32_16x16x32_bf16 v[82:85], v[186:189], v[210:213], v[82:85]
	v_mfma_f32_16x16x32_bf16 v[70:73], v[178:181], v[218:221], v[70:73]
	v_mfma_f32_16x16x32_bf16 v[66:69], v[186:189], v[218:221], v[66:69]
	s_setprio 0
	s_barrier
	s_add_i32 s50, s81, s56
	v_lshl_add_u64 v[222:223], v[222:223], 0, s[42:43]
	s_mov_b32 m0, s50
	ds_read_b128 v[190:193], v159 offset:49152
	ds_read_b128 v[194:197], v159 offset:50176
	ds_read_b128 v[198:201], v159 offset:51200
	ds_read_b128 v[202:205], v159 offset:52224
	ds_read_b128 v[206:209], v159 offset:53248
	ds_read_b128 v[210:213], v159 offset:54272
	ds_read_b128 v[214:217], v159 offset:55296
	ds_read_b128 v[218:221], v159 offset:56320
	global_load_lds_dwordx4 v[222:223], off
	s_add_i32 m0, s50, 0x2000
	s_add_u32 s50, s52, 0x30080
	v_lshl_add_u64 v[222:223], v[224:225], 0, s[42:43]
	s_addc_u32 s51, s53, 0
	s_add_i32 s52, s82, s56
	global_load_lds_dwordx4 v[222:223], off
	v_lshl_add_u64 v[222:223], s[50:51], 0, v[132:133]
	s_mov_b32 m0, s52
	s_nop 0
	global_load_lds_dwordx4 v[222:223], off
	v_lshl_add_u64 v[222:223], s[50:51], 0, v[136:137]
	s_add_i32 m0, s52, 0x2000
	s_nop 0
	global_load_lds_dwordx4 v[222:223], off
	v_lshl_add_u64 v[222:223], v[226:227], 0, s[42:43]
	s_mov_b32 m0, s61
	s_nop 0
	global_load_lds_dwordx4 v[222:223], off
	v_lshl_add_u64 v[222:223], v[228:229], 0, s[42:43]
	s_mov_b32 m0, s62
	s_nop 0
	global_load_lds_dwordx4 v[222:223], off
	s_waitcnt vmcnt(8)
	s_waitcnt lgkmcnt(0)
	s_setprio 1
	v_mfma_f32_16x16x32_bf16 v[62:65], v[152:155], v[190:193], v[62:65]
	v_mfma_f32_16x16x32_bf16 v[58:61], v[166:169], v[190:193], v[58:61]
	v_mfma_f32_16x16x32_bf16 v[46:49], v[152:155], v[198:201], v[46:49]
	v_mfma_f32_16x16x32_bf16 v[42:45], v[166:169], v[198:201], v[42:45]
	v_mfma_f32_16x16x32_bf16 v[30:33], v[152:155], v[206:209], v[30:33]
	v_mfma_f32_16x16x32_bf16 v[26:29], v[166:169], v[206:209], v[26:29]
	v_mfma_f32_16x16x32_bf16 v[14:17], v[152:155], v[214:217], v[14:17]
	v_mfma_f32_16x16x32_bf16 v[10:13], v[166:169], v[214:217], v[10:13]
	v_mfma_f32_16x16x32_bf16 v[62:65], v[162:165], v[194:197], v[62:65]
	v_mfma_f32_16x16x32_bf16 v[58:61], v[170:173], v[194:197], v[58:61]
	v_mfma_f32_16x16x32_bf16 v[46:49], v[162:165], v[202:205], v[46:49]
	v_mfma_f32_16x16x32_bf16 v[42:45], v[170:173], v[202:205], v[42:45]
	v_mfma_f32_16x16x32_bf16 v[30:33], v[162:165], v[210:213], v[30:33]
	v_mfma_f32_16x16x32_bf16 v[26:29], v[170:173], v[210:213], v[26:29]
	v_mfma_f32_16x16x32_bf16 v[14:17], v[162:165], v[218:221], v[14:17]
	v_mfma_f32_16x16x32_bf16 v[10:13], v[170:173], v[218:221], v[10:13]
	s_setprio 0
	s_setprio 1
	v_mfma_f32_16x16x32_bf16 v[54:57], v[174:177], v[190:193], v[54:57]
	v_mfma_f32_16x16x32_bf16 v[50:53], v[182:185], v[190:193], v[50:53]
	v_mfma_f32_16x16x32_bf16 v[38:41], v[174:177], v[198:201], v[38:41]
	v_mfma_f32_16x16x32_bf16 v[34:37], v[182:185], v[198:201], v[34:37]
	v_mfma_f32_16x16x32_bf16 v[22:25], v[174:177], v[206:209], v[22:25]
	v_mfma_f32_16x16x32_bf16 v[18:21], v[182:185], v[206:209], v[18:21]
	v_mfma_f32_16x16x32_bf16 v[6:9], v[174:177], v[214:217], v[6:9]
	v_mfma_f32_16x16x32_bf16 v[2:5], v[182:185], v[214:217], v[2:5]
	v_mfma_f32_16x16x32_bf16 v[54:57], v[178:181], v[194:197], v[54:57]
	v_mfma_f32_16x16x32_bf16 v[50:53], v[186:189], v[194:197], v[50:53]
	v_mfma_f32_16x16x32_bf16 v[38:41], v[178:181], v[202:205], v[38:41]
	v_mfma_f32_16x16x32_bf16 v[34:37], v[186:189], v[202:205], v[34:37]
	v_mfma_f32_16x16x32_bf16 v[22:25], v[178:181], v[210:213], v[22:25]
	v_mfma_f32_16x16x32_bf16 v[18:21], v[186:189], v[210:213], v[18:21]
	v_mfma_f32_16x16x32_bf16 v[6:9], v[178:181], v[218:221], v[6:9]
	v_mfma_f32_16x16x32_bf16 v[2:5], v[186:189], v[218:221], v[2:5]
	s_setprio 0
	s_barrier
	s_add_i32 s80, s80, 2
	s_add_u32 s10, s10, 0x100
	s_addc_u32 s79, s79, 0
	s_cmp_gt_u32 s80, 9
	s_mov_b64 s[50:51], s[6:7]
	s_cbranch_scc0 .LBB0_1486
	s_branch .Lhb_exit_p11
.Lhb_B_p11:
	ds_read_b128 v[152:155], v157
	ds_read_b128 v[162:165], v157 offset:1024
	ds_read_b128 v[166:169], v157 offset:2048
	ds_read_b128 v[170:173], v157 offset:3072
	ds_read_b128 v[174:177], v158
	ds_read_b128 v[178:181], v158 offset:1024
	ds_read_b128 v[182:185], v158 offset:2048
	ds_read_b128 v[186:189], v158 offset:3072
	s_add_u32 s6, s50, 0x100
	s_addc_u32 s7, s51, 0
	s_cmp_eq_u32 s80, 8
	s_cselect_b32 s55, s47, s7
	s_cselect_b32 s54, s46, s6
	s_cselect_b32 s53, s49, s79
	s_cselect_b32 s52, s48, s10
	v_lshl_add_u64 v[222:223], s[50:51], 0, v[144:145]
	s_add_i32 m0, s57, 0xc000
	ds_read_b128 v[190:193], v159
	ds_read_b128 v[194:197], v159 offset:1024
	ds_read_b128 v[198:201], v159 offset:2048
	ds_read_b128 v[202:205], v159 offset:3072
	ds_read_b128 v[206:209], v159 offset:4096
	ds_read_b128 v[210:213], v159 offset:5120
	ds_read_b128 v[214:217], v159 offset:6144
	ds_read_b128 v[218:221], v159 offset:7168
	global_load_lds_dwordx4 v[222:223], off
	v_lshl_add_u64 v[222:223], s[50:51], 0, v[146:147]
	s_add_i32 m0, s57, 0xe000
	s_nop 0
	global_load_lds_dwordx4 v[222:223], off
	s_waitcnt vmcnt(8)
	s_waitcnt lgkmcnt(0)
	s_setprio 1
	s_barrier
	v_mfma_f32_16x16x32_bf16 v[126:129], v[152:155], v[190:193], v[126:129]
	v_mfma_f32_16x16x32_bf16 v[122:125], v[166:169], v[190:193], v[122:125]
	v_mfma_f32_16x16x32_bf16 v[110:113], v[152:155], v[198:201], v[110:113]
	v_mfma_f32_16x16x32_bf16 v[106:109], v[166:169], v[198:201], v[106:109]
	v_mfma_f32_16x16x32_bf16 v[94:97], v[152:155], v[206:209], v[94:97]
	v_mfma_f32_16x16x32_bf16 v[90:93], v[166:169], v[206:209], v[90:93]
	v_mfma_f32_16x16x32_bf16 v[78:81], v[152:155], v[214:217], v[78:81]
	v_mfma_f32_16x16x32_bf16 v[74:77], v[166:169], v[214:217], v[74:77]
	v_mfma_f32_16x16x32_bf16 v[126:129], v[162:165], v[194:197], v[126:129]
	v_mfma_f32_16x16x32_bf16 v[122:125], v[170:173], v[194:197], v[122:125]
	v_mfma_f32_16x16x32_bf16 v[110:113], v[162:165], v[202:205], v[110:113]
	v_mfma_f32_16x16x32_bf16 v[106:109], v[170:173], v[202:205], v[106:109]
	v_mfma_f32_16x16x32_bf16 v[94:97], v[162:165], v[210:213], v[94:97]
	v_mfma_f32_16x16x32_bf16 v[90:93], v[170:173], v[210:213], v[90:93]
	v_mfma_f32_16x16x32_bf16 v[78:81], v[162:165], v[218:221], v[78:81]
	v_mfma_f32_16x16x32_bf16 v[74:77], v[170:173], v[218:221], v[74:77]
	s_setprio 0
	s_setprio 1
	v_mfma_f32_16x16x32_bf16 v[118:121], v[174:177], v[190:193], v[118:121]
	v_mfma_f32_16x16x32_bf16 v[114:117], v[182:185], v[190:193], v[114:117]
	v_mfma_f32_16x16x32_bf16 v[102:105], v[174:177], v[198:201], v[102:105]
	v_mfma_f32_16x16x32_bf16 v[98:101], v[182:185], v[198:201], v[98:101]
	v_mfma_f32_16x16x32_bf16 v[86:89], v[174:177], v[206:209], v[86:89]
	v_mfma_f32_16x16x32_bf16 v[82:85], v[182:185], v[206:209], v[82:85]
	v_mfma_f32_16x16x32_bf16 v[70:73], v[174:177], v[214:217], v[70:73]
	v_mfma_f32_16x16x32_bf16 v[66:69], v[182:185], v[214:217], v[66:69]
	v_mfma_f32_16x16x32_bf16 v[118:121], v[178:181], v[194:197], v[118:121]
	v_mfma_f32_16x16x32_bf16 v[114:117], v[186:189], v[194:197], v[114:117]
	v_mfma_f32_16x16x32_bf16 v[102:105], v[178:181], v[202:205], v[102:105]
	v_mfma_f32_16x16x32_bf16 v[98:101], v[186:189], v[202:205], v[98:101]
	v_mfma_f32_16x16x32_bf16 v[86:89], v[178:181], v[210:213], v[86:89]
	v_mfma_f32_16x16x32_bf16 v[82:85], v[186:189], v[210:213], v[82:85]
	v_mfma_f32_16x16x32_bf16 v[70:73], v[178:181], v[218:221], v[70:73]
	v_mfma_f32_16x16x32_bf16 v[66:69], v[186:189], v[218:221], v[66:69]
	s_setprio 0
	s_add_i32 s50, s68, s56
	v_lshl_add_u64 v[222:223], s[52:53], 0, v[132:133]
	s_mov_b32 m0, s50
	ds_read_b128 v[190:193], v159 offset:16384
	ds_read_b128 v[194:197], v159 offset:17408
	ds_read_b128 v[198:201], v159 offset:18432
	ds_read_b128 v[202:205], v159 offset:19456
	ds_read_b128 v[206:209], v159 offset:20480
	ds_read_b128 v[210:213], v159 offset:21504
	ds_read_b128 v[214:217], v159 offset:22528
	ds_read_b128 v[218:221], v159 offset:23552
	global_load_lds_dwordx4 v[222:223], off
	s_add_i32 m0, s50, 0x2000
	s_add_u32 s50, s52, 0x30000
	v_lshl_add_u64 v[224:225], s[52:53], 0, v[136:137]
	s_addc_u32 s51, s53, 0
	s_add_i32 s81, s69, s56
	global_load_lds_dwordx4 v[224:225], off
	v_lshl_add_u64 v[226:227], s[50:51], 0, v[132:133]
	s_mov_b32 m0, s81
	v_lshl_add_u64 v[228:229], s[54:55], 0, v[134:135]
	global_load_lds_dwordx4 v[226:227], off
	v_lshl_add_u64 v[226:227], s[50:51], 0, v[136:137]
	s_add_i32 m0, s81, 0x2000
	s_nop 0
	global_load_lds_dwordx4 v[226:227], off
	v_lshl_add_u64 v[226:227], s[54:55], 0, v[130:131]
	s_mov_b32 m0, s57
	s_nop 0
	global_load_lds_dwordx4 v[226:227], off
	s_mov_b32 m0, s58
	s_nop 0
	global_load_lds_dwordx4 v[228:229], off
	s_waitcnt vmcnt(8)
	s_waitcnt lgkmcnt(0)
	s_setprio 1
	s_barrier
	v_mfma_f32_16x16x32_bf16 v[62:65], v[152:155], v[190:193], v[62:65]
	v_mfma_f32_16x16x32_bf16 v[58:61], v[166:169], v[190:193], v[58:61]
	v_mfma_f32_16x16x32_bf16 v[46:49], v[152:155], v[198:201], v[46:49]
	v_mfma_f32_16x16x32_bf16 v[42:45], v[166:169], v[198:201], v[42:45]
	v_mfma_f32_16x16x32_bf16 v[30:33], v[152:155], v[206:209], v[30:33]
	v_mfma_f32_16x16x32_bf16 v[26:29], v[166:169], v[206:209], v[26:29]
	v_mfma_f32_16x16x32_bf16 v[14:17], v[152:155], v[214:217], v[14:17]
	v_mfma_f32_16x16x32_bf16 v[10:13], v[166:169], v[214:217], v[10:13]
	v_mfma_f32_16x16x32_bf16 v[62:65], v[162:165], v[194:197], v[62:65]
	v_mfma_f32_16x16x32_bf16 v[58:61], v[170:173], v[194:197], v[58:61]
	v_mfma_f32_16x16x32_bf16 v[46:49], v[162:165], v[202:205], v[46:49]
	v_mfma_f32_16x16x32_bf16 v[42:45], v[170:173], v[202:205], v[42:45]
	v_mfma_f32_16x16x32_bf16 v[30:33], v[162:165], v[210:213], v[30:33]
	v_mfma_f32_16x16x32_bf16 v[26:29], v[170:173], v[210:213], v[26:29]
	v_mfma_f32_16x16x32_bf16 v[14:17], v[162:165], v[218:221], v[14:17]
	v_mfma_f32_16x16x32_bf16 v[10:13], v[170:173], v[218:221], v[10:13]
	s_setprio 0
	s_setprio 1
	v_mfma_f32_16x16x32_bf16 v[54:57], v[174:177], v[190:193], v[54:57]
	v_mfma_f32_16x16x32_bf16 v[50:53], v[182:185], v[190:193], v[50:53]
	v_mfma_f32_16x16x32_bf16 v[38:41], v[174:177], v[198:201], v[38:41]
	v_mfma_f32_16x16x32_bf16 v[34:37], v[182:185], v[198:201], v[34:37]
	v_mfma_f32_16x16x32_bf16 v[22:25], v[174:177], v[206:209], v[22:25]
	v_mfma_f32_16x16x32_bf16 v[18:21], v[182:185], v[206:209], v[18:21]
	v_mfma_f32_16x16x32_bf16 v[6:9], v[174:177], v[214:217], v[6:9]
	v_mfma_f32_16x16x32_bf16 v[2:5], v[182:185], v[214:217], v[2:5]
	v_mfma_f32_16x16x32_bf16 v[54:57], v[178:181], v[194:197], v[54:57]
	v_mfma_f32_16x16x32_bf16 v[50:53], v[186:189], v[194:197], v[50:53]
	v_mfma_f32_16x16x32_bf16 v[38:41], v[178:181], v[202:205], v[38:41]
	v_mfma_f32_16x16x32_bf16 v[34:37], v[186:189], v[202:205], v[34:37]
	v_mfma_f32_16x16x32_bf16 v[22:25], v[178:181], v[210:213], v[22:25]
	v_mfma_f32_16x16x32_bf16 v[18:21], v[186:189], v[210:213], v[18:21]
	v_mfma_f32_16x16x32_bf16 v[6:9], v[178:181], v[218:221], v[6:9]
	v_mfma_f32_16x16x32_bf16 v[2:5], v[186:189], v[218:221], v[2:5]
	s_setprio 0
	s_add_i32 s81, 0, 0x18000
	v_add_u32_e32 v138, s81, v143
	s_add_i32 s82, 0, 0x1c000
	ds_read_b128 v[152:155], v138
	ds_read_b128 v[162:165], v138 offset:1024
	ds_read_b128 v[166:169], v138 offset:2048
	ds_read_b128 v[170:173], v138 offset:3072
	v_add_u32_e32 v138, s82, v143
	ds_read_b128 v[174:177], v138
	ds_read_b128 v[178:181], v138 offset:1024
	ds_read_b128 v[182:185], v138 offset:2048
	ds_read_b128 v[186:189], v138 offset:3072
	s_add_u32 s50, s54, 0x30000
	s_addc_u32 s51, s55, 0
	s_mov_b32 m0, s59
	v_lshl_add_u64 v[230:231], s[50:51], 0, v[130:131]
	ds_read_b128 v[190:193], v159 offset:32768
	ds_read_b128 v[194:197], v159 offset:33792
	ds_read_b128 v[198:201], v159 offset:34816
	ds_read_b128 v[202:205], v159 offset:35840
	ds_read_b128 v[206:209], v159 offset:36864
	ds_read_b128 v[210:213], v159 offset:37888
	ds_read_b128 v[214:217], v159 offset:38912
	ds_read_b128 v[218:221], v159 offset:39936
	global_load_lds_dwordx4 v[230:231], off
	v_lshl_add_u64 v[230:231], s[50:51], 0, v[134:135]
	s_mov_b32 m0, s60
	s_nop 0
	global_load_lds_dwordx4 v[230:231], off
	s_waitcnt vmcnt(8)
	s_waitcnt lgkmcnt(0)
	s_setprio 1
	s_barrier
	v_mfma_f32_16x16x32_bf16 v[126:129], v[152:155], v[190:193], v[126:129]
	v_mfma_f32_16x16x32_bf16 v[122:125], v[166:169], v[190:193], v[122:125]
	v_mfma_f32_16x16x32_bf16 v[110:113], v[152:155], v[198:201], v[110:113]
	v_mfma_f32_16x16x32_bf16 v[106:109], v[166:169], v[198:201], v[106:109]
	v_mfma_f32_16x16x32_bf16 v[94:97], v[152:155], v[206:209], v[94:97]
	v_mfma_f32_16x16x32_bf16 v[90:93], v[166:169], v[206:209], v[90:93]
	v_mfma_f32_16x16x32_bf16 v[78:81], v[152:155], v[214:217], v[78:81]
	v_mfma_f32_16x16x32_bf16 v[74:77], v[166:169], v[214:217], v[74:77]
	v_mfma_f32_16x16x32_bf16 v[126:129], v[162:165], v[194:197], v[126:129]
	v_mfma_f32_16x16x32_bf16 v[122:125], v[170:173], v[194:197], v[122:125]
	v_mfma_f32_16x16x32_bf16 v[110:113], v[162:165], v[202:205], v[110:113]
	v_mfma_f32_16x16x32_bf16 v[106:109], v[170:173], v[202:205], v[106:109]
	v_mfma_f32_16x16x32_bf16 v[94:97], v[162:165], v[210:213], v[94:97]
	v_mfma_f32_16x16x32_bf16 v[90:93], v[170:173], v[210:213], v[90:93]
	v_mfma_f32_16x16x32_bf16 v[78:81], v[162:165], v[218:221], v[78:81]
	v_mfma_f32_16x16x32_bf16 v[74:77], v[170:173], v[218:221], v[74:77]
	s_setprio 0
	s_setprio 1
	v_mfma_f32_16x16x32_bf16 v[118:121], v[174:177], v[190:193], v[118:121]
	v_mfma_f32_16x16x32_bf16 v[114:117], v[182:185], v[190:193], v[114:117]
	v_mfma_f32_16x16x32_bf16 v[102:105], v[174:177], v[198:201], v[102:105]
	v_mfma_f32_16x16x32_bf16 v[98:101], v[182:185], v[198:201], v[98:101]
	v_mfma_f32_16x16x32_bf16 v[86:89], v[174:177], v[206:209], v[86:89]
	v_mfma_f32_16x16x32_bf16 v[82:85], v[182:185], v[206:209], v[82:85]
	v_mfma_f32_16x16x32_bf16 v[70:73], v[174:177], v[214:217], v[70:73]
	v_mfma_f32_16x16x32_bf16 v[66:69], v[182:185], v[214:217], v[66:69]
	v_mfma_f32_16x16x32_bf16 v[118:121], v[178:181], v[194:197], v[118:121]
	v_mfma_f32_16x16x32_bf16 v[114:117], v[186:189], v[194:197], v[114:117]
	v_mfma_f32_16x16x32_bf16 v[102:105], v[178:181], v[202:205], v[102:105]
	v_mfma_f32_16x16x32_bf16 v[98:101], v[186:189], v[202:205], v[98:101]
	v_mfma_f32_16x16x32_bf16 v[86:89], v[178:181], v[210:213], v[86:89]
	v_mfma_f32_16x16x32_bf16 v[82:85], v[186:189], v[210:213], v[82:85]
	v_mfma_f32_16x16x32_bf16 v[70:73], v[178:181], v[218:221], v[70:73]
	v_mfma_f32_16x16x32_bf16 v[66:69], v[186:189], v[218:221], v[66:69]
	s_setprio 0
	s_add_i32 s50, s81, s56
	v_lshl_add_u64 v[222:223], v[222:223], 0, s[42:43]
	s_mov_b32 m0, s50
	ds_read_b128 v[190:193], v159 offset:49152
	ds_read_b128 v[194:197], v159 offset:50176
	ds_read_b128 v[198:201], v159 offset:51200
	ds_read_b128 v[202:205], v159 offset:52224
	ds_read_b128 v[206:209], v159 offset:53248
	ds_read_b128 v[210:213], v159 offset:54272
	ds_read_b128 v[214:217], v159 offset:55296
	ds_read_b128 v[218:221], v159 offset:56320
	global_load_lds_dwordx4 v[222:223], off
	s_add_i32 m0, s50, 0x2000
	s_add_u32 s50, s52, 0x30080
	v_lshl_add_u64 v[222:223], v[224:225], 0, s[42:43]
	s_addc_u32 s51, s53, 0
	s_add_i32 s52, s82, s56
	global_load_lds_dwordx4 v[222:223], off
	v_lshl_add_u64 v[222:223], s[50:51], 0, v[132:133]
	s_mov_b32 m0, s52
	s_nop 0
	global_load_lds_dwordx4 v[222:223], off
	v_lshl_add_u64 v[222:223], s[50:51], 0, v[136:137]
	s_add_i32 m0, s52, 0x2000
	s_nop 0
	global_load_lds_dwordx4 v[222:223], off
	v_lshl_add_u64 v[222:223], v[226:227], 0, s[42:43]
	s_mov_b32 m0, s61
	s_nop 0
	global_load_lds_dwordx4 v[222:223], off
	v_lshl_add_u64 v[222:223], v[228:229], 0, s[42:43]
	s_mov_b32 m0, s62
	s_nop 0
	global_load_lds_dwordx4 v[222:223], off
	s_waitcnt vmcnt(8)
	s_waitcnt lgkmcnt(0)
	s_setprio 1
	s_barrier
	v_mfma_f32_16x16x32_bf16 v[62:65], v[152:155], v[190:193], v[62:65]
	v_mfma_f32_16x16x32_bf16 v[58:61], v[166:169], v[190:193], v[58:61]
	v_mfma_f32_16x16x32_bf16 v[46:49], v[152:155], v[198:201], v[46:49]
	v_mfma_f32_16x16x32_bf16 v[42:45], v[166:169], v[198:201], v[42:45]
	v_mfma_f32_16x16x32_bf16 v[30:33], v[152:155], v[206:209], v[30:33]
	v_mfma_f32_16x16x32_bf16 v[26:29], v[166:169], v[206:209], v[26:29]
	v_mfma_f32_16x16x32_bf16 v[14:17], v[152:155], v[214:217], v[14:17]
	v_mfma_f32_16x16x32_bf16 v[10:13], v[166:169], v[214:217], v[10:13]
	v_mfma_f32_16x16x32_bf16 v[62:65], v[162:165], v[194:197], v[62:65]
	v_mfma_f32_16x16x32_bf16 v[58:61], v[170:173], v[194:197], v[58:61]
	v_mfma_f32_16x16x32_bf16 v[46:49], v[162:165], v[202:205], v[46:49]
	v_mfma_f32_16x16x32_bf16 v[42:45], v[170:173], v[202:205], v[42:45]
	v_mfma_f32_16x16x32_bf16 v[30:33], v[162:165], v[210:213], v[30:33]
	v_mfma_f32_16x16x32_bf16 v[26:29], v[170:173], v[210:213], v[26:29]
	v_mfma_f32_16x16x32_bf16 v[14:17], v[162:165], v[218:221], v[14:17]
	v_mfma_f32_16x16x32_bf16 v[10:13], v[170:173], v[218:221], v[10:13]
	s_setprio 0
	s_setprio 1
	v_mfma_f32_16x16x32_bf16 v[54:57], v[174:177], v[190:193], v[54:57]
	v_mfma_f32_16x16x32_bf16 v[50:53], v[182:185], v[190:193], v[50:53]
	v_mfma_f32_16x16x32_bf16 v[38:41], v[174:177], v[198:201], v[38:41]
	v_mfma_f32_16x16x32_bf16 v[34:37], v[182:185], v[198:201], v[34:37]
	v_mfma_f32_16x16x32_bf16 v[22:25], v[174:177], v[206:209], v[22:25]
	v_mfma_f32_16x16x32_bf16 v[18:21], v[182:185], v[206:209], v[18:21]
	v_mfma_f32_16x16x32_bf16 v[6:9], v[174:177], v[214:217], v[6:9]
	v_mfma_f32_16x16x32_bf16 v[2:5], v[182:185], v[214:217], v[2:5]
	v_mfma_f32_16x16x32_bf16 v[54:57], v[178:181], v[194:197], v[54:57]
	v_mfma_f32_16x16x32_bf16 v[50:53], v[186:189], v[194:197], v[50:53]
	v_mfma_f32_16x16x32_bf16 v[38:41], v[178:181], v[202:205], v[38:41]
	v_mfma_f32_16x16x32_bf16 v[34:37], v[186:189], v[202:205], v[34:37]
	v_mfma_f32_16x16x32_bf16 v[22:25], v[178:181], v[210:213], v[22:25]
	v_mfma_f32_16x16x32_bf16 v[18:21], v[186:189], v[210:213], v[18:21]
	v_mfma_f32_16x16x32_bf16 v[6:9], v[178:181], v[218:221], v[6:9]
	v_mfma_f32_16x16x32_bf16 v[2:5], v[186:189], v[218:221], v[2:5]
	s_setprio 0
	s_add_i32 s80, s80, 2
	s_add_u32 s10, s10, 0x100
	s_addc_u32 s79, s79, 0
	s_cmp_gt_u32 s80, 9
	s_mov_b64 s[50:51], s[6:7]
	s_cbranch_scc0 .Lhb_B_p11

.LBB0_1522:
	s_andn2_b64 vcc, exec, s[12:13]
	s_cbranch_vccnz .LBB0_1477
	s_branch .LBB0_1477

.LBB0_1696:
	s_andn2_b64 vcc, exec, s[14:15]
	s_cbranch_vccnz .LBB0_1732
	s_waitcnt lgkmcnt(0)
	v_ashrrev_i32_e32 v3, 31, v10
	v_lshrrev_b32_e32 v3, 26, v3
	v_add_u32_e32 v3, v10, v3
	v_ashrrev_i32_e32 v11, 6, v3
	v_bfe_i32 v3, v10, 27, 1
	v_lshlrev_b32_e32 v2, 4, v10
	v_lshrrev_b32_e32 v3, 22, v3
	v_add_u32_e32 v3, v2, v3
	v_and_b32_e32 v3, 0xfffffc00, v3
	v_sub_u32_e32 v3, v2, v3
	v_lshrrev_b32_e32 v4, 4, v3
	v_bitop3_b32 v3, v4, v3, 32 bitop3:0x6c
	v_ashrrev_i32_e32 v5, 31, v3
	v_lshrrev_b32_e32 v5, 26, v5
	v_add_u32_e32 v5, v3, v5
	v_lshlrev_b32_e32 v4, 3, v11
	v_ashrrev_i32_e32 v12, 6, v5
	v_and_b32_e32 v5, 0xc0, v5
	v_and_b32_e32 v4, -16, v4
	v_sub_u32_e32 v3, v3, v5
	v_mov_b32_e32 v5, 1
	v_add_u32_e32 v4, v12, v4
	v_ashrrev_i16_sdwa v3, v5, sext(v3) dst_sel:DWORD dst_unused:UNUSED_PAD src0_sel:DWORD src1_sel:BYTE_0
	s_add_u32 s3, s10, 0xa400000
	v_lshlrev_b32_e32 v6, 5, v11
	v_bfe_i32 v13, v3, 0, 16
	v_lshlrev_b32_e32 v3, 1, v4
	v_lshrrev_b32_e32 v7, 2, v4
	v_and_b32_e32 v8, 3, v12
	s_mov_b32 s10, 0x1fffe0
	v_and_b32_e32 v6, 32, v6
	v_and_b32_e32 v3, 24, v3
	v_and_b32_e32 v7, 4, v7
	v_and_or_b32 v8, v4, s10, v8
	v_or3_b32 v3, v8, v7, v3
	v_add_lshl_u32 v6, v6, v13, 1
	v_add_u32_e32 v2, 0x2000, v2
	v_lshl_add_u32 v196, v3, 11, v6
	v_ashrrev_i32_e32 v3, 31, v2
	v_lshrrev_b32_e32 v3, 22, v3
	v_add_u32_e32 v3, v2, v3
	v_ashrrev_i32_e32 v14, 10, v3
	v_mul_i32_i24_e32 v3, 0x400, v14
	v_sub_u32_e32 v2, v2, v3
	v_lshrrev_b32_e32 v3, 4, v2
	v_bitop3_b32 v2, v3, v2, 32 bitop3:0x6c
	v_lshl_add_u32 v194, v4, 11, v6
	v_ashrrev_i32_e32 v4, 31, v2
	v_lshrrev_b32_e32 v4, 26, v4
	v_add_u32_e32 v4, v2, v4
	s_addc_u32 s23, s11, 0
	v_lshlrev_b32_e32 v3, 3, v14
	v_ashrrev_i32_e32 v15, 6, v4
	v_and_b32_e32 v4, 0xc0, v4
	s_add_u32 s29, s12, 0x53c0000
	v_and_b32_e32 v3, -16, v3
	v_sub_u32_e32 v2, v2, v4
	s_addc_u32 s31, s13, 0
	v_add_u32_e32 v3, v15, v3
	v_ashrrev_i16_sdwa v2, v5, sext(v2) dst_sel:DWORD dst_unused:UNUSED_PAD src0_sel:DWORD src1_sel:BYTE_0
	v_and_b32_e32 v5, 3, v15
	s_ashr_i32 s16, s24, 6
	s_ashr_i32 s49, s48, 31
	s_ashr_i32 s51, s50, 31
	s_ashr_i32 s25, s24, 8
	v_and_or_b32 v5, v3, s10, v5
	s_lshl_b32 s58, s16, 10
	s_lshl_b64 s[10:11], s[48:49], 19
	s_lshl_b64 s[12:13], s[50:51], 19
	s_add_u32 s54, s29, s12
	v_lshlrev_b32_e32 v6, 5, v14
	v_bfe_i32 v16, v2, 0, 16
	v_lshlrev_b32_e32 v2, 1, v3
	v_lshrrev_b32_e32 v4, 2, v3
	s_addc_u32 s55, s31, s13
	s_add_i32 s59, s58, 0
	v_and_b32_e32 v6, 32, v6
	v_and_b32_e32 v2, 24, v2
	v_and_b32_e32 v4, 4, v4
	s_add_i32 m0, s59, 0x10000
	v_or3_b32 v2, v5, v4, v2
	v_add_lshl_u32 v4, v6, v16, 1
	global_load_lds_dwordx4 v196, s[54:55]
	s_add_i32 m0, s59, 0x12000
	v_lshl_add_u32 v200, v2, 11, v4
	s_add_u32 s12, s54, 0x40000
	global_load_lds_dwordx4 v200, s[54:55]
	s_addc_u32 s13, s55, 0
	s_add_i32 m0, s59, 0x14000
	v_lshl_add_u32 v198, v3, 11, v4
	global_load_lds_dwordx4 v196, s[12:13]
	s_add_i32 m0, s59, 0x16000
	s_add_u32 s52, s3, s10
	s_addc_u32 s53, s23, s11
	s_add_i32 s60, s59, 0x2000
	global_load_lds_dwordx4 v200, s[12:13]
	s_mov_b32 m0, s59
	s_add_u32 s10, s52, 0x40000
	global_load_lds_dwordx4 v194, s[52:53]
	s_mov_b32 m0, s60
	s_addc_u32 s11, s53, 0
	s_add_i32 s61, s59, 0x4000
	global_load_lds_dwordx4 v198, s[52:53]
	s_mov_b32 m0, s61
	s_add_i32 s62, s59, 0x6000
	global_load_lds_dwordx4 v194, s[10:11]
	s_mov_b32 m0, s62
	v_mov_b32_e32 v203, 0
	global_load_lds_dwordx4 v198, s[10:11]
	v_mov_b32_e32 v197, v203
	v_mov_b32_e32 v201, v203
	v_mov_b32_e32 v195, v203
	v_mov_b32_e32 v199, v203
	s_cmp_eq_u32 s25, 1
	s_mov_b32 s63, 0
	v_lshl_add_u64 v[8:9], s[54:55], 0, v[196:197]
	v_lshl_add_u64 v[6:7], s[54:55], 0, v[200:201]
	v_lshl_add_u64 v[2:3], s[52:53], 0, v[194:195]
	s_cselect_b64 s[10:11], -1, 0
	s_cmp_lg_u32 s25, 1
	v_lshl_add_u64 v[4:5], s[52:53], 0, v[198:199]
	s_cbranch_scc1 .LBB0_1699
.LBB0_1699:
	s_add_u32 s12, s4, 0x6400000
	s_addc_u32 s13, s5, 0
	s_add_u32 s14, s6, 0xe0000
	s_addc_u32 s15, s7, 0
	s_lshl_b32 s4, s16, 5
	s_mov_b64 s[16:17], 0x80
	s_and_b32 s7, s4, 0x60
	s_add_i32 m0, s59, 0x18000
	v_lshl_add_u64 v[8:9], v[8:9], 0, s[16:17]
	s_lshl_b32 s6, s25, 13
	s_lshl_b32 s26, s7, 7
	s_waitcnt vmcnt(2)
	s_barrier
	global_load_lds_dwordx4 v[8:9], off
	v_lshl_add_u64 v[6:7], v[6:7], 0, s[16:17]
	s_add_i32 m0, s59, 0x1a000
	s_add_i32 s64, s59, 0x8000
	s_add_i32 s65, s59, 0xa000
	global_load_lds_dwordx4 v[6:7], off
	v_lshl_add_u64 v[2:3], v[2:3], 0, s[16:17]
	s_mov_b32 m0, s64
	s_add_u32 s4, s54, 0x40080
	global_load_lds_dwordx4 v[2:3], off
	v_lshl_add_u64 v[2:3], v[4:5], 0, s[16:17]
	s_mov_b32 m0, s65
	s_addc_u32 s5, s55, 0
	global_load_lds_dwordx4 v[2:3], off
	s_add_i32 m0, s59, 0x1c000
	v_lshl_add_u64 v[2:3], s[4:5], 0, v[196:197]
	global_load_lds_dwordx4 v[2:3], off
	v_lshl_add_u64 v[2:3], s[4:5], 0, v[200:201]
	s_add_i32 m0, s59, 0x1e000
	s_cmpk_lt_u32 s24, 0x100
	global_load_lds_dwordx4 v[2:3], off
	v_bfe_u32 v3, v10, 4, 2
	v_and_b32_e32 v2, 15, v10
	v_lshlrev_b32_e32 v4, 4, v3
	v_lshl_or_b32 v243, s25, 6, v2
	v_lshl_or_b32 v2, v2, 6, v4
	v_lshlrev_b32_e32 v4, 2, v10
	v_and_b32_e32 v4, 32, v4
	v_bitop3_b32 v5, v2, s6, v4 bitop3:0xde
	v_bitop3_b32 v244, v2, s26, v4 bitop3:0xde
	v_lshl_or_b32 v2, v3, 3, s7
	v_cmp_eq_u32_e64 s[4:5], 0, v3
	v_lshlrev_b32_e32 v3, 14, v11
	v_and_b32_e32 v3, 0xffff8000, v3
	v_lshl_add_u32 v3, v12, 11, v3
	v_and_b32_e32 v4, 1, v11
	v_lshl_or_b32 v3, v4, 6, v3
	v_lshl_add_u32 v206, v13, 1, v3
	v_lshlrev_b32_e32 v3, 14, v14
	v_and_b32_e32 v3, 0xffff8000, v3
	v_lshl_add_u32 v3, v15, 11, v3
	v_and_b32_e32 v4, 1, v14
	s_waitcnt vmcnt(6)
	v_lshl_or_b32 v3, v4, 6, v3
	s_cselect_b64 s[24:25], -1, 0
	v_lshlrev_b32_e32 v202, 1, v2
	v_lshl_add_u32 v208, v16, 1, v3
	s_add_i32 s69, 0, 0x10000
	s_add_i32 s70, 0, 0x14000
	v_mbcnt_lo_u32_b32 v3, -1, 0
	s_ashr_i32 s66, s38, 31
	s_mov_b32 s67, s38
	s_ashr_i32 s68, s2, 31
	v_lshl_add_u64 v[204:205], s[12:13], 0, v[202:203]
	v_mov_b32_e32 v207, v203
	v_mov_b32_e32 v209, v203
	v_add_u32_e32 v245, s69, v244
	v_add_u32_e32 v246, s70, v244
	v_add_u32_e32 v247, 0, v5
	v_mbcnt_hi_u32_b32 v248, -1, v3
	v_lshlrev_b32_e32 v202, 1, v2
	s_barrier
	s_branch .LBB0_1702

.LBB0_1799:
.LBB0_1800:
	s_cmp_lt_i32 s20, 15
	s_cselect_b64 s[6:7], -1, 0
	s_and_b64 s[6:7], s[6:7], s[4:5]
	s_andn2_b64 vcc, exec, s[6:7]
	s_cbranch_vccnz .LBB0_1817
	s_mov_b64 s[4:5], s[0:1]
	s_mov_b64 s[8:9], s[0:1]
	s_mov_b64 s[10:11], s[0:1]
	s_mov_b64 s[12:13], s[0:1]
	v_mov_b32_e32 v10, v1
	s_cmpk_gt_i32 s2, 0xaff
	v_readfirstlane_b32 s17, v10
	s_cbranch_scc1 .LBB0_1817
	v_lshlrev_b32_e32 v2, 4, v10
	v_add_u32_e32 v3, 0x2000, v2
	v_ashrrev_i32_e32 v4, 31, v3
	v_lshrrev_b32_e32 v4, 22, v4
	v_add_u32_e32 v4, v3, v4
	v_ashrrev_i32_e32 v11, 10, v4
	v_mul_i32_i24_e32 v4, 0x400, v11
	v_sub_u32_e32 v3, v3, v4
	v_lshrrev_b32_e32 v4, 4, v3
	v_bitop3_b32 v3, v4, v3, 32 bitop3:0x6c
	v_ashrrev_i32_e32 v4, 31, v3
	v_lshrrev_b32_e32 v4, 26, v4
	v_add_u32_e32 v4, v3, v4
	v_lshlrev_b32_e32 v5, 3, v11
	v_ashrrev_i32_e32 v12, 6, v4
	v_and_b32_e32 v5, -16, v5
	v_add_u32_e32 v5, v12, v5
	s_load_dwordx2 s[14:15], s[10:11], 0xa8
	s_load_dwordx2 s[24:25], s[12:13], 0xa8
	v_and_b32_e32 v6, 3, v12
	s_mov_b32 s10, 0x1fffe0
	v_lshrrev_b32_e32 v7, 2, v5
	v_lshlrev_b32_e32 v8, 1, v5
	v_and_b32_e32 v4, 0xc0, v4
	v_and_or_b32 v6, v5, s10, v6
	v_and_b32_e32 v7, 4, v7
	v_and_b32_e32 v8, 24, v8
	v_sub_u32_e32 v3, v3, v4
	v_mov_b32_e32 v4, 1
	v_or3_b32 v6, v6, v7, v8
	v_lshlrev_b32_e32 v7, 5, v11
	v_ashrrev_i16_sdwa v3, v4, sext(v3) dst_sel:DWORD dst_unused:UNUSED_PAD src0_sel:DWORD src1_sel:BYTE_0
	v_and_b32_e32 v7, 32, v7
	v_bfe_i32 v13, v3, 0, 16
	v_add_lshl_u32 v3, v7, v13, 1
	v_lshl_add_u32 v130, v6, 11, v3
	v_lshl_add_u32 v132, v5, 11, v3
	v_bfe_i32 v3, v10, 27, 1
	v_lshrrev_b32_e32 v3, 22, v3
	v_add_u32_e32 v3, v2, v3
	v_and_b32_e32 v3, 0xfffffc00, v3
	v_sub_u32_e32 v2, v2, v3
	v_lshrrev_b32_e32 v3, 4, v2
	v_ashrrev_i32_e32 v5, 31, v10
	v_bitop3_b32 v2, v3, v2, 32 bitop3:0x6c
	v_lshrrev_b32_e32 v5, 26, v5
	v_ashrrev_i32_e32 v3, 31, v2
	v_add_u32_e32 v5, v10, v5
	s_waitcnt lgkmcnt(0)
	s_add_u32 s3, s14, 0x6400000
	v_lshrrev_b32_e32 v3, 26, v3
	v_ashrrev_i32_e32 v15, 6, v5
	s_addc_u32 s23, s15, 0
	v_add_u32_e32 v3, v2, v3
	v_lshlrev_b32_e32 v5, 3, v15
	s_add_u32 s29, s24, 0x2500000
	v_ashrrev_i32_e32 v14, 6, v3
	v_and_b32_e32 v5, -16, v5
	s_addc_u32 s31, s25, 0
	v_add_u32_e32 v5, v14, v5
	v_and_b32_e32 v6, 3, v14
	s_ashr_i32 s55, s2, 31
	v_and_or_b32 v6, v5, s10, v6
	s_lshr_b32 s10, s55, 29
	s_add_i32 s10, s2, s10
	s_ashr_i32 s14, s17, 6
	s_ashr_i32 s11, s10, 3
	s_and_b32 s10, s10, -8
	s_ashr_i32 s24, s17, 8
	s_lshl_b32 s54, s14, 10
	s_sub_i32 s10, s2, s10
	s_cmp_lt_i32 s10, 0
	s_movk_i32 s56, 0x161
	s_cselect_b32 s12, s56, 0x160
	s_mul_i32 s10, s10, s12
	s_add_i32 s10, s10, s11
	s_mul_hi_i32 s11, s10, 0x2e8ba2e9
	s_lshr_b32 s12, s11, 31
	s_ashr_i32 s11, s11, 5
	s_add_i32 s11, s11, s12
	s_lshl_b32 s12, s11, 3
	s_mulk_i32 s11, 0xb0
	s_sub_i32 s10, s10, s11
	s_sext_i32_i16 s11, s10
	s_bfe_u32 s11, s11, 0x3001c
	s_add_i32 s11, s10, s11
	s_sext_i32_i16 s13, s11
	s_and_b32 s11, s11, 0xfff8
	s_sub_i32 s10, s10, s11
	s_sext_i32_i16 s10, s10
	v_lshrrev_b32_e32 v7, 2, v5
	v_lshlrev_b32_e32 v8, 1, v5
	v_and_b32_e32 v3, 0xc0, v3
	s_lshr_b32 s16, s13, 3
	s_add_i32 s46, s12, s10
	v_and_b32_e32 v7, 4, v7
	v_and_b32_e32 v8, 24, v8
	v_sub_u32_e32 v2, v2, v3
	s_ashr_i32 s47, s46, 31
	s_bfe_i64 s[12:13], s[16:17], 0x100000
	v_or3_b32 v6, v6, v7, v8
	v_lshlrev_b32_e32 v7, 5, v15
	v_ashrrev_i16_sdwa v2, v4, sext(v2) dst_sel:DWORD dst_unused:UNUSED_PAD src0_sel:DWORD src1_sel:BYTE_0
	s_lshl_b64 s[10:11], s[46:47], 19
	s_lshl_b64 s[12:13], s[12:13], 19
	v_and_b32_e32 v7, 32, v7
	v_bfe_i32 v16, v2, 0, 16
	s_add_u32 s50, s29, s12
	v_add_lshl_u32 v2, v7, v16, 1
	s_addc_u32 s51, s31, s13
	s_add_i32 s57, s54, 0
	v_lshl_add_u32 v134, v6, 11, v2
	s_add_i32 m0, s57, 0x10000
	v_lshl_add_u32 v136, v5, 11, v2
	global_load_lds_dwordx4 v134, s[50:51]
	s_add_i32 m0, s57, 0x12000
	s_add_u32 s12, s50, 0x40000
	global_load_lds_dwordx4 v130, s[50:51]
	s_addc_u32 s13, s51, 0
	s_add_i32 m0, s57, 0x14000
	v_mov_b32_e32 v139, 0
	global_load_lds_dwordx4 v134, s[12:13]
	s_add_i32 m0, s57, 0x16000
	s_add_u32 s48, s3, s10
	s_addc_u32 s49, s23, s11
	s_add_i32 s58, s57, 0x2000
	global_load_lds_dwordx4 v130, s[12:13]
	s_mov_b32 m0, s57
	s_add_u32 s10, s48, 0x40000
	global_load_lds_dwordx4 v136, s[48:49]
	s_mov_b32 m0, s58
	s_addc_u32 s11, s49, 0
	s_add_i32 s59, s57, 0x4000
	global_load_lds_dwordx4 v132, s[48:49]
	s_mov_b32 m0, s59
	s_add_i32 s60, s57, 0x6000
	global_load_lds_dwordx4 v136, s[10:11]
	s_mov_b32 m0, s60
	v_mov_b32_e32 v135, v139
	global_load_lds_dwordx4 v132, s[10:11]
	s_load_dwordx2 s[10:11], s[4:5], 0xa8
	s_nop 0
	s_load_dwordx2 s[4:5], s[8:9], 0xa8
	v_mov_b32_e32 v131, v139
	v_mov_b32_e32 v137, v139
	v_mov_b32_e32 v133, v139
	s_cmp_eq_u32 s24, 1
	s_mov_b32 s61, 0
	v_lshl_add_u64 v[8:9], s[50:51], 0, v[134:135]
	v_lshl_add_u64 v[6:7], s[50:51], 0, v[130:131]
	v_lshl_add_u64 v[2:3], s[48:49], 0, v[136:137]
	s_cselect_b64 s[8:9], -1, 0
	s_cmp_lg_u32 s24, 1
	v_lshl_add_u64 v[4:5], s[48:49], 0, v[132:133]
	s_cbranch_scc1 .LBB0_1804
.LBB0_1804:
	s_waitcnt lgkmcnt(0)
	s_add_u32 s10, s10, 0xe0000
	s_addc_u32 s11, s11, 0
	s_add_u32 s12, s4, 0xa400000
	s_addc_u32 s13, s5, 0
	s_lshl_b32 s4, s14, 5
	s_mov_b64 s[14:15], 0x80
	s_and_b32 s26, s4, 0x60
	s_add_i32 m0, s57, 0x18000
	v_lshl_add_u64 v[8:9], v[8:9], 0, s[14:15]
	s_lshl_b32 s25, s24, 13
	s_lshl_b32 s27, s26, 7
	s_waitcnt vmcnt(2)
	s_barrier
	global_load_lds_dwordx4 v[8:9], off
	v_lshl_add_u64 v[6:7], v[6:7], 0, s[14:15]
	s_add_i32 m0, s57, 0x1a000
	s_add_i32 s62, s57, 0x8000
	s_add_i32 s63, s57, 0xa000
	global_load_lds_dwordx4 v[6:7], off
	v_lshl_add_u64 v[2:3], v[2:3], 0, s[14:15]
	s_mov_b32 m0, s62
	s_add_u32 s4, s50, 0x40080
	global_load_lds_dwordx4 v[2:3], off
	v_lshl_add_u64 v[2:3], v[4:5], 0, s[14:15]
	s_mov_b32 m0, s63
	s_addc_u32 s5, s51, 0
	global_load_lds_dwordx4 v[2:3], off
	s_add_i32 m0, s57, 0x1c000
	v_lshl_add_u64 v[2:3], s[4:5], 0, v[134:135]
	global_load_lds_dwordx4 v[2:3], off
	v_lshl_add_u64 v[2:3], s[4:5], 0, v[130:131]
	s_add_i32 m0, s57, 0x1e000
	s_cmpk_lt_u32 s17, 0x100
	global_load_lds_dwordx4 v[2:3], off
	v_lshrrev_b32_e32 v3, 1, v10
	v_and_b32_e32 v3, 24, v3
	v_and_b32_e32 v2, 15, v10
	v_lshlrev_b32_e32 v4, 1, v3
	v_lshl_or_b32 v150, s24, 6, v2
	v_lshl_or_b32 v2, v2, 6, v4
	v_lshlrev_b32_e32 v4, 2, v10
	v_and_b32_e32 v4, 32, v4
	v_bitop3_b32 v5, v2, s25, v4 bitop3:0xde
	v_bitop3_b32 v151, v2, s27, v4 bitop3:0xde
	v_or_b32_e32 v2, s26, v3
	v_lshlrev_b32_e32 v3, 14, v15
	v_and_b32_e32 v3, 0xffff8000, v3
	v_lshl_add_u32 v3, v14, 11, v3
	v_and_b32_e32 v4, 1, v15
	v_lshl_or_b32 v3, v4, 6, v3
	v_lshl_add_u32 v140, v16, 1, v3
	v_lshlrev_b32_e32 v3, 14, v11
	v_and_b32_e32 v3, 0xffff8000, v3
	s_waitcnt vmcnt(6)
	v_lshl_add_u32 v3, v12, 11, v3
	v_and_b32_e32 v4, 1, v11
	s_sext_i32_i16 s47, s16
	s_cselect_b64 s[16:17], -1, 0
	v_lshl_or_b32 v3, v4, 6, v3
	s_add_i32 s66, 0, 0x10000
	s_add_i32 s67, 0, 0x14000
	v_or_b32_e32 v152, 16, v150
	v_or_b32_e32 v153, 32, v150
	v_or_b32_e32 v154, 48, v150
	s_ashr_i32 s64, s38, 31
	s_mov_b32 s65, s38
	v_mov_b32_e32 v141, v139
	v_lshl_add_u32 v142, v13, 1, v3
	v_mov_b32_e32 v143, v139
	v_mov_b64_e32 v[144:145], 0xb00
	v_mov_b64_e32 v[146:147], 0xaff
	v_add_u32_e32 v155, s66, v151
	v_add_u32_e32 v156, s67, v151
	v_add_u32_e32 v157, 0, v5
	v_mov_b32_e32 v158, 0x358637bd
	s_movk_i32 s68, 0x1600
	v_lshlrev_b32_e32 v138, 1, v2
	s_barrier
	s_branch .LBB0_1807

.LBB0_1892:
	s_load_dwordx2 s[6:7], s[8:9], 0xa8
	s_load_dwordx2 s[12:13], s[16:17], 0xa0
	s_andn2_b64 vcc, exec, s[26:27]
	s_cbranch_vccnz .LBB0_1932
	v_ashrrev_i32_e32 v3, 31, v10
	v_lshrrev_b32_e32 v3, 26, v3
	v_add_u32_e32 v3, v10, v3
	v_ashrrev_i32_e32 v11, 6, v3
	v_bfe_i32 v3, v10, 27, 1
	v_lshlrev_b32_e32 v2, 4, v10
	v_lshrrev_b32_e32 v3, 22, v3
	v_add_u32_e32 v3, v2, v3
	v_and_b32_e32 v3, 0xfffffc00, v3
	v_sub_u32_e32 v3, v2, v3
	v_lshrrev_b32_e32 v4, 4, v3
	v_bitop3_b32 v3, v4, v3, 32 bitop3:0x6c
	v_ashrrev_i32_e32 v5, 31, v3
	v_lshrrev_b32_e32 v5, 26, v5
	v_lshlrev_b32_e32 v4, 3, v11
	v_add_u32_e32 v5, v3, v5
	v_and_b32_e32 v4, -16, v4
	v_ashrrev_i32_e32 v13, 6, v5
	v_and_b32_e32 v5, 0xc0, v5
	v_add_u32_e32 v4, v13, v4
	v_lshlrev_b32_e32 v6, 5, v11
	v_sub_u32_e32 v3, v3, v5
	v_mov_b32_e32 v5, 1
	s_waitcnt lgkmcnt(0)
	s_add_u32 s3, s14, 0xa400000
	v_and_b32_e32 v12, 32, v6
	v_ashrrev_i16_sdwa v3, v5, sext(v3) dst_sel:DWORD dst_unused:UNUSED_PAD src0_sel:DWORD src1_sel:BYTE_0
	v_lshlrev_b32_e32 v6, 1, v4
	v_lshrrev_b32_e32 v7, 2, v4
	v_and_b32_e32 v8, 3, v13
	s_mov_b32 s14, 0xffffe0
	v_bfe_i32 v14, v3, 0, 16
	v_and_b32_e32 v6, 24, v6
	v_and_b32_e32 v7, 4, v7
	v_and_or_b32 v8, v4, s14, v8
	s_movk_i32 s8, 0xb00
	v_add_u32_e32 v3, v12, v14
	v_or3_b32 v6, v8, v7, v6
	v_mul_lo_u32 v4, v4, s8
	v_add_lshl_u32 v186, v3, v4, 1
	v_mul_u32_u24_e32 v4, 0xb00, v6
	v_add_u32_e32 v2, 0x2000, v2
	v_add_lshl_u32 v188, v4, v3, 1
	v_ashrrev_i32_e32 v3, 31, v2
	v_lshrrev_b32_e32 v3, 22, v3
	v_add_u32_e32 v3, v2, v3
	v_ashrrev_i32_e32 v15, 10, v3
	v_mul_i32_i24_e32 v3, 0x400, v15
	v_sub_u32_e32 v2, v2, v3
	v_lshrrev_b32_e32 v3, 4, v2
	v_bitop3_b32 v2, v3, v2, 32 bitop3:0x6c
	v_ashrrev_i32_e32 v4, 31, v2
	s_addc_u32 s23, s15, 0
	v_lshrrev_b32_e32 v4, 26, v4
	s_add_u32 s29, s24, 0x4080000
	v_lshlrev_b32_e32 v3, 3, v15
	v_add_u32_e32 v4, v2, v4
	s_addc_u32 s31, s25, 0
	v_and_b32_e32 v3, -16, v3
	v_ashrrev_i32_e32 v16, 6, v4
	v_lshlrev_b32_e32 v6, 5, v15
	v_and_b32_e32 v4, 0xc0, v4
	s_ashr_i32 s24, s42, 6
	s_ashr_i32 s9, s42, 8
	v_add_u32_e32 v3, v16, v3
	v_and_b32_e32 v17, 32, v6
	v_sub_u32_e32 v2, v2, v4
	v_and_b32_e32 v6, 3, v16
	s_lshl_b32 s52, s24, 10
	s_mul_i32 s15, s68, 0x160000
	v_ashrrev_i16_sdwa v2, v5, sext(v2) dst_sel:DWORD dst_unused:UNUSED_PAD src0_sel:DWORD src1_sel:BYTE_0
	v_lshlrev_b32_e32 v4, 1, v3
	v_lshrrev_b32_e32 v5, 2, v3
	v_and_or_b32 v6, v3, s14, v6
	s_mul_hi_i32 s14, s68, 0x160000
	s_add_u32 s46, s29, s15
	v_bfe_i32 v18, v2, 0, 16
	v_and_b32_e32 v4, 24, v4
	v_and_b32_e32 v5, 4, v5
	s_addc_u32 s47, s31, s14
	s_add_i32 s53, s52, 0
	v_add_u32_e32 v2, v17, v18
	v_or3_b32 v4, v6, v5, v4
	v_mul_lo_u32 v3, v3, s8
	s_add_i32 m0, s53, 0x10000
	v_add_lshl_u32 v190, v2, v3, 1
	v_mul_u32_u24_e32 v3, 0xb00, v4
	global_load_lds_dwordx4 v188, s[46:47]
	s_add_i32 m0, s53, 0x12000
	v_add_lshl_u32 v192, v3, v2, 1
	s_add_u32 s14, s46, 0xb0000
	global_load_lds_dwordx4 v192, s[46:47]
	s_addc_u32 s15, s47, 0
	s_add_i32 m0, s53, 0x14000
	s_mul_i32 s17, s67, 0x160000
	global_load_lds_dwordx4 v188, s[14:15]
	s_add_i32 m0, s53, 0x16000
	s_mul_hi_i32 s16, s67, 0x160000
	s_add_u32 s44, s3, s17
	s_addc_u32 s45, s23, s16
	s_add_i32 s54, s53, 0x2000
	global_load_lds_dwordx4 v192, s[14:15]
	s_mov_b32 m0, s53
	s_add_u32 s14, s44, 0xb0000
	global_load_lds_dwordx4 v186, s[44:45]
	s_mov_b32 m0, s54
	s_addc_u32 s15, s45, 0
	s_add_i32 s55, s53, 0x4000
	global_load_lds_dwordx4 v190, s[44:45]
	s_mov_b32 m0, s55
	s_add_i32 s56, s53, 0x6000
	global_load_lds_dwordx4 v186, s[14:15]
	s_mov_b32 m0, s56
	v_mov_b32_e32 v189, 0
	global_load_lds_dwordx4 v190, s[14:15]
	v_mov_b32_e32 v193, v189
	v_mov_b32_e32 v187, v189
	v_mov_b32_e32 v191, v189
	s_cmp_eq_u32 s9, 1
	s_mov_b32 s57, 0
	v_lshl_add_u64 v[8:9], s[46:47], 0, v[188:189]
	v_lshl_add_u64 v[6:7], s[46:47], 0, v[192:193]
	v_lshl_add_u64 v[2:3], s[44:45], 0, v[186:187]
	s_cselect_b64 s[14:15], -1, 0
	s_cmp_lg_u32 s9, 1
	v_lshl_add_u64 v[4:5], s[44:45], 0, v[190:191]
	s_cbranch_scc1 .LBB0_1895
.LBB0_1895:
	s_add_u32 s16, s4, 0x100000
	s_addc_u32 s17, s5, 0
	s_lshl_b32 s4, s24, 5
	s_mov_b64 s[24:25], 0x80
	s_and_b32 s43, s4, 0x60
	s_add_i32 m0, s53, 0x18000
	v_lshl_add_u64 v[8:9], v[8:9], 0, s[24:25]
	s_lshl_b32 s26, s9, 13
	s_lshl_b32 s27, s43, 7
	s_waitcnt vmcnt(2)
	s_barrier
	global_load_lds_dwordx4 v[8:9], off
	v_lshl_add_u64 v[6:7], v[6:7], 0, s[24:25]
	s_add_i32 m0, s53, 0x1a000
	s_add_i32 s58, s53, 0x8000
	s_add_i32 s59, s53, 0xa000
	global_load_lds_dwordx4 v[6:7], off
	v_lshl_add_u64 v[2:3], v[2:3], 0, s[24:25]
	s_mov_b32 m0, s58
	s_add_u32 s4, s46, 0xb0080
	global_load_lds_dwordx4 v[2:3], off
	v_lshl_add_u64 v[2:3], v[4:5], 0, s[24:25]
	s_mov_b32 m0, s59
	s_addc_u32 s5, s47, 0
	global_load_lds_dwordx4 v[2:3], off
	s_add_i32 m0, s53, 0x1c000
	v_lshl_add_u64 v[2:3], s[4:5], 0, v[188:189]
	global_load_lds_dwordx4 v[2:3], off
	v_lshl_add_u64 v[2:3], s[4:5], 0, v[192:193]
	s_add_i32 m0, s53, 0x1e000
	s_mov_b64 s[48:49], 0xb0080
	global_load_lds_dwordx4 v[2:3], off
	v_bfe_u32 v3, v10, 4, 2
	v_and_b32_e32 v2, 15, v10
	v_lshlrev_b32_e32 v4, 4, v3
	v_lshl_or_b32 v195, s9, 6, v2
	v_lshl_or_b32 v2, v2, 6, v4
	v_lshlrev_b32_e32 v4, 2, v10
	v_and_b32_e32 v4, 32, v4
	v_lshl_or_b32 v194, v3, 3, s43
	v_bitop3_b32 v5, v2, s26, v4 bitop3:0xde
	v_bitop3_b32 v224, v2, s27, v4 bitop3:0xde
	v_cmp_eq_u32_e64 s[4:5], 0, v3
	v_lshlrev_b32_e32 v2, 1, v194
	v_mov_b32_e32 v3, v189
	v_lshl_add_u64 v[2:3], s[6:7], 0, v[2:3]
	s_mov_b64 s[6:7], 0x6400000
	v_lshl_add_u64 v[196:197], v[2:3], 0, s[6:7]
	v_lshrrev_b32_e32 v3, 1, v11
	v_mul_lo_u32 v2, v13, s8
	s_mov_b32 s9, 0xb000
	v_mad_u64_u32 v[2:3], s[6:7], v3, s9, v[2:3]
	v_or_b32_e32 v2, v2, v12
	v_add_lshl_u32 v2, v2, v14, 1
	v_mov_b32_e32 v3, v189
	v_lshl_add_u64 v[198:199], v[2:3], 0, s[48:49]
	v_lshrrev_b32_e32 v3, 1, v15
	v_mul_lo_u32 v2, v16, s8
	v_mad_u64_u32 v[2:3], s[6:7], v3, s9, v[2:3]
	v_or_b32_e32 v2, v2, v17
	s_waitcnt vmcnt(6)
	s_cmpk_lt_u32 s42, 0x100
	v_add_lshl_u32 v2, v2, v18, 1
	v_mov_b32_e32 v3, v189
	s_cselect_b64 s[26:27], -1, 0
	v_lshl_add_u64 v[200:201], v[2:3], 0, s[48:49]
	s_add_i32 s63, 0, 0x10000
	s_add_i32 s64, 0, 0x14000
	v_mbcnt_lo_u32_b32 v2, -1, 0
	s_ashr_i32 s60, s38, 31
	s_mov_b32 s61, s38
	s_ashr_i32 s62, s2, 31
	v_mov_b64_e32 v[202:203], 0x200
	v_mov_b64_e32 v[204:205], 0x1ff
	v_add_u32_e32 v225, s63, v224
	v_add_u32_e32 v226, s64, v224
	v_add_u32_e32 v227, 0, v5
	v_mbcnt_hi_u32_b32 v228, -1, v2
	s_barrier
	s_branch .LBB0_1898

.LBB0_1908:
	s_add_u32 s69, s46, 0x100
	v_mov_b32_e32 v2, 0
	s_addc_u32 s70, s47, 0
	s_mov_b32 s71, -2
	s_waitcnt lgkmcnt(0)
	v_mov_b32_e32 v3, v2
	v_mov_b32_e32 v4, v2
	v_mov_b32_e32 v5, v2
	v_mov_b32_e32 v6, v2
	v_mov_b32_e32 v7, v2
	v_mov_b32_e32 v8, v2
	v_mov_b32_e32 v9, v2
	v_mov_b32_e32 v18, v2
	v_mov_b32_e32 v19, v2
	v_mov_b32_e32 v20, v2
	v_mov_b32_e32 v21, v2
	v_mov_b32_e32 v22, v2
	v_mov_b32_e32 v23, v2
	v_mov_b32_e32 v24, v2
	v_mov_b32_e32 v25, v2
	v_mov_b32_e32 v34, v2
	v_mov_b32_e32 v35, v2
	v_mov_b32_e32 v36, v2
	v_mov_b32_e32 v37, v2
	v_mov_b32_e32 v38, v2
	v_mov_b32_e32 v39, v2
	v_mov_b32_e32 v40, v2
	v_mov_b32_e32 v41, v2
	v_mov_b32_e32 v50, v2
	v_mov_b32_e32 v51, v2
	v_mov_b32_e32 v52, v2
	v_mov_b32_e32 v53, v2
	v_mov_b32_e32 v54, v2
	v_mov_b32_e32 v55, v2
	v_mov_b32_e32 v56, v2
	v_mov_b32_e32 v57, v2
	v_mov_b32_e32 v10, v2
	v_mov_b32_e32 v11, v2
	v_mov_b32_e32 v12, v2
	v_mov_b32_e32 v13, v2
	v_mov_b32_e32 v14, v2
	v_mov_b32_e32 v15, v2
	v_mov_b32_e32 v16, v2
	v_mov_b32_e32 v17, v2
	v_mov_b32_e32 v26, v2
	v_mov_b32_e32 v27, v2
	v_mov_b32_e32 v28, v2
	v_mov_b32_e32 v29, v2
	v_mov_b32_e32 v30, v2
	v_mov_b32_e32 v31, v2
	v_mov_b32_e32 v32, v2
	v_mov_b32_e32 v33, v2
	v_mov_b32_e32 v42, v2
	v_mov_b32_e32 v43, v2
	v_mov_b32_e32 v44, v2
	v_mov_b32_e32 v45, v2
	v_mov_b32_e32 v46, v2
	v_mov_b32_e32 v47, v2
	v_mov_b32_e32 v48, v2
	v_mov_b32_e32 v49, v2
	v_mov_b32_e32 v58, v2
	v_mov_b32_e32 v59, v2
	v_mov_b32_e32 v60, v2
	v_mov_b32_e32 v61, v2
	v_mov_b32_e32 v62, v2
	v_mov_b32_e32 v63, v2
	v_mov_b32_e32 v64, v2
	v_mov_b32_e32 v65, v2
	v_mov_b32_e32 v66, v2
	v_mov_b32_e32 v67, v2
	v_mov_b32_e32 v68, v2
	v_mov_b32_e32 v69, v2
	v_mov_b32_e32 v70, v2
	v_mov_b32_e32 v71, v2
	v_mov_b32_e32 v72, v2
	v_mov_b32_e32 v73, v2
	s_waitcnt vmcnt(0)
	v_mov_b32_e32 v82, v2
	v_mov_b32_e32 v83, v2
	v_mov_b32_e32 v84, v2
	v_mov_b32_e32 v85, v2
	v_mov_b32_e32 v86, v2
	v_mov_b32_e32 v87, v2
	v_mov_b32_e32 v88, v2
	v_mov_b32_e32 v89, v2
	v_mov_b32_e32 v98, v2
	v_mov_b32_e32 v99, v2
	v_mov_b32_e32 v100, v2
	v_mov_b32_e32 v101, v2
	v_mov_b32_e32 v102, v2
	v_mov_b32_e32 v103, v2
	v_mov_b32_e32 v104, v2
	v_mov_b32_e32 v105, v2
	v_mov_b32_e32 v118, v2
	v_mov_b32_e32 v119, v2
	v_mov_b32_e32 v120, v2
	v_mov_b32_e32 v121, v2
	v_mov_b32_e32 v122, v2
	v_mov_b32_e32 v123, v2
	v_mov_b32_e32 v124, v2
	v_mov_b32_e32 v125, v2
	v_mov_b32_e32 v74, v2
	v_mov_b32_e32 v75, v2
	v_mov_b32_e32 v76, v2
	v_mov_b32_e32 v77, v2
	v_mov_b32_e32 v78, v2
	v_mov_b32_e32 v79, v2
	v_mov_b32_e32 v80, v2
	v_mov_b32_e32 v81, v2
	v_mov_b32_e32 v90, v2
	v_mov_b32_e32 v91, v2
	v_mov_b32_e32 v92, v2
	v_mov_b32_e32 v93, v2
	v_mov_b32_e32 v94, v2
	v_mov_b32_e32 v95, v2
	v_mov_b32_e32 v96, v2
	v_mov_b32_e32 v97, v2
	v_mov_b32_e32 v106, v2
	v_mov_b32_e32 v107, v2
	v_mov_b32_e32 v108, v2
	v_mov_b32_e32 v109, v2
	v_mov_b32_e32 v110, v2
	v_mov_b32_e32 v111, v2
	v_mov_b32_e32 v112, v2
	v_mov_b32_e32 v113, v2
	v_mov_b32_e32 v130, v2
	v_mov_b32_e32 v131, v2
	v_mov_b32_e32 v132, v2
	v_mov_b32_e32 v133, v2
	v_mov_b32_e32 v134, v2
	v_mov_b32_e32 v135, v2
	v_mov_b32_e32 v136, v2
	v_mov_b32_e32 v137, v2
	s_cmp_eq_u64 s[26:27], 0
	s_cbranch_scc1 .Lhb_B_p15
.LBB0_1909:
	ds_read_b128 v[114:117], v225
	ds_read_b128 v[126:129], v225 offset:1024
	ds_read_b128 v[138:141], v225 offset:2048
	ds_read_b128 v[142:145], v225 offset:3072
	ds_read_b128 v[146:149], v226
	ds_read_b128 v[150:153], v226 offset:1024
	ds_read_b128 v[154:157], v226 offset:2048
	ds_read_b128 v[158:161], v226 offset:3072
	s_add_u32 s46, s44, 0x100
	s_addc_u32 s47, s45, 0
	s_cmp_eq_u32 s71, 40
	s_cselect_b32 s51, s9, s47
	s_cselect_b32 s50, s8, s46
	s_cselect_b32 s49, s43, s70
	s_cselect_b32 s48, s42, s69
	v_lshl_add_u64 v[214:215], s[44:45], 0, v[198:199]
	s_add_i32 m0, s53, 0xc000
	ds_read_b128 v[162:165], v227
	ds_read_b128 v[166:169], v227 offset:1024
	ds_read_b128 v[170:173], v227 offset:2048
	ds_read_b128 v[174:177], v227 offset:3072
	ds_read_b128 v[178:181], v227 offset:4096
	ds_read_b128 v[182:185], v227 offset:5120
	ds_read_b128 v[206:209], v227 offset:6144
	ds_read_b128 v[210:213], v227 offset:7168
	global_load_lds_dwordx4 v[214:215], off
	v_lshl_add_u64 v[214:215], s[44:45], 0, v[200:201]
	s_add_i32 m0, s53, 0xe000
	s_nop 0
	global_load_lds_dwordx4 v[214:215], off
	s_waitcnt vmcnt(8)
	s_waitcnt lgkmcnt(0)
	s_setprio 1
	v_mfma_f32_16x16x32_bf16 v[134:137], v[114:117], v[162:165], v[134:137]
	v_mfma_f32_16x16x32_bf16 v[130:133], v[138:141], v[162:165], v[130:133]
	v_mfma_f32_16x16x32_bf16 v[110:113], v[114:117], v[170:173], v[110:113]
	v_mfma_f32_16x16x32_bf16 v[106:109], v[138:141], v[170:173], v[106:109]
	v_mfma_f32_16x16x32_bf16 v[94:97], v[114:117], v[178:181], v[94:97]
	v_mfma_f32_16x16x32_bf16 v[90:93], v[138:141], v[178:181], v[90:93]
	v_mfma_f32_16x16x32_bf16 v[78:81], v[114:117], v[206:209], v[78:81]
	v_mfma_f32_16x16x32_bf16 v[74:77], v[138:141], v[206:209], v[74:77]
	v_mfma_f32_16x16x32_bf16 v[134:137], v[126:129], v[166:169], v[134:137]
	v_mfma_f32_16x16x32_bf16 v[130:133], v[142:145], v[166:169], v[130:133]
	v_mfma_f32_16x16x32_bf16 v[110:113], v[126:129], v[174:177], v[110:113]
	v_mfma_f32_16x16x32_bf16 v[106:109], v[142:145], v[174:177], v[106:109]
	v_mfma_f32_16x16x32_bf16 v[94:97], v[126:129], v[182:185], v[94:97]
	v_mfma_f32_16x16x32_bf16 v[90:93], v[142:145], v[182:185], v[90:93]
	v_mfma_f32_16x16x32_bf16 v[78:81], v[126:129], v[210:213], v[78:81]
	v_mfma_f32_16x16x32_bf16 v[74:77], v[142:145], v[210:213], v[74:77]
	s_setprio 0
	s_setprio 1
	v_mfma_f32_16x16x32_bf16 v[122:125], v[146:149], v[162:165], v[122:125]
	v_mfma_f32_16x16x32_bf16 v[118:121], v[154:157], v[162:165], v[118:121]
	v_mfma_f32_16x16x32_bf16 v[102:105], v[146:149], v[170:173], v[102:105]
	v_mfma_f32_16x16x32_bf16 v[98:101], v[154:157], v[170:173], v[98:101]
	v_mfma_f32_16x16x32_bf16 v[86:89], v[146:149], v[178:181], v[86:89]
	v_mfma_f32_16x16x32_bf16 v[82:85], v[154:157], v[178:181], v[82:85]
	v_mfma_f32_16x16x32_bf16 v[70:73], v[146:149], v[206:209], v[70:73]
	v_mfma_f32_16x16x32_bf16 v[66:69], v[154:157], v[206:209], v[66:69]
	v_mfma_f32_16x16x32_bf16 v[122:125], v[150:153], v[166:169], v[122:125]
	v_mfma_f32_16x16x32_bf16 v[118:121], v[158:161], v[166:169], v[118:121]
	v_mfma_f32_16x16x32_bf16 v[102:105], v[150:153], v[174:177], v[102:105]
	v_mfma_f32_16x16x32_bf16 v[98:101], v[158:161], v[174:177], v[98:101]
	v_mfma_f32_16x16x32_bf16 v[86:89], v[150:153], v[182:185], v[86:89]
	v_mfma_f32_16x16x32_bf16 v[82:85], v[158:161], v[182:185], v[82:85]
	v_mfma_f32_16x16x32_bf16 v[70:73], v[150:153], v[210:213], v[70:73]
	v_mfma_f32_16x16x32_bf16 v[66:69], v[158:161], v[210:213], v[66:69]
	s_setprio 0
	s_barrier
	s_add_i32 s44, s63, s52
	v_lshl_add_u64 v[214:215], s[48:49], 0, v[188:189]
	s_mov_b32 m0, s44
	ds_read_b128 v[162:165], v227 offset:16384
	ds_read_b128 v[166:169], v227 offset:17408
	ds_read_b128 v[170:173], v227 offset:18432
	ds_read_b128 v[174:177], v227 offset:19456
	ds_read_b128 v[178:181], v227 offset:20480
	ds_read_b128 v[182:185], v227 offset:21504
	ds_read_b128 v[206:209], v227 offset:22528
	ds_read_b128 v[210:213], v227 offset:23552
	global_load_lds_dwordx4 v[214:215], off
	s_add_i32 m0, s44, 0x2000
	s_add_u32 s44, s48, 0xb0000
	v_lshl_add_u64 v[216:217], s[48:49], 0, v[192:193]
	s_addc_u32 s45, s49, 0
	s_add_i32 s72, s64, s52
	global_load_lds_dwordx4 v[216:217], off
	v_lshl_add_u64 v[218:219], s[44:45], 0, v[188:189]
	s_mov_b32 m0, s72
	v_lshl_add_u64 v[220:221], s[50:51], 0, v[190:191]
	global_load_lds_dwordx4 v[218:219], off
	v_lshl_add_u64 v[218:219], s[44:45], 0, v[192:193]
	s_add_i32 m0, s72, 0x2000
	s_nop 0
	global_load_lds_dwordx4 v[218:219], off
	v_lshl_add_u64 v[218:219], s[50:51], 0, v[186:187]
	s_mov_b32 m0, s53
	s_nop 0
	global_load_lds_dwordx4 v[218:219], off
	s_mov_b32 m0, s54
	s_nop 0
	global_load_lds_dwordx4 v[220:221], off
	s_waitcnt vmcnt(8)
	s_waitcnt lgkmcnt(0)
	s_setprio 1
	v_mfma_f32_16x16x32_bf16 v[62:65], v[114:117], v[162:165], v[62:65]
	v_mfma_f32_16x16x32_bf16 v[58:61], v[138:141], v[162:165], v[58:61]
	v_mfma_f32_16x16x32_bf16 v[46:49], v[114:117], v[170:173], v[46:49]
	v_mfma_f32_16x16x32_bf16 v[42:45], v[138:141], v[170:173], v[42:45]
	v_mfma_f32_16x16x32_bf16 v[30:33], v[114:117], v[178:181], v[30:33]
	v_mfma_f32_16x16x32_bf16 v[26:29], v[138:141], v[178:181], v[26:29]
	v_mfma_f32_16x16x32_bf16 v[14:17], v[114:117], v[206:209], v[14:17]
	v_mfma_f32_16x16x32_bf16 v[10:13], v[138:141], v[206:209], v[10:13]
	v_mfma_f32_16x16x32_bf16 v[62:65], v[126:129], v[166:169], v[62:65]
	v_mfma_f32_16x16x32_bf16 v[58:61], v[142:145], v[166:169], v[58:61]
	v_mfma_f32_16x16x32_bf16 v[46:49], v[126:129], v[174:177], v[46:49]
	v_mfma_f32_16x16x32_bf16 v[42:45], v[142:145], v[174:177], v[42:45]
	v_mfma_f32_16x16x32_bf16 v[30:33], v[126:129], v[182:185], v[30:33]
	v_mfma_f32_16x16x32_bf16 v[26:29], v[142:145], v[182:185], v[26:29]
	v_mfma_f32_16x16x32_bf16 v[14:17], v[126:129], v[210:213], v[14:17]
	v_mfma_f32_16x16x32_bf16 v[10:13], v[142:145], v[210:213], v[10:13]
	s_setprio 0
	s_setprio 1
	v_mfma_f32_16x16x32_bf16 v[54:57], v[146:149], v[162:165], v[54:57]
	v_mfma_f32_16x16x32_bf16 v[50:53], v[154:157], v[162:165], v[50:53]
	v_mfma_f32_16x16x32_bf16 v[38:41], v[146:149], v[170:173], v[38:41]
	v_mfma_f32_16x16x32_bf16 v[34:37], v[154:157], v[170:173], v[34:37]
	v_mfma_f32_16x16x32_bf16 v[22:25], v[146:149], v[178:181], v[22:25]
	v_mfma_f32_16x16x32_bf16 v[18:21], v[154:157], v[178:181], v[18:21]
	v_mfma_f32_16x16x32_bf16 v[6:9], v[146:149], v[206:209], v[6:9]
	v_mfma_f32_16x16x32_bf16 v[2:5], v[154:157], v[206:209], v[2:5]
	v_mfma_f32_16x16x32_bf16 v[54:57], v[150:153], v[166:169], v[54:57]
	v_mfma_f32_16x16x32_bf16 v[50:53], v[158:161], v[166:169], v[50:53]
	v_mfma_f32_16x16x32_bf16 v[38:41], v[150:153], v[174:177], v[38:41]
	v_mfma_f32_16x16x32_bf16 v[34:37], v[158:161], v[174:177], v[34:37]
	v_mfma_f32_16x16x32_bf16 v[22:25], v[150:153], v[182:185], v[22:25]
	v_mfma_f32_16x16x32_bf16 v[18:21], v[158:161], v[182:185], v[18:21]
	v_mfma_f32_16x16x32_bf16 v[6:9], v[150:153], v[210:213], v[6:9]
	v_mfma_f32_16x16x32_bf16 v[2:5], v[158:161], v[210:213], v[2:5]
	s_setprio 0
	s_barrier
	s_add_i32 s72, 0, 0x18000
	s_add_i32 s73, 0, 0x1c000
	v_add_u32_e32 v142, s72, v224
	v_add_u32_e32 v158, s73, v224
	ds_read_b128 v[114:117], v142
	ds_read_b128 v[126:129], v142 offset:1024
	ds_read_b128 v[138:141], v142 offset:2048
	ds_read_b128 v[142:145], v142 offset:3072
	ds_read_b128 v[146:149], v158
	ds_read_b128 v[150:153], v158 offset:1024
	ds_read_b128 v[154:157], v158 offset:2048
	ds_read_b128 v[158:161], v158 offset:3072
	s_add_u32 s44, s50, 0xb0000
	s_addc_u32 s45, s51, 0
	s_mov_b32 m0, s55
	v_lshl_add_u64 v[222:223], s[44:45], 0, v[186:187]
	ds_read_b128 v[162:165], v227 offset:32768
	ds_read_b128 v[166:169], v227 offset:33792
	ds_read_b128 v[170:173], v227 offset:34816
	ds_read_b128 v[174:177], v227 offset:35840
	ds_read_b128 v[178:181], v227 offset:36864
	ds_read_b128 v[182:185], v227 offset:37888
	ds_read_b128 v[206:209], v227 offset:38912
	ds_read_b128 v[210:213], v227 offset:39936
	global_load_lds_dwordx4 v[222:223], off
	v_lshl_add_u64 v[222:223], s[44:45], 0, v[190:191]
	s_mov_b32 m0, s56
	s_nop 0
	global_load_lds_dwordx4 v[222:223], off
	s_waitcnt vmcnt(8)
	s_waitcnt lgkmcnt(0)
	s_setprio 1
	v_mfma_f32_16x16x32_bf16 v[134:137], v[114:117], v[162:165], v[134:137]
	v_mfma_f32_16x16x32_bf16 v[130:133], v[138:141], v[162:165], v[130:133]
	v_mfma_f32_16x16x32_bf16 v[110:113], v[114:117], v[170:173], v[110:113]
	v_mfma_f32_16x16x32_bf16 v[106:109], v[138:141], v[170:173], v[106:109]
	v_mfma_f32_16x16x32_bf16 v[94:97], v[114:117], v[178:181], v[94:97]
	v_mfma_f32_16x16x32_bf16 v[90:93], v[138:141], v[178:181], v[90:93]
	v_mfma_f32_16x16x32_bf16 v[78:81], v[114:117], v[206:209], v[78:81]
	v_mfma_f32_16x16x32_bf16 v[74:77], v[138:141], v[206:209], v[74:77]
	v_mfma_f32_16x16x32_bf16 v[134:137], v[126:129], v[166:169], v[134:137]
	v_mfma_f32_16x16x32_bf16 v[130:133], v[142:145], v[166:169], v[130:133]
	v_mfma_f32_16x16x32_bf16 v[110:113], v[126:129], v[174:177], v[110:113]
	v_mfma_f32_16x16x32_bf16 v[106:109], v[142:145], v[174:177], v[106:109]
	v_mfma_f32_16x16x32_bf16 v[94:97], v[126:129], v[182:185], v[94:97]
	v_mfma_f32_16x16x32_bf16 v[90:93], v[142:145], v[182:185], v[90:93]
	v_mfma_f32_16x16x32_bf16 v[78:81], v[126:129], v[210:213], v[78:81]
	v_mfma_f32_16x16x32_bf16 v[74:77], v[142:145], v[210:213], v[74:77]
	s_setprio 0
	s_setprio 1
	v_mfma_f32_16x16x32_bf16 v[122:125], v[146:149], v[162:165], v[122:125]
	v_mfma_f32_16x16x32_bf16 v[118:121], v[154:157], v[162:165], v[118:121]
	v_mfma_f32_16x16x32_bf16 v[102:105], v[146:149], v[170:173], v[102:105]
	v_mfma_f32_16x16x32_bf16 v[98:101], v[154:157], v[170:173], v[98:101]
	v_mfma_f32_16x16x32_bf16 v[86:89], v[146:149], v[178:181], v[86:89]
	v_mfma_f32_16x16x32_bf16 v[82:85], v[154:157], v[178:181], v[82:85]
	v_mfma_f32_16x16x32_bf16 v[70:73], v[146:149], v[206:209], v[70:73]
	v_mfma_f32_16x16x32_bf16 v[66:69], v[154:157], v[206:209], v[66:69]
	v_mfma_f32_16x16x32_bf16 v[122:125], v[150:153], v[166:169], v[122:125]
	v_mfma_f32_16x16x32_bf16 v[118:121], v[158:161], v[166:169], v[118:121]
	v_mfma_f32_16x16x32_bf16 v[102:105], v[150:153], v[174:177], v[102:105]
	v_mfma_f32_16x16x32_bf16 v[98:101], v[158:161], v[174:177], v[98:101]
	v_mfma_f32_16x16x32_bf16 v[86:89], v[150:153], v[182:185], v[86:89]
	v_mfma_f32_16x16x32_bf16 v[82:85], v[158:161], v[182:185], v[82:85]
	v_mfma_f32_16x16x32_bf16 v[70:73], v[150:153], v[210:213], v[70:73]
	v_mfma_f32_16x16x32_bf16 v[66:69], v[158:161], v[210:213], v[66:69]
	s_setprio 0
	s_barrier
	s_add_i32 s44, s72, s52
	v_lshl_add_u64 v[214:215], v[214:215], 0, s[24:25]
	s_mov_b32 m0, s44
	ds_read_b128 v[162:165], v227 offset:49152
	ds_read_b128 v[166:169], v227 offset:50176
	ds_read_b128 v[170:173], v227 offset:51200
	ds_read_b128 v[174:177], v227 offset:52224
	ds_read_b128 v[178:181], v227 offset:53248
	ds_read_b128 v[182:185], v227 offset:54272
	ds_read_b128 v[206:209], v227 offset:55296
	ds_read_b128 v[210:213], v227 offset:56320
	global_load_lds_dwordx4 v[214:215], off
	s_add_i32 m0, s44, 0x2000
	s_add_u32 s44, s48, 0xb0080
	v_lshl_add_u64 v[214:215], v[216:217], 0, s[24:25]
	s_addc_u32 s45, s49, 0
	s_add_i32 s48, s73, s52
	global_load_lds_dwordx4 v[214:215], off
	v_lshl_add_u64 v[214:215], s[44:45], 0, v[188:189]
	s_mov_b32 m0, s48
	s_nop 0
	global_load_lds_dwordx4 v[214:215], off
	v_lshl_add_u64 v[214:215], s[44:45], 0, v[192:193]
	s_add_i32 m0, s48, 0x2000
	s_nop 0
	global_load_lds_dwordx4 v[214:215], off
	v_lshl_add_u64 v[214:215], v[218:219], 0, s[24:25]
	s_mov_b32 m0, s58
	s_nop 0
	global_load_lds_dwordx4 v[214:215], off
	v_lshl_add_u64 v[214:215], v[220:221], 0, s[24:25]
	s_mov_b32 m0, s59
	s_nop 0
	global_load_lds_dwordx4 v[214:215], off
	s_waitcnt vmcnt(8)
	s_waitcnt lgkmcnt(0)
	s_setprio 1
	v_mfma_f32_16x16x32_bf16 v[62:65], v[114:117], v[162:165], v[62:65]
	v_mfma_f32_16x16x32_bf16 v[58:61], v[138:141], v[162:165], v[58:61]
	v_mfma_f32_16x16x32_bf16 v[46:49], v[114:117], v[170:173], v[46:49]
	v_mfma_f32_16x16x32_bf16 v[42:45], v[138:141], v[170:173], v[42:45]
	v_mfma_f32_16x16x32_bf16 v[30:33], v[114:117], v[178:181], v[30:33]
	v_mfma_f32_16x16x32_bf16 v[26:29], v[138:141], v[178:181], v[26:29]
	v_mfma_f32_16x16x32_bf16 v[14:17], v[114:117], v[206:209], v[14:17]
	v_mfma_f32_16x16x32_bf16 v[10:13], v[138:141], v[206:209], v[10:13]
	v_mfma_f32_16x16x32_bf16 v[62:65], v[126:129], v[166:169], v[62:65]
	v_mfma_f32_16x16x32_bf16 v[58:61], v[142:145], v[166:169], v[58:61]
	v_mfma_f32_16x16x32_bf16 v[46:49], v[126:129], v[174:177], v[46:49]
	v_mfma_f32_16x16x32_bf16 v[42:45], v[142:145], v[174:177], v[42:45]
	v_mfma_f32_16x16x32_bf16 v[30:33], v[126:129], v[182:185], v[30:33]
	v_mfma_f32_16x16x32_bf16 v[26:29], v[142:145], v[182:185], v[26:29]
	v_mfma_f32_16x16x32_bf16 v[14:17], v[126:129], v[210:213], v[14:17]
	v_mfma_f32_16x16x32_bf16 v[10:13], v[142:145], v[210:213], v[10:13]
	s_setprio 0
	s_setprio 1
	v_mfma_f32_16x16x32_bf16 v[54:57], v[146:149], v[162:165], v[54:57]
	v_mfma_f32_16x16x32_bf16 v[50:53], v[154:157], v[162:165], v[50:53]
	v_mfma_f32_16x16x32_bf16 v[38:41], v[146:149], v[170:173], v[38:41]
	v_mfma_f32_16x16x32_bf16 v[34:37], v[154:157], v[170:173], v[34:37]
	v_mfma_f32_16x16x32_bf16 v[22:25], v[146:149], v[178:181], v[22:25]
	v_mfma_f32_16x16x32_bf16 v[18:21], v[154:157], v[178:181], v[18:21]
	v_mfma_f32_16x16x32_bf16 v[6:9], v[146:149], v[206:209], v[6:9]
	v_mfma_f32_16x16x32_bf16 v[2:5], v[154:157], v[206:209], v[2:5]
	v_mfma_f32_16x16x32_bf16 v[54:57], v[150:153], v[166:169], v[54:57]
	v_mfma_f32_16x16x32_bf16 v[50:53], v[158:161], v[166:169], v[50:53]
	v_mfma_f32_16x16x32_bf16 v[38:41], v[150:153], v[174:177], v[38:41]
	v_mfma_f32_16x16x32_bf16 v[34:37], v[158:161], v[174:177], v[34:37]
	v_mfma_f32_16x16x32_bf16 v[22:25], v[150:153], v[182:185], v[22:25]
	v_mfma_f32_16x16x32_bf16 v[18:21], v[158:161], v[182:185], v[18:21]
	v_mfma_f32_16x16x32_bf16 v[6:9], v[150:153], v[210:213], v[6:9]
	v_mfma_f32_16x16x32_bf16 v[2:5], v[158:161], v[210:213], v[2:5]
	s_setprio 0
	s_barrier
	s_add_i32 s71, s71, 2
	s_add_u32 s69, s69, 0x100
	s_addc_u32 s70, s70, 0
	s_cmp_gt_u32 s71, 41
	s_mov_b64 s[44:45], s[46:47]
	s_cbranch_scc0 .LBB0_1909
	s_branch .Lhb_exit_p15
.Lhb_B_p15:
	ds_read_b128 v[114:117], v225
	ds_read_b128 v[126:129], v225 offset:1024
	ds_read_b128 v[138:141], v225 offset:2048
	ds_read_b128 v[142:145], v225 offset:3072
	ds_read_b128 v[146:149], v226
	ds_read_b128 v[150:153], v226 offset:1024
	ds_read_b128 v[154:157], v226 offset:2048
	ds_read_b128 v[158:161], v226 offset:3072
	s_add_u32 s46, s44, 0x100
	s_addc_u32 s47, s45, 0
	s_cmp_eq_u32 s71, 40
	s_cselect_b32 s51, s9, s47
	s_cselect_b32 s50, s8, s46
	s_cselect_b32 s49, s43, s70
	s_cselect_b32 s48, s42, s69
	v_lshl_add_u64 v[214:215], s[44:45], 0, v[198:199]
	s_add_i32 m0, s53, 0xc000
	ds_read_b128 v[162:165], v227
	ds_read_b128 v[166:169], v227 offset:1024
	ds_read_b128 v[170:173], v227 offset:2048
	ds_read_b128 v[174:177], v227 offset:3072
	ds_read_b128 v[178:181], v227 offset:4096
	ds_read_b128 v[182:185], v227 offset:5120
	ds_read_b128 v[206:209], v227 offset:6144
	ds_read_b128 v[210:213], v227 offset:7168
	global_load_lds_dwordx4 v[214:215], off
	v_lshl_add_u64 v[214:215], s[44:45], 0, v[200:201]
	s_add_i32 m0, s53, 0xe000
	s_nop 0
	global_load_lds_dwordx4 v[214:215], off
	s_waitcnt vmcnt(8)
	s_waitcnt lgkmcnt(0)
	s_setprio 1
	s_barrier
	v_mfma_f32_16x16x32_bf16 v[134:137], v[114:117], v[162:165], v[134:137]
	v_mfma_f32_16x16x32_bf16 v[130:133], v[138:141], v[162:165], v[130:133]
	v_mfma_f32_16x16x32_bf16 v[110:113], v[114:117], v[170:173], v[110:113]
	v_mfma_f32_16x16x32_bf16 v[106:109], v[138:141], v[170:173], v[106:109]
	v_mfma_f32_16x16x32_bf16 v[94:97], v[114:117], v[178:181], v[94:97]
	v_mfma_f32_16x16x32_bf16 v[90:93], v[138:141], v[178:181], v[90:93]
	v_mfma_f32_16x16x32_bf16 v[78:81], v[114:117], v[206:209], v[78:81]
	v_mfma_f32_16x16x32_bf16 v[74:77], v[138:141], v[206:209], v[74:77]
	v_mfma_f32_16x16x32_bf16 v[134:137], v[126:129], v[166:169], v[134:137]
	v_mfma_f32_16x16x32_bf16 v[130:133], v[142:145], v[166:169], v[130:133]
	v_mfma_f32_16x16x32_bf16 v[110:113], v[126:129], v[174:177], v[110:113]
	v_mfma_f32_16x16x32_bf16 v[106:109], v[142:145], v[174:177], v[106:109]
	v_mfma_f32_16x16x32_bf16 v[94:97], v[126:129], v[182:185], v[94:97]
	v_mfma_f32_16x16x32_bf16 v[90:93], v[142:145], v[182:185], v[90:93]
	v_mfma_f32_16x16x32_bf16 v[78:81], v[126:129], v[210:213], v[78:81]
	v_mfma_f32_16x16x32_bf16 v[74:77], v[142:145], v[210:213], v[74:77]
	s_setprio 0
	s_setprio 1
	v_mfma_f32_16x16x32_bf16 v[122:125], v[146:149], v[162:165], v[122:125]
	v_mfma_f32_16x16x32_bf16 v[118:121], v[154:157], v[162:165], v[118:121]
	v_mfma_f32_16x16x32_bf16 v[102:105], v[146:149], v[170:173], v[102:105]
	v_mfma_f32_16x16x32_bf16 v[98:101], v[154:157], v[170:173], v[98:101]
	v_mfma_f32_16x16x32_bf16 v[86:89], v[146:149], v[178:181], v[86:89]
	v_mfma_f32_16x16x32_bf16 v[82:85], v[154:157], v[178:181], v[82:85]
	v_mfma_f32_16x16x32_bf16 v[70:73], v[146:149], v[206:209], v[70:73]
	v_mfma_f32_16x16x32_bf16 v[66:69], v[154:157], v[206:209], v[66:69]
	v_mfma_f32_16x16x32_bf16 v[122:125], v[150:153], v[166:169], v[122:125]
	v_mfma_f32_16x16x32_bf16 v[118:121], v[158:161], v[166:169], v[118:121]
	v_mfma_f32_16x16x32_bf16 v[102:105], v[150:153], v[174:177], v[102:105]
	v_mfma_f32_16x16x32_bf16 v[98:101], v[158:161], v[174:177], v[98:101]
	v_mfma_f32_16x16x32_bf16 v[86:89], v[150:153], v[182:185], v[86:89]
	v_mfma_f32_16x16x32_bf16 v[82:85], v[158:161], v[182:185], v[82:85]
	v_mfma_f32_16x16x32_bf16 v[70:73], v[150:153], v[210:213], v[70:73]
	v_mfma_f32_16x16x32_bf16 v[66:69], v[158:161], v[210:213], v[66:69]
	s_setprio 0
	s_add_i32 s44, s63, s52
	v_lshl_add_u64 v[214:215], s[48:49], 0, v[188:189]
	s_mov_b32 m0, s44
	ds_read_b128 v[162:165], v227 offset:16384
	ds_read_b128 v[166:169], v227 offset:17408
	ds_read_b128 v[170:173], v227 offset:18432
	ds_read_b128 v[174:177], v227 offset:19456
	ds_read_b128 v[178:181], v227 offset:20480
	ds_read_b128 v[182:185], v227 offset:21504
	ds_read_b128 v[206:209], v227 offset:22528
	ds_read_b128 v[210:213], v227 offset:23552
	global_load_lds_dwordx4 v[214:215], off
	s_add_i32 m0, s44, 0x2000
	s_add_u32 s44, s48, 0xb0000
	v_lshl_add_u64 v[216:217], s[48:49], 0, v[192:193]
	s_addc_u32 s45, s49, 0
	s_add_i32 s72, s64, s52
	global_load_lds_dwordx4 v[216:217], off
	v_lshl_add_u64 v[218:219], s[44:45], 0, v[188:189]
	s_mov_b32 m0, s72
	v_lshl_add_u64 v[220:221], s[50:51], 0, v[190:191]
	global_load_lds_dwordx4 v[218:219], off
	v_lshl_add_u64 v[218:219], s[44:45], 0, v[192:193]
	s_add_i32 m0, s72, 0x2000
	s_nop 0
	global_load_lds_dwordx4 v[218:219], off
	v_lshl_add_u64 v[218:219], s[50:51], 0, v[186:187]
	s_mov_b32 m0, s53
	s_nop 0
	global_load_lds_dwordx4 v[218:219], off
	s_mov_b32 m0, s54
	s_nop 0
	global_load_lds_dwordx4 v[220:221], off
	s_waitcnt vmcnt(8)
	s_waitcnt lgkmcnt(0)
	s_setprio 1
	s_barrier
	v_mfma_f32_16x16x32_bf16 v[62:65], v[114:117], v[162:165], v[62:65]
	v_mfma_f32_16x16x32_bf16 v[58:61], v[138:141], v[162:165], v[58:61]
	v_mfma_f32_16x16x32_bf16 v[46:49], v[114:117], v[170:173], v[46:49]
	v_mfma_f32_16x16x32_bf16 v[42:45], v[138:141], v[170:173], v[42:45]
	v_mfma_f32_16x16x32_bf16 v[30:33], v[114:117], v[178:181], v[30:33]
	v_mfma_f32_16x16x32_bf16 v[26:29], v[138:141], v[178:181], v[26:29]
	v_mfma_f32_16x16x32_bf16 v[14:17], v[114:117], v[206:209], v[14:17]
	v_mfma_f32_16x16x32_bf16 v[10:13], v[138:141], v[206:209], v[10:13]
	v_mfma_f32_16x16x32_bf16 v[62:65], v[126:129], v[166:169], v[62:65]
	v_mfma_f32_16x16x32_bf16 v[58:61], v[142:145], v[166:169], v[58:61]
	v_mfma_f32_16x16x32_bf16 v[46:49], v[126:129], v[174:177], v[46:49]
	v_mfma_f32_16x16x32_bf16 v[42:45], v[142:145], v[174:177], v[42:45]
	v_mfma_f32_16x16x32_bf16 v[30:33], v[126:129], v[182:185], v[30:33]
	v_mfma_f32_16x16x32_bf16 v[26:29], v[142:145], v[182:185], v[26:29]
	v_mfma_f32_16x16x32_bf16 v[14:17], v[126:129], v[210:213], v[14:17]
	v_mfma_f32_16x16x32_bf16 v[10:13], v[142:145], v[210:213], v[10:13]
	s_setprio 0
	s_setprio 1
	v_mfma_f32_16x16x32_bf16 v[54:57], v[146:149], v[162:165], v[54:57]
	v_mfma_f32_16x16x32_bf16 v[50:53], v[154:157], v[162:165], v[50:53]
	v_mfma_f32_16x16x32_bf16 v[38:41], v[146:149], v[170:173], v[38:41]
	v_mfma_f32_16x16x32_bf16 v[34:37], v[154:157], v[170:173], v[34:37]
	v_mfma_f32_16x16x32_bf16 v[22:25], v[146:149], v[178:181], v[22:25]
	v_mfma_f32_16x16x32_bf16 v[18:21], v[154:157], v[178:181], v[18:21]
	v_mfma_f32_16x16x32_bf16 v[6:9], v[146:149], v[206:209], v[6:9]
	v_mfma_f32_16x16x32_bf16 v[2:5], v[154:157], v[206:209], v[2:5]
	v_mfma_f32_16x16x32_bf16 v[54:57], v[150:153], v[166:169], v[54:57]
	v_mfma_f32_16x16x32_bf16 v[50:53], v[158:161], v[166:169], v[50:53]
	v_mfma_f32_16x16x32_bf16 v[38:41], v[150:153], v[174:177], v[38:41]
	v_mfma_f32_16x16x32_bf16 v[34:37], v[158:161], v[174:177], v[34:37]
	v_mfma_f32_16x16x32_bf16 v[22:25], v[150:153], v[182:185], v[22:25]
	v_mfma_f32_16x16x32_bf16 v[18:21], v[158:161], v[182:185], v[18:21]
	v_mfma_f32_16x16x32_bf16 v[6:9], v[150:153], v[210:213], v[6:9]
	v_mfma_f32_16x16x32_bf16 v[2:5], v[158:161], v[210:213], v[2:5]
	s_setprio 0
	s_add_i32 s72, 0, 0x18000
	s_add_i32 s73, 0, 0x1c000
	v_add_u32_e32 v142, s72, v224
	v_add_u32_e32 v158, s73, v224
	ds_read_b128 v[114:117], v142
	ds_read_b128 v[126:129], v142 offset:1024
	ds_read_b128 v[138:141], v142 offset:2048
	ds_read_b128 v[142:145], v142 offset:3072
	ds_read_b128 v[146:149], v158
	ds_read_b128 v[150:153], v158 offset:1024
	ds_read_b128 v[154:157], v158 offset:2048
	ds_read_b128 v[158:161], v158 offset:3072
	s_add_u32 s44, s50, 0xb0000
	s_addc_u32 s45, s51, 0
	s_mov_b32 m0, s55
	v_lshl_add_u64 v[222:223], s[44:45], 0, v[186:187]
	ds_read_b128 v[162:165], v227 offset:32768
	ds_read_b128 v[166:169], v227 offset:33792
	ds_read_b128 v[170:173], v227 offset:34816
	ds_read_b128 v[174:177], v227 offset:35840
	ds_read_b128 v[178:181], v227 offset:36864
	ds_read_b128 v[182:185], v227 offset:37888
	ds_read_b128 v[206:209], v227 offset:38912
	ds_read_b128 v[210:213], v227 offset:39936
	global_load_lds_dwordx4 v[222:223], off
	v_lshl_add_u64 v[222:223], s[44:45], 0, v[190:191]
	s_mov_b32 m0, s56
	s_nop 0
	global_load_lds_dwordx4 v[222:223], off
	s_waitcnt vmcnt(8)
	s_waitcnt lgkmcnt(0)
	s_setprio 1
	s_barrier
	v_mfma_f32_16x16x32_bf16 v[134:137], v[114:117], v[162:165], v[134:137]
	v_mfma_f32_16x16x32_bf16 v[130:133], v[138:141], v[162:165], v[130:133]
	v_mfma_f32_16x16x32_bf16 v[110:113], v[114:117], v[170:173], v[110:113]
	v_mfma_f32_16x16x32_bf16 v[106:109], v[138:141], v[170:173], v[106:109]
	v_mfma_f32_16x16x32_bf16 v[94:97], v[114:117], v[178:181], v[94:97]
	v_mfma_f32_16x16x32_bf16 v[90:93], v[138:141], v[178:181], v[90:93]
	v_mfma_f32_16x16x32_bf16 v[78:81], v[114:117], v[206:209], v[78:81]
	v_mfma_f32_16x16x32_bf16 v[74:77], v[138:141], v[206:209], v[74:77]
	v_mfma_f32_16x16x32_bf16 v[134:137], v[126:129], v[166:169], v[134:137]
	v_mfma_f32_16x16x32_bf16 v[130:133], v[142:145], v[166:169], v[130:133]
	v_mfma_f32_16x16x32_bf16 v[110:113], v[126:129], v[174:177], v[110:113]
	v_mfma_f32_16x16x32_bf16 v[106:109], v[142:145], v[174:177], v[106:109]
	v_mfma_f32_16x16x32_bf16 v[94:97], v[126:129], v[182:185], v[94:97]
	v_mfma_f32_16x16x32_bf16 v[90:93], v[142:145], v[182:185], v[90:93]
	v_mfma_f32_16x16x32_bf16 v[78:81], v[126:129], v[210:213], v[78:81]
	v_mfma_f32_16x16x32_bf16 v[74:77], v[142:145], v[210:213], v[74:77]
	s_setprio 0
	s_setprio 1
	v_mfma_f32_16x16x32_bf16 v[122:125], v[146:149], v[162:165], v[122:125]
	v_mfma_f32_16x16x32_bf16 v[118:121], v[154:157], v[162:165], v[118:121]
	v_mfma_f32_16x16x32_bf16 v[102:105], v[146:149], v[170:173], v[102:105]
	v_mfma_f32_16x16x32_bf16 v[98:101], v[154:157], v[170:173], v[98:101]
	v_mfma_f32_16x16x32_bf16 v[86:89], v[146:149], v[178:181], v[86:89]
	v_mfma_f32_16x16x32_bf16 v[82:85], v[154:157], v[178:181], v[82:85]
	v_mfma_f32_16x16x32_bf16 v[70:73], v[146:149], v[206:209], v[70:73]
	v_mfma_f32_16x16x32_bf16 v[66:69], v[154:157], v[206:209], v[66:69]
	v_mfma_f32_16x16x32_bf16 v[122:125], v[150:153], v[166:169], v[122:125]
	v_mfma_f32_16x16x32_bf16 v[118:121], v[158:161], v[166:169], v[118:121]
	v_mfma_f32_16x16x32_bf16 v[102:105], v[150:153], v[174:177], v[102:105]
	v_mfma_f32_16x16x32_bf16 v[98:101], v[158:161], v[174:177], v[98:101]
	v_mfma_f32_16x16x32_bf16 v[86:89], v[150:153], v[182:185], v[86:89]
	v_mfma_f32_16x16x32_bf16 v[82:85], v[158:161], v[182:185], v[82:85]
	v_mfma_f32_16x16x32_bf16 v[70:73], v[150:153], v[210:213], v[70:73]
	v_mfma_f32_16x16x32_bf16 v[66:69], v[158:161], v[210:213], v[66:69]
	s_setprio 0
	s_add_i32 s44, s72, s52
	v_lshl_add_u64 v[214:215], v[214:215], 0, s[24:25]
	s_mov_b32 m0, s44
	ds_read_b128 v[162:165], v227 offset:49152
	ds_read_b128 v[166:169], v227 offset:50176
	ds_read_b128 v[170:173], v227 offset:51200
	ds_read_b128 v[174:177], v227 offset:52224
	ds_read_b128 v[178:181], v227 offset:53248
	ds_read_b128 v[182:185], v227 offset:54272
	ds_read_b128 v[206:209], v227 offset:55296
	ds_read_b128 v[210:213], v227 offset:56320
	global_load_lds_dwordx4 v[214:215], off
	s_add_i32 m0, s44, 0x2000
	s_add_u32 s44, s48, 0xb0080
	v_lshl_add_u64 v[214:215], v[216:217], 0, s[24:25]
	s_addc_u32 s45, s49, 0
	s_add_i32 s48, s73, s52
	global_load_lds_dwordx4 v[214:215], off
	v_lshl_add_u64 v[214:215], s[44:45], 0, v[188:189]
	s_mov_b32 m0, s48
	s_nop 0
	global_load_lds_dwordx4 v[214:215], off
	v_lshl_add_u64 v[214:215], s[44:45], 0, v[192:193]
	s_add_i32 m0, s48, 0x2000
	s_nop 0
	global_load_lds_dwordx4 v[214:215], off
	v_lshl_add_u64 v[214:215], v[218:219], 0, s[24:25]
	s_mov_b32 m0, s58
	s_nop 0
	global_load_lds_dwordx4 v[214:215], off
	v_lshl_add_u64 v[214:215], v[220:221], 0, s[24:25]
	s_mov_b32 m0, s59
	s_nop 0
	global_load_lds_dwordx4 v[214:215], off
	s_waitcnt vmcnt(8)
	s_waitcnt lgkmcnt(0)
	s_setprio 1
	s_barrier
	v_mfma_f32_16x16x32_bf16 v[62:65], v[114:117], v[162:165], v[62:65]
	v_mfma_f32_16x16x32_bf16 v[58:61], v[138:141], v[162:165], v[58:61]
	v_mfma_f32_16x16x32_bf16 v[46:49], v[114:117], v[170:173], v[46:49]
	v_mfma_f32_16x16x32_bf16 v[42:45], v[138:141], v[170:173], v[42:45]
	v_mfma_f32_16x16x32_bf16 v[30:33], v[114:117], v[178:181], v[30:33]
	v_mfma_f32_16x16x32_bf16 v[26:29], v[138:141], v[178:181], v[26:29]
	v_mfma_f32_16x16x32_bf16 v[14:17], v[114:117], v[206:209], v[14:17]
	v_mfma_f32_16x16x32_bf16 v[10:13], v[138:141], v[206:209], v[10:13]
	v_mfma_f32_16x16x32_bf16 v[62:65], v[126:129], v[166:169], v[62:65]
	v_mfma_f32_16x16x32_bf16 v[58:61], v[142:145], v[166:169], v[58:61]
	v_mfma_f32_16x16x32_bf16 v[46:49], v[126:129], v[174:177], v[46:49]
	v_mfma_f32_16x16x32_bf16 v[42:45], v[142:145], v[174:177], v[42:45]
	v_mfma_f32_16x16x32_bf16 v[30:33], v[126:129], v[182:185], v[30:33]
	v_mfma_f32_16x16x32_bf16 v[26:29], v[142:145], v[182:185], v[26:29]
	v_mfma_f32_16x16x32_bf16 v[14:17], v[126:129], v[210:213], v[14:17]
	v_mfma_f32_16x16x32_bf16 v[10:13], v[142:145], v[210:213], v[10:13]
	s_setprio 0
	s_setprio 1
	v_mfma_f32_16x16x32_bf16 v[54:57], v[146:149], v[162:165], v[54:57]
	v_mfma_f32_16x16x32_bf16 v[50:53], v[154:157], v[162:165], v[50:53]
	v_mfma_f32_16x16x32_bf16 v[38:41], v[146:149], v[170:173], v[38:41]
	v_mfma_f32_16x16x32_bf16 v[34:37], v[154:157], v[170:173], v[34:37]
	v_mfma_f32_16x16x32_bf16 v[22:25], v[146:149], v[178:181], v[22:25]
	v_mfma_f32_16x16x32_bf16 v[18:21], v[154:157], v[178:181], v[18:21]
	v_mfma_f32_16x16x32_bf16 v[6:9], v[146:149], v[206:209], v[6:9]
	v_mfma_f32_16x16x32_bf16 v[2:5], v[154:157], v[206:209], v[2:5]
	v_mfma_f32_16x16x32_bf16 v[54:57], v[150:153], v[166:169], v[54:57]
	v_mfma_f32_16x16x32_bf16 v[50:53], v[158:161], v[166:169], v[50:53]
	v_mfma_f32_16x16x32_bf16 v[38:41], v[150:153], v[174:177], v[38:41]
	v_mfma_f32_16x16x32_bf16 v[34:37], v[158:161], v[174:177], v[34:37]
	v_mfma_f32_16x16x32_bf16 v[22:25], v[150:153], v[182:185], v[22:25]
	v_mfma_f32_16x16x32_bf16 v[18:21], v[158:161], v[182:185], v[18:21]
	v_mfma_f32_16x16x32_bf16 v[6:9], v[150:153], v[210:213], v[6:9]
	v_mfma_f32_16x16x32_bf16 v[2:5], v[158:161], v[210:213], v[2:5]
	s_setprio 0
	s_add_i32 s71, s71, 2
	s_add_u32 s69, s69, 0x100
	s_addc_u32 s70, s70, 0
	s_cmp_gt_u32 s71, 41
	s_mov_b64 s[44:45], s[46:47]
	s_cbranch_scc0 .Lhb_B_p15
.Lhb_exit_p15:
	s_and_b64 vcc, exec, s[26:27]
	s_cbranch_vccz .LBB0_1912
.LBB0_1912:
	v_lshl_add_u32 v222, s67, 8, v195
	s_lshl_b32 s44, s68, 8
	s_ashr_i32 s45, s44, 31
	v_ashrrev_i32_e32 v223, 31, v222
	v_lshl_add_u64 v[114:115], s[44:45], 1, v[196:197]
	v_lshlrev_b64 v[116:117], 11, v[222:223]
	v_lshl_add_u64 v[116:117], v[114:115], 0, v[116:117]
	global_load_dwordx4 v[230:233], v[116:117], off
	global_load_dwordx4 v[234:237], v[116:117], off offset:256
	v_or_b32_e32 v220, 16, v222
	v_or_b32_e32 v218, 32, v222
	v_or_b32_e32 v216, 48, v222
	v_add_u32_e32 v214, 0x80, v222
	v_add_u32_e32 v212, 0x90, v222
	v_add_u32_e32 v210, 0xa0, v222
	v_add_u32_e32 v206, 0xb0, v222
	v_ashrrev_i32_e32 v221, 31, v220
	v_ashrrev_i32_e32 v219, 31, v218
	v_ashrrev_i32_e32 v217, 31, v216
	v_ashrrev_i32_e32 v215, 31, v214
	v_ashrrev_i32_e32 v213, 31, v212
	v_ashrrev_i32_e32 v211, 31, v210
	v_ashrrev_i32_e32 v207, 31, v206
	v_lshlrev_b64 v[116:117], 11, v[220:221]
	v_lshlrev_b64 v[126:127], 11, v[218:219]
	v_lshlrev_b64 v[128:129], 11, v[216:217]
	v_lshlrev_b64 v[138:139], 11, v[214:215]
	v_lshlrev_b64 v[140:141], 11, v[212:213]
	v_lshlrev_b64 v[142:143], 11, v[210:211]
	v_lshlrev_b64 v[144:145], 11, v[206:207]
	v_lshl_add_u64 v[116:117], v[114:115], 0, v[116:117]
	v_lshl_add_u64 v[126:127], v[114:115], 0, v[126:127]
	v_lshl_add_u64 v[128:129], v[114:115], 0, v[128:129]
	v_lshl_add_u64 v[138:139], v[114:115], 0, v[138:139]
	v_lshl_add_u64 v[140:141], v[114:115], 0, v[140:141]
	v_lshl_add_u64 v[208:209], v[114:115], 0, v[142:143]
	v_lshl_add_u64 v[114:115], v[114:115], 0, v[144:145]
	global_load_dwordx4 v[182:185], v[116:117], off
	global_load_dwordx4 v[178:181], v[116:117], off offset:256
	global_load_dwordx4 v[174:177], v[126:127], off
	global_load_dwordx4 v[170:173], v[126:127], off offset:256
	global_load_dwordx4 v[166:169], v[128:129], off
	global_load_dwordx4 v[162:165], v[128:129], off offset:256
	global_load_dwordx4 v[158:161], v[138:139], off
	global_load_dwordx4 v[154:157], v[138:139], off offset:256
	global_load_dwordx4 v[150:153], v[140:141], off
	global_load_dwordx4 v[146:149], v[140:141], off offset:256
	global_load_dwordx4 v[142:145], v[208:209], off
	s_nop 0
	global_load_dwordx4 v[138:141], v[208:209], off offset:256
	global_load_dwordx4 v[126:129], v[114:115], off
	s_nop 0
	global_load_dwordx4 v[114:117], v[114:115], off offset:256
	v_and_b32_e32 v209, 64, v228
	v_xor_b32_e32 v229, 16, v228
	v_add_u32_e32 v239, 64, v209
	v_xor_b32_e32 v238, 32, v228
	v_cmp_lt_i32_e32 vcc, v229, v239
	v_or_b32_e32 v208, s44, v194
	v_mov_b32_e32 v209, s45
	v_cndmask_b32_e32 v229, v228, v229, vcc
	v_cmp_lt_i32_e32 vcc, v238, v239
	v_lshlrev_b32_e32 v229, 2, v229
	s_waitcnt vmcnt(0)
	v_and_b32_e32 v239, 0xffff0000, v230
	v_cndmask_b32_e32 v243, v228, v238, vcc
	v_lshlrev_b32_e32 v238, 16, v230
	v_lshlrev_b32_e32 v230, 16, v231
	v_and_b32_e32 v231, 0xffff0000, v231
	v_lshlrev_b32_e32 v240, 16, v232
	v_and_b32_e32 v241, 0xffff0000, v232
	v_lshlrev_b32_e32 v232, 16, v233
	v_and_b32_e32 v233, 0xffff0000, v233
	v_pk_fma_f32 v[136:137], v[136:137], 0.5, v[230:231] op_sel_hi:[1,0,1]
	v_pk_fma_f32 v[134:135], v[134:135], 0.5, v[238:239] op_sel_hi:[1,0,1]
	v_pk_fma_f32 v[132:133], v[132:133], 0.5, v[232:233] op_sel_hi:[1,0,1]
	v_pk_fma_f32 v[130:131], v[130:131], 0.5, v[240:241] op_sel_hi:[1,0,1]
	v_mul_f32_e32 v230, v135, v135
	v_mul_f32_e32 v231, v137, v137
	v_mul_f32_e32 v232, v131, v131
	v_mul_f32_e32 v233, v133, v133
	v_fmac_f32_e32 v230, v134, v134
	v_fmac_f32_e32 v231, v136, v136
	v_fmac_f32_e32 v232, v130, v130
	v_fmac_f32_e32 v233, v132, v132
	v_lshlrev_b32_e32 v244, 16, v234
	v_and_b32_e32 v245, 0xffff0000, v234
	v_lshlrev_b32_e32 v234, 16, v235
	v_and_b32_e32 v235, 0xffff0000, v235
	v_add_f32_e32 v230, v230, v231
	v_add_f32_e32 v231, v232, v233
	v_lshlrev_b32_e32 v246, 16, v236
	v_add_f32_e32 v238, v230, v231
	v_and_b32_e32 v247, 0xffff0000, v236
	v_lshlrev_b32_e32 v230, 16, v237
	v_and_b32_e32 v231, 0xffff0000, v237
	v_pk_fma_f32 v[124:125], v[124:125], 0.5, v[234:235] op_sel_hi:[1,0,1]
	v_pk_fma_f32 v[122:123], v[122:123], 0.5, v[244:245] op_sel_hi:[1,0,1]
	v_pk_fma_f32 v[232:233], v[120:121], 0.5, v[230:231] op_sel_hi:[1,0,1]
	v_pk_fma_f32 v[230:231], v[118:119], 0.5, v[246:247] op_sel_hi:[1,0,1]
	v_mul_f32_e32 v118, v123, v123
	v_mul_f32_e32 v119, v125, v125
	v_fmac_f32_e32 v118, v122, v122
	v_fmac_f32_e32 v119, v124, v124
	v_add_f32_e32 v118, v118, v119
	v_mul_f32_e32 v119, v231, v231
	v_mul_f32_e32 v120, v233, v233
	v_fmac_f32_e32 v119, v230, v230
	v_fmac_f32_e32 v120, v232, v232
	v_add_f32_e32 v119, v119, v120
	v_add_f32_e32 v118, v118, v119
	v_add_f32_e32 v119, v238, v118
	ds_bpermute_b32 v236, v229, v119
	v_lshlrev_b64 v[120:121], 12, v[222:223]
	v_lshlrev_b32_e32 v118, 2, v243
	v_lshl_add_u64 v[120:121], s[12:13], 0, v[120:121]
	v_lshl_add_u64 v[234:235], v[208:209], 2, v[120:121]
	s_waitcnt lgkmcnt(0)
	v_add_f32_e32 v119, v119, v236
	ds_bpermute_b32 v120, v118, v119
	global_store_dwordx4 v[234:235], v[134:137], off
	global_store_dwordx4 v[234:235], v[130:133], off offset:16
	global_store_dwordx4 v[234:235], v[122:125], off offset:512
	global_store_dwordx4 v[234:235], v[230:233], off offset:528
	s_and_saveexec_b64 s[44:45], s[4:5]
	s_cbranch_execz .LBB0_1914
	v_lshl_add_u64 v[122:123], v[222:223], 2, s[16:17]
	s_waitcnt lgkmcnt(0)
	v_add_f32_e32 v119, v119, v120
	global_atomic_add_f32 v[122:123], v119, off

.LBB0_1928:
	s_or_b64 exec, exec, s[44:45]
	s_and_b64 vcc, exec, s[6:7]
	s_mov_b64 s[6:7], -1
	s_cbranch_vccnz .LBB0_1897
	s_andn2_b64 vcc, exec, s[14:15]
	s_cbranch_vccnz .LBB0_1896
	s_branch .LBB0_1896
